# GEMM loops: loop-control scalar block moved from the MFMA-segment tail into the phase-8 load segment (back-edge rotation idea, 7.11)
# baseline (speedup 1.0000x reference)
; #define PG8_STAGE(bufoff, gbase, voff) do { _Pragma("unroll") for (int _i = 0; _i < 2; ++_i) \
;         __builtin_amdgcn_global_load_lds((const unsigned*)((const char*)(gbase) + (voff)[_i]), (PG8_LAS unsigned*)(lds + (bufoff) + ldsw + _i * 8192), 16, 0, 0); } while (0)
; #define PG8_LDA(dst, b, h) do { _Pragma("unroll") for (int m = 0; m < 4; ++m) _Pragma("unroll") for (int k = 0; k < 2; ++k) dst[m][k] = *(const PG8_LAS bf16x8*)(lds + PG8_SA(b, h) + aoff + m * 2048 + k * 1024); } while (0)
; template <class Epi, class Sched, bool STAMP = false>
; __device__ __forceinline__ void gemm_phase(PG8_LAS unsigned char* lds, const Gemm g, const Sched& S, const Epi& E, unsigned long long* stamps) {
;     ...
;         for (int t = 0; t < nt; t += 2) {
;             const bool last = (t == nt - 2);
;             const char* a1 = cA + (size_t)(t + 1) * kstep;
;             const char* a2 = last ? nA : cA + (size_t)(t + 2) * kstep; const char* b2 = last ? nB : cB + (size_t)(t + 2) * kstep;
;             const char* a3 = a2 + kstep; const char* b3 = b2 + kstep;
;             if (last && has_next) S.a_ready(nxt);
;             PG8_LDB(B0, 0, 0); PG8_SCHED; PG8_LDA(At, 0, 0); PG8_STAGE(PG8_SA(1, 1), a1 + hstep, voffA);
;             PG8_WAIT_L(8); PG8_BAR; PG8_WAIT_L(0); PG8_MMA(0, 0, At, B0); PG8_BAR; PG8_SCHED;
;             PG8_LDB(B1, 0, 1); PG8_STAGE(PG8_SB(0, 0), b2, voffB);
;             PG8_BAR; PG8_WAIT_L(0); PG8_MMA(0, 1, At, B1); PG8_BAR;
;             PG8_LDA(At, 0, 1); PG8_STAGE(PG8_SA(0, 0), a2, voffA);
;             PG8_BAR; PG8_WAIT_L(0); PG8_MMA(1, 0, At, B0); PG8_BAR; PG8_SCHED;
;             PG8_STAGE(PG8_SB(0, 1), b2 + hstep, voffB);
;             PG8_WAIT_V(6); PG8_BAR; PG8_MMA(1, 1, At, B1); PG8_BAR;
;             PG8_LDB(B0, 1, 0); PG8_SCHED; PG8_LDA(At, 1, 0); PG8_STAGE(PG8_SA(0, 1), a2 + hstep, voffA);
;             PG8_WAIT_L(8); PG8_BAR; PG8_WAIT_L(0); PG8_MMA(0, 0, At, B0); PG8_BAR; PG8_SCHED;
;             PG8_LDB(B1, 1, 1); PG8_STAGE(PG8_SB(1, 0), b3, voffB);
;             PG8_BAR; PG8_WAIT_L(0); PG8_MMA(0, 1, At, B1); PG8_BAR;
;             PG8_LDA(At, 1, 1); PG8_STAGE(PG8_SA(1, 0), a3, voffA);
;             PG8_BAR; PG8_WAIT_L(0); PG8_MMA(1, 0, At, B0); PG8_BAR; PG8_SCHED;
;             PG8_STAGE(PG8_SB(1, 1), b3 + hstep, voffB);
;             PG8_WAIT_V(6); PG8_BAR; PG8_MMA(1, 1, At, B1); PG8_BAR;
;         }
.Lzp1_mid:
	ds_read_b128 v[140:143], v156
	ds_read_b128 v[166:169], v157
	ds_read_b128 v[170:173], v159
	ds_read_b128 v[174:177], v160
	s_add_u32 s14, s28, 0x44000
	s_addc_u32 s15, s29, 0
	s_mov_b32 m0, s57
	ds_read_b128 v[178:181], v146 offset:32768
	ds_read_b128 v[182:185], v146 offset:33792
	ds_read_b128 v[186:189], v146 offset:34816
	ds_read_b128 v[190:193], v146 offset:35840
	ds_read_b128 v[194:197], v146 offset:36864
	ds_read_b128 v[198:201], v146 offset:37888
	ds_read_b128 v[202:205], v146 offset:38912
	ds_read_b128 v[206:209], v146 offset:39936
	global_load_lds_dwordx4 v130, s[14:15]
	s_mov_b32 m0, s58
	s_nop 0
	global_load_lds_dwordx4 v128, s[14:15]
	s_waitcnt lgkmcnt(8)
	s_barrier
	s_waitcnt lgkmcnt(0)
	s_setprio 1
	s_waitcnt lgkmcnt(0)
	v_mfma_f32_16x16x32_bf16 v[124:127], v[140:143], v[178:181], v[124:127]
	v_mfma_f32_16x16x32_bf16 v[120:123], v[170:173], v[178:181], v[120:123]
	v_mfma_f32_16x16x32_bf16 v[108:111], v[140:143], v[186:189], v[108:111]
	v_mfma_f32_16x16x32_bf16 v[104:107], v[170:173], v[186:189], v[104:107]
	v_mfma_f32_16x16x32_bf16 v[92:95], v[140:143], v[194:197], v[92:95]
	v_mfma_f32_16x16x32_bf16 v[88:91], v[170:173], v[194:197], v[88:91]
	v_mfma_f32_16x16x32_bf16 v[76:79], v[140:143], v[202:205], v[76:79]
	v_mfma_f32_16x16x32_bf16 v[72:75], v[170:173], v[202:205], v[72:75]
	v_mfma_f32_16x16x32_bf16 v[124:127], v[166:169], v[182:185], v[124:127]
	v_mfma_f32_16x16x32_bf16 v[120:123], v[174:177], v[182:185], v[120:123]
	v_mfma_f32_16x16x32_bf16 v[108:111], v[166:169], v[190:193], v[108:111]
	v_mfma_f32_16x16x32_bf16 v[104:107], v[174:177], v[190:193], v[104:107]
	v_mfma_f32_16x16x32_bf16 v[92:95], v[166:169], v[198:201], v[92:95]
	v_mfma_f32_16x16x32_bf16 v[88:91], v[174:177], v[198:201], v[88:91]
	v_mfma_f32_16x16x32_bf16 v[76:79], v[166:169], v[206:209], v[76:79]
	v_mfma_f32_16x16x32_bf16 v[72:75], v[174:177], v[206:209], v[72:75]
	s_setprio 0
	s_barrier
	s_mov_b32 m0, s61
	ds_read_b128 v[210:213], v161
	ds_read_b128 v[214:217], v162
	ds_read_b128 v[218:221], v163
	ds_read_b128 v[222:225], v164
	s_add_u32 s100, s18, 0x80
	s_addc_u32 s101, s19, 0
	global_load_lds_dwordx4 v130, s[100:101]
	s_mov_b32 m0, s62
	s_nop 0
	global_load_lds_dwordx4 v128, s[100:101]
	s_barrier
	s_waitcnt lgkmcnt(0)
	s_setprio 1
	s_waitcnt lgkmcnt(0)
	v_mfma_f32_16x16x32_bf16 v[116:119], v[210:213], v[178:181], v[116:119]
	v_mfma_f32_16x16x32_bf16 v[112:115], v[218:221], v[178:181], v[112:115]
	v_mfma_f32_16x16x32_bf16 v[100:103], v[210:213], v[186:189], v[100:103]
	v_mfma_f32_16x16x32_bf16 v[96:99], v[218:221], v[186:189], v[96:99]
	v_mfma_f32_16x16x32_bf16 v[84:87], v[210:213], v[194:197], v[84:87]
	v_mfma_f32_16x16x32_bf16 v[80:83], v[218:221], v[194:197], v[80:83]
	v_mfma_f32_16x16x32_bf16 v[68:71], v[210:213], v[202:205], v[68:71]
	v_mfma_f32_16x16x32_bf16 v[64:67], v[218:221], v[202:205], v[64:67]
	v_mfma_f32_16x16x32_bf16 v[116:119], v[214:217], v[182:185], v[116:119]
	v_mfma_f32_16x16x32_bf16 v[112:115], v[222:225], v[182:185], v[112:115]
	v_mfma_f32_16x16x32_bf16 v[100:103], v[214:217], v[190:193], v[100:103]
	v_mfma_f32_16x16x32_bf16 v[96:99], v[222:225], v[190:193], v[96:99]
	v_mfma_f32_16x16x32_bf16 v[84:87], v[214:217], v[198:201], v[84:87]
	v_mfma_f32_16x16x32_bf16 v[80:83], v[222:225], v[198:201], v[80:83]
	v_mfma_f32_16x16x32_bf16 v[68:71], v[214:217], v[206:209], v[68:71]
	v_mfma_f32_16x16x32_bf16 v[64:67], v[222:225], v[206:209], v[64:67]
	s_setprio 0
	s_mov_b32 m0, s63
	s_barrier
	ds_read_b128 v[178:181], v146 offset:49152
	ds_read_b128 v[182:185], v146 offset:50176
	ds_read_b128 v[186:189], v146 offset:51200
	ds_read_b128 v[190:193], v146 offset:52224
	ds_read_b128 v[194:197], v146 offset:53248
	ds_read_b128 v[198:201], v146 offset:54272
	ds_read_b128 v[202:205], v146 offset:55296
	ds_read_b128 v[206:209], v146 offset:56320
	s_add_u32 s100, s28, 0x80
	s_addc_u32 s101, s29, 0
	global_load_lds_dwordx4 v130, s[100:101]
	s_mov_b32 m0, s64
	s_nop 0
	global_load_lds_dwordx4 v128, s[100:101]
	s_barrier
	s_waitcnt lgkmcnt(0)
	s_setprio 1
	s_waitcnt lgkmcnt(0)
	v_mfma_f32_16x16x32_bf16 v[60:63], v[140:143], v[178:181], v[60:63]
	v_mfma_f32_16x16x32_bf16 v[56:59], v[170:173], v[178:181], v[56:59]
	v_mfma_f32_16x16x32_bf16 v[44:47], v[140:143], v[186:189], v[44:47]
	v_mfma_f32_16x16x32_bf16 v[40:43], v[170:173], v[186:189], v[40:43]
	v_mfma_f32_16x16x32_bf16 v[28:31], v[140:143], v[194:197], v[28:31]
	v_mfma_f32_16x16x32_bf16 v[24:27], v[170:173], v[194:197], v[24:27]
	v_mfma_f32_16x16x32_bf16 v[12:15], v[140:143], v[202:205], v[12:15]
	v_mfma_f32_16x16x32_bf16 v[8:11], v[170:173], v[202:205], v[8:11]
	v_mfma_f32_16x16x32_bf16 v[60:63], v[166:169], v[182:185], v[60:63]
	v_mfma_f32_16x16x32_bf16 v[56:59], v[174:177], v[182:185], v[56:59]
	v_mfma_f32_16x16x32_bf16 v[44:47], v[166:169], v[190:193], v[44:47]
	v_mfma_f32_16x16x32_bf16 v[40:43], v[174:177], v[190:193], v[40:43]
	v_mfma_f32_16x16x32_bf16 v[28:31], v[166:169], v[198:201], v[28:31]
	v_mfma_f32_16x16x32_bf16 v[24:27], v[174:177], v[198:201], v[24:27]
	v_mfma_f32_16x16x32_bf16 v[12:15], v[166:169], v[206:209], v[12:15]
	v_mfma_f32_16x16x32_bf16 v[8:11], v[174:177], v[206:209], v[8:11]
	s_setprio 0
	s_barrier
	s_add_u32 s14, s18, 0x44080
	s_addc_u32 s15, s19, 0
	s_mov_b32 m0, s65
	s_nop 0
	global_load_lds_dwordx4 v130, s[14:15]
	s_mov_b32 m0, s66
	s_nop 0
	global_load_lds_dwordx4 v128, s[14:15]
	s_add_i32 s77, s77, 2
	s_add_u32 s75, s75, 0x100
	s_addc_u32 s76, s76, 0
	s_cmp_gt_u32 s77, 13
	s_mov_b64 s[14:15], s[16:17]
	s_waitcnt vmcnt(6)
	s_barrier
; DI float ex2(float x) { return __builtin_amdgcn_exp2f(x); }
; #define PG8_STAGE(bufoff, gbase, voff) do { _Pragma("unroll") for (int _i = 0; _i < 2; ++_i) \
;         __builtin_amdgcn_global_load_lds((const unsigned*)((const char*)(gbase) + (voff)[_i]), (PG8_LAS unsigned*)(lds + (bufoff) + ldsw + _i * 8192), 16, 0, 0); } while (0)
; #define PG8_LDA(dst, b, h) do { _Pragma("unroll") for (int m = 0; m < 4; ++m) _Pragma("unroll") for (int k = 0; k < 2; ++k) dst[m][k] = *(const PG8_LAS bf16x8*)(lds + PG8_SA(b, h) + aoff + m * 2048 + k * 1024); } while (0)
; #define PG8_WAIT_V(n) asm volatile("s_waitcnt vmcnt(" #n ")" ::: "memory")
; #define PG8_BAR __builtin_amdgcn_s_barrier()
;     DI void operator()(const f32x4 (&acc)[2][2][4][2], const Unit& u, int wr, int wc, int fr, int fq) const {
;         const int row0 = u.pm * BM + wr * 64 + fr, hcol0 = ((u.pn * BM + wc * 32) >> 1) + 4 * fq;
; #pragma unroll
;         for (int ai = 0; ai < 2; ++ai)
; #pragma unroll
;             for (int m = 0; m < 4; ++m) { u16* rowp = O + (size_t)(row0 + ai * HALF + m * 16) * ldc + hcol0;
; #pragma unroll
;                 for (int bj = 0; bj < 2; ++bj) { const f32x4 g = acc[ai][bj][m][0], up = acc[ai][bj][m][1]; float r[4];
; #pragma unroll
;                     for (int j = 0; j < 4; ++j) r[j] = g[j] * up[j] * __builtin_amdgcn_rcpf(1.f + ex2(-LOG2E * g[j]));
;                     uint2 w = {pack2(r[0], r[1]), pack2(r[2], r[3])}; *(uint2*)(rowp + bj * (HALF / 2)) = w; } }
; template <class Epi, class Sched, bool STAMP = false>
; __device__ __forceinline__ void gemm_phase(PG8_LAS unsigned char* lds, const Gemm g, const Sched& S, const Epi& E, unsigned long long* stamps) {
;     ...
;             PG8_WAIT_V(6); PG8_BAR; PG8_MMA(1, 1, At, B1); PG8_BAR;
;             PG8_LDB(B0, 1, 0); PG8_SCHED; PG8_LDA(At, 1, 0); PG8_STAGE(PG8_SA(0, 1), a2 + hstep, voffA);
;             PG8_WAIT_L(8); PG8_BAR; PG8_WAIT_L(0); PG8_MMA(0, 0, At, B0); PG8_BAR; PG8_SCHED;
;             PG8_LDB(B1, 1, 1); PG8_STAGE(PG8_SB(1, 0), b3, voffB);
;             PG8_BAR; PG8_WAIT_L(0); PG8_MMA(0, 1, At, B1); PG8_BAR;
;             PG8_LDA(At, 1, 1); PG8_STAGE(PG8_SA(1, 0), a3, voffA);
;             PG8_BAR; PG8_WAIT_L(0); PG8_MMA(1, 0, At, B0); PG8_BAR; PG8_SCHED;
;             PG8_STAGE(PG8_SB(1, 1), b3 + hstep, voffB);
;             PG8_WAIT_V(6); PG8_BAR; PG8_MMA(1, 1, At, B1); PG8_BAR;
;         }
	s_setprio 1
	v_mfma_f32_16x16x32_bf16 v[52:55], v[210:213], v[178:181], v[52:55]
	v_mfma_f32_16x16x32_bf16 v[48:51], v[218:221], v[178:181], v[48:51]
	v_mfma_f32_16x16x32_bf16 v[36:39], v[210:213], v[186:189], v[36:39]
	v_mfma_f32_16x16x32_bf16 v[32:35], v[218:221], v[186:189], v[32:35]
	v_mfma_f32_16x16x32_bf16 v[20:23], v[210:213], v[194:197], v[20:23]
	v_mfma_f32_16x16x32_bf16 v[16:19], v[218:221], v[194:197], v[16:19]
	v_mfma_f32_16x16x32_bf16 v[4:7], v[210:213], v[202:205], v[4:7]
	v_mfma_f32_16x16x32_bf16 v[0:3], v[218:221], v[202:205], v[0:3]
	v_mfma_f32_16x16x32_bf16 v[52:55], v[214:217], v[182:185], v[52:55]
	v_mfma_f32_16x16x32_bf16 v[48:51], v[222:225], v[182:185], v[48:51]
	v_mfma_f32_16x16x32_bf16 v[36:39], v[214:217], v[190:193], v[36:39]
	v_mfma_f32_16x16x32_bf16 v[32:35], v[222:225], v[190:193], v[32:35]
	v_mfma_f32_16x16x32_bf16 v[20:23], v[214:217], v[198:201], v[20:23]
	v_mfma_f32_16x16x32_bf16 v[16:19], v[222:225], v[198:201], v[16:19]
	v_mfma_f32_16x16x32_bf16 v[4:7], v[214:217], v[206:209], v[4:7]
	v_mfma_f32_16x16x32_bf16 v[0:3], v[222:225], v[206:209], v[0:3]
	s_setprio 0
	s_barrier
	s_cbranch_scc0 .LBB0_63
	v_exp_f32_e64 v168, -v124
	v_exp_f32_e64 v169, -v125
	v_exp_f32_e64 v170, -v126
	v_exp_f32_e64 v171, -v127
	v_add_f32_e32 v168, 1.0, v168
	v_add_f32_e32 v169, 1.0, v169
	v_add_f32_e32 v170, 1.0, v170
	v_add_f32_e32 v171, 1.0, v171
	v_rcp_f32_e32 v168, v168
	v_rcp_f32_e32 v169, v169
	v_rcp_f32_e32 v170, v170
	v_rcp_f32_e32 v171, v171
	s_lshl_b32 s10, s74, 8
	v_pk_mul_f32 v[122:123], v[126:127], v[122:123]
	v_pk_mul_f32 v[120:121], v[124:125], v[120:121]
	s_or_b32 s10, s10, s60
	v_pk_mul_f32 v[120:121], v[120:121], v[168:169]
	v_pk_mul_f32 v[122:123], v[122:123], v[170:171]
	s_ashr_i32 s10, s10, 1
	v_cvt_pk_bf16_f32 v120, v120, v121
	v_cvt_pk_bf16_f32 v121, v122, v123
	v_or_b32_e32 v140, s10, v147
	v_exp_f32_e64 v122, -v116
	v_exp_f32_e64 v123, -v117
	v_lshl_add_u32 v165, s73, 8, v145
	v_ashrrev_i32_e32 v141, 31, v140
	v_mov_b64_e32 v[142:143], s[12:13]
	v_mad_i64_i32 v[166:167], s[14:15], v165, s70, v[142:143]
	v_lshlrev_b64 v[140:141], 1, v[140:141]
	v_lshl_add_u64 v[166:167], v[166:167], 0, v[140:141]
	global_store_dwordx2 v[166:167], v[120:121], off
	v_add_f32_e32 v120, 1.0, v122
	v_add_f32_e32 v121, 1.0, v123
	v_exp_f32_e64 v122, -v118
	v_exp_f32_e64 v123, -v119
	v_rcp_f32_e32 v120, v120
	v_rcp_f32_e32 v121, v121
	v_add_f32_e32 v122, 1.0, v122
	v_add_f32_e32 v123, 1.0, v123
	v_rcp_f32_e32 v122, v122
	v_rcp_f32_e32 v123, v123
	v_pk_mul_f32 v[114:115], v[118:119], v[114:115]
	v_pk_mul_f32 v[112:113], v[116:117], v[112:113]
	v_pk_mul_f32 v[112:113], v[112:113], v[120:121]
	v_pk_mul_f32 v[114:115], v[114:115], v[122:123]
	v_cvt_pk_bf16_f32 v112, v112, v113
	v_cvt_pk_bf16_f32 v113, v114, v115
	v_exp_f32_e64 v114, -v108
	v_exp_f32_e64 v115, -v109
	v_exp_f32_e64 v116, -v110
	v_exp_f32_e64 v117, -v111
	v_add_f32_e32 v114, 1.0, v114
	v_add_f32_e32 v115, 1.0, v115
	v_add_f32_e32 v116, 1.0, v116
	v_add_f32_e32 v117, 1.0, v117
	v_rcp_f32_e32 v114, v114
	v_rcp_f32_e32 v115, v115
	v_rcp_f32_e32 v116, v116
	v_rcp_f32_e32 v117, v117
	v_pk_mul_f32 v[106:107], v[110:111], v[106:107]
	v_pk_mul_f32 v[104:105], v[108:109], v[104:105]
	global_store_dwordx2 v[166:167], v[112:113], off offset:128
	v_pk_mul_f32 v[104:105], v[104:105], v[114:115]
	v_pk_mul_f32 v[106:107], v[106:107], v[116:117]
	v_cvt_pk_bf16_f32 v104, v104, v105
	v_cvt_pk_bf16_f32 v105, v106, v107
	v_exp_f32_e64 v106, -v100
	v_exp_f32_e64 v107, -v101
	v_or_b32_e32 v112, 16, v165
	v_mad_i64_i32 v[112:113], s[14:15], v112, s70, v[142:143]
	v_lshl_add_u64 v[112:113], v[112:113], 0, v[140:141]
	global_store_dwordx2 v[112:113], v[104:105], off
	v_add_f32_e32 v104, 1.0, v106
	v_add_f32_e32 v105, 1.0, v107
	v_exp_f32_e64 v106, -v102
	v_exp_f32_e64 v107, -v103
	v_rcp_f32_e32 v104, v104
	v_rcp_f32_e32 v105, v105
	v_add_f32_e32 v106, 1.0, v106
	v_add_f32_e32 v107, 1.0, v107
	v_rcp_f32_e32 v106, v106
	v_rcp_f32_e32 v107, v107
	v_pk_mul_f32 v[98:99], v[102:103], v[98:99]
	v_pk_mul_f32 v[96:97], v[100:101], v[96:97]
	v_pk_mul_f32 v[96:97], v[96:97], v[104:105]
	v_pk_mul_f32 v[98:99], v[98:99], v[106:107]
	v_cvt_pk_bf16_f32 v96, v96, v97
	v_cvt_pk_bf16_f32 v97, v98, v99
	v_exp_f32_e64 v98, -v92
	v_exp_f32_e64 v99, -v93
	v_exp_f32_e64 v100, -v94
	v_exp_f32_e64 v101, -v95
	v_add_f32_e32 v98, 1.0, v98
	v_add_f32_e32 v99, 1.0, v99
	v_add_f32_e32 v100, 1.0, v100
	v_add_f32_e32 v101, 1.0, v101
	v_rcp_f32_e32 v98, v98
	v_rcp_f32_e32 v99, v99
	v_rcp_f32_e32 v100, v100
	v_rcp_f32_e32 v101, v101
	v_pk_mul_f32 v[90:91], v[94:95], v[90:91]
	v_pk_mul_f32 v[88:89], v[92:93], v[88:89]
	global_store_dwordx2 v[112:113], v[96:97], off offset:128
	v_pk_mul_f32 v[88:89], v[88:89], v[98:99]
	v_pk_mul_f32 v[90:91], v[90:91], v[100:101]
	v_cvt_pk_bf16_f32 v88, v88, v89
	v_cvt_pk_bf16_f32 v89, v90, v91
	v_exp_f32_e64 v90, -v84
	v_exp_f32_e64 v91, -v85
	v_or_b32_e32 v96, 32, v165
	v_mad_i64_i32 v[96:97], s[14:15], v96, s70, v[142:143]
	v_lshl_add_u64 v[96:97], v[96:97], 0, v[140:141]
	global_store_dwordx2 v[96:97], v[88:89], off
	v_add_f32_e32 v88, 1.0, v90
	v_add_f32_e32 v89, 1.0, v91
	v_exp_f32_e64 v90, -v86
	v_exp_f32_e64 v91, -v87
	v_rcp_f32_e32 v88, v88
	v_rcp_f32_e32 v89, v89
	v_add_f32_e32 v90, 1.0, v90
	v_add_f32_e32 v91, 1.0, v91
	v_rcp_f32_e32 v90, v90
	v_rcp_f32_e32 v91, v91
	v_pk_mul_f32 v[82:83], v[86:87], v[82:83]
	v_pk_mul_f32 v[80:81], v[84:85], v[80:81]
	v_pk_mul_f32 v[80:81], v[80:81], v[88:89]
	v_pk_mul_f32 v[82:83], v[82:83], v[90:91]
	v_cvt_pk_bf16_f32 v80, v80, v81
	v_cvt_pk_bf16_f32 v81, v82, v83
	v_exp_f32_e64 v82, -v76
	v_exp_f32_e64 v83, -v77
	v_exp_f32_e64 v84, -v78
; DI float ex2(float x) { return __builtin_amdgcn_exp2f(x); }
; #define PG8_STAMP() do { if (STAMP && wid == 0 && nts < 64) { const unsigned long long _c = 0ull; \
;         ts_lo = (lane == nts) ? (int)(unsigned)_c : ts_lo; ts_hi = (lane == nts) ? (int)(unsigned)(_c >> 32) : ts_hi; ++nts; } } while (0)
;     DI void operator()(const f32x4 (&acc)[2][2][4][2], const Unit& u, int wr, int wc, int fr, int fq) const {
;         const int row0 = u.pm * BM + wr * 64 + fr, hcol0 = ((u.pn * BM + wc * 32) >> 1) + 4 * fq;
; #pragma unroll
;         for (int ai = 0; ai < 2; ++ai)
; #pragma unroll
;             for (int m = 0; m < 4; ++m) { u16* rowp = O + (size_t)(row0 + ai * HALF + m * 16) * ldc + hcol0;
; #pragma unroll
;                 for (int bj = 0; bj < 2; ++bj) { const f32x4 g = acc[ai][bj][m][0], up = acc[ai][bj][m][1]; float r[4];
; #pragma unroll
;                     for (int j = 0; j < 4; ++j) r[j] = g[j] * up[j] * __builtin_amdgcn_rcpf(1.f + ex2(-LOG2E * g[j]));
;                     uint2 w = {pack2(r[0], r[1]), pack2(r[2], r[3])}; *(uint2*)(rowp + bj * (HALF / 2)) = w; } }
; template <class Epi, class Sched, bool STAMP = false>
; __device__ __forceinline__ void gemm_phase(PG8_LAS unsigned char* lds, const Gemm g, const Sched& S, const Epi& E, unsigned long long* stamps) {
;     ...
;         if constexpr (!Epi::AFTER_DRAIN) { E(acc, cur, wr, wc, fr, fq); S.done(cur); }
;         PG8_STAMP();
;         if (!has_next) break;
; #pragma unroll
;         for (int a = 0; a < 2; ++a)
; #pragma unroll
;             for (int b = 0; b < 2; ++b)
; #pragma unroll
;                 for (int m = 0; m < 4; ++m)
; #pragma unroll
;                     for (int n = 0; n < 2; ++n) acc[a][b][m][n] = (f32x4){0.f, 0.f, 0.f, 0.f};
;         cur = nxt; cA = nA; cB = nB; ++ui;
	v_exp_f32_e64 v85, -v79
	v_add_f32_e32 v82, 1.0, v82
	v_add_f32_e32 v83, 1.0, v83
	v_add_f32_e32 v84, 1.0, v84
	v_add_f32_e32 v85, 1.0, v85
	v_rcp_f32_e32 v82, v82
	v_rcp_f32_e32 v83, v83
	v_rcp_f32_e32 v84, v84
	v_rcp_f32_e32 v85, v85
	v_pk_mul_f32 v[74:75], v[78:79], v[74:75]
	v_pk_mul_f32 v[72:73], v[76:77], v[72:73]
	global_store_dwordx2 v[96:97], v[80:81], off offset:128
	v_pk_mul_f32 v[72:73], v[72:73], v[82:83]
	v_pk_mul_f32 v[74:75], v[74:75], v[84:85]
	v_cvt_pk_bf16_f32 v72, v72, v73
	v_cvt_pk_bf16_f32 v73, v74, v75
	v_exp_f32_e64 v74, -v68
	v_exp_f32_e64 v75, -v69
	v_or_b32_e32 v80, 48, v165
	v_mad_i64_i32 v[80:81], s[14:15], v80, s70, v[142:143]
	v_lshl_add_u64 v[80:81], v[80:81], 0, v[140:141]
	global_store_dwordx2 v[80:81], v[72:73], off
	v_add_f32_e32 v72, 1.0, v74
	v_add_f32_e32 v73, 1.0, v75
	v_exp_f32_e64 v74, -v70
	v_exp_f32_e64 v75, -v71
	v_rcp_f32_e32 v72, v72
	v_rcp_f32_e32 v73, v73
	v_add_f32_e32 v74, 1.0, v74
	v_add_f32_e32 v75, 1.0, v75
	v_rcp_f32_e32 v74, v74
	v_rcp_f32_e32 v75, v75
	v_pk_mul_f32 v[66:67], v[70:71], v[66:67]
	v_pk_mul_f32 v[64:65], v[68:69], v[64:65]
	v_pk_mul_f32 v[64:65], v[64:65], v[72:73]
	v_pk_mul_f32 v[66:67], v[66:67], v[74:75]
	v_cvt_pk_bf16_f32 v64, v64, v65
	v_cvt_pk_bf16_f32 v65, v66, v67
	v_exp_f32_e64 v66, -v60
	v_exp_f32_e64 v67, -v61
	v_exp_f32_e64 v68, -v62
	v_exp_f32_e64 v69, -v63
	v_add_f32_e32 v66, 1.0, v66
	v_add_f32_e32 v67, 1.0, v67
	v_add_f32_e32 v68, 1.0, v68
	v_add_f32_e32 v69, 1.0, v69
	v_rcp_f32_e32 v66, v66
	v_rcp_f32_e32 v67, v67
	v_rcp_f32_e32 v68, v68
	v_rcp_f32_e32 v69, v69
	v_pk_mul_f32 v[58:59], v[62:63], v[58:59]
	v_pk_mul_f32 v[56:57], v[60:61], v[56:57]
	global_store_dwordx2 v[80:81], v[64:65], off offset:128
	v_pk_mul_f32 v[56:57], v[56:57], v[66:67]
	v_pk_mul_f32 v[58:59], v[58:59], v[68:69]
	v_cvt_pk_bf16_f32 v56, v56, v57
	v_cvt_pk_bf16_f32 v57, v58, v59
	v_exp_f32_e64 v58, -v52
	v_exp_f32_e64 v59, -v53
	v_add_u32_e32 v64, 0x80, v165
	v_mad_i64_i32 v[64:65], s[14:15], v64, s70, v[142:143]
	v_lshl_add_u64 v[64:65], v[64:65], 0, v[140:141]
	global_store_dwordx2 v[64:65], v[56:57], off
	v_add_f32_e32 v56, 1.0, v58
	v_add_f32_e32 v57, 1.0, v59
	v_exp_f32_e64 v58, -v54
	v_exp_f32_e64 v59, -v55
	v_rcp_f32_e32 v56, v56
	v_rcp_f32_e32 v57, v57
	v_add_f32_e32 v58, 1.0, v58
	v_add_f32_e32 v59, 1.0, v59
	v_rcp_f32_e32 v58, v58
	v_rcp_f32_e32 v59, v59
	v_pk_mul_f32 v[50:51], v[54:55], v[50:51]
	v_pk_mul_f32 v[48:49], v[52:53], v[48:49]
	v_pk_mul_f32 v[48:49], v[48:49], v[56:57]
	v_pk_mul_f32 v[50:51], v[50:51], v[58:59]
	v_cvt_pk_bf16_f32 v48, v48, v49
	v_cvt_pk_bf16_f32 v49, v50, v51
	v_exp_f32_e64 v50, -v44
	v_exp_f32_e64 v51, -v45
	v_exp_f32_e64 v52, -v46
	v_exp_f32_e64 v53, -v47
	v_add_f32_e32 v50, 1.0, v50
	v_add_f32_e32 v51, 1.0, v51
	v_add_f32_e32 v52, 1.0, v52
	v_add_f32_e32 v53, 1.0, v53
	v_rcp_f32_e32 v50, v50
	v_rcp_f32_e32 v51, v51
	v_rcp_f32_e32 v52, v52
	v_rcp_f32_e32 v53, v53
	v_pk_mul_f32 v[42:43], v[46:47], v[42:43]
	v_pk_mul_f32 v[40:41], v[44:45], v[40:41]
	global_store_dwordx2 v[64:65], v[48:49], off offset:128
	v_pk_mul_f32 v[40:41], v[40:41], v[50:51]
	v_pk_mul_f32 v[42:43], v[42:43], v[52:53]
	v_cvt_pk_bf16_f32 v40, v40, v41
	v_cvt_pk_bf16_f32 v41, v42, v43
	v_exp_f32_e64 v42, -v36
	v_exp_f32_e64 v43, -v37
	v_add_u32_e32 v48, 0x90, v165
	v_mad_i64_i32 v[48:49], s[14:15], v48, s70, v[142:143]
	v_lshl_add_u64 v[48:49], v[48:49], 0, v[140:141]
	global_store_dwordx2 v[48:49], v[40:41], off
	v_add_f32_e32 v40, 1.0, v42
	v_add_f32_e32 v41, 1.0, v43
	v_exp_f32_e64 v42, -v38
	v_exp_f32_e64 v43, -v39
	v_rcp_f32_e32 v40, v40
	v_rcp_f32_e32 v41, v41
	v_add_f32_e32 v42, 1.0, v42
	v_add_f32_e32 v43, 1.0, v43
	v_rcp_f32_e32 v42, v42
	v_rcp_f32_e32 v43, v43
	v_pk_mul_f32 v[34:35], v[38:39], v[34:35]
	v_pk_mul_f32 v[32:33], v[36:37], v[32:33]
	v_pk_mul_f32 v[32:33], v[32:33], v[40:41]
	v_pk_mul_f32 v[34:35], v[34:35], v[42:43]
	v_cvt_pk_bf16_f32 v32, v32, v33
	v_cvt_pk_bf16_f32 v33, v34, v35
	v_exp_f32_e64 v34, -v28
	v_exp_f32_e64 v35, -v29
	v_exp_f32_e64 v36, -v30
	v_exp_f32_e64 v37, -v31
	v_add_f32_e32 v34, 1.0, v34
	v_add_f32_e32 v35, 1.0, v35
	v_add_f32_e32 v36, 1.0, v36
	v_add_f32_e32 v37, 1.0, v37
	v_rcp_f32_e32 v34, v34
	v_rcp_f32_e32 v35, v35
	v_rcp_f32_e32 v36, v36
	v_rcp_f32_e32 v37, v37
	v_pk_mul_f32 v[26:27], v[30:31], v[26:27]
	v_pk_mul_f32 v[24:25], v[28:29], v[24:25]
	global_store_dwordx2 v[48:49], v[32:33], off offset:128
	v_pk_mul_f32 v[24:25], v[24:25], v[34:35]
	v_pk_mul_f32 v[26:27], v[26:27], v[36:37]
	v_cvt_pk_bf16_f32 v24, v24, v25
	v_cvt_pk_bf16_f32 v25, v26, v27
	v_exp_f32_e64 v26, -v20
	v_exp_f32_e64 v27, -v21
	v_add_u32_e32 v32, 0xa0, v165
	v_mad_i64_i32 v[32:33], s[14:15], v32, s70, v[142:143]
	v_lshl_add_u64 v[32:33], v[32:33], 0, v[140:141]
	global_store_dwordx2 v[32:33], v[24:25], off
	v_add_f32_e32 v24, 1.0, v26
	v_add_f32_e32 v25, 1.0, v27
	v_exp_f32_e64 v26, -v22
	v_exp_f32_e64 v27, -v23
	v_rcp_f32_e32 v24, v24
	v_rcp_f32_e32 v25, v25
	v_add_f32_e32 v26, 1.0, v26
	v_add_f32_e32 v27, 1.0, v27
	v_rcp_f32_e32 v26, v26
	v_rcp_f32_e32 v27, v27
	v_pk_mul_f32 v[18:19], v[22:23], v[18:19]
	v_pk_mul_f32 v[16:17], v[20:21], v[16:17]
	v_pk_mul_f32 v[16:17], v[16:17], v[24:25]
	v_pk_mul_f32 v[18:19], v[18:19], v[26:27]
	v_cvt_pk_bf16_f32 v16, v16, v17
	v_cvt_pk_bf16_f32 v17, v18, v19
	v_exp_f32_e64 v18, -v12
	v_exp_f32_e64 v19, -v13
	v_exp_f32_e64 v20, -v14
	v_exp_f32_e64 v21, -v15
	v_add_f32_e32 v18, 1.0, v18
	v_add_f32_e32 v19, 1.0, v19
	v_add_f32_e32 v20, 1.0, v20
	v_add_f32_e32 v21, 1.0, v21
	v_rcp_f32_e32 v18, v18
	v_rcp_f32_e32 v19, v19
	v_rcp_f32_e32 v20, v20
	v_rcp_f32_e32 v21, v21
	v_pk_mul_f32 v[10:11], v[14:15], v[10:11]
	v_pk_mul_f32 v[8:9], v[12:13], v[8:9]
	global_store_dwordx2 v[32:33], v[16:17], off offset:128
	v_pk_mul_f32 v[8:9], v[8:9], v[18:19]
	v_pk_mul_f32 v[10:11], v[10:11], v[20:21]
	v_cvt_pk_bf16_f32 v8, v8, v9
	v_cvt_pk_bf16_f32 v9, v10, v11
	v_exp_f32_e64 v10, -v4
	v_exp_f32_e64 v11, -v5
	v_add_u32_e32 v16, 0xb0, v165
	v_mad_i64_i32 v[16:17], s[14:15], v16, s70, v[142:143]
	v_lshl_add_u64 v[16:17], v[16:17], 0, v[140:141]
	global_store_dwordx2 v[16:17], v[8:9], off
	v_add_f32_e32 v8, 1.0, v10
	v_add_f32_e32 v9, 1.0, v11
	v_exp_f32_e64 v10, -v6
	v_exp_f32_e64 v11, -v7
	v_rcp_f32_e32 v8, v8
	v_rcp_f32_e32 v9, v9
	v_add_f32_e32 v10, 1.0, v10
	v_add_f32_e32 v11, 1.0, v11
	v_rcp_f32_e32 v10, v10
	v_rcp_f32_e32 v11, v11
	v_pk_mul_f32 v[2:3], v[6:7], v[2:3]
	v_pk_mul_f32 v[0:1], v[4:5], v[0:1]
	s_and_b64 vcc, exec, s[2:3]
	v_pk_mul_f32 v[0:1], v[0:1], v[8:9]
	v_pk_mul_f32 v[2:3], v[2:3], v[10:11]
	v_cvt_pk_bf16_f32 v0, v0, v1
	v_cvt_pk_bf16_f32 v1, v2, v3
	s_mov_b32 s74, s71
	s_mov_b32 s73, s72
	s_mov_b64 s[16:17], s[0:1]
	s_mov_b64 s[14:15], s[4:5]
	global_store_dwordx2 v[16:17], v[0:1], off offset:128
	s_cbranch_vccz .LBB0_56
	s_branch .Lgu1_done

; #define PG8_STAGE(bufoff, gbase, voff) do { _Pragma("unroll") for (int _i = 0; _i < 2; ++_i) \
;         __builtin_amdgcn_global_load_lds((const unsigned*)((const char*)(gbase) + (voff)[_i]), (PG8_LAS unsigned*)(lds + (bufoff) + ldsw + _i * 8192), 16, 0, 0); } while (0)
; #define PG8_LDA(dst, b, h) do { _Pragma("unroll") for (int m = 0; m < 4; ++m) _Pragma("unroll") for (int k = 0; k < 2; ++k) dst[m][k] = *(const PG8_LAS bf16x8*)(lds + PG8_SA(b, h) + aoff + m * 2048 + k * 1024); } while (0)
; template <class Epi, class Sched, bool STAMP = false>
; __device__ __forceinline__ void gemm_phase(PG8_LAS unsigned char* lds, const Gemm g, const Sched& S, const Epi& E, unsigned long long* stamps) {
;     ...
;         for (int t = 0; t < nt; t += 2) {
;             const bool last = (t == nt - 2);
;             const char* a1 = cA + (size_t)(t + 1) * kstep;
;             const char* a2 = last ? nA : cA + (size_t)(t + 2) * kstep; const char* b2 = last ? nB : cB + (size_t)(t + 2) * kstep;
;             const char* a3 = a2 + kstep; const char* b3 = b2 + kstep;
;             if (last && has_next) S.a_ready(nxt);
;             PG8_LDB(B0, 0, 0); PG8_SCHED; PG8_LDA(At, 0, 0); PG8_STAGE(PG8_SA(1, 1), a1 + hstep, voffA);
;             PG8_WAIT_L(8); PG8_BAR; PG8_WAIT_L(0); PG8_MMA(0, 0, At, B0); PG8_BAR; PG8_SCHED;
;             PG8_LDB(B1, 0, 1); PG8_STAGE(PG8_SB(0, 0), b2, voffB);
;             PG8_BAR; PG8_WAIT_L(0); PG8_MMA(0, 1, At, B1); PG8_BAR;
;             PG8_LDA(At, 0, 1); PG8_STAGE(PG8_SA(0, 0), a2, voffA);
;             PG8_BAR; PG8_WAIT_L(0); PG8_MMA(1, 0, At, B0); PG8_BAR; PG8_SCHED;
;             PG8_STAGE(PG8_SB(0, 1), b2 + hstep, voffB);
;             PG8_WAIT_V(6); PG8_BAR; PG8_MMA(1, 1, At, B1); PG8_BAR;
;             PG8_LDB(B0, 1, 0); PG8_SCHED; PG8_LDA(At, 1, 0); PG8_STAGE(PG8_SA(0, 1), a2 + hstep, voffA);
;             PG8_WAIT_L(8); PG8_BAR; PG8_WAIT_L(0); PG8_MMA(0, 0, At, B0); PG8_BAR; PG8_SCHED;
;             PG8_LDB(B1, 1, 1); PG8_STAGE(PG8_SB(1, 0), b3, voffB);
;             PG8_BAR; PG8_WAIT_L(0); PG8_MMA(0, 1, At, B1); PG8_BAR;
;             PG8_LDA(At, 1, 1); PG8_STAGE(PG8_SA(1, 0), a3, voffA);
;             PG8_BAR; PG8_WAIT_L(0); PG8_MMA(1, 0, At, B0); PG8_BAR; PG8_SCHED;
;             PG8_STAGE(PG8_SB(1, 1), b3 + hstep, voffB);
;             PG8_WAIT_V(6); PG8_BAR; PG8_MMA(1, 1, At, B1); PG8_BAR;
;         }
.Lgu1_half_loop:
	ds_read_b128 v[140:143], v148
	ds_read_b128 v[166:169], v149
	ds_read_b128 v[170:173], v150
	ds_read_b128 v[174:177], v151
	s_add_u32 s16, s14, 0x100
	s_addc_u32 s17, s15, 0
	s_cmp_eq_u32 s77, 12
	s_cselect_b32 s29, s5, s17
	s_cselect_b32 s28, s4, s16
	s_cselect_b32 s19, s1, s76
	s_cselect_b32 s18, s0, s75
	s_mov_b32 m0, s68
	ds_read_b128 v[178:181], v146
	ds_read_b128 v[182:185], v146 offset:1024
	ds_read_b128 v[186:189], v146 offset:2048
	ds_read_b128 v[190:193], v146 offset:3072
	ds_read_b128 v[194:197], v146 offset:4096
	ds_read_b128 v[198:201], v146 offset:5120
	ds_read_b128 v[202:205], v146 offset:6144
	ds_read_b128 v[206:209], v146 offset:7168
	global_load_lds_dwordx4 v132, s[14:15]
	s_mov_b32 m0, s69
	s_nop 0
	global_load_lds_dwordx4 v134, s[14:15]
	s_waitcnt lgkmcnt(8)
	s_barrier
	s_waitcnt lgkmcnt(0)
	s_setprio 1
	s_waitcnt lgkmcnt(0)
	v_mfma_f32_16x16x32_bf16 v[124:127], v[140:143], v[178:181], v[124:127]
	v_mfma_f32_16x16x32_bf16 v[120:123], v[170:173], v[178:181], v[120:123]
	v_mfma_f32_16x16x32_bf16 v[108:111], v[140:143], v[186:189], v[108:111]
	v_mfma_f32_16x16x32_bf16 v[104:107], v[170:173], v[186:189], v[104:107]
	v_mfma_f32_16x16x32_bf16 v[92:95], v[140:143], v[194:197], v[92:95]
	v_mfma_f32_16x16x32_bf16 v[88:91], v[170:173], v[194:197], v[88:91]
	v_mfma_f32_16x16x32_bf16 v[76:79], v[140:143], v[202:205], v[76:79]
	v_mfma_f32_16x16x32_bf16 v[72:75], v[170:173], v[202:205], v[72:75]
	v_mfma_f32_16x16x32_bf16 v[124:127], v[166:169], v[182:185], v[124:127]
	v_mfma_f32_16x16x32_bf16 v[120:123], v[174:177], v[182:185], v[120:123]
	v_mfma_f32_16x16x32_bf16 v[108:111], v[166:169], v[190:193], v[108:111]
	v_mfma_f32_16x16x32_bf16 v[104:107], v[174:177], v[190:193], v[104:107]
	v_mfma_f32_16x16x32_bf16 v[92:95], v[166:169], v[198:201], v[92:95]
	v_mfma_f32_16x16x32_bf16 v[88:91], v[174:177], v[198:201], v[88:91]
	v_mfma_f32_16x16x32_bf16 v[76:79], v[166:169], v[206:209], v[76:79]
	v_mfma_f32_16x16x32_bf16 v[72:75], v[174:177], v[206:209], v[72:75]
	s_setprio 0
	s_barrier
	s_mov_b32 m0, s52
	s_nop 0
	global_load_lds_dwordx4 v130, s[18:19]
	s_mov_b32 m0, s53
	s_nop 0
	global_load_lds_dwordx4 v128, s[18:19]
	s_barrier
	s_waitcnt lgkmcnt(0)
	s_setprio 1
	s_waitcnt lgkmcnt(0)
	s_setprio 0
	s_mov_b32 m0, s33
	s_barrier
	ds_read_b128 v[178:181], v146 offset:16384
	ds_read_b128 v[182:185], v146 offset:17408
	ds_read_b128 v[186:189], v146 offset:18432
	ds_read_b128 v[190:193], v146 offset:19456
	ds_read_b128 v[194:197], v146 offset:20480
	ds_read_b128 v[198:201], v146 offset:21504
	ds_read_b128 v[202:205], v146 offset:22528
	ds_read_b128 v[206:209], v146 offset:23552
	global_load_lds_dwordx4 v130, s[28:29]
	s_mov_b32 m0, s54
	s_nop 0
	global_load_lds_dwordx4 v128, s[28:29]
	s_barrier
	s_waitcnt lgkmcnt(0)
	s_setprio 1
	s_waitcnt lgkmcnt(0)
	v_mfma_f32_16x16x32_bf16 v[60:63], v[140:143], v[178:181], v[60:63]
	v_mfma_f32_16x16x32_bf16 v[56:59], v[170:173], v[178:181], v[56:59]
	v_mfma_f32_16x16x32_bf16 v[44:47], v[140:143], v[186:189], v[44:47]
	v_mfma_f32_16x16x32_bf16 v[40:43], v[170:173], v[186:189], v[40:43]
	v_mfma_f32_16x16x32_bf16 v[28:31], v[140:143], v[194:197], v[28:31]
	v_mfma_f32_16x16x32_bf16 v[24:27], v[170:173], v[194:197], v[24:27]
	v_mfma_f32_16x16x32_bf16 v[12:15], v[140:143], v[202:205], v[12:15]
	v_mfma_f32_16x16x32_bf16 v[8:11], v[170:173], v[202:205], v[8:11]
	v_mfma_f32_16x16x32_bf16 v[60:63], v[166:169], v[182:185], v[60:63]
	v_mfma_f32_16x16x32_bf16 v[56:59], v[174:177], v[182:185], v[56:59]
	v_mfma_f32_16x16x32_bf16 v[44:47], v[166:169], v[190:193], v[44:47]
	v_mfma_f32_16x16x32_bf16 v[40:43], v[174:177], v[190:193], v[40:43]
	v_mfma_f32_16x16x32_bf16 v[28:31], v[166:169], v[198:201], v[28:31]
	v_mfma_f32_16x16x32_bf16 v[24:27], v[174:177], v[198:201], v[24:27]
	v_mfma_f32_16x16x32_bf16 v[12:15], v[166:169], v[206:209], v[12:15]
	v_mfma_f32_16x16x32_bf16 v[8:11], v[174:177], v[206:209], v[8:11]
	s_setprio 0
	s_barrier
	s_add_u32 s14, s18, 0x44000
	s_addc_u32 s15, s19, 0
	s_mov_b32 m0, s55
	s_nop 0
	s_mov_b32 m0, s56
	s_nop 0
	s_waitcnt vmcnt(4)
	s_barrier
	s_setprio 1
	s_setprio 0
	s_barrier
	ds_read_b128 v[140:143], v156
	ds_read_b128 v[166:169], v157
	ds_read_b128 v[170:173], v159
	ds_read_b128 v[174:177], v160
	s_add_u32 s14, s28, 0x44000
	s_addc_u32 s15, s29, 0
	s_mov_b32 m0, s57
	ds_read_b128 v[178:181], v146 offset:32768
	ds_read_b128 v[182:185], v146 offset:33792
	ds_read_b128 v[186:189], v146 offset:34816
	ds_read_b128 v[190:193], v146 offset:35840
	ds_read_b128 v[194:197], v146 offset:36864
	ds_read_b128 v[198:201], v146 offset:37888
	ds_read_b128 v[202:205], v146 offset:38912
	ds_read_b128 v[206:209], v146 offset:39936
	global_load_lds_dwordx4 v130, s[14:15]
	s_mov_b32 m0, s58
	s_nop 0
	global_load_lds_dwordx4 v128, s[14:15]
	s_waitcnt lgkmcnt(8)
	s_barrier
	s_waitcnt lgkmcnt(0)
	s_setprio 1
	s_waitcnt lgkmcnt(0)
	v_mfma_f32_16x16x32_bf16 v[124:127], v[140:143], v[178:181], v[124:127]
	v_mfma_f32_16x16x32_bf16 v[120:123], v[170:173], v[178:181], v[120:123]
	v_mfma_f32_16x16x32_bf16 v[108:111], v[140:143], v[186:189], v[108:111]
	v_mfma_f32_16x16x32_bf16 v[104:107], v[170:173], v[186:189], v[104:107]
	v_mfma_f32_16x16x32_bf16 v[92:95], v[140:143], v[194:197], v[92:95]
	v_mfma_f32_16x16x32_bf16 v[88:91], v[170:173], v[194:197], v[88:91]
	v_mfma_f32_16x16x32_bf16 v[76:79], v[140:143], v[202:205], v[76:79]
	v_mfma_f32_16x16x32_bf16 v[72:75], v[170:173], v[202:205], v[72:75]
	v_mfma_f32_16x16x32_bf16 v[124:127], v[166:169], v[182:185], v[124:127]
	v_mfma_f32_16x16x32_bf16 v[120:123], v[174:177], v[182:185], v[120:123]
	v_mfma_f32_16x16x32_bf16 v[108:111], v[166:169], v[190:193], v[108:111]
	v_mfma_f32_16x16x32_bf16 v[104:107], v[174:177], v[190:193], v[104:107]
	v_mfma_f32_16x16x32_bf16 v[92:95], v[166:169], v[198:201], v[92:95]
	v_mfma_f32_16x16x32_bf16 v[88:91], v[174:177], v[198:201], v[88:91]
	v_mfma_f32_16x16x32_bf16 v[76:79], v[166:169], v[206:209], v[76:79]
	v_mfma_f32_16x16x32_bf16 v[72:75], v[174:177], v[206:209], v[72:75]
	s_setprio 0
	s_barrier
; #define PG8_STAGE(bufoff, gbase, voff) do { _Pragma("unroll") for (int _i = 0; _i < 2; ++_i) \
;         __builtin_amdgcn_global_load_lds((const unsigned*)((const char*)(gbase) + (voff)[_i]), (PG8_LAS unsigned*)(lds + (bufoff) + ldsw + _i * 8192), 16, 0, 0); } while (0)
; #define PG8_LDA(dst, b, h) do { _Pragma("unroll") for (int m = 0; m < 4; ++m) _Pragma("unroll") for (int k = 0; k < 2; ++k) dst[m][k] = *(const PG8_LAS bf16x8*)(lds + PG8_SA(b, h) + aoff + m * 2048 + k * 1024); } while (0)
; template <class Epi, class Sched, bool STAMP = false>
; __device__ __forceinline__ void gemm_phase(PG8_LAS unsigned char* lds, const Gemm g, const Sched& S, const Epi& E, unsigned long long* stamps) {
;     ...
;         for (int t = 0; t < nt; t += 2) {
;             const bool last = (t == nt - 2);
;             const char* a1 = cA + (size_t)(t + 1) * kstep;
;             const char* a2 = last ? nA : cA + (size_t)(t + 2) * kstep; const char* b2 = last ? nB : cB + (size_t)(t + 2) * kstep;
;             const char* a3 = a2 + kstep; const char* b3 = b2 + kstep;
;             if (last && has_next) S.a_ready(nxt);
;             PG8_LDB(B0, 0, 0); PG8_SCHED; PG8_LDA(At, 0, 0); PG8_STAGE(PG8_SA(1, 1), a1 + hstep, voffA);
;             PG8_WAIT_L(8); PG8_BAR; PG8_WAIT_L(0); PG8_MMA(0, 0, At, B0); PG8_BAR; PG8_SCHED;
;             PG8_LDB(B1, 0, 1); PG8_STAGE(PG8_SB(0, 0), b2, voffB);
;             PG8_BAR; PG8_WAIT_L(0); PG8_MMA(0, 1, At, B1); PG8_BAR;
;             PG8_LDA(At, 0, 1); PG8_STAGE(PG8_SA(0, 0), a2, voffA);
;             PG8_BAR; PG8_WAIT_L(0); PG8_MMA(1, 0, At, B0); PG8_BAR; PG8_SCHED;
;             PG8_STAGE(PG8_SB(0, 1), b2 + hstep, voffB);
;             PG8_WAIT_V(6); PG8_BAR; PG8_MMA(1, 1, At, B1); PG8_BAR;
;             PG8_LDB(B0, 1, 0); PG8_SCHED; PG8_LDA(At, 1, 0); PG8_STAGE(PG8_SA(0, 1), a2 + hstep, voffA);
;             PG8_WAIT_L(8); PG8_BAR; PG8_WAIT_L(0); PG8_MMA(0, 0, At, B0); PG8_BAR; PG8_SCHED;
;             PG8_LDB(B1, 1, 1); PG8_STAGE(PG8_SB(1, 0), b3, voffB);
;             PG8_BAR; PG8_WAIT_L(0); PG8_MMA(0, 1, At, B1); PG8_BAR;
;             PG8_LDA(At, 1, 1); PG8_STAGE(PG8_SA(1, 0), a3, voffA);
;             PG8_BAR; PG8_WAIT_L(0); PG8_MMA(1, 0, At, B0); PG8_BAR; PG8_SCHED;
;             PG8_STAGE(PG8_SB(1, 1), b3 + hstep, voffB);
;             PG8_WAIT_V(6); PG8_BAR; PG8_MMA(1, 1, At, B1); PG8_BAR;
;         }
	s_mov_b32 m0, s61
	s_add_u32 s100, s18, 0x80
	s_addc_u32 s101, s19, 0
	global_load_lds_dwordx4 v130, s[100:101]
	s_mov_b32 m0, s62
	s_nop 0
	global_load_lds_dwordx4 v128, s[100:101]
	s_barrier
	s_waitcnt lgkmcnt(0)
	s_setprio 1
	s_waitcnt lgkmcnt(0)
	s_setprio 0
	s_mov_b32 m0, s63
	s_barrier
	ds_read_b128 v[178:181], v146 offset:49152
	ds_read_b128 v[182:185], v146 offset:50176
	ds_read_b128 v[186:189], v146 offset:51200
	ds_read_b128 v[190:193], v146 offset:52224
	ds_read_b128 v[194:197], v146 offset:53248
	ds_read_b128 v[198:201], v146 offset:54272
	ds_read_b128 v[202:205], v146 offset:55296
	ds_read_b128 v[206:209], v146 offset:56320
	s_add_u32 s100, s28, 0x80
	s_addc_u32 s101, s29, 0
	global_load_lds_dwordx4 v130, s[100:101]
	s_mov_b32 m0, s64
	s_nop 0
	global_load_lds_dwordx4 v128, s[100:101]
	s_barrier
	s_waitcnt lgkmcnt(0)
	s_setprio 1
	s_waitcnt lgkmcnt(0)
	v_mfma_f32_16x16x32_bf16 v[60:63], v[140:143], v[178:181], v[60:63]
	v_mfma_f32_16x16x32_bf16 v[56:59], v[170:173], v[178:181], v[56:59]
	v_mfma_f32_16x16x32_bf16 v[44:47], v[140:143], v[186:189], v[44:47]
	v_mfma_f32_16x16x32_bf16 v[40:43], v[170:173], v[186:189], v[40:43]
	v_mfma_f32_16x16x32_bf16 v[28:31], v[140:143], v[194:197], v[28:31]
	v_mfma_f32_16x16x32_bf16 v[24:27], v[170:173], v[194:197], v[24:27]
	v_mfma_f32_16x16x32_bf16 v[12:15], v[140:143], v[202:205], v[12:15]
	v_mfma_f32_16x16x32_bf16 v[8:11], v[170:173], v[202:205], v[8:11]
	v_mfma_f32_16x16x32_bf16 v[60:63], v[166:169], v[182:185], v[60:63]
	v_mfma_f32_16x16x32_bf16 v[56:59], v[174:177], v[182:185], v[56:59]
	v_mfma_f32_16x16x32_bf16 v[44:47], v[166:169], v[190:193], v[44:47]
	v_mfma_f32_16x16x32_bf16 v[40:43], v[174:177], v[190:193], v[40:43]
	v_mfma_f32_16x16x32_bf16 v[28:31], v[166:169], v[198:201], v[28:31]
	v_mfma_f32_16x16x32_bf16 v[24:27], v[174:177], v[198:201], v[24:27]
	v_mfma_f32_16x16x32_bf16 v[12:15], v[166:169], v[206:209], v[12:15]
	v_mfma_f32_16x16x32_bf16 v[8:11], v[174:177], v[206:209], v[8:11]
	s_setprio 0
	s_barrier
	s_add_u32 s14, s18, 0x44080
	s_addc_u32 s15, s19, 0
	s_mov_b32 m0, s65
	s_nop 0
	s_mov_b32 m0, s66
	s_nop 0
	s_add_i32 s77, s77, 2
	s_add_u32 s75, s75, 0x100
	s_addc_u32 s76, s76, 0
	s_cmp_gt_u32 s77, 13
	s_mov_b64 s[14:15], s[16:17]
	s_waitcnt vmcnt(4)
	s_barrier
	s_setprio 1
	s_setprio 0
	s_barrier
	s_cbranch_scc0 .Lgu1_half_loop
; DI float ex2(float x) { return __builtin_amdgcn_exp2f(x); }
;     DI void operator()(const f32x4 (&acc)[2][2][4][2], const Unit& u, int wr, int wc, int fr, int fq) const {
;         const int row0 = u.pm * BM + wr * 64 + fr, hcol0 = ((u.pn * BM + wc * 32) >> 1) + 4 * fq;
; #pragma unroll
;         for (int ai = 0; ai < 2; ++ai)
; #pragma unroll
;             for (int m = 0; m < 4; ++m) { u16* rowp = O + (size_t)(row0 + ai * HALF + m * 16) * ldc + hcol0;
; #pragma unroll
;                 for (int bj = 0; bj < 2; ++bj) { const f32x4 g = acc[ai][bj][m][0], up = acc[ai][bj][m][1]; float r[4];
; #pragma unroll
;                     for (int j = 0; j < 4; ++j) r[j] = g[j] * up[j] * __builtin_amdgcn_rcpf(1.f + ex2(-LOG2E * g[j]));
;                     uint2 w = {pack2(r[0], r[1]), pack2(r[2], r[3])}; *(uint2*)(rowp + bj * (HALF / 2)) = w; } }
	v_exp_f32_e64 v168, -v124
	v_exp_f32_e64 v169, -v125
	v_exp_f32_e64 v170, -v126
	v_exp_f32_e64 v171, -v127
	v_add_f32_e32 v168, 1.0, v168
	v_add_f32_e32 v169, 1.0, v169
	v_add_f32_e32 v170, 1.0, v170
	v_add_f32_e32 v171, 1.0, v171
	v_rcp_f32_e32 v168, v168
	v_rcp_f32_e32 v169, v169
	v_rcp_f32_e32 v170, v170
	v_rcp_f32_e32 v171, v171
	s_lshl_b32 s10, s74, 8
	v_pk_mul_f32 v[122:123], v[126:127], v[122:123]
	v_pk_mul_f32 v[120:121], v[124:125], v[120:121]
	s_or_b32 s10, s10, s60
	s_or_b32 s10, s10, s98
	v_pk_mul_f32 v[120:121], v[120:121], v[168:169]
	v_pk_mul_f32 v[122:123], v[122:123], v[170:171]
	s_ashr_i32 s10, s10, 1
	v_cvt_pk_bf16_f32 v120, v120, v121
	v_cvt_pk_bf16_f32 v121, v122, v123
	v_or_b32_e32 v140, s10, v147
	v_lshl_add_u32 v165, s73, 8, v145
	v_ashrrev_i32_e32 v141, 31, v140
	v_mov_b64_e32 v[142:143], s[12:13]
	v_mad_i64_i32 v[166:167], s[14:15], v165, s70, v[142:143]
	v_lshlrev_b64 v[140:141], 1, v[140:141]
	v_lshl_add_u64 v[166:167], v[166:167], 0, v[140:141]
	global_store_dwordx2 v[166:167], v[120:121], off
	v_exp_f32_e64 v114, -v108
	v_exp_f32_e64 v115, -v109
	v_exp_f32_e64 v116, -v110
	v_exp_f32_e64 v117, -v111
	v_add_f32_e32 v114, 1.0, v114
	v_add_f32_e32 v115, 1.0, v115
	v_add_f32_e32 v116, 1.0, v116
	v_add_f32_e32 v117, 1.0, v117
	v_rcp_f32_e32 v114, v114
	v_rcp_f32_e32 v115, v115
	v_rcp_f32_e32 v116, v116
	v_rcp_f32_e32 v117, v117
	v_pk_mul_f32 v[106:107], v[110:111], v[106:107]
	v_pk_mul_f32 v[104:105], v[108:109], v[104:105]
	v_pk_mul_f32 v[104:105], v[104:105], v[114:115]
	v_pk_mul_f32 v[106:107], v[106:107], v[116:117]
	v_cvt_pk_bf16_f32 v104, v104, v105
	v_cvt_pk_bf16_f32 v105, v106, v107
	v_or_b32_e32 v112, 16, v165
	v_mad_i64_i32 v[112:113], s[14:15], v112, s70, v[142:143]
	v_lshl_add_u64 v[112:113], v[112:113], 0, v[140:141]
	global_store_dwordx2 v[112:113], v[104:105], off
	v_exp_f32_e64 v98, -v92
	v_exp_f32_e64 v99, -v93
	v_exp_f32_e64 v100, -v94
	v_exp_f32_e64 v101, -v95
	v_add_f32_e32 v98, 1.0, v98
	v_add_f32_e32 v99, 1.0, v99
	v_add_f32_e32 v100, 1.0, v100
	v_add_f32_e32 v101, 1.0, v101
	v_rcp_f32_e32 v98, v98
	v_rcp_f32_e32 v99, v99
	v_rcp_f32_e32 v100, v100
	v_rcp_f32_e32 v101, v101
	v_pk_mul_f32 v[90:91], v[94:95], v[90:91]
	v_pk_mul_f32 v[88:89], v[92:93], v[88:89]
	v_pk_mul_f32 v[88:89], v[88:89], v[98:99]
	v_pk_mul_f32 v[90:91], v[90:91], v[100:101]
	v_cvt_pk_bf16_f32 v88, v88, v89
	v_cvt_pk_bf16_f32 v89, v90, v91
	v_or_b32_e32 v96, 32, v165
	v_mad_i64_i32 v[96:97], s[14:15], v96, s70, v[142:143]
	v_lshl_add_u64 v[96:97], v[96:97], 0, v[140:141]
	global_store_dwordx2 v[96:97], v[88:89], off
	v_exp_f32_e64 v82, -v76
	v_exp_f32_e64 v83, -v77
	v_exp_f32_e64 v84, -v78
	v_exp_f32_e64 v85, -v79
	v_add_f32_e32 v82, 1.0, v82
	v_add_f32_e32 v83, 1.0, v83
	v_add_f32_e32 v84, 1.0, v84
	v_add_f32_e32 v85, 1.0, v85
	v_rcp_f32_e32 v82, v82
	v_rcp_f32_e32 v83, v83
	v_rcp_f32_e32 v84, v84
	v_rcp_f32_e32 v85, v85
	v_pk_mul_f32 v[74:75], v[78:79], v[74:75]
	v_pk_mul_f32 v[72:73], v[76:77], v[72:73]
	v_pk_mul_f32 v[72:73], v[72:73], v[82:83]
	v_pk_mul_f32 v[74:75], v[74:75], v[84:85]
	v_cvt_pk_bf16_f32 v72, v72, v73
	v_cvt_pk_bf16_f32 v73, v74, v75
	v_or_b32_e32 v80, 48, v165
	v_mad_i64_i32 v[80:81], s[14:15], v80, s70, v[142:143]
	v_lshl_add_u64 v[80:81], v[80:81], 0, v[140:141]
	global_store_dwordx2 v[80:81], v[72:73], off
	v_exp_f32_e64 v66, -v60
	v_exp_f32_e64 v67, -v61
	v_exp_f32_e64 v68, -v62
	v_exp_f32_e64 v69, -v63
	v_add_f32_e32 v66, 1.0, v66
	v_add_f32_e32 v67, 1.0, v67
	v_add_f32_e32 v68, 1.0, v68
	v_add_f32_e32 v69, 1.0, v69
	v_rcp_f32_e32 v66, v66
	v_rcp_f32_e32 v67, v67
	v_rcp_f32_e32 v68, v68
	v_rcp_f32_e32 v69, v69
	v_pk_mul_f32 v[58:59], v[62:63], v[58:59]
	v_pk_mul_f32 v[56:57], v[60:61], v[56:57]
	v_pk_mul_f32 v[56:57], v[56:57], v[66:67]
	v_pk_mul_f32 v[58:59], v[58:59], v[68:69]
	v_cvt_pk_bf16_f32 v56, v56, v57
	v_cvt_pk_bf16_f32 v57, v58, v59
	v_add_u32_e32 v64, 0x80, v165
	v_mad_i64_i32 v[64:65], s[14:15], v64, s70, v[142:143]
	v_lshl_add_u64 v[64:65], v[64:65], 0, v[140:141]
	global_store_dwordx2 v[64:65], v[56:57], off
	v_exp_f32_e64 v50, -v44
	v_exp_f32_e64 v51, -v45
	v_exp_f32_e64 v52, -v46
	v_exp_f32_e64 v53, -v47
	v_add_f32_e32 v50, 1.0, v50
	v_add_f32_e32 v51, 1.0, v51
	v_add_f32_e32 v52, 1.0, v52
	v_add_f32_e32 v53, 1.0, v53
	v_rcp_f32_e32 v50, v50
	v_rcp_f32_e32 v51, v51
	v_rcp_f32_e32 v52, v52
	v_rcp_f32_e32 v53, v53
	v_pk_mul_f32 v[42:43], v[46:47], v[42:43]
	v_pk_mul_f32 v[40:41], v[44:45], v[40:41]
	v_pk_mul_f32 v[40:41], v[40:41], v[50:51]
	v_pk_mul_f32 v[42:43], v[42:43], v[52:53]
	v_cvt_pk_bf16_f32 v40, v40, v41
	v_cvt_pk_bf16_f32 v41, v42, v43
	v_add_u32_e32 v48, 0x90, v165
	v_mad_i64_i32 v[48:49], s[14:15], v48, s70, v[142:143]
	v_lshl_add_u64 v[48:49], v[48:49], 0, v[140:141]
	global_store_dwordx2 v[48:49], v[40:41], off
	v_exp_f32_e64 v34, -v28
	v_exp_f32_e64 v35, -v29
	v_exp_f32_e64 v36, -v30
	v_exp_f32_e64 v37, -v31
	v_add_f32_e32 v34, 1.0, v34
	v_add_f32_e32 v35, 1.0, v35
	v_add_f32_e32 v36, 1.0, v36
	v_add_f32_e32 v37, 1.0, v37
	v_rcp_f32_e32 v34, v34
	v_rcp_f32_e32 v35, v35
	v_rcp_f32_e32 v36, v36
	v_rcp_f32_e32 v37, v37
	v_pk_mul_f32 v[26:27], v[30:31], v[26:27]
	v_pk_mul_f32 v[24:25], v[28:29], v[24:25]
	v_pk_mul_f32 v[24:25], v[24:25], v[34:35]
	v_pk_mul_f32 v[26:27], v[26:27], v[36:37]
	v_cvt_pk_bf16_f32 v24, v24, v25
	v_cvt_pk_bf16_f32 v25, v26, v27
	v_add_u32_e32 v32, 0xa0, v165
	v_mad_i64_i32 v[32:33], s[14:15], v32, s70, v[142:143]
	v_lshl_add_u64 v[32:33], v[32:33], 0, v[140:141]
	global_store_dwordx2 v[32:33], v[24:25], off
	v_exp_f32_e64 v18, -v12
	v_exp_f32_e64 v19, -v13
	v_exp_f32_e64 v20, -v14
	v_exp_f32_e64 v21, -v15
	v_add_f32_e32 v18, 1.0, v18
	v_add_f32_e32 v19, 1.0, v19
	v_add_f32_e32 v20, 1.0, v20
	v_add_f32_e32 v21, 1.0, v21
	v_rcp_f32_e32 v18, v18
	v_rcp_f32_e32 v19, v19
	v_rcp_f32_e32 v20, v20
	v_rcp_f32_e32 v21, v21
	v_pk_mul_f32 v[10:11], v[14:15], v[10:11]
	v_pk_mul_f32 v[8:9], v[12:13], v[8:9]
	v_pk_mul_f32 v[8:9], v[8:9], v[18:19]
	v_pk_mul_f32 v[10:11], v[10:11], v[20:21]
	v_cvt_pk_bf16_f32 v8, v8, v9
	v_cvt_pk_bf16_f32 v9, v10, v11
	v_add_u32_e32 v16, 0xb0, v165
	v_mad_i64_i32 v[16:17], s[14:15], v16, s70, v[142:143]
	v_lshl_add_u64 v[16:17], v[16:17], 0, v[140:141]
	global_store_dwordx2 v[16:17], v[8:9], off
	s_and_b64 vcc, exec, s[2:3]
	s_mov_b32 s74, s71
	s_mov_b32 s73, s72
	s_mov_b64 s[16:17], s[0:1]
	s_mov_b64 s[14:15], s[4:5]

; #define PG8_STAGE(bufoff, gbase, voff) do { _Pragma("unroll") for (int _i = 0; _i < 2; ++_i) \
;         __builtin_amdgcn_global_load_lds((const unsigned*)((const char*)(gbase) + (voff)[_i]), (PG8_LAS unsigned*)(lds + (bufoff) + ldsw + _i * 8192), 16, 0, 0); } while (0)
; #define PG8_LDA(dst, b, h) do { _Pragma("unroll") for (int m = 0; m < 4; ++m) _Pragma("unroll") for (int k = 0; k < 2; ++k) dst[m][k] = *(const PG8_LAS bf16x8*)(lds + PG8_SA(b, h) + aoff + m * 2048 + k * 1024); } while (0)
; template <class Epi, class Sched, bool STAMP = false>
; __device__ __forceinline__ void gemm_phase(PG8_LAS unsigned char* lds, const Gemm g, const Sched& S, const Epi& E, unsigned long long* stamps) {
;     ...
;         for (int t = 0; t < nt; t += 2) {
;             const bool last = (t == nt - 2);
;             const char* a1 = cA + (size_t)(t + 1) * kstep;
;             const char* a2 = last ? nA : cA + (size_t)(t + 2) * kstep; const char* b2 = last ? nB : cB + (size_t)(t + 2) * kstep;
;             const char* a3 = a2 + kstep; const char* b3 = b2 + kstep;
;             if (last && has_next) S.a_ready(nxt);
;             PG8_LDB(B0, 0, 0); PG8_SCHED; PG8_LDA(At, 0, 0); PG8_STAGE(PG8_SA(1, 1), a1 + hstep, voffA);
;             PG8_WAIT_L(8); PG8_BAR; PG8_WAIT_L(0); PG8_MMA(0, 0, At, B0); PG8_BAR; PG8_SCHED;
;             PG8_LDB(B1, 0, 1); PG8_STAGE(PG8_SB(0, 0), b2, voffB);
;             PG8_BAR; PG8_WAIT_L(0); PG8_MMA(0, 1, At, B1); PG8_BAR;
;             PG8_LDA(At, 0, 1); PG8_STAGE(PG8_SA(0, 0), a2, voffA);
;             PG8_BAR; PG8_WAIT_L(0); PG8_MMA(1, 0, At, B0); PG8_BAR; PG8_SCHED;
;             PG8_STAGE(PG8_SB(0, 1), b2 + hstep, voffB);
;             PG8_WAIT_V(6); PG8_BAR; PG8_MMA(1, 1, At, B1); PG8_BAR;
;             PG8_LDB(B0, 1, 0); PG8_SCHED; PG8_LDA(At, 1, 0); PG8_STAGE(PG8_SA(0, 1), a2 + hstep, voffA);
;             PG8_WAIT_L(8); PG8_BAR; PG8_WAIT_L(0); PG8_MMA(0, 0, At, B0); PG8_BAR; PG8_SCHED;
;             PG8_LDB(B1, 1, 1); PG8_STAGE(PG8_SB(1, 0), b3, voffB);
;             PG8_BAR; PG8_WAIT_L(0); PG8_MMA(0, 1, At, B1); PG8_BAR;
;             PG8_LDA(At, 1, 1); PG8_STAGE(PG8_SA(1, 0), a3, voffA);
;             PG8_BAR; PG8_WAIT_L(0); PG8_MMA(1, 0, At, B0); PG8_BAR; PG8_SCHED;
;             PG8_STAGE(PG8_SB(1, 1), b3 + hstep, voffB);
;             PG8_WAIT_V(6); PG8_BAR; PG8_MMA(1, 1, At, B1); PG8_BAR;
;         }
.Lzp2_mid:
	ds_read_b128 v[166:169], v156
	ds_read_b128 v[170:173], v157
	ds_read_b128 v[174:177], v159
	ds_read_b128 v[178:181], v160
	s_add_u32 s34, s56, 0xb4000
	s_addc_u32 s35, s57, 0
	s_mov_b32 m0, s66
	ds_read_b128 v[182:185], v146 offset:32768
	ds_read_b128 v[186:189], v146 offset:33792
	ds_read_b128 v[190:193], v146 offset:34816
	ds_read_b128 v[194:197], v146 offset:35840
	ds_read_b128 v[198:201], v146 offset:36864
	ds_read_b128 v[202:205], v146 offset:37888
	ds_read_b128 v[206:209], v146 offset:38912
	ds_read_b128 v[210:213], v146 offset:39936
	global_load_lds_dwordx4 v128, s[34:35]
	s_mov_b32 m0, s67
	s_nop 0
	global_load_lds_dwordx4 v132, s[34:35]
	s_waitcnt lgkmcnt(8)
	s_barrier
	s_waitcnt lgkmcnt(0)
	s_setprio 1
	s_waitcnt lgkmcnt(0)
	v_mfma_f32_16x16x32_bf16 v[124:127], v[166:169], v[182:185], v[124:127]
	v_mfma_f32_16x16x32_bf16 v[120:123], v[174:177], v[182:185], v[120:123]
	v_mfma_f32_16x16x32_bf16 v[116:119], v[166:169], v[190:193], v[116:119]
	v_mfma_f32_16x16x32_bf16 v[112:115], v[174:177], v[190:193], v[112:115]
	v_mfma_f32_16x16x32_bf16 v[100:103], v[166:169], v[198:201], v[100:103]
	v_mfma_f32_16x16x32_bf16 v[96:99], v[174:177], v[198:201], v[96:99]
	v_mfma_f32_16x16x32_bf16 v[84:87], v[166:169], v[206:209], v[84:87]
	v_mfma_f32_16x16x32_bf16 v[80:83], v[174:177], v[206:209], v[80:83]
	v_mfma_f32_16x16x32_bf16 v[124:127], v[170:173], v[186:189], v[124:127]
	v_mfma_f32_16x16x32_bf16 v[120:123], v[178:181], v[186:189], v[120:123]
	v_mfma_f32_16x16x32_bf16 v[116:119], v[170:173], v[194:197], v[116:119]
	v_mfma_f32_16x16x32_bf16 v[112:115], v[178:181], v[194:197], v[112:115]
	v_mfma_f32_16x16x32_bf16 v[100:103], v[170:173], v[202:205], v[100:103]
	v_mfma_f32_16x16x32_bf16 v[96:99], v[178:181], v[202:205], v[96:99]
	v_mfma_f32_16x16x32_bf16 v[84:87], v[170:173], v[210:213], v[84:87]
	v_mfma_f32_16x16x32_bf16 v[80:83], v[178:181], v[210:213], v[80:83]
	s_setprio 0
	s_barrier
	s_mov_b32 m0, s68
	ds_read_b128 v[214:217], v161
	ds_read_b128 v[218:221], v162
	ds_read_b128 v[222:225], v163
	ds_read_b128 v[226:229], v164
	s_add_u32 s100, s54, 0x80
	s_addc_u32 s101, s55, 0
	global_load_lds_dwordx4 v130, s[100:101]
	s_mov_b32 m0, s69
	s_nop 0
	global_load_lds_dwordx4 v134, s[100:101]
	s_barrier
	s_waitcnt lgkmcnt(0)
	s_setprio 1
	s_waitcnt lgkmcnt(0)
	v_mfma_f32_16x16x32_bf16 v[108:111], v[214:217], v[182:185], v[108:111]
	v_mfma_f32_16x16x32_bf16 v[104:107], v[222:225], v[182:185], v[104:107]
	v_mfma_f32_16x16x32_bf16 v[92:95], v[214:217], v[190:193], v[92:95]
	v_mfma_f32_16x16x32_bf16 v[88:91], v[222:225], v[190:193], v[88:91]
	v_mfma_f32_16x16x32_bf16 v[76:79], v[214:217], v[198:201], v[76:79]
	v_mfma_f32_16x16x32_bf16 v[72:75], v[222:225], v[198:201], v[72:75]
	v_mfma_f32_16x16x32_bf16 v[68:71], v[214:217], v[206:209], v[68:71]
	v_mfma_f32_16x16x32_bf16 v[64:67], v[222:225], v[206:209], v[64:67]
	v_mfma_f32_16x16x32_bf16 v[108:111], v[218:221], v[186:189], v[108:111]
	v_mfma_f32_16x16x32_bf16 v[104:107], v[226:229], v[186:189], v[104:107]
	v_mfma_f32_16x16x32_bf16 v[92:95], v[218:221], v[194:197], v[92:95]
	v_mfma_f32_16x16x32_bf16 v[88:91], v[226:229], v[194:197], v[88:91]
	v_mfma_f32_16x16x32_bf16 v[76:79], v[218:221], v[202:205], v[76:79]
	v_mfma_f32_16x16x32_bf16 v[72:75], v[226:229], v[202:205], v[72:75]
	v_mfma_f32_16x16x32_bf16 v[68:71], v[218:221], v[210:213], v[68:71]
	v_mfma_f32_16x16x32_bf16 v[64:67], v[226:229], v[210:213], v[64:67]
	s_setprio 0
	s_mov_b32 m0, s70
	s_barrier
	ds_read_b128 v[182:185], v146 offset:49152
	ds_read_b128 v[186:189], v146 offset:50176
	ds_read_b128 v[190:193], v146 offset:51200
	ds_read_b128 v[194:197], v146 offset:52224
	ds_read_b128 v[198:201], v146 offset:53248
	ds_read_b128 v[202:205], v146 offset:54272
	ds_read_b128 v[206:209], v146 offset:55296
	ds_read_b128 v[210:213], v146 offset:56320
	s_add_u32 s100, s56, 0x80
	s_addc_u32 s101, s57, 0
	global_load_lds_dwordx4 v128, s[100:101]
	s_mov_b32 m0, s71
	s_nop 0
	global_load_lds_dwordx4 v132, s[100:101]
	s_barrier
	s_waitcnt lgkmcnt(0)
	s_setprio 1
	s_waitcnt lgkmcnt(0)
	v_mfma_f32_16x16x32_bf16 v[60:63], v[166:169], v[182:185], v[60:63]
	v_mfma_f32_16x16x32_bf16 v[56:59], v[174:177], v[182:185], v[56:59]
	v_mfma_f32_16x16x32_bf16 v[52:55], v[166:169], v[190:193], v[52:55]
	v_mfma_f32_16x16x32_bf16 v[48:51], v[174:177], v[190:193], v[48:51]
	v_mfma_f32_16x16x32_bf16 v[36:39], v[166:169], v[198:201], v[36:39]
	v_mfma_f32_16x16x32_bf16 v[32:35], v[174:177], v[198:201], v[32:35]
	v_mfma_f32_16x16x32_bf16 v[20:23], v[166:169], v[206:209], v[20:23]
	v_mfma_f32_16x16x32_bf16 v[16:19], v[174:177], v[206:209], v[16:19]
	v_mfma_f32_16x16x32_bf16 v[60:63], v[170:173], v[186:189], v[60:63]
	v_mfma_f32_16x16x32_bf16 v[56:59], v[178:181], v[186:189], v[56:59]
	v_mfma_f32_16x16x32_bf16 v[52:55], v[170:173], v[194:197], v[52:55]
	v_mfma_f32_16x16x32_bf16 v[48:51], v[178:181], v[194:197], v[48:51]
	v_mfma_f32_16x16x32_bf16 v[36:39], v[170:173], v[202:205], v[36:39]
	v_mfma_f32_16x16x32_bf16 v[32:35], v[178:181], v[202:205], v[32:35]
	v_mfma_f32_16x16x32_bf16 v[20:23], v[170:173], v[210:213], v[20:23]
	v_mfma_f32_16x16x32_bf16 v[16:19], v[178:181], v[210:213], v[16:19]
	s_setprio 0
	s_barrier
	s_add_u32 s34, s54, 0xb4080
	s_addc_u32 s35, s55, 0
	s_mov_b32 m0, s72
	s_nop 0
	global_load_lds_dwordx4 v130, s[34:35]
	s_mov_b32 m0, s73
	s_nop 0
	global_load_lds_dwordx4 v134, s[34:35]
	s_add_i32 s90, s90, 2
	s_add_u32 s88, s88, 0x100
	s_addc_u32 s89, s89, 0
	s_cmp_gt_u32 s90, 41
	s_mov_b64 s[34:35], s[52:53]
	s_waitcnt vmcnt(6)
	s_barrier
; #define PG8_STAGE(bufoff, gbase, voff) do { _Pragma("unroll") for (int _i = 0; _i < 2; ++_i) \
;         __builtin_amdgcn_global_load_lds((const unsigned*)((const char*)(gbase) + (voff)[_i]), (PG8_LAS unsigned*)(lds + (bufoff) + ldsw + _i * 8192), 16, 0, 0); } while (0)
; #define PG8_LDA(dst, b, h) do { _Pragma("unroll") for (int m = 0; m < 4; ++m) _Pragma("unroll") for (int k = 0; k < 2; ++k) dst[m][k] = *(const PG8_LAS bf16x8*)(lds + PG8_SA(b, h) + aoff + m * 2048 + k * 1024); } while (0)
; #define PG8_LDB(dst, b, h) do { _Pragma("unroll") for (int n = 0; n < 2; ++n) _Pragma("unroll") for (int k = 0; k < 2; ++k) dst[n][k] = *(const PG8_LAS bf16x8*)(lds + PG8_SB(b, h) + boff + n * 2048 + k * 1024); } while (0)
; #define PG8_WAIT_V(n) asm volatile("s_waitcnt vmcnt(" #n ")" ::: "memory")
;     DI void operator()(const f32x4 (&acc)[2][2][4][2], const Unit& u, int wr, int wc, int fr, int fq) const {
;         const int row0 = u.pm * BM + wr * 64 + fr, col0 = u.pn * BM + wc * 32 + 8 * fq;
; #pragma unroll
;         for (int ai = 0; ai < 2; ++ai)
; #pragma unroll
;             for (int m = 0; m < 4; ++m) { u16* rowp = O + (size_t)(row0 + ai * HALF + m * 16) * ldc + col0;
; #pragma unroll
;                 for (int bj = 0; bj < 2; ++bj) { const f32x4 v0 = acc[ai][bj][m][0], v1 = acc[ai][bj][m][1];
;                     uint4 w = {pack2(v0[0], v0[1]), pack2(v0[2], v0[3]), pack2(v1[0], v1[1]), pack2(v1[2], v1[3])}; *(uint4*)(rowp + bj * HALF) = w; } }
; template <class Epi, class Sched, bool STAMP = false>
; __device__ __forceinline__ void gemm_phase(PG8_LAS unsigned char* lds, const Gemm g, const Sched& S, const Epi& E, unsigned long long* stamps) {
;     ...
;             PG8_WAIT_V(6); PG8_BAR; PG8_MMA(1, 1, At, B1); PG8_BAR;
;             PG8_LDB(B0, 1, 0); PG8_SCHED; PG8_LDA(At, 1, 0); PG8_STAGE(PG8_SA(0, 1), a2 + hstep, voffA);
;             PG8_WAIT_L(8); PG8_BAR; PG8_WAIT_L(0); PG8_MMA(0, 0, At, B0); PG8_BAR; PG8_SCHED;
;             PG8_LDB(B1, 1, 1); PG8_STAGE(PG8_SB(1, 0), b3, voffB);
;             PG8_BAR; PG8_WAIT_L(0); PG8_MMA(0, 1, At, B1); PG8_BAR;
;             PG8_LDA(At, 1, 1); PG8_STAGE(PG8_SA(1, 0), a3, voffA);
;             PG8_BAR; PG8_WAIT_L(0); PG8_MMA(1, 0, At, B0); PG8_BAR; PG8_SCHED;
;             PG8_STAGE(PG8_SB(1, 1), b3 + hstep, voffB);
;             PG8_WAIT_V(6); PG8_BAR; PG8_MMA(1, 1, At, B1); PG8_BAR;
;         }
	s_setprio 1
	v_mfma_f32_16x16x32_bf16 v[44:47], v[214:217], v[182:185], v[44:47]
	v_mfma_f32_16x16x32_bf16 v[40:43], v[222:225], v[182:185], v[40:43]
	v_mfma_f32_16x16x32_bf16 v[28:31], v[214:217], v[190:193], v[28:31]
	v_mfma_f32_16x16x32_bf16 v[24:27], v[222:225], v[190:193], v[24:27]
	v_mfma_f32_16x16x32_bf16 v[12:15], v[214:217], v[198:201], v[12:15]
	v_mfma_f32_16x16x32_bf16 v[8:11], v[222:225], v[198:201], v[8:11]
	v_mfma_f32_16x16x32_bf16 v[4:7], v[214:217], v[206:209], v[4:7]
	v_mfma_f32_16x16x32_bf16 v[0:3], v[222:225], v[206:209], v[0:3]
	v_mfma_f32_16x16x32_bf16 v[44:47], v[218:221], v[186:189], v[44:47]
	v_mfma_f32_16x16x32_bf16 v[40:43], v[226:229], v[186:189], v[40:43]
	v_mfma_f32_16x16x32_bf16 v[28:31], v[218:221], v[194:197], v[28:31]
	v_mfma_f32_16x16x32_bf16 v[24:27], v[226:229], v[194:197], v[24:27]
	v_mfma_f32_16x16x32_bf16 v[12:15], v[218:221], v[202:205], v[12:15]
	v_mfma_f32_16x16x32_bf16 v[8:11], v[226:229], v[202:205], v[8:11]
	v_mfma_f32_16x16x32_bf16 v[4:7], v[218:221], v[210:213], v[4:7]
	v_mfma_f32_16x16x32_bf16 v[0:3], v[226:229], v[210:213], v[0:3]
	s_setprio 0
	s_barrier
	s_cbranch_scc0 .LBB0_97
	v_lshl_add_u32 v166, s84, 8, v145
	v_lshl_or_b32 v168, s87, 8, v147
	v_ashrrev_i32_e32 v167, 31, v166
	v_ashrrev_i32_e32 v169, 31, v168
	v_lshlrev_b64 v[170:171], 11, v[166:167]
	v_lshl_add_u64 v[170:171], s[14:15], 0, v[170:171]
	v_lshlrev_b64 v[168:169], 1, v[168:169]
	v_lshl_add_u64 v[170:171], v[170:171], 0, v[168:169]
	v_cvt_pk_bf16_f32 v60, v60, v61
	v_cvt_pk_bf16_f32 v61, v62, v63
	v_cvt_pk_bf16_f32 v62, v56, v57
	v_add_co_u32_e32 v56, vcc, s78, v170
	v_cvt_pk_bf16_f32 v68, v68, v69
	v_cvt_pk_bf16_f32 v69, v70, v71
	v_cvt_pk_bf16_f32 v70, v64, v65
	v_lshl_add_u64 v[64:65], v[170:171], 0, s[16:17]
	v_addc_co_u32_e32 v57, vcc, 0, v171, vcc
	v_cvt_pk_bf16_f32 v44, v44, v45
	v_cvt_pk_bf16_f32 v45, v46, v47
	v_cvt_pk_bf16_f32 v46, v40, v41
	v_cvt_pk_bf16_f32 v47, v42, v43
	v_cvt_pk_bf16_f32 v108, v108, v109
	v_cvt_pk_bf16_f32 v109, v110, v111
	v_cvt_pk_bf16_f32 v110, v104, v105
	v_or_b32_e32 v104, 16, v166
	global_store_dwordx4 v[64:65], v[44:47], off offset:256
	v_ashrrev_i32_e32 v105, 31, v104
	v_cvt_pk_bf16_f32 v92, v92, v93
	v_add_co_u32_e32 v46, vcc, s79, v170
	v_cvt_pk_bf16_f32 v93, v94, v95
	v_cvt_pk_bf16_f32 v94, v88, v89
	v_or_b32_e32 v88, 32, v166
	v_lshl_add_u64 v[44:45], v[170:171], 0, s[18:19]
	v_addc_co_u32_e32 v47, vcc, 0, v171, vcc
	v_cvt_pk_bf16_f32 v28, v28, v29
	v_cvt_pk_bf16_f32 v29, v30, v31
	v_cvt_pk_bf16_f32 v30, v24, v25
	v_cvt_pk_bf16_f32 v31, v26, v27
	v_lshlrev_b64 v[104:105], 11, v[104:105]
	v_ashrrev_i32_e32 v89, 31, v88
	v_cvt_pk_bf16_f32 v76, v76, v77
	v_cvt_pk_bf16_f32 v77, v78, v79
	v_cvt_pk_bf16_f32 v78, v72, v73
	v_or_b32_e32 v72, 48, v166
	global_store_dwordx4 v[44:45], v[28:31], off offset:256
	v_cvt_pk_bf16_f32 v111, v106, v107
	v_lshl_add_u64 v[104:105], s[14:15], 0, v[104:105]
	v_add_co_u32_e32 v30, vcc, s82, v170
	v_lshlrev_b64 v[88:89], 11, v[88:89]
	v_ashrrev_i32_e32 v73, 31, v72
	v_lshl_add_u64 v[28:29], v[170:171], 0, s[28:29]
	v_addc_co_u32_e32 v31, vcc, 0, v171, vcc
	v_cvt_pk_bf16_f32 v12, v12, v13
	v_cvt_pk_bf16_f32 v13, v14, v15
	v_cvt_pk_bf16_f32 v14, v8, v9
	v_cvt_pk_bf16_f32 v15, v10, v11
	global_store_dwordx4 v[170:171], v[108:111], off offset:256
	v_cvt_pk_bf16_f32 v95, v90, v91
	v_lshl_add_u64 v[88:89], s[14:15], 0, v[88:89]
	v_lshl_add_u64 v[108:109], v[104:105], 0, v[168:169]
	v_lshlrev_b64 v[72:73], 11, v[72:73]
	global_store_dwordx4 v[28:29], v[12:15], off offset:256
	global_store_dwordx4 v[108:109], v[92:95], off offset:256
	v_cvt_pk_bf16_f32 v79, v74, v75
	v_add_co_u32_e32 v14, vcc, s83, v170
	v_lshl_add_u64 v[92:93], v[88:89], 0, v[168:169]
	v_lshl_add_u64 v[72:73], s[14:15], 0, v[72:73]
	v_addc_co_u32_e32 v15, vcc, 0, v171, vcc
	v_cvt_pk_bf16_f32 v124, v124, v125
	v_cvt_pk_bf16_f32 v125, v126, v127
	v_cvt_pk_bf16_f32 v126, v120, v121
	v_cvt_pk_bf16_f32 v127, v122, v123
	v_cvt_pk_bf16_f32 v104, v116, v117
	v_cvt_pk_bf16_f32 v105, v118, v119
	v_cvt_pk_bf16_f32 v106, v112, v113
	v_cvt_pk_bf16_f32 v107, v114, v115
	v_cvt_pk_bf16_f32 v88, v100, v101
	v_cvt_pk_bf16_f32 v89, v102, v103
	v_cvt_pk_bf16_f32 v90, v96, v97
	v_cvt_pk_bf16_f32 v91, v98, v99
	global_store_dwordx4 v[92:93], v[76:79], off offset:256
	v_cvt_pk_bf16_f32 v74, v80, v81
	v_cvt_pk_bf16_f32 v75, v82, v83
	v_lshl_add_u64 v[76:77], v[72:73], 0, v[168:169]
	v_cvt_pk_bf16_f32 v72, v84, v85
	v_cvt_pk_bf16_f32 v73, v86, v87
	v_cvt_pk_bf16_f32 v71, v66, v67
	v_cvt_pk_bf16_f32 v63, v58, v59
	v_cvt_pk_bf16_f32 v40, v52, v53
	v_cvt_pk_bf16_f32 v41, v54, v55
	v_cvt_pk_bf16_f32 v42, v48, v49
	v_cvt_pk_bf16_f32 v43, v50, v51
	v_cvt_pk_bf16_f32 v24, v36, v37
	v_cvt_pk_bf16_f32 v25, v38, v39
	v_cvt_pk_bf16_f32 v26, v32, v33
	v_cvt_pk_bf16_f32 v27, v34, v35
	v_lshl_add_u64 v[12:13], v[170:171], 0, s[30:31]
	v_cvt_pk_bf16_f32 v8, v20, v21
	v_cvt_pk_bf16_f32 v9, v22, v23
	v_cvt_pk_bf16_f32 v10, v16, v17
	v_cvt_pk_bf16_f32 v11, v18, v19
	v_cvt_pk_bf16_f32 v4, v4, v5
	v_cvt_pk_bf16_f32 v5, v6, v7
	v_cvt_pk_bf16_f32 v6, v0, v1
	v_cvt_pk_bf16_f32 v7, v2, v3
	s_and_b64 vcc, exec, s[2:3]
	s_mov_b32 s87, s85
	s_mov_b32 s84, s86
	s_mov_b64 s[52:53], s[0:1]
	s_mov_b64 s[34:35], s[4:5]
	global_store_dwordx4 v[170:171], v[124:127], off
	global_store_dwordx4 v[108:109], v[104:107], off
	global_store_dwordx4 v[92:93], v[88:91], off
	global_store_dwordx4 v[76:77], v[72:75], off
	global_store_dwordx4 v[76:77], v[68:71], off offset:256
	global_store_dwordx4 v[56:57], v[60:63], off
	global_store_dwordx4 v[46:47], v[40:43], off
	global_store_dwordx4 v[30:31], v[24:27], off
	global_store_dwordx4 v[14:15], v[8:11], off
	global_store_dwordx4 v[12:13], v[4:7], off offset:256
	s_cbranch_vccz .LBB0_86
	s_waitcnt vmcnt(0)
	s_cmpk_gt_u32 s58, 0xff
	s_cbranch_scc1 .LBB0_101
	s_barrier

; #define PG8_STAGE(bufoff, gbase, voff) do { _Pragma("unroll") for (int _i = 0; _i < 2; ++_i) \
;         __builtin_amdgcn_global_load_lds((const unsigned*)((const char*)(gbase) + (voff)[_i]), (PG8_LAS unsigned*)(lds + (bufoff) + ldsw + _i * 8192), 16, 0, 0); } while (0)
; #define PG8_LDA(dst, b, h) do { _Pragma("unroll") for (int m = 0; m < 4; ++m) _Pragma("unroll") for (int k = 0; k < 2; ++k) dst[m][k] = *(const PG8_LAS bf16x8*)(lds + PG8_SA(b, h) + aoff + m * 2048 + k * 1024); } while (0)
; template <class Epi, class Sched, bool STAMP = false>
; __device__ __forceinline__ void gemm_phase(PG8_LAS unsigned char* lds, const Gemm g, const Sched& S, const Epi& E, unsigned long long* stamps) {
;     ...
;         for (int t = 0; t < nt; t += 2) {
;             const bool last = (t == nt - 2);
;             const char* a1 = cA + (size_t)(t + 1) * kstep;
;             const char* a2 = last ? nA : cA + (size_t)(t + 2) * kstep; const char* b2 = last ? nB : cB + (size_t)(t + 2) * kstep;
;             const char* a3 = a2 + kstep; const char* b3 = b2 + kstep;
;             if (last && has_next) S.a_ready(nxt);
;             PG8_LDB(B0, 0, 0); PG8_SCHED; PG8_LDA(At, 0, 0); PG8_STAGE(PG8_SA(1, 1), a1 + hstep, voffA);
;             PG8_WAIT_L(8); PG8_BAR; PG8_WAIT_L(0); PG8_MMA(0, 0, At, B0); PG8_BAR; PG8_SCHED;
;             PG8_LDB(B1, 0, 1); PG8_STAGE(PG8_SB(0, 0), b2, voffB);
;             PG8_BAR; PG8_WAIT_L(0); PG8_MMA(0, 1, At, B1); PG8_BAR;
;             PG8_LDA(At, 0, 1); PG8_STAGE(PG8_SA(0, 0), a2, voffA);
;             PG8_BAR; PG8_WAIT_L(0); PG8_MMA(1, 0, At, B0); PG8_BAR; PG8_SCHED;
;             PG8_STAGE(PG8_SB(0, 1), b2 + hstep, voffB);
;             PG8_WAIT_V(6); PG8_BAR; PG8_MMA(1, 1, At, B1); PG8_BAR;
;             PG8_LDB(B0, 1, 0); PG8_SCHED; PG8_LDA(At, 1, 0); PG8_STAGE(PG8_SA(0, 1), a2 + hstep, voffA);
;             PG8_WAIT_L(8); PG8_BAR; PG8_WAIT_L(0); PG8_MMA(0, 0, At, B0); PG8_BAR; PG8_SCHED;
;             PG8_LDB(B1, 1, 1); PG8_STAGE(PG8_SB(1, 0), b3, voffB);
;             PG8_BAR; PG8_WAIT_L(0); PG8_MMA(0, 1, At, B1); PG8_BAR;
;             PG8_LDA(At, 1, 1); PG8_STAGE(PG8_SA(1, 0), a3, voffA);
;             PG8_BAR; PG8_WAIT_L(0); PG8_MMA(1, 0, At, B0); PG8_BAR; PG8_SCHED;
;             PG8_STAGE(PG8_SB(1, 1), b3 + hstep, voffB);
;             PG8_WAIT_V(6); PG8_BAR; PG8_MMA(1, 1, At, B1); PG8_BAR;
;         }
.Lzp3_mid:
	ds_read_b128 v[166:169], v156
	ds_read_b128 v[170:173], v157
	ds_read_b128 v[174:177], v159
	ds_read_b128 v[178:181], v160
	s_add_u32 s28, s52, 0x44000
	s_addc_u32 s29, s53, 0
	s_mov_b32 m0, s63
	ds_read_b128 v[182:185], v146 offset:32768
	ds_read_b128 v[186:189], v146 offset:33792
	ds_read_b128 v[190:193], v146 offset:34816
	ds_read_b128 v[194:197], v146 offset:35840
	ds_read_b128 v[198:201], v146 offset:36864
	ds_read_b128 v[202:205], v146 offset:37888
	ds_read_b128 v[206:209], v146 offset:38912
	ds_read_b128 v[210:213], v146 offset:39936
	global_load_lds_dwordx4 v134, s[28:29]
	s_mov_b32 m0, s64
	s_nop 0
	global_load_lds_dwordx4 v130, s[28:29]
	s_waitcnt lgkmcnt(8)
	s_barrier
	s_waitcnt lgkmcnt(0)
	s_setprio 1
	s_waitcnt lgkmcnt(0)
	v_mfma_f32_16x16x32_bf16 v[124:127], v[166:169], v[182:185], v[124:127]
	v_mfma_f32_16x16x32_bf16 v[120:123], v[174:177], v[182:185], v[120:123]
	v_mfma_f32_16x16x32_bf16 v[116:119], v[166:169], v[190:193], v[116:119]
	v_mfma_f32_16x16x32_bf16 v[112:115], v[174:177], v[190:193], v[112:115]
	v_mfma_f32_16x16x32_bf16 v[108:111], v[166:169], v[198:201], v[108:111]
	v_mfma_f32_16x16x32_bf16 v[104:107], v[174:177], v[198:201], v[104:107]
	v_mfma_f32_16x16x32_bf16 v[100:103], v[166:169], v[206:209], v[100:103]
	v_mfma_f32_16x16x32_bf16 v[96:99], v[174:177], v[206:209], v[96:99]
	v_mfma_f32_16x16x32_bf16 v[124:127], v[170:173], v[186:189], v[124:127]
	v_mfma_f32_16x16x32_bf16 v[120:123], v[178:181], v[186:189], v[120:123]
	v_mfma_f32_16x16x32_bf16 v[116:119], v[170:173], v[194:197], v[116:119]
	v_mfma_f32_16x16x32_bf16 v[112:115], v[178:181], v[194:197], v[112:115]
	v_mfma_f32_16x16x32_bf16 v[108:111], v[170:173], v[202:205], v[108:111]
	v_mfma_f32_16x16x32_bf16 v[104:107], v[178:181], v[202:205], v[104:107]
	v_mfma_f32_16x16x32_bf16 v[100:103], v[170:173], v[210:213], v[100:103]
	v_mfma_f32_16x16x32_bf16 v[96:99], v[178:181], v[210:213], v[96:99]
	s_setprio 0
	s_barrier
	s_mov_b32 m0, s67
	ds_read_b128 v[214:217], v161
	ds_read_b128 v[218:221], v162
	ds_read_b128 v[222:225], v163
	ds_read_b128 v[226:229], v164
	s_add_u32 s100, s36, 0x80
	s_addc_u32 s101, s37, 0
	global_load_lds_dwordx4 v132, s[100:101]
	s_mov_b32 m0, s68
	s_nop 0
	global_load_lds_dwordx4 v128, s[100:101]
	s_barrier
	s_waitcnt lgkmcnt(0)
	s_setprio 1
	s_waitcnt lgkmcnt(0)
	v_mfma_f32_16x16x32_bf16 v[60:63], v[214:217], v[182:185], v[60:63]
	v_mfma_f32_16x16x32_bf16 v[56:59], v[222:225], v[182:185], v[56:59]
	v_mfma_f32_16x16x32_bf16 v[52:55], v[214:217], v[190:193], v[52:55]
	v_mfma_f32_16x16x32_bf16 v[48:51], v[222:225], v[190:193], v[48:51]
	v_mfma_f32_16x16x32_bf16 v[44:47], v[214:217], v[198:201], v[44:47]
	v_mfma_f32_16x16x32_bf16 v[40:43], v[222:225], v[198:201], v[40:43]
	v_mfma_f32_16x16x32_bf16 v[36:39], v[214:217], v[206:209], v[36:39]
	v_mfma_f32_16x16x32_bf16 v[32:35], v[222:225], v[206:209], v[32:35]
	v_mfma_f32_16x16x32_bf16 v[60:63], v[218:221], v[186:189], v[60:63]
	v_mfma_f32_16x16x32_bf16 v[56:59], v[226:229], v[186:189], v[56:59]
	v_mfma_f32_16x16x32_bf16 v[52:55], v[218:221], v[194:197], v[52:55]
	v_mfma_f32_16x16x32_bf16 v[48:51], v[226:229], v[194:197], v[48:51]
	v_mfma_f32_16x16x32_bf16 v[44:47], v[218:221], v[202:205], v[44:47]
	v_mfma_f32_16x16x32_bf16 v[40:43], v[226:229], v[202:205], v[40:43]
	v_mfma_f32_16x16x32_bf16 v[36:39], v[218:221], v[210:213], v[36:39]
	v_mfma_f32_16x16x32_bf16 v[32:35], v[226:229], v[210:213], v[32:35]
	s_setprio 0
	s_mov_b32 m0, s69
	s_barrier
	ds_read_b128 v[182:185], v146 offset:49152
	ds_read_b128 v[186:189], v146 offset:50176
	ds_read_b128 v[190:193], v146 offset:51200
	ds_read_b128 v[194:197], v146 offset:52224
	ds_read_b128 v[198:201], v146 offset:53248
	ds_read_b128 v[202:205], v146 offset:54272
	ds_read_b128 v[206:209], v146 offset:55296
	ds_read_b128 v[210:213], v146 offset:56320
	s_add_u32 s100, s52, 0x80
	s_addc_u32 s101, s53, 0
	global_load_lds_dwordx4 v134, s[100:101]
	s_mov_b32 m0, s70
	s_nop 0
	global_load_lds_dwordx4 v130, s[100:101]
	s_barrier
	s_waitcnt lgkmcnt(0)
	s_setprio 1
	s_waitcnt lgkmcnt(0)
	v_mfma_f32_16x16x32_bf16 v[92:95], v[166:169], v[182:185], v[92:95]
	v_mfma_f32_16x16x32_bf16 v[88:91], v[174:177], v[182:185], v[88:91]
	v_mfma_f32_16x16x32_bf16 v[84:87], v[166:169], v[190:193], v[84:87]
	v_mfma_f32_16x16x32_bf16 v[80:83], v[174:177], v[190:193], v[80:83]
	v_mfma_f32_16x16x32_bf16 v[76:79], v[166:169], v[198:201], v[76:79]
	v_mfma_f32_16x16x32_bf16 v[72:75], v[174:177], v[198:201], v[72:75]
	v_mfma_f32_16x16x32_bf16 v[68:71], v[166:169], v[206:209], v[68:71]
	v_mfma_f32_16x16x32_bf16 v[64:67], v[174:177], v[206:209], v[64:67]
	v_mfma_f32_16x16x32_bf16 v[92:95], v[170:173], v[186:189], v[92:95]
	v_mfma_f32_16x16x32_bf16 v[88:91], v[178:181], v[186:189], v[88:91]
	v_mfma_f32_16x16x32_bf16 v[84:87], v[170:173], v[194:197], v[84:87]
	v_mfma_f32_16x16x32_bf16 v[80:83], v[178:181], v[194:197], v[80:83]
	v_mfma_f32_16x16x32_bf16 v[76:79], v[170:173], v[202:205], v[76:79]
	v_mfma_f32_16x16x32_bf16 v[72:75], v[178:181], v[202:205], v[72:75]
	v_mfma_f32_16x16x32_bf16 v[68:71], v[170:173], v[210:213], v[68:71]
	v_mfma_f32_16x16x32_bf16 v[64:67], v[178:181], v[210:213], v[64:67]
	s_setprio 0
	s_barrier
	s_add_u32 s28, s36, 0x44080
	s_addc_u32 s29, s37, 0
	s_mov_b32 m0, s71
	s_nop 0
	global_load_lds_dwordx4 v132, s[28:29]
	s_mov_b32 m0, s72
	s_nop 0
	global_load_lds_dwordx4 v128, s[28:29]
	s_add_i32 s85, s85, 2
	s_add_u32 s83, s83, 0x100
	s_addc_u32 s84, s84, 0
	s_cmp_gt_u32 s85, 13
	s_mov_b64 s[28:29], s[34:35]
	s_waitcnt vmcnt(6)
	s_barrier
; #define PG8_STAGE(bufoff, gbase, voff) do { _Pragma("unroll") for (int _i = 0; _i < 2; ++_i) \
;         __builtin_amdgcn_global_load_lds((const unsigned*)((const char*)(gbase) + (voff)[_i]), (PG8_LAS unsigned*)(lds + (bufoff) + ldsw + _i * 8192), 16, 0, 0); } while (0)
; #define PG8_LDA(dst, b, h) do { _Pragma("unroll") for (int m = 0; m < 4; ++m) _Pragma("unroll") for (int k = 0; k < 2; ++k) dst[m][k] = *(const PG8_LAS bf16x8*)(lds + PG8_SA(b, h) + aoff + m * 2048 + k * 1024); } while (0)
; #define PG8_WAIT_V(n) asm volatile("s_waitcnt vmcnt(" #n ")" ::: "memory")
;     DI void operator()(const f32x4 (&acc)[2][2][4][2], const Unit& u, int wr, int wc, int fr, int fq) const {
;         const int row0 = u.pm * BM + wr * 64 + fr, col0 = u.pn * BM + wc * 32 + 8 * fq;
; #pragma unroll
;         for (int ai = 0; ai < 2; ++ai)
; #pragma unroll
;             for (int m = 0; m < 4; ++m) { u16* rowp = O + (size_t)(row0 + ai * HALF + m * 16) * ldc + col0;
; #pragma unroll
;                 for (int bj = 0; bj < 2; ++bj) { const f32x4 v0 = acc[ai][bj][m][0], v1 = acc[ai][bj][m][1];
;                     uint4 w = {pack2(v0[0], v0[1]), pack2(v0[2], v0[3]), pack2(v1[0], v1[1]), pack2(v1[2], v1[3])}; *(uint4*)(rowp + bj * HALF) = w; } }
;         if (kmaxp) {
; #pragma unroll
;             for (int bj = 0; bj < 2; ++bj) {
;                 const int cb = u.pn * BM + bj * HALF + wc * 32;
;                 const bool isA = (cb >= 384 && cb < 768), isB = (cb >= 1408 && cb < 1664);
; template <class Epi, class Sched, bool STAMP = false>
; __device__ __forceinline__ void gemm_phase(PG8_LAS unsigned char* lds, const Gemm g, const Sched& S, const Epi& E, unsigned long long* stamps) {
;     ...
;             PG8_WAIT_V(6); PG8_BAR; PG8_MMA(1, 1, At, B1); PG8_BAR;
;             PG8_LDB(B0, 1, 0); PG8_SCHED; PG8_LDA(At, 1, 0); PG8_STAGE(PG8_SA(0, 1), a2 + hstep, voffA);
;             PG8_WAIT_L(8); PG8_BAR; PG8_WAIT_L(0); PG8_MMA(0, 0, At, B0); PG8_BAR; PG8_SCHED;
;             PG8_LDB(B1, 1, 1); PG8_STAGE(PG8_SB(1, 0), b3, voffB);
;             PG8_BAR; PG8_WAIT_L(0); PG8_MMA(0, 1, At, B1); PG8_BAR;
;             PG8_LDA(At, 1, 1); PG8_STAGE(PG8_SA(1, 0), a3, voffA);
;             PG8_BAR; PG8_WAIT_L(0); PG8_MMA(1, 0, At, B0); PG8_BAR; PG8_SCHED;
;             PG8_STAGE(PG8_SB(1, 1), b3 + hstep, voffB);
;             PG8_WAIT_V(6); PG8_BAR; PG8_MMA(1, 1, At, B1); PG8_BAR;
;         }
	s_setprio 1
	v_mfma_f32_16x16x32_bf16 v[28:31], v[214:217], v[182:185], v[28:31]
	v_mfma_f32_16x16x32_bf16 v[24:27], v[222:225], v[182:185], v[24:27]
	v_mfma_f32_16x16x32_bf16 v[20:23], v[214:217], v[190:193], v[20:23]
	v_mfma_f32_16x16x32_bf16 v[16:19], v[222:225], v[190:193], v[16:19]
	v_mfma_f32_16x16x32_bf16 v[12:15], v[214:217], v[198:201], v[12:15]
	v_mfma_f32_16x16x32_bf16 v[8:11], v[222:225], v[198:201], v[8:11]
	v_mfma_f32_16x16x32_bf16 v[4:7], v[214:217], v[206:209], v[4:7]
	v_mfma_f32_16x16x32_bf16 v[0:3], v[222:225], v[206:209], v[0:3]
	v_mfma_f32_16x16x32_bf16 v[28:31], v[218:221], v[186:189], v[28:31]
	v_mfma_f32_16x16x32_bf16 v[24:27], v[226:229], v[186:189], v[24:27]
	v_mfma_f32_16x16x32_bf16 v[20:23], v[218:221], v[194:197], v[20:23]
	v_mfma_f32_16x16x32_bf16 v[16:19], v[226:229], v[194:197], v[16:19]
	v_mfma_f32_16x16x32_bf16 v[12:15], v[218:221], v[202:205], v[12:15]
	v_mfma_f32_16x16x32_bf16 v[8:11], v[226:229], v[202:205], v[8:11]
	v_mfma_f32_16x16x32_bf16 v[4:7], v[218:221], v[210:213], v[4:7]
	v_mfma_f32_16x16x32_bf16 v[0:3], v[226:229], v[210:213], v[0:3]
	s_setprio 0
	s_barrier
	s_cbranch_scc0 .LBB0_138
	s_lshl_b32 s52, s79, 8
	v_or_b32_e32 v166, s52, v147
	v_lshl_add_u32 v176, s82, 8, v145
	v_ashrrev_i32_e32 v167, 31, v166
	v_mov_b64_e32 v[170:171], s[12:13]
	v_mad_i64_i32 v[168:169], s[28:29], v176, s76, v[170:171]
	v_lshlrev_b64 v[172:173], 1, v[166:167]
	v_lshl_add_u64 v[174:175], v[168:169], 0, v[172:173]
	v_cvt_pk_bf16_f32 v166, v124, v125
	v_cvt_pk_bf16_f32 v167, v126, v127
	v_cvt_pk_bf16_f32 v168, v120, v121
	v_cvt_pk_bf16_f32 v169, v122, v123
	global_store_dwordx4 v[174:175], v[166:169], off
	s_or_b32 s10, s52, s66
	s_nop 0
	v_cvt_pk_bf16_f32 v166, v60, v61
	v_cvt_pk_bf16_f32 v167, v62, v63
	v_cvt_pk_bf16_f32 v168, v56, v57
	v_cvt_pk_bf16_f32 v169, v58, v59
	global_store_dwordx4 v[174:175], v[166:169], off offset:256
	s_nop 1
	v_or_b32_e32 v166, 16, v176
	v_mad_i64_i32 v[166:167], s[28:29], v166, s76, v[170:171]
	v_lshl_add_u64 v[174:175], v[166:167], 0, v[172:173]
	v_cvt_pk_bf16_f32 v166, v116, v117
	v_cvt_pk_bf16_f32 v167, v118, v119
	v_cvt_pk_bf16_f32 v168, v112, v113
	v_cvt_pk_bf16_f32 v169, v114, v115
	global_store_dwordx4 v[174:175], v[166:169], off
	s_nop 1
	v_cvt_pk_bf16_f32 v166, v52, v53
	v_cvt_pk_bf16_f32 v167, v54, v55
	v_cvt_pk_bf16_f32 v168, v48, v49
	v_cvt_pk_bf16_f32 v169, v50, v51
	global_store_dwordx4 v[174:175], v[166:169], off offset:256
	s_nop 1
	v_or_b32_e32 v166, 32, v176
	v_mad_i64_i32 v[166:167], s[28:29], v166, s76, v[170:171]
	v_lshl_add_u64 v[174:175], v[166:167], 0, v[172:173]
	v_cvt_pk_bf16_f32 v166, v108, v109
	v_cvt_pk_bf16_f32 v167, v110, v111
	v_cvt_pk_bf16_f32 v168, v104, v105
	v_cvt_pk_bf16_f32 v169, v106, v107
	global_store_dwordx4 v[174:175], v[166:169], off
	s_nop 1
	v_cvt_pk_bf16_f32 v166, v44, v45
	v_cvt_pk_bf16_f32 v167, v46, v47
	v_cvt_pk_bf16_f32 v168, v40, v41
	v_cvt_pk_bf16_f32 v169, v42, v43
	global_store_dwordx4 v[174:175], v[166:169], off offset:256
	s_nop 1
	v_or_b32_e32 v166, 48, v176
	v_mad_i64_i32 v[166:167], s[28:29], v166, s76, v[170:171]
	v_lshl_add_u64 v[174:175], v[166:167], 0, v[172:173]
	v_cvt_pk_bf16_f32 v166, v100, v101
	v_cvt_pk_bf16_f32 v167, v102, v103
	v_cvt_pk_bf16_f32 v168, v96, v97
	v_cvt_pk_bf16_f32 v169, v98, v99
	global_store_dwordx4 v[174:175], v[166:169], off
	s_nop 1
	v_cvt_pk_bf16_f32 v166, v36, v37
	v_cvt_pk_bf16_f32 v167, v38, v39
	v_cvt_pk_bf16_f32 v168, v32, v33
	v_cvt_pk_bf16_f32 v169, v34, v35
	global_store_dwordx4 v[174:175], v[166:169], off offset:256
	s_nop 1
	v_add_u32_e32 v166, 0x80, v176
	v_mad_i64_i32 v[166:167], s[28:29], v166, s76, v[170:171]
	v_lshl_add_u64 v[174:175], v[166:167], 0, v[172:173]
	v_cvt_pk_bf16_f32 v166, v92, v93
	v_cvt_pk_bf16_f32 v167, v94, v95
	v_cvt_pk_bf16_f32 v168, v88, v89
	v_cvt_pk_bf16_f32 v169, v90, v91
	global_store_dwordx4 v[174:175], v[166:169], off
	s_nop 1
	v_cvt_pk_bf16_f32 v166, v28, v29
	v_cvt_pk_bf16_f32 v167, v30, v31
	v_cvt_pk_bf16_f32 v168, v24, v25
	v_cvt_pk_bf16_f32 v169, v26, v27
	global_store_dwordx4 v[174:175], v[166:169], off offset:256
	s_nop 1
	v_add_u32_e32 v166, 0x90, v176
	v_mad_i64_i32 v[166:167], s[28:29], v166, s76, v[170:171]
	v_lshl_add_u64 v[174:175], v[166:167], 0, v[172:173]
	v_cvt_pk_bf16_f32 v166, v84, v85
	v_cvt_pk_bf16_f32 v167, v86, v87
	v_cvt_pk_bf16_f32 v168, v80, v81
	v_cvt_pk_bf16_f32 v169, v82, v83
	global_store_dwordx4 v[174:175], v[166:169], off
	s_nop 1
	v_cvt_pk_bf16_f32 v166, v20, v21
	v_cvt_pk_bf16_f32 v167, v22, v23
	v_cvt_pk_bf16_f32 v168, v16, v17
	v_cvt_pk_bf16_f32 v169, v18, v19
	global_store_dwordx4 v[174:175], v[166:169], off offset:256
	s_nop 1
	v_add_u32_e32 v166, 0xa0, v176
	v_mad_i64_i32 v[166:167], s[28:29], v166, s76, v[170:171]
	v_lshl_add_u64 v[174:175], v[166:167], 0, v[172:173]
	v_cvt_pk_bf16_f32 v166, v76, v77
	v_cvt_pk_bf16_f32 v167, v78, v79
	v_cvt_pk_bf16_f32 v168, v72, v73
	v_cvt_pk_bf16_f32 v169, v74, v75
	global_store_dwordx4 v[174:175], v[166:169], off
	s_nop 1
	v_cvt_pk_bf16_f32 v166, v12, v13
	v_cvt_pk_bf16_f32 v167, v14, v15
	v_cvt_pk_bf16_f32 v168, v8, v9
	v_cvt_pk_bf16_f32 v169, v10, v11
	global_store_dwordx4 v[174:175], v[166:169], off offset:256
	s_nop 1
	v_add_u32_e32 v166, 0xb0, v176
	v_mad_i64_i32 v[166:167], s[28:29], v166, s76, v[170:171]
	s_add_i32 s28, s52, 0xfffffe80
	s_cmpk_gt_u32 s28, 0x17f
	s_cselect_b64 s[28:29], -1, 0
	s_add_i32 s34, s52, 0xfffffa80
	s_cmpk_gt_u32 s34, 0xff
	s_cselect_b64 s[34:35], -1, 0
	v_lshl_add_u64 v[170:171], v[166:167], 0, v[172:173]
	v_cvt_pk_bf16_f32 v166, v68, v69
	v_cvt_pk_bf16_f32 v167, v70, v71
	v_cvt_pk_bf16_f32 v168, v64, v65
	v_cvt_pk_bf16_f32 v169, v66, v67
	s_and_b64 s[34:35], s[28:29], s[34:35]
	global_store_dwordx4 v[170:171], v[166:169], off
	s_and_b64 vcc, exec, s[34:35]
	s_nop 0
	v_cvt_pk_bf16_f32 v166, v4, v5
	v_cvt_pk_bf16_f32 v167, v6, v7
	v_cvt_pk_bf16_f32 v168, v0, v1
	v_cvt_pk_bf16_f32 v169, v2, v3
	global_store_dwordx4 v[170:171], v[166:169], off offset:256
	s_cbranch_vccnz .LBB0_150
;     DI void operator()(const f32x4 (&acc)[2][2][4][2], const Unit& u, int wr, int wc, int fr, int fq) const {
;     ...
;         if (kmaxp) {
; #pragma unroll
;             for (int bj = 0; bj < 2; ++bj) {
;                 const int cb = u.pn * BM + bj * HALF + wc * 32;
;                 const bool isA = (cb >= 384 && cb < 768), isB = (cb >= 1408 && cb < 1664);
;                 if (isA || isB) {
;                     float mx = 0.f;
; #pragma unroll
;                     for (int ai = 0; ai < 2; ++ai)
; #pragma unroll
;                         for (int m = 0; m < 4; ++m) {
;                             const f32x4 a = acc[ai][bj][m][0], b = acc[ai][bj][m][1];
;                             float s0 = a[0] * a[0] + a[1] * a[1] + a[2] * a[2] + a[3] * a[3] + b[0] * b[0] + b[1] * b[1] + b[2] * b[2] + b[3] * b[3];
;                             s0 += __shfl_xor(s0, 16);
;                             s0 += __shfl_xor(s0, 32);
;                             mx = fmaxf(mx, s0);
;                         }
; #pragma unroll
;                     for (int o = 1; o <= 8; o <<= 1) mx = fmaxf(mx, __shfl_xor(mx, o));
;                     if ((threadIdx.x & 63) == 0) atomicMax((unsigned*)kmaxp + (isA ? ((cb - 384) >> 5) : (12 + ((cb - 1408) >> 5))), __float_as_uint(mx));
;                 }
;             }
;         }
	v_mul_f32_e32 v125, v125, v125
	v_mul_f32_e32 v117, v117, v117
	v_fmac_f32_e32 v125, v124, v124
	v_fmac_f32_e32 v117, v116, v116
	v_mul_f32_e32 v109, v109, v109
	v_mul_f32_e32 v101, v101, v101
	v_fmac_f32_e32 v125, v126, v126
	v_fmac_f32_e32 v117, v118, v118
	v_fmac_f32_e32 v109, v108, v108
	v_fmac_f32_e32 v101, v100, v100
	v_and_b32_e32 v167, 64, v165
	v_fmac_f32_e32 v125, v127, v127
	v_fmac_f32_e32 v117, v119, v119
	v_fmac_f32_e32 v109, v110, v110
	v_fmac_f32_e32 v101, v102, v102
	v_xor_b32_e32 v166, 16, v165
	v_add_u32_e32 v167, 64, v167
	v_fmac_f32_e32 v125, v120, v120
	v_fmac_f32_e32 v117, v112, v112
	v_fmac_f32_e32 v109, v111, v111
	v_fmac_f32_e32 v101, v103, v103
	v_cmp_lt_i32_e32 vcc, v166, v167
	v_fmac_f32_e32 v125, v121, v121
	v_fmac_f32_e32 v117, v113, v113
	v_fmac_f32_e32 v109, v104, v104
	v_fmac_f32_e32 v101, v96, v96
	v_cndmask_b32_e32 v166, v165, v166, vcc
	v_fmac_f32_e32 v125, v122, v122
	v_fmac_f32_e32 v117, v114, v114
	v_fmac_f32_e32 v109, v105, v105
	v_fmac_f32_e32 v101, v97, v97
	v_lshlrev_b32_e32 v166, 2, v166
	v_fmac_f32_e32 v125, v123, v123
	v_fmac_f32_e32 v117, v115, v115
	v_fmac_f32_e32 v109, v106, v106
	v_fmac_f32_e32 v101, v98, v98
	v_mul_f32_e32 v93, v93, v93
	v_mul_f32_e32 v85, v85, v85
	ds_bpermute_b32 v120, v166, v125
	ds_bpermute_b32 v112, v166, v117
	v_fmac_f32_e32 v109, v107, v107
	v_fmac_f32_e32 v101, v99, v99
	v_fmac_f32_e32 v93, v92, v92
	v_fmac_f32_e32 v85, v84, v84
	v_mul_f32_e32 v77, v77, v77
	v_mul_f32_e32 v69, v69, v69
	ds_bpermute_b32 v104, v166, v109
	ds_bpermute_b32 v96, v166, v101
	v_fmac_f32_e32 v93, v94, v94
	v_fmac_f32_e32 v85, v86, v86
	v_fmac_f32_e32 v77, v76, v76
	v_fmac_f32_e32 v69, v68, v68
	v_xor_b32_e32 v168, 32, v165
	v_fmac_f32_e32 v93, v95, v95
	v_fmac_f32_e32 v85, v87, v87
	v_fmac_f32_e32 v77, v78, v78
	v_fmac_f32_e32 v69, v70, v70
	v_cmp_lt_i32_e32 vcc, v168, v167
	v_fmac_f32_e32 v93, v88, v88
	v_fmac_f32_e32 v85, v80, v80
	v_fmac_f32_e32 v77, v79, v79
	v_fmac_f32_e32 v69, v71, v71
	v_cndmask_b32_e32 v113, v165, v168, vcc
	v_fmac_f32_e32 v93, v89, v89
	v_fmac_f32_e32 v85, v81, v81
	v_fmac_f32_e32 v77, v72, v72
	v_fmac_f32_e32 v69, v64, v64
	v_lshlrev_b32_e32 v113, 2, v113
	s_waitcnt lgkmcnt(0)
	v_add_f32_e32 v114, v125, v120
	v_add_f32_e32 v112, v117, v112
	v_fmac_f32_e32 v93, v90, v90
	v_fmac_f32_e32 v85, v82, v82
	v_fmac_f32_e32 v77, v73, v73
	v_fmac_f32_e32 v69, v65, v65
	ds_bpermute_b32 v115, v113, v114
	ds_bpermute_b32 v116, v113, v112
	v_add_f32_e32 v99, v109, v104
	v_add_f32_e32 v96, v101, v96
	v_fmac_f32_e32 v93, v91, v91
	v_fmac_f32_e32 v85, v83, v83
	v_fmac_f32_e32 v77, v74, v74
	v_fmac_f32_e32 v69, v66, v66
	ds_bpermute_b32 v100, v113, v99
	ds_bpermute_b32 v101, v113, v96
	ds_bpermute_b32 v88, v166, v93
	ds_bpermute_b32 v80, v166, v85
	v_fmac_f32_e32 v77, v75, v75
	v_fmac_f32_e32 v69, v67, v67
	ds_bpermute_b32 v72, v166, v77
	ds_bpermute_b32 v64, v166, v69
	s_waitcnt lgkmcnt(0)
	v_add_f32_e32 v97, v114, v115
	v_add_f32_e32 v98, v112, v116
	v_max3_f32 v89, v97, 0, v98
	v_add_f32_e32 v90, v99, v100
	v_add_f32_e32 v91, v96, v101
	v_add_f32_e32 v88, v93, v88
	v_add_f32_e32 v65, v85, v80
	v_max3_f32 v89, v89, v90, v91
	ds_bpermute_b32 v90, v113, v88
	ds_bpermute_b32 v66, v113, v65
	v_add_f32_e32 v67, v77, v72
	v_add_f32_e32 v64, v69, v64
	ds_bpermute_b32 v68, v113, v67
	ds_bpermute_b32 v69, v113, v64
	s_waitcnt lgkmcnt(0)
	v_add_f32_e32 v70, v88, v90
	v_add_f32_e32 v65, v65, v66
	v_max3_f32 v65, v89, v70, v65
	v_add_f32_e32 v66, v67, v68
	v_add_f32_e32 v64, v64, v69
	v_max3_f32 v64, v65, v66, v64
	v_xor_b32_e32 v65, 1, v165
	v_cmp_lt_i32_e32 vcc, v65, v167
	s_nop 1
	v_cndmask_b32_e32 v65, v165, v65, vcc
	v_lshlrev_b32_e32 v65, 2, v65
	ds_bpermute_b32 v65, v65, v64
	s_waitcnt lgkmcnt(0)
	v_max_f32_e32 v65, v65, v65
	v_max_f32_e32 v64, v64, v65
	v_xor_b32_e32 v65, 2, v165
	v_cmp_lt_i32_e32 vcc, v65, v167
	s_nop 1
	v_cndmask_b32_e32 v65, v165, v65, vcc
	v_lshlrev_b32_e32 v65, 2, v65
	ds_bpermute_b32 v65, v65, v64
	s_waitcnt lgkmcnt(0)
	v_max_f32_e32 v65, v65, v65
	v_max_f32_e32 v64, v64, v65
	v_xor_b32_e32 v65, 4, v165
	v_cmp_lt_i32_e32 vcc, v65, v167
	s_nop 1
	v_cndmask_b32_e32 v65, v165, v65, vcc
	v_lshlrev_b32_e32 v65, 2, v65
	ds_bpermute_b32 v65, v65, v64
	s_waitcnt lgkmcnt(0)
	v_max_f32_e32 v65, v65, v65
	v_max_f32_e32 v64, v64, v65
	v_xor_b32_e32 v65, 8, v165
	v_cmp_lt_i32_e32 vcc, v65, v167
	s_nop 1
	v_cndmask_b32_e32 v65, v165, v65, vcc
	v_lshlrev_b32_e32 v65, 2, v65
	ds_bpermute_b32 v65, v65, v64
	s_and_saveexec_b64 s[34:35], s[2:3]
	s_cbranch_execz .LBB0_149
	s_mov_b64 s[36:37], -1
	s_and_b64 vcc, exec, s[28:29]
	s_cbranch_vccz .LBB0_143
	s_add_i32 s28, s10, 0xfffffa80
	s_ashr_i32 s28, s28, 5
	s_add_i32 s28, s28, 12
	s_mov_b64 s[36:37], 0

; #define PG8_STAGE(bufoff, gbase, voff) do { _Pragma("unroll") for (int _i = 0; _i < 2; ++_i) \
;         __builtin_amdgcn_global_load_lds((const unsigned*)((const char*)(gbase) + (voff)[_i]), (PG8_LAS unsigned*)(lds + (bufoff) + ldsw + _i * 8192), 16, 0, 0); } while (0)
; #define PG8_LDA(dst, b, h) do { _Pragma("unroll") for (int m = 0; m < 4; ++m) _Pragma("unroll") for (int k = 0; k < 2; ++k) dst[m][k] = *(const PG8_LAS bf16x8*)(lds + PG8_SA(b, h) + aoff + m * 2048 + k * 1024); } while (0)
; template <class Epi, class Sched, bool STAMP = false>
; __device__ __forceinline__ void gemm_phase(PG8_LAS unsigned char* lds, const Gemm g, const Sched& S, const Epi& E, unsigned long long* stamps) {
;     ...
;         for (int t = 0; t < nt; t += 2) {
;             const bool last = (t == nt - 2);
;             const char* a1 = cA + (size_t)(t + 1) * kstep;
;             const char* a2 = last ? nA : cA + (size_t)(t + 2) * kstep; const char* b2 = last ? nB : cB + (size_t)(t + 2) * kstep;
;             const char* a3 = a2 + kstep; const char* b3 = b2 + kstep;
;             if (last && has_next) S.a_ready(nxt);
;             PG8_LDB(B0, 0, 0); PG8_SCHED; PG8_LDA(At, 0, 0); PG8_STAGE(PG8_SA(1, 1), a1 + hstep, voffA);
;             PG8_WAIT_L(8); PG8_BAR; PG8_WAIT_L(0); PG8_MMA(0, 0, At, B0); PG8_BAR; PG8_SCHED;
;             PG8_LDB(B1, 0, 1); PG8_STAGE(PG8_SB(0, 0), b2, voffB);
;             PG8_BAR; PG8_WAIT_L(0); PG8_MMA(0, 1, At, B1); PG8_BAR;
;             PG8_LDA(At, 0, 1); PG8_STAGE(PG8_SA(0, 0), a2, voffA);
;             PG8_BAR; PG8_WAIT_L(0); PG8_MMA(1, 0, At, B0); PG8_BAR; PG8_SCHED;
;             PG8_STAGE(PG8_SB(0, 1), b2 + hstep, voffB);
;             PG8_WAIT_V(6); PG8_BAR; PG8_MMA(1, 1, At, B1); PG8_BAR;
;             PG8_LDB(B0, 1, 0); PG8_SCHED; PG8_LDA(At, 1, 0); PG8_STAGE(PG8_SA(0, 1), a2 + hstep, voffA);
;             PG8_WAIT_L(8); PG8_BAR; PG8_WAIT_L(0); PG8_MMA(0, 0, At, B0); PG8_BAR; PG8_SCHED;
;             PG8_LDB(B1, 1, 1); PG8_STAGE(PG8_SB(1, 0), b3, voffB);
;             PG8_BAR; PG8_WAIT_L(0); PG8_MMA(0, 1, At, B1); PG8_BAR;
;             PG8_LDA(At, 1, 1); PG8_STAGE(PG8_SA(1, 0), a3, voffA);
;             PG8_BAR; PG8_WAIT_L(0); PG8_MMA(1, 0, At, B0); PG8_BAR; PG8_SCHED;
;             PG8_STAGE(PG8_SB(1, 1), b3 + hstep, voffB);
;             PG8_WAIT_V(6); PG8_BAR; PG8_MMA(1, 1, At, B1); PG8_BAR;
;         }
.Lzp4_mid:
	ds_read_b128 v[170:173], v155
	ds_read_b128 v[174:177], v156
	ds_read_b128 v[178:181], v157
	ds_read_b128 v[182:185], v165
	s_add_u32 s56, s62, 0x44000
	s_addc_u32 s57, s63, 0
	s_mov_b32 m0, s72
	ds_read_b128 v[186:189], v145 offset:32768
	ds_read_b128 v[190:193], v145 offset:33792
	ds_read_b128 v[194:197], v145 offset:34816
	ds_read_b128 v[198:201], v145 offset:35840
	ds_read_b128 v[202:205], v145 offset:36864
	ds_read_b128 v[206:209], v145 offset:37888
	ds_read_b128 v[210:213], v145 offset:38912
	ds_read_b128 v[214:217], v145 offset:39936
	global_load_lds_dwordx4 v128, s[56:57]
	s_mov_b32 m0, s73
	s_nop 0
	global_load_lds_dwordx4 v132, s[56:57]
	s_waitcnt lgkmcnt(8)
	s_barrier
	s_waitcnt lgkmcnt(0)
	s_setprio 1
	s_waitcnt lgkmcnt(0)
	v_mfma_f32_16x16x32_bf16 v[124:127], v[170:173], v[186:189], v[124:127]
	v_mfma_f32_16x16x32_bf16 v[120:123], v[178:181], v[186:189], v[120:123]
	v_mfma_f32_16x16x32_bf16 v[116:119], v[170:173], v[194:197], v[116:119]
	v_mfma_f32_16x16x32_bf16 v[112:115], v[178:181], v[194:197], v[112:115]
	v_mfma_f32_16x16x32_bf16 v[100:103], v[170:173], v[202:205], v[100:103]
	v_mfma_f32_16x16x32_bf16 v[96:99], v[178:181], v[202:205], v[96:99]
	v_mfma_f32_16x16x32_bf16 v[84:87], v[170:173], v[210:213], v[84:87]
	v_mfma_f32_16x16x32_bf16 v[80:83], v[178:181], v[210:213], v[80:83]
	v_mfma_f32_16x16x32_bf16 v[124:127], v[174:177], v[190:193], v[124:127]
	v_mfma_f32_16x16x32_bf16 v[120:123], v[182:185], v[190:193], v[120:123]
	v_mfma_f32_16x16x32_bf16 v[116:119], v[174:177], v[198:201], v[116:119]
	v_mfma_f32_16x16x32_bf16 v[112:115], v[182:185], v[198:201], v[112:115]
	v_mfma_f32_16x16x32_bf16 v[100:103], v[174:177], v[206:209], v[100:103]
	v_mfma_f32_16x16x32_bf16 v[96:99], v[182:185], v[206:209], v[96:99]
	v_mfma_f32_16x16x32_bf16 v[84:87], v[174:177], v[214:217], v[84:87]
	v_mfma_f32_16x16x32_bf16 v[80:83], v[182:185], v[214:217], v[80:83]
	s_setprio 0
	s_barrier
	s_mov_b32 m0, s74
	ds_read_b128 v[218:221], v166
	ds_read_b128 v[222:225], v167
	ds_read_b128 v[226:229], v168
	ds_read_b128 v[230:233], v169
	s_add_u32 s100, s60, 0x80
	s_addc_u32 s101, s61, 0
	global_load_lds_dwordx4 v130, s[100:101]
	s_mov_b32 m0, s75
	s_nop 0
	global_load_lds_dwordx4 v134, s[100:101]
	s_barrier
	s_waitcnt lgkmcnt(0)
	s_setprio 1
	s_waitcnt lgkmcnt(0)
	v_mfma_f32_16x16x32_bf16 v[108:111], v[218:221], v[186:189], v[108:111]
	v_mfma_f32_16x16x32_bf16 v[104:107], v[226:229], v[186:189], v[104:107]
	v_mfma_f32_16x16x32_bf16 v[92:95], v[218:221], v[194:197], v[92:95]
	v_mfma_f32_16x16x32_bf16 v[88:91], v[226:229], v[194:197], v[88:91]
	v_mfma_f32_16x16x32_bf16 v[76:79], v[218:221], v[202:205], v[76:79]
	v_mfma_f32_16x16x32_bf16 v[72:75], v[226:229], v[202:205], v[72:75]
	v_mfma_f32_16x16x32_bf16 v[68:71], v[218:221], v[210:213], v[68:71]
	v_mfma_f32_16x16x32_bf16 v[64:67], v[226:229], v[210:213], v[64:67]
	v_mfma_f32_16x16x32_bf16 v[108:111], v[222:225], v[190:193], v[108:111]
	v_mfma_f32_16x16x32_bf16 v[104:107], v[230:233], v[190:193], v[104:107]
	v_mfma_f32_16x16x32_bf16 v[92:95], v[222:225], v[198:201], v[92:95]
	v_mfma_f32_16x16x32_bf16 v[88:91], v[230:233], v[198:201], v[88:91]
	v_mfma_f32_16x16x32_bf16 v[76:79], v[222:225], v[206:209], v[76:79]
	v_mfma_f32_16x16x32_bf16 v[72:75], v[230:233], v[206:209], v[72:75]
	v_mfma_f32_16x16x32_bf16 v[68:71], v[222:225], v[214:217], v[68:71]
	v_mfma_f32_16x16x32_bf16 v[64:67], v[230:233], v[214:217], v[64:67]
	s_setprio 0
	s_mov_b32 m0, s76
	s_barrier
	ds_read_b128 v[186:189], v145 offset:49152
	ds_read_b128 v[190:193], v145 offset:50176
	ds_read_b128 v[194:197], v145 offset:51200
	ds_read_b128 v[198:201], v145 offset:52224
	ds_read_b128 v[202:205], v145 offset:53248
	ds_read_b128 v[206:209], v145 offset:54272
	ds_read_b128 v[210:213], v145 offset:55296
	ds_read_b128 v[214:217], v145 offset:56320
	s_add_u32 s100, s62, 0x80
	s_addc_u32 s101, s63, 0
	global_load_lds_dwordx4 v128, s[100:101]
	s_mov_b32 m0, s77
	s_nop 0
	global_load_lds_dwordx4 v132, s[100:101]
	s_barrier
	s_waitcnt lgkmcnt(0)
	s_setprio 1
	s_waitcnt lgkmcnt(0)
	v_mfma_f32_16x16x32_bf16 v[60:63], v[170:173], v[186:189], v[60:63]
	v_mfma_f32_16x16x32_bf16 v[56:59], v[178:181], v[186:189], v[56:59]
	v_mfma_f32_16x16x32_bf16 v[52:55], v[170:173], v[194:197], v[52:55]
	v_mfma_f32_16x16x32_bf16 v[48:51], v[178:181], v[194:197], v[48:51]
	v_mfma_f32_16x16x32_bf16 v[36:39], v[170:173], v[202:205], v[36:39]
	v_mfma_f32_16x16x32_bf16 v[32:35], v[178:181], v[202:205], v[32:35]
	v_mfma_f32_16x16x32_bf16 v[20:23], v[170:173], v[210:213], v[20:23]
	v_mfma_f32_16x16x32_bf16 v[16:19], v[178:181], v[210:213], v[16:19]
	v_mfma_f32_16x16x32_bf16 v[60:63], v[174:177], v[190:193], v[60:63]
	v_mfma_f32_16x16x32_bf16 v[56:59], v[182:185], v[190:193], v[56:59]
	v_mfma_f32_16x16x32_bf16 v[52:55], v[174:177], v[198:201], v[52:55]
	v_mfma_f32_16x16x32_bf16 v[48:51], v[182:185], v[198:201], v[48:51]
	v_mfma_f32_16x16x32_bf16 v[36:39], v[174:177], v[206:209], v[36:39]
	v_mfma_f32_16x16x32_bf16 v[32:35], v[182:185], v[206:209], v[32:35]
	v_mfma_f32_16x16x32_bf16 v[20:23], v[174:177], v[214:217], v[20:23]
	v_mfma_f32_16x16x32_bf16 v[16:19], v[182:185], v[214:217], v[16:19]
	s_setprio 0
	s_barrier
	s_add_u32 s56, s60, 0x44080
	s_addc_u32 s57, s61, 0
	s_mov_b32 m0, s78
	s_nop 0
	global_load_lds_dwordx4 v130, s[56:57]
	s_mov_b32 m0, s79
	s_nop 0
	global_load_lds_dwordx4 v134, s[56:57]
	s_add_i32 s96, s96, 2
	s_add_u32 s94, s94, 0x100
	s_addc_u32 s95, s95, 0
	s_cmp_gt_u32 s96, 13
	s_mov_b64 s[56:57], s[58:59]
	s_waitcnt vmcnt(6)
	s_barrier
; #define PG8_STAGE(bufoff, gbase, voff) do { _Pragma("unroll") for (int _i = 0; _i < 2; ++_i) \
;         __builtin_amdgcn_global_load_lds((const unsigned*)((const char*)(gbase) + (voff)[_i]), (PG8_LAS unsigned*)(lds + (bufoff) + ldsw + _i * 8192), 16, 0, 0); } while (0)
; #define PG8_LDA(dst, b, h) do { _Pragma("unroll") for (int m = 0; m < 4; ++m) _Pragma("unroll") for (int k = 0; k < 2; ++k) dst[m][k] = *(const PG8_LAS bf16x8*)(lds + PG8_SA(b, h) + aoff + m * 2048 + k * 1024); } while (0)
; #define PG8_LDB(dst, b, h) do { _Pragma("unroll") for (int n = 0; n < 2; ++n) _Pragma("unroll") for (int k = 0; k < 2; ++k) dst[n][k] = *(const PG8_LAS bf16x8*)(lds + PG8_SB(b, h) + boff + n * 2048 + k * 1024); } while (0)
; #define PG8_WAIT_V(n) asm volatile("s_waitcnt vmcnt(" #n ")" ::: "memory")
;     DI void operator()(const f32x4 (&acc)[2][2][4][2], const Unit& u, int wr, int wc, int fr, int fq) const {
;         const int row0 = u.pm * BM + wr * 64 + fr, col0 = u.pn * BM + wc * 32 + 8 * fq;
; #pragma unroll
;         for (int ai = 0; ai < 2; ++ai)
; #pragma unroll
;             for (int m = 0; m < 4; ++m) { u16* rowp = O + (size_t)(row0 + ai * HALF + m * 16) * ldc + col0;
; #pragma unroll
;                 for (int bj = 0; bj < 2; ++bj) { const f32x4 v0 = acc[ai][bj][m][0], v1 = acc[ai][bj][m][1];
;                     uint4 w = {pack2(v0[0], v0[1]), pack2(v0[2], v0[3]), pack2(v1[0], v1[1]), pack2(v1[2], v1[3])}; *(uint4*)(rowp + bj * HALF) = w; } }
; template <class Epi, class Sched, bool STAMP = false>
; __device__ __forceinline__ void gemm_phase(PG8_LAS unsigned char* lds, const Gemm g, const Sched& S, const Epi& E, unsigned long long* stamps) {
;     ...
;             PG8_WAIT_V(6); PG8_BAR; PG8_MMA(1, 1, At, B1); PG8_BAR;
;             PG8_LDB(B0, 1, 0); PG8_SCHED; PG8_LDA(At, 1, 0); PG8_STAGE(PG8_SA(0, 1), a2 + hstep, voffA);
;             PG8_WAIT_L(8); PG8_BAR; PG8_WAIT_L(0); PG8_MMA(0, 0, At, B0); PG8_BAR; PG8_SCHED;
;             PG8_LDB(B1, 1, 1); PG8_STAGE(PG8_SB(1, 0), b3, voffB);
;             PG8_BAR; PG8_WAIT_L(0); PG8_MMA(0, 1, At, B1); PG8_BAR;
;             PG8_LDA(At, 1, 1); PG8_STAGE(PG8_SA(1, 0), a3, voffA);
;             PG8_BAR; PG8_WAIT_L(0); PG8_MMA(1, 0, At, B0); PG8_BAR; PG8_SCHED;
;             PG8_STAGE(PG8_SB(1, 1), b3 + hstep, voffB);
;             PG8_WAIT_V(6); PG8_BAR; PG8_MMA(1, 1, At, B1); PG8_BAR;
;         }
	s_setprio 1
	v_mfma_f32_16x16x32_bf16 v[44:47], v[218:221], v[186:189], v[44:47]
	v_mfma_f32_16x16x32_bf16 v[40:43], v[226:229], v[186:189], v[40:43]
	v_mfma_f32_16x16x32_bf16 v[28:31], v[218:221], v[194:197], v[28:31]
	v_mfma_f32_16x16x32_bf16 v[24:27], v[226:229], v[194:197], v[24:27]
	v_mfma_f32_16x16x32_bf16 v[12:15], v[218:221], v[202:205], v[12:15]
	v_mfma_f32_16x16x32_bf16 v[8:11], v[226:229], v[202:205], v[8:11]
	v_mfma_f32_16x16x32_bf16 v[4:7], v[218:221], v[210:213], v[4:7]
	v_mfma_f32_16x16x32_bf16 v[0:3], v[226:229], v[210:213], v[0:3]
	v_mfma_f32_16x16x32_bf16 v[44:47], v[222:225], v[190:193], v[44:47]
	v_mfma_f32_16x16x32_bf16 v[40:43], v[230:233], v[190:193], v[40:43]
	v_mfma_f32_16x16x32_bf16 v[28:31], v[222:225], v[198:201], v[28:31]
	v_mfma_f32_16x16x32_bf16 v[24:27], v[230:233], v[198:201], v[24:27]
	v_mfma_f32_16x16x32_bf16 v[12:15], v[222:225], v[206:209], v[12:15]
	v_mfma_f32_16x16x32_bf16 v[8:11], v[230:233], v[206:209], v[8:11]
	v_mfma_f32_16x16x32_bf16 v[4:7], v[222:225], v[214:217], v[4:7]
	v_mfma_f32_16x16x32_bf16 v[0:3], v[230:233], v[214:217], v[0:3]
	s_setprio 0
	s_barrier
	s_cbranch_scc0 .LBB0_312
	v_lshl_add_u32 v170, s90, 8, v144
	v_lshl_or_b32 v172, s93, 8, v146
	v_ashrrev_i32_e32 v171, 31, v170
	v_ashrrev_i32_e32 v173, 31, v172
	v_lshlrev_b64 v[174:175], 11, v[170:171]
	v_lshl_add_u64 v[174:175], s[14:15], 0, v[174:175]
	v_lshlrev_b64 v[172:173], 1, v[172:173]
	v_lshl_add_u64 v[174:175], v[174:175], 0, v[172:173]
	v_cvt_pk_bf16_f32 v60, v60, v61
	v_cvt_pk_bf16_f32 v61, v62, v63
	v_cvt_pk_bf16_f32 v62, v56, v57
	v_add_co_u32_e32 v56, vcc, s86, v174
	v_cvt_pk_bf16_f32 v68, v68, v69
	v_cvt_pk_bf16_f32 v69, v70, v71
	v_cvt_pk_bf16_f32 v70, v64, v65
	v_lshl_add_u64 v[64:65], v[174:175], 0, s[34:35]
	v_addc_co_u32_e32 v57, vcc, 0, v175, vcc
	v_cvt_pk_bf16_f32 v44, v44, v45
	v_cvt_pk_bf16_f32 v45, v46, v47
	v_cvt_pk_bf16_f32 v46, v40, v41
	v_cvt_pk_bf16_f32 v47, v42, v43
	v_cvt_pk_bf16_f32 v108, v108, v109
	v_cvt_pk_bf16_f32 v109, v110, v111
	v_cvt_pk_bf16_f32 v110, v104, v105
	v_or_b32_e32 v104, 16, v170
	global_store_dwordx4 v[64:65], v[44:47], off offset:256
	v_ashrrev_i32_e32 v105, 31, v104
	v_cvt_pk_bf16_f32 v92, v92, v93
	v_add_co_u32_e32 v46, vcc, s87, v174
	v_cvt_pk_bf16_f32 v93, v94, v95
	v_cvt_pk_bf16_f32 v94, v88, v89
	v_or_b32_e32 v88, 32, v170
	v_lshl_add_u64 v[44:45], v[174:175], 0, s[36:37]
	v_addc_co_u32_e32 v47, vcc, 0, v175, vcc
	v_cvt_pk_bf16_f32 v28, v28, v29
	v_cvt_pk_bf16_f32 v29, v30, v31
	v_cvt_pk_bf16_f32 v30, v24, v25
	v_cvt_pk_bf16_f32 v31, v26, v27
	v_lshlrev_b64 v[104:105], 11, v[104:105]
	v_ashrrev_i32_e32 v89, 31, v88
	v_cvt_pk_bf16_f32 v76, v76, v77
	v_cvt_pk_bf16_f32 v77, v78, v79
	v_cvt_pk_bf16_f32 v78, v72, v73
	v_or_b32_e32 v72, 48, v170
	global_store_dwordx4 v[44:45], v[28:31], off offset:256
	v_cvt_pk_bf16_f32 v111, v106, v107
	v_lshl_add_u64 v[104:105], s[14:15], 0, v[104:105]
	v_add_co_u32_e32 v30, vcc, s88, v174
	v_lshlrev_b64 v[88:89], 11, v[88:89]
	v_ashrrev_i32_e32 v73, 31, v72
	v_lshl_add_u64 v[28:29], v[174:175], 0, s[52:53]
	v_addc_co_u32_e32 v31, vcc, 0, v175, vcc
	v_cvt_pk_bf16_f32 v12, v12, v13
	v_cvt_pk_bf16_f32 v13, v14, v15
	v_cvt_pk_bf16_f32 v14, v8, v9
	v_cvt_pk_bf16_f32 v15, v10, v11
	global_store_dwordx4 v[174:175], v[108:111], off offset:256
	v_cvt_pk_bf16_f32 v95, v90, v91
	v_lshl_add_u64 v[88:89], s[14:15], 0, v[88:89]
	v_lshl_add_u64 v[108:109], v[104:105], 0, v[172:173]
	v_lshlrev_b64 v[72:73], 11, v[72:73]
	global_store_dwordx4 v[28:29], v[12:15], off offset:256
	global_store_dwordx4 v[108:109], v[92:95], off offset:256
	v_cvt_pk_bf16_f32 v79, v74, v75
	v_add_co_u32_e32 v14, vcc, s89, v174
	v_lshl_add_u64 v[92:93], v[88:89], 0, v[172:173]
	v_lshl_add_u64 v[72:73], s[14:15], 0, v[72:73]
	v_addc_co_u32_e32 v15, vcc, 0, v175, vcc
	v_cvt_pk_bf16_f32 v124, v124, v125
	v_cvt_pk_bf16_f32 v125, v126, v127
	v_cvt_pk_bf16_f32 v126, v120, v121
	v_cvt_pk_bf16_f32 v127, v122, v123
	v_cvt_pk_bf16_f32 v104, v116, v117
	v_cvt_pk_bf16_f32 v105, v118, v119
	v_cvt_pk_bf16_f32 v106, v112, v113
	v_cvt_pk_bf16_f32 v107, v114, v115
	v_cvt_pk_bf16_f32 v88, v100, v101
	v_cvt_pk_bf16_f32 v89, v102, v103
	v_cvt_pk_bf16_f32 v90, v96, v97
	v_cvt_pk_bf16_f32 v91, v98, v99
	global_store_dwordx4 v[92:93], v[76:79], off offset:256
	v_cvt_pk_bf16_f32 v74, v80, v81
	v_cvt_pk_bf16_f32 v75, v82, v83
	v_lshl_add_u64 v[76:77], v[72:73], 0, v[172:173]
	v_cvt_pk_bf16_f32 v72, v84, v85
	v_cvt_pk_bf16_f32 v73, v86, v87
	v_cvt_pk_bf16_f32 v71, v66, v67
	v_cvt_pk_bf16_f32 v63, v58, v59
	v_cvt_pk_bf16_f32 v40, v52, v53
	v_cvt_pk_bf16_f32 v41, v54, v55
	v_cvt_pk_bf16_f32 v42, v48, v49
	v_cvt_pk_bf16_f32 v43, v50, v51
	v_cvt_pk_bf16_f32 v24, v36, v37
	v_cvt_pk_bf16_f32 v25, v38, v39
	v_cvt_pk_bf16_f32 v26, v32, v33
	v_cvt_pk_bf16_f32 v27, v34, v35
	v_lshl_add_u64 v[12:13], v[174:175], 0, s[54:55]
	v_cvt_pk_bf16_f32 v8, v20, v21
	v_cvt_pk_bf16_f32 v9, v22, v23
	v_cvt_pk_bf16_f32 v10, v16, v17
	v_cvt_pk_bf16_f32 v11, v18, v19
	v_cvt_pk_bf16_f32 v4, v4, v5
	v_cvt_pk_bf16_f32 v5, v6, v7
	v_cvt_pk_bf16_f32 v6, v0, v1
	v_cvt_pk_bf16_f32 v7, v2, v3
	s_and_b64 vcc, exec, s[2:3]
	s_mov_b32 s93, s91
	s_mov_b32 s90, s92
	s_mov_b64 s[58:59], s[0:1]
	s_mov_b64 s[56:57], s[4:5]
	global_store_dwordx4 v[174:175], v[124:127], off
	global_store_dwordx4 v[108:109], v[104:107], off
	global_store_dwordx4 v[92:93], v[88:91], off
	global_store_dwordx4 v[76:77], v[72:75], off
	global_store_dwordx4 v[76:77], v[68:71], off offset:256
	global_store_dwordx4 v[56:57], v[60:63], off
	global_store_dwordx4 v[46:47], v[40:43], off
	global_store_dwordx4 v[30:31], v[24:27], off
	global_store_dwordx4 v[14:15], v[8:11], off
	global_store_dwordx4 v[12:13], v[4:7], off offset:256
	s_cbranch_vccz .LBB0_301
	s_waitcnt vmcnt(0)
	s_cmpk_gt_u32 s64, 0xff
	s_cbranch_scc1 .LBB0_316
	s_barrier

; #define PG8_STAGE(bufoff, gbase, voff) do { _Pragma("unroll") for (int _i = 0; _i < 2; ++_i) \
;         __builtin_amdgcn_global_load_lds((const unsigned*)((const char*)(gbase) + (voff)[_i]), (PG8_LAS unsigned*)(lds + (bufoff) + ldsw + _i * 8192), 16, 0, 0); } while (0)
; #define PG8_LDA(dst, b, h) do { _Pragma("unroll") for (int m = 0; m < 4; ++m) _Pragma("unroll") for (int k = 0; k < 2; ++k) dst[m][k] = *(const PG8_LAS bf16x8*)(lds + PG8_SA(b, h) + aoff + m * 2048 + k * 1024); } while (0)
; template <class Epi, class Sched, bool STAMP = false>
; __device__ __forceinline__ void gemm_phase(PG8_LAS unsigned char* lds, const Gemm g, const Sched& S, const Epi& E, unsigned long long* stamps) {
;     ...
;         for (int t = 0; t < nt; t += 2) {
;             const bool last = (t == nt - 2);
;             const char* a1 = cA + (size_t)(t + 1) * kstep;
;             const char* a2 = last ? nA : cA + (size_t)(t + 2) * kstep; const char* b2 = last ? nB : cB + (size_t)(t + 2) * kstep;
;             const char* a3 = a2 + kstep; const char* b3 = b2 + kstep;
;             if (last && has_next) S.a_ready(nxt);
;             PG8_LDB(B0, 0, 0); PG8_SCHED; PG8_LDA(At, 0, 0); PG8_STAGE(PG8_SA(1, 1), a1 + hstep, voffA);
;             PG8_WAIT_L(8); PG8_BAR; PG8_WAIT_L(0); PG8_MMA(0, 0, At, B0); PG8_BAR; PG8_SCHED;
;             PG8_LDB(B1, 0, 1); PG8_STAGE(PG8_SB(0, 0), b2, voffB);
;             PG8_BAR; PG8_WAIT_L(0); PG8_MMA(0, 1, At, B1); PG8_BAR;
;             PG8_LDA(At, 0, 1); PG8_STAGE(PG8_SA(0, 0), a2, voffA);
;             PG8_BAR; PG8_WAIT_L(0); PG8_MMA(1, 0, At, B0); PG8_BAR; PG8_SCHED;
;             PG8_STAGE(PG8_SB(0, 1), b2 + hstep, voffB);
;             PG8_WAIT_V(6); PG8_BAR; PG8_MMA(1, 1, At, B1); PG8_BAR;
;             PG8_LDB(B0, 1, 0); PG8_SCHED; PG8_LDA(At, 1, 0); PG8_STAGE(PG8_SA(0, 1), a2 + hstep, voffA);
;             PG8_WAIT_L(8); PG8_BAR; PG8_WAIT_L(0); PG8_MMA(0, 0, At, B0); PG8_BAR; PG8_SCHED;
;             PG8_LDB(B1, 1, 1); PG8_STAGE(PG8_SB(1, 0), b3, voffB);
;             PG8_BAR; PG8_WAIT_L(0); PG8_MMA(0, 1, At, B1); PG8_BAR;
;             PG8_LDA(At, 1, 1); PG8_STAGE(PG8_SA(1, 0), a3, voffA);
;             PG8_BAR; PG8_WAIT_L(0); PG8_MMA(1, 0, At, B0); PG8_BAR; PG8_SCHED;
;             PG8_STAGE(PG8_SB(1, 1), b3 + hstep, voffB);
;             PG8_WAIT_V(6); PG8_BAR; PG8_MMA(1, 1, At, B1); PG8_BAR;
;         }
.Lzp5_mid:
	ds_read_b128 v[140:143], v155
	ds_read_b128 v[170:173], v156
	ds_read_b128 v[174:177], v157
	ds_read_b128 v[178:181], v165
	s_add_u32 s34, s54, 0x44000
	s_addc_u32 s35, s55, 0
	s_mov_b32 m0, s66
	ds_read_b128 v[182:185], v145 offset:32768
	ds_read_b128 v[186:189], v145 offset:33792
	ds_read_b128 v[190:193], v145 offset:34816
	ds_read_b128 v[194:197], v145 offset:35840
	ds_read_b128 v[198:201], v145 offset:36864
	ds_read_b128 v[202:205], v145 offset:37888
	ds_read_b128 v[206:209], v145 offset:38912
	ds_read_b128 v[210:213], v145 offset:39936
	global_load_lds_dwordx4 v130, s[34:35]
	s_mov_b32 m0, s67
	s_nop 0
	global_load_lds_dwordx4 v128, s[34:35]
	s_waitcnt lgkmcnt(8)
	s_barrier
	s_waitcnt lgkmcnt(0)
	s_setprio 1
	s_waitcnt lgkmcnt(0)
	v_mfma_f32_16x16x32_bf16 v[124:127], v[140:143], v[182:185], v[124:127]
	v_mfma_f32_16x16x32_bf16 v[120:123], v[174:177], v[182:185], v[120:123]
	v_mfma_f32_16x16x32_bf16 v[108:111], v[140:143], v[190:193], v[108:111]
	v_mfma_f32_16x16x32_bf16 v[104:107], v[174:177], v[190:193], v[104:107]
	v_mfma_f32_16x16x32_bf16 v[92:95], v[140:143], v[198:201], v[92:95]
	v_mfma_f32_16x16x32_bf16 v[88:91], v[174:177], v[198:201], v[88:91]
	v_mfma_f32_16x16x32_bf16 v[76:79], v[140:143], v[206:209], v[76:79]
	v_mfma_f32_16x16x32_bf16 v[72:75], v[174:177], v[206:209], v[72:75]
	v_mfma_f32_16x16x32_bf16 v[124:127], v[170:173], v[186:189], v[124:127]
	v_mfma_f32_16x16x32_bf16 v[120:123], v[178:181], v[186:189], v[120:123]
	v_mfma_f32_16x16x32_bf16 v[108:111], v[170:173], v[194:197], v[108:111]
	v_mfma_f32_16x16x32_bf16 v[104:107], v[178:181], v[194:197], v[104:107]
	v_mfma_f32_16x16x32_bf16 v[92:95], v[170:173], v[202:205], v[92:95]
	v_mfma_f32_16x16x32_bf16 v[88:91], v[178:181], v[202:205], v[88:91]
	v_mfma_f32_16x16x32_bf16 v[76:79], v[170:173], v[210:213], v[76:79]
	v_mfma_f32_16x16x32_bf16 v[72:75], v[178:181], v[210:213], v[72:75]
	s_setprio 0
	s_barrier
	s_mov_b32 m0, s70
	ds_read_b128 v[214:217], v166
	ds_read_b128 v[218:221], v167
	ds_read_b128 v[222:225], v168
	ds_read_b128 v[226:229], v169
	s_add_u32 s100, s52, 0x80
	s_addc_u32 s101, s53, 0
	global_load_lds_dwordx4 v130, s[100:101]
	s_mov_b32 m0, s71
	s_nop 0
	global_load_lds_dwordx4 v128, s[100:101]
	s_barrier
	s_waitcnt lgkmcnt(0)
	s_setprio 1
	s_waitcnt lgkmcnt(0)
	v_mfma_f32_16x16x32_bf16 v[116:119], v[214:217], v[182:185], v[116:119]
	v_mfma_f32_16x16x32_bf16 v[112:115], v[222:225], v[182:185], v[112:115]
	v_mfma_f32_16x16x32_bf16 v[100:103], v[214:217], v[190:193], v[100:103]
	v_mfma_f32_16x16x32_bf16 v[96:99], v[222:225], v[190:193], v[96:99]
	v_mfma_f32_16x16x32_bf16 v[84:87], v[214:217], v[198:201], v[84:87]
	v_mfma_f32_16x16x32_bf16 v[80:83], v[222:225], v[198:201], v[80:83]
	v_mfma_f32_16x16x32_bf16 v[68:71], v[214:217], v[206:209], v[68:71]
	v_mfma_f32_16x16x32_bf16 v[64:67], v[222:225], v[206:209], v[64:67]
	v_mfma_f32_16x16x32_bf16 v[116:119], v[218:221], v[186:189], v[116:119]
	v_mfma_f32_16x16x32_bf16 v[112:115], v[226:229], v[186:189], v[112:115]
	v_mfma_f32_16x16x32_bf16 v[100:103], v[218:221], v[194:197], v[100:103]
	v_mfma_f32_16x16x32_bf16 v[96:99], v[226:229], v[194:197], v[96:99]
	v_mfma_f32_16x16x32_bf16 v[84:87], v[218:221], v[202:205], v[84:87]
	v_mfma_f32_16x16x32_bf16 v[80:83], v[226:229], v[202:205], v[80:83]
	v_mfma_f32_16x16x32_bf16 v[68:71], v[218:221], v[210:213], v[68:71]
	v_mfma_f32_16x16x32_bf16 v[64:67], v[226:229], v[210:213], v[64:67]
	s_setprio 0
	s_mov_b32 m0, s73
	s_barrier
	ds_read_b128 v[182:185], v145 offset:49152
	ds_read_b128 v[186:189], v145 offset:50176
	ds_read_b128 v[190:193], v145 offset:51200
	ds_read_b128 v[194:197], v145 offset:52224
	ds_read_b128 v[198:201], v145 offset:53248
	ds_read_b128 v[202:205], v145 offset:54272
	ds_read_b128 v[206:209], v145 offset:55296
	ds_read_b128 v[210:213], v145 offset:56320
	s_add_u32 s100, s54, 0x80
	s_addc_u32 s101, s55, 0
	global_load_lds_dwordx4 v130, s[100:101]
	s_mov_b32 m0, s74
	s_nop 0
	global_load_lds_dwordx4 v128, s[100:101]
	s_barrier
	s_waitcnt lgkmcnt(0)
	s_setprio 1
	s_waitcnt lgkmcnt(0)
	v_mfma_f32_16x16x32_bf16 v[60:63], v[140:143], v[182:185], v[60:63]
	v_mfma_f32_16x16x32_bf16 v[56:59], v[174:177], v[182:185], v[56:59]
	v_mfma_f32_16x16x32_bf16 v[44:47], v[140:143], v[190:193], v[44:47]
	v_mfma_f32_16x16x32_bf16 v[40:43], v[174:177], v[190:193], v[40:43]
	v_mfma_f32_16x16x32_bf16 v[28:31], v[140:143], v[198:201], v[28:31]
	v_mfma_f32_16x16x32_bf16 v[24:27], v[174:177], v[198:201], v[24:27]
	v_mfma_f32_16x16x32_bf16 v[12:15], v[140:143], v[206:209], v[12:15]
	v_mfma_f32_16x16x32_bf16 v[8:11], v[174:177], v[206:209], v[8:11]
	v_mfma_f32_16x16x32_bf16 v[60:63], v[170:173], v[186:189], v[60:63]
	v_mfma_f32_16x16x32_bf16 v[56:59], v[178:181], v[186:189], v[56:59]
	v_mfma_f32_16x16x32_bf16 v[44:47], v[170:173], v[194:197], v[44:47]
	v_mfma_f32_16x16x32_bf16 v[40:43], v[178:181], v[194:197], v[40:43]
	v_mfma_f32_16x16x32_bf16 v[28:31], v[170:173], v[202:205], v[28:31]
	v_mfma_f32_16x16x32_bf16 v[24:27], v[178:181], v[202:205], v[24:27]
	v_mfma_f32_16x16x32_bf16 v[12:15], v[170:173], v[210:213], v[12:15]
	v_mfma_f32_16x16x32_bf16 v[8:11], v[178:181], v[210:213], v[8:11]
	s_setprio 0
	s_barrier
	s_add_u32 s34, s52, 0x44080
	s_addc_u32 s35, s53, 0
	s_mov_b32 m0, s75
	s_nop 0
	global_load_lds_dwordx4 v130, s[34:35]
	s_mov_b32 m0, s76
	s_nop 0
	global_load_lds_dwordx4 v128, s[34:35]
	s_add_i32 s89, s89, 2
	s_add_u32 s87, s87, 0x100
	s_addc_u32 s88, s88, 0
	s_cmp_gt_u32 s89, 13
	s_mov_b64 s[34:35], s[36:37]
	s_waitcnt vmcnt(6)
	s_barrier
; DI float ex2(float x) { return __builtin_amdgcn_exp2f(x); }
; #define PG8_STAGE(bufoff, gbase, voff) do { _Pragma("unroll") for (int _i = 0; _i < 2; ++_i) \
;         __builtin_amdgcn_global_load_lds((const unsigned*)((const char*)(gbase) + (voff)[_i]), (PG8_LAS unsigned*)(lds + (bufoff) + ldsw + _i * 8192), 16, 0, 0); } while (0)
; #define PG8_LDA(dst, b, h) do { _Pragma("unroll") for (int m = 0; m < 4; ++m) _Pragma("unroll") for (int k = 0; k < 2; ++k) dst[m][k] = *(const PG8_LAS bf16x8*)(lds + PG8_SA(b, h) + aoff + m * 2048 + k * 1024); } while (0)
; #define PG8_WAIT_V(n) asm volatile("s_waitcnt vmcnt(" #n ")" ::: "memory")
; #define PG8_BAR __builtin_amdgcn_s_barrier()
;     DI void operator()(const f32x4 (&acc)[2][2][4][2], const Unit& u, int wr, int wc, int fr, int fq) const {
;         const int row0 = u.pm * BM + wr * 64 + fr, hcol0 = ((u.pn * BM + wc * 32) >> 1) + 4 * fq;
; #pragma unroll
;         for (int ai = 0; ai < 2; ++ai)
; #pragma unroll
;             for (int m = 0; m < 4; ++m) { u16* rowp = O + (size_t)(row0 + ai * HALF + m * 16) * ldc + hcol0;
; #pragma unroll
;                 for (int bj = 0; bj < 2; ++bj) { const f32x4 g = acc[ai][bj][m][0], up = acc[ai][bj][m][1]; float r[4];
; #pragma unroll
;                     for (int j = 0; j < 4; ++j) r[j] = g[j] * up[j] * __builtin_amdgcn_rcpf(1.f + ex2(-LOG2E * g[j]));
;                     uint2 w = {pack2(r[0], r[1]), pack2(r[2], r[3])}; *(uint2*)(rowp + bj * (HALF / 2)) = w; } }
; template <class Epi, class Sched, bool STAMP = false>
; __device__ __forceinline__ void gemm_phase(PG8_LAS unsigned char* lds, const Gemm g, const Sched& S, const Epi& E, unsigned long long* stamps) {
;     ...
;             PG8_WAIT_V(6); PG8_BAR; PG8_MMA(1, 1, At, B1); PG8_BAR;
;             PG8_LDB(B0, 1, 0); PG8_SCHED; PG8_LDA(At, 1, 0); PG8_STAGE(PG8_SA(0, 1), a2 + hstep, voffA);
;             PG8_WAIT_L(8); PG8_BAR; PG8_WAIT_L(0); PG8_MMA(0, 0, At, B0); PG8_BAR; PG8_SCHED;
;             PG8_LDB(B1, 1, 1); PG8_STAGE(PG8_SB(1, 0), b3, voffB);
;             PG8_BAR; PG8_WAIT_L(0); PG8_MMA(0, 1, At, B1); PG8_BAR;
;             PG8_LDA(At, 1, 1); PG8_STAGE(PG8_SA(1, 0), a3, voffA);
;             PG8_BAR; PG8_WAIT_L(0); PG8_MMA(1, 0, At, B0); PG8_BAR; PG8_SCHED;
;             PG8_STAGE(PG8_SB(1, 1), b3 + hstep, voffB);
;             PG8_WAIT_V(6); PG8_BAR; PG8_MMA(1, 1, At, B1); PG8_BAR;
;         }
	s_setprio 1
	v_mfma_f32_16x16x32_bf16 v[52:55], v[214:217], v[182:185], v[52:55]
	v_mfma_f32_16x16x32_bf16 v[48:51], v[222:225], v[182:185], v[48:51]
	v_mfma_f32_16x16x32_bf16 v[36:39], v[214:217], v[190:193], v[36:39]
	v_mfma_f32_16x16x32_bf16 v[32:35], v[222:225], v[190:193], v[32:35]
	v_mfma_f32_16x16x32_bf16 v[20:23], v[214:217], v[198:201], v[20:23]
	v_mfma_f32_16x16x32_bf16 v[16:19], v[222:225], v[198:201], v[16:19]
	v_mfma_f32_16x16x32_bf16 v[4:7], v[214:217], v[206:209], v[4:7]
	v_mfma_f32_16x16x32_bf16 v[0:3], v[222:225], v[206:209], v[0:3]
	v_mfma_f32_16x16x32_bf16 v[52:55], v[218:221], v[186:189], v[52:55]
	v_mfma_f32_16x16x32_bf16 v[48:51], v[226:229], v[186:189], v[48:51]
	v_mfma_f32_16x16x32_bf16 v[36:39], v[218:221], v[194:197], v[36:39]
	v_mfma_f32_16x16x32_bf16 v[32:35], v[226:229], v[194:197], v[32:35]
	v_mfma_f32_16x16x32_bf16 v[20:23], v[218:221], v[202:205], v[20:23]
	v_mfma_f32_16x16x32_bf16 v[16:19], v[226:229], v[202:205], v[16:19]
	v_mfma_f32_16x16x32_bf16 v[4:7], v[218:221], v[210:213], v[4:7]
	v_mfma_f32_16x16x32_bf16 v[0:3], v[226:229], v[210:213], v[0:3]
	s_setprio 0
	s_barrier
	s_cbranch_scc0 .LBB0_351
	v_exp_f32_e64 v171, -v124
	v_exp_f32_e64 v175, -v125
	s_lshl_b32 s10, s86, 8
	v_add_f32_e32 v171, 1.0, v171
	v_rcp_f32_e32 v174, v171
	v_add_f32_e32 v171, 1.0, v175
	v_exp_f32_e64 v176, -v126
	v_exp_f32_e64 v177, -v127
	v_rcp_f32_e32 v175, v171
	v_add_f32_e32 v171, 1.0, v176
	v_rcp_f32_e32 v176, v171
	v_add_f32_e32 v171, 1.0, v177
	v_rcp_f32_e32 v177, v171
	v_pk_mul_f32 v[122:123], v[126:127], v[122:123]
	v_pk_mul_f32 v[120:121], v[124:125], v[120:121]
	s_or_b32 s10, s10, s69
	v_pk_mul_f32 v[120:121], v[120:121], v[174:175]
	v_pk_mul_f32 v[122:123], v[122:123], v[176:177]
	s_ashr_i32 s10, s10, 1
	v_cvt_pk_bf16_f32 v120, v120, v121
	v_cvt_pk_bf16_f32 v121, v122, v123
	v_or_b32_e32 v140, s10, v146
	v_exp_f32_e64 v122, -v116
	v_exp_f32_e64 v123, -v117
	v_lshl_add_u32 v170, s85, 8, v144
	v_ashrrev_i32_e32 v141, 31, v140
	v_mov_b64_e32 v[142:143], s[12:13]
	v_mad_i64_i32 v[172:173], s[34:35], v170, s82, v[142:143]
	v_lshlrev_b64 v[140:141], 1, v[140:141]
	v_lshl_add_u64 v[172:173], v[172:173], 0, v[140:141]
	global_store_dwordx2 v[172:173], v[120:121], off
	v_add_f32_e32 v120, 1.0, v122
	v_add_f32_e32 v121, 1.0, v123
	v_exp_f32_e64 v122, -v118
	v_exp_f32_e64 v123, -v119
	v_rcp_f32_e32 v120, v120
	v_rcp_f32_e32 v121, v121
	v_add_f32_e32 v122, 1.0, v122
	v_add_f32_e32 v123, 1.0, v123
	v_rcp_f32_e32 v122, v122
	v_rcp_f32_e32 v123, v123
	v_pk_mul_f32 v[114:115], v[118:119], v[114:115]
	v_pk_mul_f32 v[112:113], v[116:117], v[112:113]
	v_pk_mul_f32 v[112:113], v[112:113], v[120:121]
	v_pk_mul_f32 v[114:115], v[114:115], v[122:123]
	v_cvt_pk_bf16_f32 v112, v112, v113
	v_cvt_pk_bf16_f32 v113, v114, v115
	v_exp_f32_e64 v114, -v108
	v_exp_f32_e64 v115, -v109
	v_exp_f32_e64 v116, -v110
	v_exp_f32_e64 v117, -v111
	v_add_f32_e32 v114, 1.0, v114
	v_add_f32_e32 v115, 1.0, v115
	v_add_f32_e32 v116, 1.0, v116
	v_add_f32_e32 v117, 1.0, v117
	v_rcp_f32_e32 v114, v114
	v_rcp_f32_e32 v115, v115
	v_rcp_f32_e32 v116, v116
	v_rcp_f32_e32 v117, v117
	v_pk_mul_f32 v[106:107], v[110:111], v[106:107]
	v_pk_mul_f32 v[104:105], v[108:109], v[104:105]
	global_store_dwordx2 v[172:173], v[112:113], off offset:128
	v_pk_mul_f32 v[104:105], v[104:105], v[114:115]
	v_pk_mul_f32 v[106:107], v[106:107], v[116:117]
	v_cvt_pk_bf16_f32 v104, v104, v105
	v_cvt_pk_bf16_f32 v105, v106, v107
	v_exp_f32_e64 v106, -v100
	v_exp_f32_e64 v107, -v101
	v_or_b32_e32 v112, 16, v170
	v_mad_i64_i32 v[112:113], s[34:35], v112, s82, v[142:143]
	v_lshl_add_u64 v[112:113], v[112:113], 0, v[140:141]
	global_store_dwordx2 v[112:113], v[104:105], off
	v_add_f32_e32 v104, 1.0, v106
	v_add_f32_e32 v105, 1.0, v107
	v_exp_f32_e64 v106, -v102
	v_exp_f32_e64 v107, -v103
	v_rcp_f32_e32 v104, v104
	v_rcp_f32_e32 v105, v105
	v_add_f32_e32 v106, 1.0, v106
	v_add_f32_e32 v107, 1.0, v107
	v_rcp_f32_e32 v106, v106
	v_rcp_f32_e32 v107, v107
	v_pk_mul_f32 v[98:99], v[102:103], v[98:99]
	v_pk_mul_f32 v[96:97], v[100:101], v[96:97]
	v_pk_mul_f32 v[96:97], v[96:97], v[104:105]
	v_pk_mul_f32 v[98:99], v[98:99], v[106:107]
	v_cvt_pk_bf16_f32 v96, v96, v97
	v_cvt_pk_bf16_f32 v97, v98, v99
	v_exp_f32_e64 v98, -v92
	v_exp_f32_e64 v99, -v93
	v_exp_f32_e64 v100, -v94
	v_exp_f32_e64 v101, -v95
	v_add_f32_e32 v98, 1.0, v98
	v_add_f32_e32 v99, 1.0, v99
	v_add_f32_e32 v100, 1.0, v100
	v_add_f32_e32 v101, 1.0, v101
	v_rcp_f32_e32 v98, v98
	v_rcp_f32_e32 v99, v99
	v_rcp_f32_e32 v100, v100
	v_rcp_f32_e32 v101, v101
	v_pk_mul_f32 v[90:91], v[94:95], v[90:91]
	v_pk_mul_f32 v[88:89], v[92:93], v[88:89]
	global_store_dwordx2 v[112:113], v[96:97], off offset:128
	v_pk_mul_f32 v[88:89], v[88:89], v[98:99]
	v_pk_mul_f32 v[90:91], v[90:91], v[100:101]
	v_cvt_pk_bf16_f32 v88, v88, v89
	v_cvt_pk_bf16_f32 v89, v90, v91
	v_exp_f32_e64 v90, -v84
	v_exp_f32_e64 v91, -v85
	v_or_b32_e32 v96, 32, v170
	v_mad_i64_i32 v[96:97], s[34:35], v96, s82, v[142:143]
	v_lshl_add_u64 v[96:97], v[96:97], 0, v[140:141]
	global_store_dwordx2 v[96:97], v[88:89], off
	v_add_f32_e32 v88, 1.0, v90
	v_add_f32_e32 v89, 1.0, v91
	v_exp_f32_e64 v90, -v86
	v_exp_f32_e64 v91, -v87
	v_rcp_f32_e32 v88, v88
	v_rcp_f32_e32 v89, v89
	v_add_f32_e32 v90, 1.0, v90
	v_add_f32_e32 v91, 1.0, v91
	v_rcp_f32_e32 v90, v90
	v_rcp_f32_e32 v91, v91
	v_pk_mul_f32 v[82:83], v[86:87], v[82:83]
	v_pk_mul_f32 v[80:81], v[84:85], v[80:81]
	v_pk_mul_f32 v[80:81], v[80:81], v[88:89]
	v_pk_mul_f32 v[82:83], v[82:83], v[90:91]
	v_cvt_pk_bf16_f32 v80, v80, v81
	v_cvt_pk_bf16_f32 v81, v82, v83
	v_exp_f32_e64 v82, -v76
	v_exp_f32_e64 v83, -v77
	v_exp_f32_e64 v84, -v78
; DI float ex2(float x) { return __builtin_amdgcn_exp2f(x); }
; #define PG8_STAMP() do { if (STAMP && wid == 0 && nts < 64) { const unsigned long long _c = 0ull; \
;         ts_lo = (lane == nts) ? (int)(unsigned)_c : ts_lo; ts_hi = (lane == nts) ? (int)(unsigned)(_c >> 32) : ts_hi; ++nts; } } while (0)
;     DI void operator()(const f32x4 (&acc)[2][2][4][2], const Unit& u, int wr, int wc, int fr, int fq) const {
;         const int row0 = u.pm * BM + wr * 64 + fr, hcol0 = ((u.pn * BM + wc * 32) >> 1) + 4 * fq;
; #pragma unroll
;         for (int ai = 0; ai < 2; ++ai)
; #pragma unroll
;             for (int m = 0; m < 4; ++m) { u16* rowp = O + (size_t)(row0 + ai * HALF + m * 16) * ldc + hcol0;
; #pragma unroll
;                 for (int bj = 0; bj < 2; ++bj) { const f32x4 g = acc[ai][bj][m][0], up = acc[ai][bj][m][1]; float r[4];
; #pragma unroll
;                     for (int j = 0; j < 4; ++j) r[j] = g[j] * up[j] * __builtin_amdgcn_rcpf(1.f + ex2(-LOG2E * g[j]));
;                     uint2 w = {pack2(r[0], r[1]), pack2(r[2], r[3])}; *(uint2*)(rowp + bj * (HALF / 2)) = w; } }
; template <class Epi, class Sched, bool STAMP = false>
; __device__ __forceinline__ void gemm_phase(PG8_LAS unsigned char* lds, const Gemm g, const Sched& S, const Epi& E, unsigned long long* stamps) {
;     ...
;         if constexpr (!Epi::AFTER_DRAIN) { E(acc, cur, wr, wc, fr, fq); S.done(cur); }
;         PG8_STAMP();
;         if (!has_next) break;
; #pragma unroll
;         for (int a = 0; a < 2; ++a)
; #pragma unroll
;             for (int b = 0; b < 2; ++b)
; #pragma unroll
;                 for (int m = 0; m < 4; ++m)
; #pragma unroll
;                     for (int n = 0; n < 2; ++n) acc[a][b][m][n] = (f32x4){0.f, 0.f, 0.f, 0.f};
;         cur = nxt; cA = nA; cB = nB; ++ui;
	v_exp_f32_e64 v85, -v79
	v_add_f32_e32 v82, 1.0, v82
	v_add_f32_e32 v83, 1.0, v83
	v_add_f32_e32 v84, 1.0, v84
	v_add_f32_e32 v85, 1.0, v85
	v_rcp_f32_e32 v82, v82
	v_rcp_f32_e32 v83, v83
	v_rcp_f32_e32 v84, v84
	v_rcp_f32_e32 v85, v85
	v_pk_mul_f32 v[74:75], v[78:79], v[74:75]
	v_pk_mul_f32 v[72:73], v[76:77], v[72:73]
	global_store_dwordx2 v[96:97], v[80:81], off offset:128
	v_pk_mul_f32 v[72:73], v[72:73], v[82:83]
	v_pk_mul_f32 v[74:75], v[74:75], v[84:85]
	v_cvt_pk_bf16_f32 v72, v72, v73
	v_cvt_pk_bf16_f32 v73, v74, v75
	v_exp_f32_e64 v74, -v68
	v_exp_f32_e64 v75, -v69
	v_or_b32_e32 v80, 48, v170
	v_mad_i64_i32 v[80:81], s[34:35], v80, s82, v[142:143]
	v_lshl_add_u64 v[80:81], v[80:81], 0, v[140:141]
	global_store_dwordx2 v[80:81], v[72:73], off
	v_add_f32_e32 v72, 1.0, v74
	v_add_f32_e32 v73, 1.0, v75
	v_exp_f32_e64 v74, -v70
	v_exp_f32_e64 v75, -v71
	v_rcp_f32_e32 v72, v72
	v_rcp_f32_e32 v73, v73
	v_add_f32_e32 v74, 1.0, v74
	v_add_f32_e32 v75, 1.0, v75
	v_rcp_f32_e32 v74, v74
	v_rcp_f32_e32 v75, v75
	v_pk_mul_f32 v[66:67], v[70:71], v[66:67]
	v_pk_mul_f32 v[64:65], v[68:69], v[64:65]
	v_pk_mul_f32 v[64:65], v[64:65], v[72:73]
	v_pk_mul_f32 v[66:67], v[66:67], v[74:75]
	v_cvt_pk_bf16_f32 v64, v64, v65
	v_cvt_pk_bf16_f32 v65, v66, v67
	v_exp_f32_e64 v66, -v60
	v_exp_f32_e64 v67, -v61
	v_exp_f32_e64 v68, -v62
	v_exp_f32_e64 v69, -v63
	v_add_f32_e32 v66, 1.0, v66
	v_add_f32_e32 v67, 1.0, v67
	v_add_f32_e32 v68, 1.0, v68
	v_add_f32_e32 v69, 1.0, v69
	v_rcp_f32_e32 v66, v66
	v_rcp_f32_e32 v67, v67
	v_rcp_f32_e32 v68, v68
	v_rcp_f32_e32 v69, v69
	v_pk_mul_f32 v[58:59], v[62:63], v[58:59]
	v_pk_mul_f32 v[56:57], v[60:61], v[56:57]
	global_store_dwordx2 v[80:81], v[64:65], off offset:128
	v_pk_mul_f32 v[56:57], v[56:57], v[66:67]
	v_pk_mul_f32 v[58:59], v[58:59], v[68:69]
	v_cvt_pk_bf16_f32 v56, v56, v57
	v_cvt_pk_bf16_f32 v57, v58, v59
	v_exp_f32_e64 v58, -v52
	v_exp_f32_e64 v59, -v53
	v_add_u32_e32 v64, 0x80, v170
	v_mad_i64_i32 v[64:65], s[34:35], v64, s82, v[142:143]
	v_lshl_add_u64 v[64:65], v[64:65], 0, v[140:141]
	global_store_dwordx2 v[64:65], v[56:57], off
	v_add_f32_e32 v56, 1.0, v58
	v_add_f32_e32 v57, 1.0, v59
	v_exp_f32_e64 v58, -v54
	v_exp_f32_e64 v59, -v55
	v_rcp_f32_e32 v56, v56
	v_rcp_f32_e32 v57, v57
	v_add_f32_e32 v58, 1.0, v58
	v_add_f32_e32 v59, 1.0, v59
	v_rcp_f32_e32 v58, v58
	v_rcp_f32_e32 v59, v59
	v_pk_mul_f32 v[50:51], v[54:55], v[50:51]
	v_pk_mul_f32 v[48:49], v[52:53], v[48:49]
	v_pk_mul_f32 v[48:49], v[48:49], v[56:57]
	v_pk_mul_f32 v[50:51], v[50:51], v[58:59]
	v_cvt_pk_bf16_f32 v48, v48, v49
	v_cvt_pk_bf16_f32 v49, v50, v51
	v_exp_f32_e64 v50, -v44
	v_exp_f32_e64 v51, -v45
	v_exp_f32_e64 v52, -v46
	v_exp_f32_e64 v53, -v47
	v_add_f32_e32 v50, 1.0, v50
	v_add_f32_e32 v51, 1.0, v51
	v_add_f32_e32 v52, 1.0, v52
	v_add_f32_e32 v53, 1.0, v53
	v_rcp_f32_e32 v50, v50
	v_rcp_f32_e32 v51, v51
	v_rcp_f32_e32 v52, v52
	v_rcp_f32_e32 v53, v53
	v_pk_mul_f32 v[42:43], v[46:47], v[42:43]
	v_pk_mul_f32 v[40:41], v[44:45], v[40:41]
	global_store_dwordx2 v[64:65], v[48:49], off offset:128
	v_pk_mul_f32 v[40:41], v[40:41], v[50:51]
	v_pk_mul_f32 v[42:43], v[42:43], v[52:53]
	v_cvt_pk_bf16_f32 v40, v40, v41
	v_cvt_pk_bf16_f32 v41, v42, v43
	v_exp_f32_e64 v42, -v36
	v_exp_f32_e64 v43, -v37
	v_add_u32_e32 v48, 0x90, v170
	v_mad_i64_i32 v[48:49], s[34:35], v48, s82, v[142:143]
	v_lshl_add_u64 v[48:49], v[48:49], 0, v[140:141]
	global_store_dwordx2 v[48:49], v[40:41], off
	v_add_f32_e32 v40, 1.0, v42
	v_add_f32_e32 v41, 1.0, v43
	v_exp_f32_e64 v42, -v38
	v_exp_f32_e64 v43, -v39
	v_rcp_f32_e32 v40, v40
	v_rcp_f32_e32 v41, v41
	v_add_f32_e32 v42, 1.0, v42
	v_add_f32_e32 v43, 1.0, v43
	v_rcp_f32_e32 v42, v42
	v_rcp_f32_e32 v43, v43
	v_pk_mul_f32 v[34:35], v[38:39], v[34:35]
	v_pk_mul_f32 v[32:33], v[36:37], v[32:33]
	v_pk_mul_f32 v[32:33], v[32:33], v[40:41]
	v_pk_mul_f32 v[34:35], v[34:35], v[42:43]
	v_cvt_pk_bf16_f32 v32, v32, v33
	v_cvt_pk_bf16_f32 v33, v34, v35
	v_exp_f32_e64 v34, -v28
	v_exp_f32_e64 v35, -v29
	v_exp_f32_e64 v36, -v30
	v_exp_f32_e64 v37, -v31
	v_add_f32_e32 v34, 1.0, v34
	v_add_f32_e32 v35, 1.0, v35
	v_add_f32_e32 v36, 1.0, v36
	v_add_f32_e32 v37, 1.0, v37
	v_rcp_f32_e32 v34, v34
	v_rcp_f32_e32 v35, v35
	v_rcp_f32_e32 v36, v36
	v_rcp_f32_e32 v37, v37
	v_pk_mul_f32 v[26:27], v[30:31], v[26:27]
	v_pk_mul_f32 v[24:25], v[28:29], v[24:25]
	global_store_dwordx2 v[48:49], v[32:33], off offset:128
	v_pk_mul_f32 v[24:25], v[24:25], v[34:35]
	v_pk_mul_f32 v[26:27], v[26:27], v[36:37]
	v_cvt_pk_bf16_f32 v24, v24, v25
	v_cvt_pk_bf16_f32 v25, v26, v27
	v_exp_f32_e64 v26, -v20
	v_exp_f32_e64 v27, -v21
	v_add_u32_e32 v32, 0xa0, v170
	v_mad_i64_i32 v[32:33], s[34:35], v32, s82, v[142:143]
	v_lshl_add_u64 v[32:33], v[32:33], 0, v[140:141]
	global_store_dwordx2 v[32:33], v[24:25], off
	v_add_f32_e32 v24, 1.0, v26
	v_add_f32_e32 v25, 1.0, v27
	v_exp_f32_e64 v26, -v22
	v_exp_f32_e64 v27, -v23
	v_rcp_f32_e32 v24, v24
	v_rcp_f32_e32 v25, v25
	v_add_f32_e32 v26, 1.0, v26
	v_add_f32_e32 v27, 1.0, v27
	v_rcp_f32_e32 v26, v26
	v_rcp_f32_e32 v27, v27
	v_pk_mul_f32 v[18:19], v[22:23], v[18:19]
	v_pk_mul_f32 v[16:17], v[20:21], v[16:17]
	v_pk_mul_f32 v[16:17], v[16:17], v[24:25]
	v_pk_mul_f32 v[18:19], v[18:19], v[26:27]
	v_cvt_pk_bf16_f32 v16, v16, v17
	v_cvt_pk_bf16_f32 v17, v18, v19
	v_exp_f32_e64 v18, -v12
	v_exp_f32_e64 v19, -v13
	v_exp_f32_e64 v20, -v14
	v_exp_f32_e64 v21, -v15
	v_add_f32_e32 v18, 1.0, v18
	v_add_f32_e32 v19, 1.0, v19
	v_add_f32_e32 v20, 1.0, v20
	v_add_f32_e32 v21, 1.0, v21
	v_rcp_f32_e32 v18, v18
	v_rcp_f32_e32 v19, v19
	v_rcp_f32_e32 v20, v20
	v_rcp_f32_e32 v21, v21
	v_pk_mul_f32 v[10:11], v[14:15], v[10:11]
	v_pk_mul_f32 v[8:9], v[12:13], v[8:9]
	global_store_dwordx2 v[32:33], v[16:17], off offset:128
	v_pk_mul_f32 v[8:9], v[8:9], v[18:19]
	v_pk_mul_f32 v[10:11], v[10:11], v[20:21]
	v_cvt_pk_bf16_f32 v8, v8, v9
	v_cvt_pk_bf16_f32 v9, v10, v11
	v_exp_f32_e64 v10, -v4
	v_exp_f32_e64 v11, -v5
	v_add_u32_e32 v16, 0xb0, v170
	v_mad_i64_i32 v[16:17], s[34:35], v16, s82, v[142:143]
	v_lshl_add_u64 v[16:17], v[16:17], 0, v[140:141]
	global_store_dwordx2 v[16:17], v[8:9], off
	v_add_f32_e32 v8, 1.0, v10
	v_add_f32_e32 v9, 1.0, v11
	v_exp_f32_e64 v10, -v6
	v_exp_f32_e64 v11, -v7
	v_rcp_f32_e32 v8, v8
	v_rcp_f32_e32 v9, v9
	v_add_f32_e32 v10, 1.0, v10
	v_add_f32_e32 v11, 1.0, v11
	v_rcp_f32_e32 v10, v10
	v_rcp_f32_e32 v11, v11
	v_pk_mul_f32 v[2:3], v[6:7], v[2:3]
	v_pk_mul_f32 v[0:1], v[4:5], v[0:1]
	s_and_b64 vcc, exec, s[2:3]
	v_pk_mul_f32 v[0:1], v[0:1], v[8:9]
	v_pk_mul_f32 v[2:3], v[2:3], v[10:11]
	v_cvt_pk_bf16_f32 v0, v0, v1
	v_cvt_pk_bf16_f32 v1, v2, v3
	s_mov_b32 s86, s83
	s_mov_b32 s85, s84
	s_mov_b64 s[36:37], s[0:1]
	s_mov_b64 s[34:35], s[4:5]
	global_store_dwordx2 v[16:17], v[0:1], off offset:128
	s_cbranch_vccz .LBB0_344
	s_branch .Lgu2_done

; #define PG8_STAGE(bufoff, gbase, voff) do { _Pragma("unroll") for (int _i = 0; _i < 2; ++_i) \
;         __builtin_amdgcn_global_load_lds((const unsigned*)((const char*)(gbase) + (voff)[_i]), (PG8_LAS unsigned*)(lds + (bufoff) + ldsw + _i * 8192), 16, 0, 0); } while (0)
; #define PG8_LDA(dst, b, h) do { _Pragma("unroll") for (int m = 0; m < 4; ++m) _Pragma("unroll") for (int k = 0; k < 2; ++k) dst[m][k] = *(const PG8_LAS bf16x8*)(lds + PG8_SA(b, h) + aoff + m * 2048 + k * 1024); } while (0)
; template <class Epi, class Sched, bool STAMP = false>
; __device__ __forceinline__ void gemm_phase(PG8_LAS unsigned char* lds, const Gemm g, const Sched& S, const Epi& E, unsigned long long* stamps) {
;     ...
;         for (int t = 0; t < nt; t += 2) {
;             const bool last = (t == nt - 2);
;             const char* a1 = cA + (size_t)(t + 1) * kstep;
;             const char* a2 = last ? nA : cA + (size_t)(t + 2) * kstep; const char* b2 = last ? nB : cB + (size_t)(t + 2) * kstep;
;             const char* a3 = a2 + kstep; const char* b3 = b2 + kstep;
;             if (last && has_next) S.a_ready(nxt);
;             PG8_LDB(B0, 0, 0); PG8_SCHED; PG8_LDA(At, 0, 0); PG8_STAGE(PG8_SA(1, 1), a1 + hstep, voffA);
;             PG8_WAIT_L(8); PG8_BAR; PG8_WAIT_L(0); PG8_MMA(0, 0, At, B0); PG8_BAR; PG8_SCHED;
;             PG8_LDB(B1, 0, 1); PG8_STAGE(PG8_SB(0, 0), b2, voffB);
;             PG8_BAR; PG8_WAIT_L(0); PG8_MMA(0, 1, At, B1); PG8_BAR;
;             PG8_LDA(At, 0, 1); PG8_STAGE(PG8_SA(0, 0), a2, voffA);
;             PG8_BAR; PG8_WAIT_L(0); PG8_MMA(1, 0, At, B0); PG8_BAR; PG8_SCHED;
;             PG8_STAGE(PG8_SB(0, 1), b2 + hstep, voffB);
;             PG8_WAIT_V(6); PG8_BAR; PG8_MMA(1, 1, At, B1); PG8_BAR;
;             PG8_LDB(B0, 1, 0); PG8_SCHED; PG8_LDA(At, 1, 0); PG8_STAGE(PG8_SA(0, 1), a2 + hstep, voffA);
;             PG8_WAIT_L(8); PG8_BAR; PG8_WAIT_L(0); PG8_MMA(0, 0, At, B0); PG8_BAR; PG8_SCHED;
;             PG8_LDB(B1, 1, 1); PG8_STAGE(PG8_SB(1, 0), b3, voffB);
;             PG8_BAR; PG8_WAIT_L(0); PG8_MMA(0, 1, At, B1); PG8_BAR;
;             PG8_LDA(At, 1, 1); PG8_STAGE(PG8_SA(1, 0), a3, voffA);
;             PG8_BAR; PG8_WAIT_L(0); PG8_MMA(1, 0, At, B0); PG8_BAR; PG8_SCHED;
;             PG8_STAGE(PG8_SB(1, 1), b3 + hstep, voffB);
;             PG8_WAIT_V(6); PG8_BAR; PG8_MMA(1, 1, At, B1); PG8_BAR;
;         }
.Lgu2_half_loop:
	ds_read_b128 v[140:143], v147
	ds_read_b128 v[170:173], v148
	ds_read_b128 v[174:177], v149
	ds_read_b128 v[178:181], v150
	s_add_u32 s36, s34, 0x100
	s_addc_u32 s37, s35, 0
	s_cmp_eq_u32 s89, 12
	s_cselect_b32 s55, s5, s37
	s_cselect_b32 s54, s4, s36
	s_cselect_b32 s53, s1, s88
	s_cselect_b32 s52, s0, s87
	s_mov_b32 m0, s78
	ds_read_b128 v[182:185], v145
	ds_read_b128 v[186:189], v145 offset:1024
	ds_read_b128 v[190:193], v145 offset:2048
	ds_read_b128 v[194:197], v145 offset:3072
	ds_read_b128 v[198:201], v145 offset:4096
	ds_read_b128 v[202:205], v145 offset:5120
	ds_read_b128 v[206:209], v145 offset:6144
	ds_read_b128 v[210:213], v145 offset:7168
	global_load_lds_dwordx4 v132, s[34:35]
	s_mov_b32 m0, s79
	s_nop 0
	global_load_lds_dwordx4 v134, s[34:35]
	s_waitcnt lgkmcnt(8)
	s_barrier
	s_waitcnt lgkmcnt(0)
	s_setprio 1
	s_waitcnt lgkmcnt(0)
	v_mfma_f32_16x16x32_bf16 v[124:127], v[140:143], v[182:185], v[124:127]
	v_mfma_f32_16x16x32_bf16 v[120:123], v[174:177], v[182:185], v[120:123]
	v_mfma_f32_16x16x32_bf16 v[108:111], v[140:143], v[190:193], v[108:111]
	v_mfma_f32_16x16x32_bf16 v[104:107], v[174:177], v[190:193], v[104:107]
	v_mfma_f32_16x16x32_bf16 v[92:95], v[140:143], v[198:201], v[92:95]
	v_mfma_f32_16x16x32_bf16 v[88:91], v[174:177], v[198:201], v[88:91]
	v_mfma_f32_16x16x32_bf16 v[76:79], v[140:143], v[206:209], v[76:79]
	v_mfma_f32_16x16x32_bf16 v[72:75], v[174:177], v[206:209], v[72:75]
	v_mfma_f32_16x16x32_bf16 v[124:127], v[170:173], v[186:189], v[124:127]
	v_mfma_f32_16x16x32_bf16 v[120:123], v[178:181], v[186:189], v[120:123]
	v_mfma_f32_16x16x32_bf16 v[108:111], v[170:173], v[194:197], v[108:111]
	v_mfma_f32_16x16x32_bf16 v[104:107], v[178:181], v[194:197], v[104:107]
	v_mfma_f32_16x16x32_bf16 v[92:95], v[170:173], v[202:205], v[92:95]
	v_mfma_f32_16x16x32_bf16 v[88:91], v[178:181], v[202:205], v[88:91]
	v_mfma_f32_16x16x32_bf16 v[76:79], v[170:173], v[210:213], v[76:79]
	v_mfma_f32_16x16x32_bf16 v[72:75], v[178:181], v[210:213], v[72:75]
	s_setprio 0
	s_barrier
	s_mov_b32 m0, s61
	s_nop 0
	global_load_lds_dwordx4 v130, s[52:53]
	s_mov_b32 m0, s62
	s_nop 0
	global_load_lds_dwordx4 v128, s[52:53]
	s_barrier
	s_waitcnt lgkmcnt(0)
	s_setprio 1
	s_waitcnt lgkmcnt(0)
	s_setprio 0
	s_mov_b32 m0, s58
	s_barrier
	ds_read_b128 v[182:185], v145 offset:16384
	ds_read_b128 v[186:189], v145 offset:17408
	ds_read_b128 v[190:193], v145 offset:18432
	ds_read_b128 v[194:197], v145 offset:19456
	ds_read_b128 v[198:201], v145 offset:20480
	ds_read_b128 v[202:205], v145 offset:21504
	ds_read_b128 v[206:209], v145 offset:22528
	ds_read_b128 v[210:213], v145 offset:23552
	global_load_lds_dwordx4 v130, s[54:55]
	s_mov_b32 m0, s63
	s_nop 0
	global_load_lds_dwordx4 v128, s[54:55]
	s_barrier
	s_waitcnt lgkmcnt(0)
	s_setprio 1
	s_waitcnt lgkmcnt(0)
	v_mfma_f32_16x16x32_bf16 v[60:63], v[140:143], v[182:185], v[60:63]
	v_mfma_f32_16x16x32_bf16 v[56:59], v[174:177], v[182:185], v[56:59]
	v_mfma_f32_16x16x32_bf16 v[44:47], v[140:143], v[190:193], v[44:47]
	v_mfma_f32_16x16x32_bf16 v[40:43], v[174:177], v[190:193], v[40:43]
	v_mfma_f32_16x16x32_bf16 v[28:31], v[140:143], v[198:201], v[28:31]
	v_mfma_f32_16x16x32_bf16 v[24:27], v[174:177], v[198:201], v[24:27]
	v_mfma_f32_16x16x32_bf16 v[12:15], v[140:143], v[206:209], v[12:15]
	v_mfma_f32_16x16x32_bf16 v[8:11], v[174:177], v[206:209], v[8:11]
	v_mfma_f32_16x16x32_bf16 v[60:63], v[170:173], v[186:189], v[60:63]
	v_mfma_f32_16x16x32_bf16 v[56:59], v[178:181], v[186:189], v[56:59]
	v_mfma_f32_16x16x32_bf16 v[44:47], v[170:173], v[194:197], v[44:47]
	v_mfma_f32_16x16x32_bf16 v[40:43], v[178:181], v[194:197], v[40:43]
	v_mfma_f32_16x16x32_bf16 v[28:31], v[170:173], v[202:205], v[28:31]
	v_mfma_f32_16x16x32_bf16 v[24:27], v[178:181], v[202:205], v[24:27]
	v_mfma_f32_16x16x32_bf16 v[12:15], v[170:173], v[210:213], v[12:15]
	v_mfma_f32_16x16x32_bf16 v[8:11], v[178:181], v[210:213], v[8:11]
	s_setprio 0
	s_barrier
	s_add_u32 s34, s52, 0x44000
	s_addc_u32 s35, s53, 0
	s_mov_b32 m0, s64
	s_nop 0
	s_mov_b32 m0, s65
	s_nop 0
	s_waitcnt vmcnt(4)
	s_barrier
	s_setprio 1
	s_setprio 0
	s_barrier
	ds_read_b128 v[140:143], v155
	ds_read_b128 v[170:173], v156
	ds_read_b128 v[174:177], v157
	ds_read_b128 v[178:181], v165
	s_add_u32 s34, s54, 0x44000
	s_addc_u32 s35, s55, 0
	s_mov_b32 m0, s66
	ds_read_b128 v[182:185], v145 offset:32768
	ds_read_b128 v[186:189], v145 offset:33792
	ds_read_b128 v[190:193], v145 offset:34816
	ds_read_b128 v[194:197], v145 offset:35840
	ds_read_b128 v[198:201], v145 offset:36864
	ds_read_b128 v[202:205], v145 offset:37888
	ds_read_b128 v[206:209], v145 offset:38912
	ds_read_b128 v[210:213], v145 offset:39936
	global_load_lds_dwordx4 v130, s[34:35]
	s_mov_b32 m0, s67
	s_nop 0
	global_load_lds_dwordx4 v128, s[34:35]
	s_waitcnt lgkmcnt(8)
	s_barrier
	s_waitcnt lgkmcnt(0)
	s_setprio 1
	s_waitcnt lgkmcnt(0)
	v_mfma_f32_16x16x32_bf16 v[124:127], v[140:143], v[182:185], v[124:127]
	v_mfma_f32_16x16x32_bf16 v[120:123], v[174:177], v[182:185], v[120:123]
	v_mfma_f32_16x16x32_bf16 v[108:111], v[140:143], v[190:193], v[108:111]
	v_mfma_f32_16x16x32_bf16 v[104:107], v[174:177], v[190:193], v[104:107]
	v_mfma_f32_16x16x32_bf16 v[92:95], v[140:143], v[198:201], v[92:95]
	v_mfma_f32_16x16x32_bf16 v[88:91], v[174:177], v[198:201], v[88:91]
	v_mfma_f32_16x16x32_bf16 v[76:79], v[140:143], v[206:209], v[76:79]
	v_mfma_f32_16x16x32_bf16 v[72:75], v[174:177], v[206:209], v[72:75]
	v_mfma_f32_16x16x32_bf16 v[124:127], v[170:173], v[186:189], v[124:127]
	v_mfma_f32_16x16x32_bf16 v[120:123], v[178:181], v[186:189], v[120:123]
	v_mfma_f32_16x16x32_bf16 v[108:111], v[170:173], v[194:197], v[108:111]
	v_mfma_f32_16x16x32_bf16 v[104:107], v[178:181], v[194:197], v[104:107]
	v_mfma_f32_16x16x32_bf16 v[92:95], v[170:173], v[202:205], v[92:95]
	v_mfma_f32_16x16x32_bf16 v[88:91], v[178:181], v[202:205], v[88:91]
	v_mfma_f32_16x16x32_bf16 v[76:79], v[170:173], v[210:213], v[76:79]
	v_mfma_f32_16x16x32_bf16 v[72:75], v[178:181], v[210:213], v[72:75]
	s_setprio 0
	s_barrier
; #define PG8_STAGE(bufoff, gbase, voff) do { _Pragma("unroll") for (int _i = 0; _i < 2; ++_i) \
;         __builtin_amdgcn_global_load_lds((const unsigned*)((const char*)(gbase) + (voff)[_i]), (PG8_LAS unsigned*)(lds + (bufoff) + ldsw + _i * 8192), 16, 0, 0); } while (0)
; #define PG8_LDA(dst, b, h) do { _Pragma("unroll") for (int m = 0; m < 4; ++m) _Pragma("unroll") for (int k = 0; k < 2; ++k) dst[m][k] = *(const PG8_LAS bf16x8*)(lds + PG8_SA(b, h) + aoff + m * 2048 + k * 1024); } while (0)
; template <class Epi, class Sched, bool STAMP = false>
; __device__ __forceinline__ void gemm_phase(PG8_LAS unsigned char* lds, const Gemm g, const Sched& S, const Epi& E, unsigned long long* stamps) {
;     ...
;         for (int t = 0; t < nt; t += 2) {
;             const bool last = (t == nt - 2);
;             const char* a1 = cA + (size_t)(t + 1) * kstep;
;             const char* a2 = last ? nA : cA + (size_t)(t + 2) * kstep; const char* b2 = last ? nB : cB + (size_t)(t + 2) * kstep;
;             const char* a3 = a2 + kstep; const char* b3 = b2 + kstep;
;             if (last && has_next) S.a_ready(nxt);
;             PG8_LDB(B0, 0, 0); PG8_SCHED; PG8_LDA(At, 0, 0); PG8_STAGE(PG8_SA(1, 1), a1 + hstep, voffA);
;             PG8_WAIT_L(8); PG8_BAR; PG8_WAIT_L(0); PG8_MMA(0, 0, At, B0); PG8_BAR; PG8_SCHED;
;             PG8_LDB(B1, 0, 1); PG8_STAGE(PG8_SB(0, 0), b2, voffB);
;             PG8_BAR; PG8_WAIT_L(0); PG8_MMA(0, 1, At, B1); PG8_BAR;
;             PG8_LDA(At, 0, 1); PG8_STAGE(PG8_SA(0, 0), a2, voffA);
;             PG8_BAR; PG8_WAIT_L(0); PG8_MMA(1, 0, At, B0); PG8_BAR; PG8_SCHED;
;             PG8_STAGE(PG8_SB(0, 1), b2 + hstep, voffB);
;             PG8_WAIT_V(6); PG8_BAR; PG8_MMA(1, 1, At, B1); PG8_BAR;
;             PG8_LDB(B0, 1, 0); PG8_SCHED; PG8_LDA(At, 1, 0); PG8_STAGE(PG8_SA(0, 1), a2 + hstep, voffA);
;             PG8_WAIT_L(8); PG8_BAR; PG8_WAIT_L(0); PG8_MMA(0, 0, At, B0); PG8_BAR; PG8_SCHED;
;             PG8_LDB(B1, 1, 1); PG8_STAGE(PG8_SB(1, 0), b3, voffB);
;             PG8_BAR; PG8_WAIT_L(0); PG8_MMA(0, 1, At, B1); PG8_BAR;
;             PG8_LDA(At, 1, 1); PG8_STAGE(PG8_SA(1, 0), a3, voffA);
;             PG8_BAR; PG8_WAIT_L(0); PG8_MMA(1, 0, At, B0); PG8_BAR; PG8_SCHED;
;             PG8_STAGE(PG8_SB(1, 1), b3 + hstep, voffB);
;             PG8_WAIT_V(6); PG8_BAR; PG8_MMA(1, 1, At, B1); PG8_BAR;
;         }
	s_mov_b32 m0, s70
	s_add_u32 s100, s52, 0x80
	s_addc_u32 s101, s53, 0
	global_load_lds_dwordx4 v130, s[100:101]
	s_mov_b32 m0, s71
	s_nop 0
	global_load_lds_dwordx4 v128, s[100:101]
	s_barrier
	s_waitcnt lgkmcnt(0)
	s_setprio 1
	s_waitcnt lgkmcnt(0)
	s_setprio 0
	s_mov_b32 m0, s73
	s_barrier
	ds_read_b128 v[182:185], v145 offset:49152
	ds_read_b128 v[186:189], v145 offset:50176
	ds_read_b128 v[190:193], v145 offset:51200
	ds_read_b128 v[194:197], v145 offset:52224
	ds_read_b128 v[198:201], v145 offset:53248
	ds_read_b128 v[202:205], v145 offset:54272
	ds_read_b128 v[206:209], v145 offset:55296
	ds_read_b128 v[210:213], v145 offset:56320
	s_add_u32 s100, s54, 0x80
	s_addc_u32 s101, s55, 0
	global_load_lds_dwordx4 v130, s[100:101]
	s_mov_b32 m0, s74
	s_nop 0
	global_load_lds_dwordx4 v128, s[100:101]
	s_barrier
	s_waitcnt lgkmcnt(0)
	s_setprio 1
	s_waitcnt lgkmcnt(0)
	v_mfma_f32_16x16x32_bf16 v[60:63], v[140:143], v[182:185], v[60:63]
	v_mfma_f32_16x16x32_bf16 v[56:59], v[174:177], v[182:185], v[56:59]
	v_mfma_f32_16x16x32_bf16 v[44:47], v[140:143], v[190:193], v[44:47]
	v_mfma_f32_16x16x32_bf16 v[40:43], v[174:177], v[190:193], v[40:43]
	v_mfma_f32_16x16x32_bf16 v[28:31], v[140:143], v[198:201], v[28:31]
	v_mfma_f32_16x16x32_bf16 v[24:27], v[174:177], v[198:201], v[24:27]
	v_mfma_f32_16x16x32_bf16 v[12:15], v[140:143], v[206:209], v[12:15]
	v_mfma_f32_16x16x32_bf16 v[8:11], v[174:177], v[206:209], v[8:11]
	v_mfma_f32_16x16x32_bf16 v[60:63], v[170:173], v[186:189], v[60:63]
	v_mfma_f32_16x16x32_bf16 v[56:59], v[178:181], v[186:189], v[56:59]
	v_mfma_f32_16x16x32_bf16 v[44:47], v[170:173], v[194:197], v[44:47]
	v_mfma_f32_16x16x32_bf16 v[40:43], v[178:181], v[194:197], v[40:43]
	v_mfma_f32_16x16x32_bf16 v[28:31], v[170:173], v[202:205], v[28:31]
	v_mfma_f32_16x16x32_bf16 v[24:27], v[178:181], v[202:205], v[24:27]
	v_mfma_f32_16x16x32_bf16 v[12:15], v[170:173], v[210:213], v[12:15]
	v_mfma_f32_16x16x32_bf16 v[8:11], v[178:181], v[210:213], v[8:11]
	s_setprio 0
	s_barrier
	s_add_u32 s34, s52, 0x44080
	s_addc_u32 s35, s53, 0
	s_mov_b32 m0, s75
	s_nop 0
	s_mov_b32 m0, s76
	s_nop 0
	s_add_i32 s89, s89, 2
	s_add_u32 s87, s87, 0x100
	s_addc_u32 s88, s88, 0
	s_cmp_gt_u32 s89, 13
	s_mov_b64 s[34:35], s[36:37]
	s_waitcnt vmcnt(4)
	s_barrier
	s_setprio 1
	s_setprio 0
	s_barrier
	s_cbranch_scc0 .Lgu2_half_loop
; DI float ex2(float x) { return __builtin_amdgcn_exp2f(x); }
;     DI void operator()(const f32x4 (&acc)[2][2][4][2], const Unit& u, int wr, int wc, int fr, int fq) const {
;         const int row0 = u.pm * BM + wr * 64 + fr, hcol0 = ((u.pn * BM + wc * 32) >> 1) + 4 * fq;
; #pragma unroll
;         for (int ai = 0; ai < 2; ++ai)
; #pragma unroll
;             for (int m = 0; m < 4; ++m) { u16* rowp = O + (size_t)(row0 + ai * HALF + m * 16) * ldc + hcol0;
; #pragma unroll
;                 for (int bj = 0; bj < 2; ++bj) { const f32x4 g = acc[ai][bj][m][0], up = acc[ai][bj][m][1]; float r[4];
; #pragma unroll
;                     for (int j = 0; j < 4; ++j) r[j] = g[j] * up[j] * __builtin_amdgcn_rcpf(1.f + ex2(-LOG2E * g[j]));
;                     uint2 w = {pack2(r[0], r[1]), pack2(r[2], r[3])}; *(uint2*)(rowp + bj * (HALF / 2)) = w; } }
	v_exp_f32_e64 v171, -v124
	v_exp_f32_e64 v175, -v125
	s_lshl_b32 s10, s86, 8
	v_add_f32_e32 v171, 1.0, v171
	v_rcp_f32_e32 v174, v171
	v_add_f32_e32 v171, 1.0, v175
	v_exp_f32_e64 v176, -v126
	v_exp_f32_e64 v177, -v127
	v_rcp_f32_e32 v175, v171
	v_add_f32_e32 v171, 1.0, v176
	v_rcp_f32_e32 v176, v171
	v_add_f32_e32 v171, 1.0, v177
	v_rcp_f32_e32 v177, v171
	v_pk_mul_f32 v[122:123], v[126:127], v[122:123]
	v_pk_mul_f32 v[120:121], v[124:125], v[120:121]
	s_or_b32 s10, s10, s69
	s_or_b32 s10, s10, s98
	v_pk_mul_f32 v[120:121], v[120:121], v[174:175]
	v_pk_mul_f32 v[122:123], v[122:123], v[176:177]
	s_ashr_i32 s10, s10, 1
	v_cvt_pk_bf16_f32 v120, v120, v121
	v_cvt_pk_bf16_f32 v121, v122, v123
	v_or_b32_e32 v140, s10, v146
	v_lshl_add_u32 v170, s85, 8, v144
	v_ashrrev_i32_e32 v141, 31, v140
	v_mov_b64_e32 v[142:143], s[12:13]
	v_mad_i64_i32 v[172:173], s[34:35], v170, s82, v[142:143]
	v_lshlrev_b64 v[140:141], 1, v[140:141]
	v_lshl_add_u64 v[172:173], v[172:173], 0, v[140:141]
	global_store_dwordx2 v[172:173], v[120:121], off
	v_exp_f32_e64 v114, -v108
	v_exp_f32_e64 v115, -v109
	v_exp_f32_e64 v116, -v110
	v_exp_f32_e64 v117, -v111
	v_add_f32_e32 v114, 1.0, v114
	v_add_f32_e32 v115, 1.0, v115
	v_add_f32_e32 v116, 1.0, v116
	v_add_f32_e32 v117, 1.0, v117
	v_rcp_f32_e32 v114, v114
	v_rcp_f32_e32 v115, v115
	v_rcp_f32_e32 v116, v116
	v_rcp_f32_e32 v117, v117
	v_pk_mul_f32 v[106:107], v[110:111], v[106:107]
	v_pk_mul_f32 v[104:105], v[108:109], v[104:105]
	v_pk_mul_f32 v[104:105], v[104:105], v[114:115]
	v_pk_mul_f32 v[106:107], v[106:107], v[116:117]
	v_cvt_pk_bf16_f32 v104, v104, v105
	v_cvt_pk_bf16_f32 v105, v106, v107
	v_or_b32_e32 v112, 16, v170
	v_mad_i64_i32 v[112:113], s[34:35], v112, s82, v[142:143]
	v_lshl_add_u64 v[112:113], v[112:113], 0, v[140:141]
	global_store_dwordx2 v[112:113], v[104:105], off
	v_exp_f32_e64 v98, -v92
	v_exp_f32_e64 v99, -v93
	v_exp_f32_e64 v100, -v94
	v_exp_f32_e64 v101, -v95
	v_add_f32_e32 v98, 1.0, v98
	v_add_f32_e32 v99, 1.0, v99
	v_add_f32_e32 v100, 1.0, v100
	v_add_f32_e32 v101, 1.0, v101
	v_rcp_f32_e32 v98, v98
	v_rcp_f32_e32 v99, v99
	v_rcp_f32_e32 v100, v100
	v_rcp_f32_e32 v101, v101
	v_pk_mul_f32 v[90:91], v[94:95], v[90:91]
	v_pk_mul_f32 v[88:89], v[92:93], v[88:89]
	v_pk_mul_f32 v[88:89], v[88:89], v[98:99]
	v_pk_mul_f32 v[90:91], v[90:91], v[100:101]
	v_cvt_pk_bf16_f32 v88, v88, v89
	v_cvt_pk_bf16_f32 v89, v90, v91
	v_or_b32_e32 v96, 32, v170
	v_mad_i64_i32 v[96:97], s[34:35], v96, s82, v[142:143]
	v_lshl_add_u64 v[96:97], v[96:97], 0, v[140:141]
	global_store_dwordx2 v[96:97], v[88:89], off
	v_exp_f32_e64 v82, -v76
	v_exp_f32_e64 v83, -v77
	v_exp_f32_e64 v84, -v78
	v_exp_f32_e64 v85, -v79
	v_add_f32_e32 v82, 1.0, v82
	v_add_f32_e32 v83, 1.0, v83
	v_add_f32_e32 v84, 1.0, v84
	v_add_f32_e32 v85, 1.0, v85
	v_rcp_f32_e32 v82, v82
	v_rcp_f32_e32 v83, v83
	v_rcp_f32_e32 v84, v84
	v_rcp_f32_e32 v85, v85
	v_pk_mul_f32 v[74:75], v[78:79], v[74:75]
	v_pk_mul_f32 v[72:73], v[76:77], v[72:73]
	v_pk_mul_f32 v[72:73], v[72:73], v[82:83]
	v_pk_mul_f32 v[74:75], v[74:75], v[84:85]
	v_cvt_pk_bf16_f32 v72, v72, v73
	v_cvt_pk_bf16_f32 v73, v74, v75
	v_or_b32_e32 v80, 48, v170
	v_mad_i64_i32 v[80:81], s[34:35], v80, s82, v[142:143]
	v_lshl_add_u64 v[80:81], v[80:81], 0, v[140:141]
	global_store_dwordx2 v[80:81], v[72:73], off
	v_exp_f32_e64 v66, -v60
	v_exp_f32_e64 v67, -v61
	v_exp_f32_e64 v68, -v62
	v_exp_f32_e64 v69, -v63
	v_add_f32_e32 v66, 1.0, v66
	v_add_f32_e32 v67, 1.0, v67
	v_add_f32_e32 v68, 1.0, v68
	v_add_f32_e32 v69, 1.0, v69
	v_rcp_f32_e32 v66, v66
	v_rcp_f32_e32 v67, v67
	v_rcp_f32_e32 v68, v68
	v_rcp_f32_e32 v69, v69
	v_pk_mul_f32 v[58:59], v[62:63], v[58:59]
	v_pk_mul_f32 v[56:57], v[60:61], v[56:57]
	v_pk_mul_f32 v[56:57], v[56:57], v[66:67]
	v_pk_mul_f32 v[58:59], v[58:59], v[68:69]
	v_cvt_pk_bf16_f32 v56, v56, v57
	v_cvt_pk_bf16_f32 v57, v58, v59
	v_add_u32_e32 v64, 0x80, v170
	v_mad_i64_i32 v[64:65], s[34:35], v64, s82, v[142:143]
	v_lshl_add_u64 v[64:65], v[64:65], 0, v[140:141]
	global_store_dwordx2 v[64:65], v[56:57], off
	v_exp_f32_e64 v50, -v44
	v_exp_f32_e64 v51, -v45
	v_exp_f32_e64 v52, -v46
	v_exp_f32_e64 v53, -v47
	v_add_f32_e32 v50, 1.0, v50
	v_add_f32_e32 v51, 1.0, v51
	v_add_f32_e32 v52, 1.0, v52
	v_add_f32_e32 v53, 1.0, v53
	v_rcp_f32_e32 v50, v50
	v_rcp_f32_e32 v51, v51
	v_rcp_f32_e32 v52, v52
	v_rcp_f32_e32 v53, v53
	v_pk_mul_f32 v[42:43], v[46:47], v[42:43]
	v_pk_mul_f32 v[40:41], v[44:45], v[40:41]
	v_pk_mul_f32 v[40:41], v[40:41], v[50:51]
	v_pk_mul_f32 v[42:43], v[42:43], v[52:53]
	v_cvt_pk_bf16_f32 v40, v40, v41
	v_cvt_pk_bf16_f32 v41, v42, v43
	v_add_u32_e32 v48, 0x90, v170
	v_mad_i64_i32 v[48:49], s[34:35], v48, s82, v[142:143]
	v_lshl_add_u64 v[48:49], v[48:49], 0, v[140:141]
	global_store_dwordx2 v[48:49], v[40:41], off
	v_exp_f32_e64 v34, -v28
	v_exp_f32_e64 v35, -v29
	v_exp_f32_e64 v36, -v30
	v_exp_f32_e64 v37, -v31
	v_add_f32_e32 v34, 1.0, v34
	v_add_f32_e32 v35, 1.0, v35
	v_add_f32_e32 v36, 1.0, v36
	v_add_f32_e32 v37, 1.0, v37
	v_rcp_f32_e32 v34, v34
	v_rcp_f32_e32 v35, v35
	v_rcp_f32_e32 v36, v36
	v_rcp_f32_e32 v37, v37
	v_pk_mul_f32 v[26:27], v[30:31], v[26:27]
	v_pk_mul_f32 v[24:25], v[28:29], v[24:25]
	v_pk_mul_f32 v[24:25], v[24:25], v[34:35]
	v_pk_mul_f32 v[26:27], v[26:27], v[36:37]
	v_cvt_pk_bf16_f32 v24, v24, v25
	v_cvt_pk_bf16_f32 v25, v26, v27
	v_add_u32_e32 v32, 0xa0, v170
	v_mad_i64_i32 v[32:33], s[34:35], v32, s82, v[142:143]
	v_lshl_add_u64 v[32:33], v[32:33], 0, v[140:141]
	global_store_dwordx2 v[32:33], v[24:25], off
	v_exp_f32_e64 v18, -v12
	v_exp_f32_e64 v19, -v13
	v_exp_f32_e64 v20, -v14
	v_exp_f32_e64 v21, -v15
	v_add_f32_e32 v18, 1.0, v18
	v_add_f32_e32 v19, 1.0, v19
	v_add_f32_e32 v20, 1.0, v20
	v_add_f32_e32 v21, 1.0, v21
	v_rcp_f32_e32 v18, v18
	v_rcp_f32_e32 v19, v19
	v_rcp_f32_e32 v20, v20
	v_rcp_f32_e32 v21, v21
	v_pk_mul_f32 v[10:11], v[14:15], v[10:11]
	v_pk_mul_f32 v[8:9], v[12:13], v[8:9]
	v_pk_mul_f32 v[8:9], v[8:9], v[18:19]
	v_pk_mul_f32 v[10:11], v[10:11], v[20:21]
	v_cvt_pk_bf16_f32 v8, v8, v9
	v_cvt_pk_bf16_f32 v9, v10, v11
	v_add_u32_e32 v16, 0xb0, v170
	v_mad_i64_i32 v[16:17], s[34:35], v16, s82, v[142:143]
	v_lshl_add_u64 v[16:17], v[16:17], 0, v[140:141]
	global_store_dwordx2 v[16:17], v[8:9], off
	s_and_b64 vcc, exec, s[2:3]
	s_mov_b32 s86, s83
	s_mov_b32 s85, s84
	s_mov_b64 s[36:37], s[0:1]
	s_mov_b64 s[34:35], s[4:5]

; #define PG8_STAGE(bufoff, gbase, voff) do { _Pragma("unroll") for (int _i = 0; _i < 2; ++_i) \
;         __builtin_amdgcn_global_load_lds((const unsigned*)((const char*)(gbase) + (voff)[_i]), (PG8_LAS unsigned*)(lds + (bufoff) + ldsw + _i * 8192), 16, 0, 0); } while (0)
; #define PG8_LDA(dst, b, h) do { _Pragma("unroll") for (int m = 0; m < 4; ++m) _Pragma("unroll") for (int k = 0; k < 2; ++k) dst[m][k] = *(const PG8_LAS bf16x8*)(lds + PG8_SA(b, h) + aoff + m * 2048 + k * 1024); } while (0)
; template <class Epi, class Sched, bool STAMP = false>
; __device__ __forceinline__ void gemm_phase(PG8_LAS unsigned char* lds, const Gemm g, const Sched& S, const Epi& E, unsigned long long* stamps) {
;     ...
;         for (int t = 0; t < nt; t += 2) {
;             const bool last = (t == nt - 2);
;             const char* a1 = cA + (size_t)(t + 1) * kstep;
;             const char* a2 = last ? nA : cA + (size_t)(t + 2) * kstep; const char* b2 = last ? nB : cB + (size_t)(t + 2) * kstep;
;             const char* a3 = a2 + kstep; const char* b3 = b2 + kstep;
;             if (last && has_next) S.a_ready(nxt);
;             PG8_LDB(B0, 0, 0); PG8_SCHED; PG8_LDA(At, 0, 0); PG8_STAGE(PG8_SA(1, 1), a1 + hstep, voffA);
;             PG8_WAIT_L(8); PG8_BAR; PG8_WAIT_L(0); PG8_MMA(0, 0, At, B0); PG8_BAR; PG8_SCHED;
;             PG8_LDB(B1, 0, 1); PG8_STAGE(PG8_SB(0, 0), b2, voffB);
;             PG8_BAR; PG8_WAIT_L(0); PG8_MMA(0, 1, At, B1); PG8_BAR;
;             PG8_LDA(At, 0, 1); PG8_STAGE(PG8_SA(0, 0), a2, voffA);
;             PG8_BAR; PG8_WAIT_L(0); PG8_MMA(1, 0, At, B0); PG8_BAR; PG8_SCHED;
;             PG8_STAGE(PG8_SB(0, 1), b2 + hstep, voffB);
;             PG8_WAIT_V(6); PG8_BAR; PG8_MMA(1, 1, At, B1); PG8_BAR;
;             PG8_LDB(B0, 1, 0); PG8_SCHED; PG8_LDA(At, 1, 0); PG8_STAGE(PG8_SA(0, 1), a2 + hstep, voffA);
;             PG8_WAIT_L(8); PG8_BAR; PG8_WAIT_L(0); PG8_MMA(0, 0, At, B0); PG8_BAR; PG8_SCHED;
;             PG8_LDB(B1, 1, 1); PG8_STAGE(PG8_SB(1, 0), b3, voffB);
;             PG8_BAR; PG8_WAIT_L(0); PG8_MMA(0, 1, At, B1); PG8_BAR;
;             PG8_LDA(At, 1, 1); PG8_STAGE(PG8_SA(1, 0), a3, voffA);
;             PG8_BAR; PG8_WAIT_L(0); PG8_MMA(1, 0, At, B0); PG8_BAR; PG8_SCHED;
;             PG8_STAGE(PG8_SB(1, 1), b3 + hstep, voffB);
;             PG8_WAIT_V(6); PG8_BAR; PG8_MMA(1, 1, At, B1); PG8_BAR;
;         }
.Lzp6_mid:
	ds_read_b128 v[170:173], v155
	ds_read_b128 v[174:177], v156
	ds_read_b128 v[178:181], v157
	ds_read_b128 v[182:185], v165
	s_add_u32 s56, s62, 0xb4000
	s_addc_u32 s57, s63, 0
	s_mov_b32 m0, s76
	ds_read_b128 v[186:189], v145 offset:32768
	ds_read_b128 v[190:193], v145 offset:33792
	ds_read_b128 v[194:197], v145 offset:34816
	ds_read_b128 v[198:201], v145 offset:35840
	ds_read_b128 v[202:205], v145 offset:36864
	ds_read_b128 v[206:209], v145 offset:37888
	ds_read_b128 v[210:213], v145 offset:38912
	ds_read_b128 v[214:217], v145 offset:39936
	global_load_lds_dwordx4 v128, s[56:57]
	s_mov_b32 m0, s77
	s_nop 0
	global_load_lds_dwordx4 v132, s[56:57]
	s_waitcnt lgkmcnt(8)
	s_barrier
	s_waitcnt lgkmcnt(0)
	s_setprio 1
	s_waitcnt lgkmcnt(0)
	v_mfma_f32_16x16x32_bf16 v[124:127], v[170:173], v[186:189], v[124:127]
	v_mfma_f32_16x16x32_bf16 v[120:123], v[178:181], v[186:189], v[120:123]
	v_mfma_f32_16x16x32_bf16 v[116:119], v[170:173], v[194:197], v[116:119]
	v_mfma_f32_16x16x32_bf16 v[112:115], v[178:181], v[194:197], v[112:115]
	v_mfma_f32_16x16x32_bf16 v[100:103], v[170:173], v[202:205], v[100:103]
	v_mfma_f32_16x16x32_bf16 v[96:99], v[178:181], v[202:205], v[96:99]
	v_mfma_f32_16x16x32_bf16 v[84:87], v[170:173], v[210:213], v[84:87]
	v_mfma_f32_16x16x32_bf16 v[80:83], v[178:181], v[210:213], v[80:83]
	v_mfma_f32_16x16x32_bf16 v[124:127], v[174:177], v[190:193], v[124:127]
	v_mfma_f32_16x16x32_bf16 v[120:123], v[182:185], v[190:193], v[120:123]
	v_mfma_f32_16x16x32_bf16 v[116:119], v[174:177], v[198:201], v[116:119]
	v_mfma_f32_16x16x32_bf16 v[112:115], v[182:185], v[198:201], v[112:115]
	v_mfma_f32_16x16x32_bf16 v[100:103], v[174:177], v[206:209], v[100:103]
	v_mfma_f32_16x16x32_bf16 v[96:99], v[182:185], v[206:209], v[96:99]
	v_mfma_f32_16x16x32_bf16 v[84:87], v[174:177], v[214:217], v[84:87]
	v_mfma_f32_16x16x32_bf16 v[80:83], v[182:185], v[214:217], v[80:83]
	s_setprio 0
	s_barrier
	s_mov_b32 m0, s78
	ds_read_b128 v[218:221], v166
	ds_read_b128 v[222:225], v167
	ds_read_b128 v[226:229], v168
	ds_read_b128 v[230:233], v169
	s_add_u32 s100, s60, 0x80
	s_addc_u32 s101, s61, 0
	global_load_lds_dwordx4 v130, s[100:101]
	s_mov_b32 m0, s79
	s_nop 0
	global_load_lds_dwordx4 v134, s[100:101]
	s_barrier
	s_waitcnt lgkmcnt(0)
	s_setprio 1
	s_waitcnt lgkmcnt(0)
	v_mfma_f32_16x16x32_bf16 v[108:111], v[218:221], v[186:189], v[108:111]
	v_mfma_f32_16x16x32_bf16 v[104:107], v[226:229], v[186:189], v[104:107]
	v_mfma_f32_16x16x32_bf16 v[92:95], v[218:221], v[194:197], v[92:95]
	v_mfma_f32_16x16x32_bf16 v[88:91], v[226:229], v[194:197], v[88:91]
	v_mfma_f32_16x16x32_bf16 v[76:79], v[218:221], v[202:205], v[76:79]
	v_mfma_f32_16x16x32_bf16 v[72:75], v[226:229], v[202:205], v[72:75]
	v_mfma_f32_16x16x32_bf16 v[68:71], v[218:221], v[210:213], v[68:71]
	v_mfma_f32_16x16x32_bf16 v[64:67], v[226:229], v[210:213], v[64:67]
	v_mfma_f32_16x16x32_bf16 v[108:111], v[222:225], v[190:193], v[108:111]
	v_mfma_f32_16x16x32_bf16 v[104:107], v[230:233], v[190:193], v[104:107]
	v_mfma_f32_16x16x32_bf16 v[92:95], v[222:225], v[198:201], v[92:95]
	v_mfma_f32_16x16x32_bf16 v[88:91], v[230:233], v[198:201], v[88:91]
	v_mfma_f32_16x16x32_bf16 v[76:79], v[222:225], v[206:209], v[76:79]
	v_mfma_f32_16x16x32_bf16 v[72:75], v[230:233], v[206:209], v[72:75]
	v_mfma_f32_16x16x32_bf16 v[68:71], v[222:225], v[214:217], v[68:71]
	v_mfma_f32_16x16x32_bf16 v[64:67], v[230:233], v[214:217], v[64:67]
	s_setprio 0
	s_mov_b32 m0, s82
	s_barrier
	ds_read_b128 v[186:189], v145 offset:49152
	ds_read_b128 v[190:193], v145 offset:50176
	ds_read_b128 v[194:197], v145 offset:51200
	ds_read_b128 v[198:201], v145 offset:52224
	ds_read_b128 v[202:205], v145 offset:53248
	ds_read_b128 v[206:209], v145 offset:54272
	ds_read_b128 v[210:213], v145 offset:55296
	ds_read_b128 v[214:217], v145 offset:56320
	s_add_u32 s100, s62, 0x80
	s_addc_u32 s101, s63, 0
	global_load_lds_dwordx4 v128, s[100:101]
	s_mov_b32 m0, s83
	s_nop 0
	global_load_lds_dwordx4 v132, s[100:101]
	s_barrier
	s_waitcnt lgkmcnt(0)
	s_setprio 1
	s_waitcnt lgkmcnt(0)
	v_mfma_f32_16x16x32_bf16 v[60:63], v[170:173], v[186:189], v[60:63]
	v_mfma_f32_16x16x32_bf16 v[56:59], v[178:181], v[186:189], v[56:59]
	v_mfma_f32_16x16x32_bf16 v[52:55], v[170:173], v[194:197], v[52:55]
	v_mfma_f32_16x16x32_bf16 v[48:51], v[178:181], v[194:197], v[48:51]
	v_mfma_f32_16x16x32_bf16 v[36:39], v[170:173], v[202:205], v[36:39]
	v_mfma_f32_16x16x32_bf16 v[32:35], v[178:181], v[202:205], v[32:35]
	v_mfma_f32_16x16x32_bf16 v[20:23], v[170:173], v[210:213], v[20:23]
	v_mfma_f32_16x16x32_bf16 v[16:19], v[178:181], v[210:213], v[16:19]
	v_mfma_f32_16x16x32_bf16 v[60:63], v[174:177], v[190:193], v[60:63]
	v_mfma_f32_16x16x32_bf16 v[56:59], v[182:185], v[190:193], v[56:59]
	v_mfma_f32_16x16x32_bf16 v[52:55], v[174:177], v[198:201], v[52:55]
	v_mfma_f32_16x16x32_bf16 v[48:51], v[182:185], v[198:201], v[48:51]
	v_mfma_f32_16x16x32_bf16 v[36:39], v[174:177], v[206:209], v[36:39]
	v_mfma_f32_16x16x32_bf16 v[32:35], v[182:185], v[206:209], v[32:35]
	v_mfma_f32_16x16x32_bf16 v[20:23], v[174:177], v[214:217], v[20:23]
	v_mfma_f32_16x16x32_bf16 v[16:19], v[182:185], v[214:217], v[16:19]
	s_setprio 0
	s_barrier
	s_add_u32 s56, s60, 0xb4080
	s_addc_u32 s57, s61, 0
	s_mov_b32 m0, s84
	s_nop 0
	global_load_lds_dwordx4 v130, s[56:57]
	s_mov_b32 m0, s85
	s_nop 0
	global_load_lds_dwordx4 v134, s[56:57]
	s_add_i32 s10, s10, 2
	s_add_u32 vcc_lo, vcc_lo, 0x100
	s_addc_u32 vcc_hi, vcc_hi, 0
	s_cmp_gt_u32 s10, 41
	s_mov_b64 s[56:57], s[58:59]
	s_waitcnt vmcnt(6)
	s_barrier
; #define PG8_STAGE(bufoff, gbase, voff) do { _Pragma("unroll") for (int _i = 0; _i < 2; ++_i) \
;         __builtin_amdgcn_global_load_lds((const unsigned*)((const char*)(gbase) + (voff)[_i]), (PG8_LAS unsigned*)(lds + (bufoff) + ldsw + _i * 8192), 16, 0, 0); } while (0)
; #define PG8_LDA(dst, b, h) do { _Pragma("unroll") for (int m = 0; m < 4; ++m) _Pragma("unroll") for (int k = 0; k < 2; ++k) dst[m][k] = *(const PG8_LAS bf16x8*)(lds + PG8_SA(b, h) + aoff + m * 2048 + k * 1024); } while (0)
; #define PG8_LDB(dst, b, h) do { _Pragma("unroll") for (int n = 0; n < 2; ++n) _Pragma("unroll") for (int k = 0; k < 2; ++k) dst[n][k] = *(const PG8_LAS bf16x8*)(lds + PG8_SB(b, h) + boff + n * 2048 + k * 1024); } while (0)
; #define PG8_WAIT_V(n) asm volatile("s_waitcnt vmcnt(" #n ")" ::: "memory")
;     DI void operator()(const f32x4 (&acc)[2][2][4][2], const Unit& u, int wr, int wc, int fr, int fq) const {
;         const int row0 = u.pm * BM + wr * 64 + fr, col0 = u.pn * BM + wc * 32 + 8 * fq;
; #pragma unroll
;         for (int ai = 0; ai < 2; ++ai)
; #pragma unroll
;             for (int m = 0; m < 4; ++m) { u16* rowp = O + (size_t)(row0 + ai * HALF + m * 16) * ldc + col0;
; #pragma unroll
;                 for (int bj = 0; bj < 2; ++bj) { const f32x4 v0 = acc[ai][bj][m][0], v1 = acc[ai][bj][m][1];
;                     uint4 w = {pack2(v0[0], v0[1]), pack2(v0[2], v0[3]), pack2(v1[0], v1[1]), pack2(v1[2], v1[3])}; *(uint4*)(rowp + bj * HALF) = w; } }
; template <class Epi, class Sched, bool STAMP = false>
; __device__ __forceinline__ void gemm_phase(PG8_LAS unsigned char* lds, const Gemm g, const Sched& S, const Epi& E, unsigned long long* stamps) {
;     ...
;             PG8_WAIT_V(6); PG8_BAR; PG8_MMA(1, 1, At, B1); PG8_BAR;
;             PG8_LDB(B0, 1, 0); PG8_SCHED; PG8_LDA(At, 1, 0); PG8_STAGE(PG8_SA(0, 1), a2 + hstep, voffA);
;             PG8_WAIT_L(8); PG8_BAR; PG8_WAIT_L(0); PG8_MMA(0, 0, At, B0); PG8_BAR; PG8_SCHED;
;             PG8_LDB(B1, 1, 1); PG8_STAGE(PG8_SB(1, 0), b3, voffB);
;             PG8_BAR; PG8_WAIT_L(0); PG8_MMA(0, 1, At, B1); PG8_BAR;
;             PG8_LDA(At, 1, 1); PG8_STAGE(PG8_SA(1, 0), a3, voffA);
;             PG8_BAR; PG8_WAIT_L(0); PG8_MMA(1, 0, At, B0); PG8_BAR; PG8_SCHED;
;             PG8_STAGE(PG8_SB(1, 1), b3 + hstep, voffB);
;             PG8_WAIT_V(6); PG8_BAR; PG8_MMA(1, 1, At, B1); PG8_BAR;
;         }
	s_setprio 1
	v_mfma_f32_16x16x32_bf16 v[44:47], v[218:221], v[186:189], v[44:47]
	v_mfma_f32_16x16x32_bf16 v[40:43], v[226:229], v[186:189], v[40:43]
	v_mfma_f32_16x16x32_bf16 v[28:31], v[218:221], v[194:197], v[28:31]
	v_mfma_f32_16x16x32_bf16 v[24:27], v[226:229], v[194:197], v[24:27]
	v_mfma_f32_16x16x32_bf16 v[12:15], v[218:221], v[202:205], v[12:15]
	v_mfma_f32_16x16x32_bf16 v[8:11], v[226:229], v[202:205], v[8:11]
	v_mfma_f32_16x16x32_bf16 v[4:7], v[218:221], v[210:213], v[4:7]
	v_mfma_f32_16x16x32_bf16 v[0:3], v[226:229], v[210:213], v[0:3]
	v_mfma_f32_16x16x32_bf16 v[44:47], v[222:225], v[190:193], v[44:47]
	v_mfma_f32_16x16x32_bf16 v[40:43], v[230:233], v[190:193], v[40:43]
	v_mfma_f32_16x16x32_bf16 v[28:31], v[222:225], v[198:201], v[28:31]
	v_mfma_f32_16x16x32_bf16 v[24:27], v[230:233], v[198:201], v[24:27]
	v_mfma_f32_16x16x32_bf16 v[12:15], v[222:225], v[206:209], v[12:15]
	v_mfma_f32_16x16x32_bf16 v[8:11], v[230:233], v[206:209], v[8:11]
	v_mfma_f32_16x16x32_bf16 v[4:7], v[222:225], v[214:217], v[4:7]
	v_mfma_f32_16x16x32_bf16 v[0:3], v[230:233], v[214:217], v[0:3]
	s_setprio 0
	s_barrier
	s_cbranch_scc0 .LBB0_385
	v_lshl_add_u32 v170, s94, 8, v144
	v_lshl_or_b32 v172, s97, 8, v146
	v_ashrrev_i32_e32 v171, 31, v170
	v_ashrrev_i32_e32 v173, 31, v172
	v_lshlrev_b64 v[174:175], 11, v[170:171]
	v_lshl_add_u64 v[174:175], s[14:15], 0, v[174:175]
	v_lshlrev_b64 v[172:173], 1, v[172:173]
	v_lshl_add_u64 v[174:175], v[174:175], 0, v[172:173]
	v_cvt_pk_bf16_f32 v60, v60, v61
	v_cvt_pk_bf16_f32 v61, v62, v63
	v_cvt_pk_bf16_f32 v62, v56, v57
	v_add_co_u32_e32 v56, vcc, s90, v174
	v_cvt_pk_bf16_f32 v68, v68, v69
	v_cvt_pk_bf16_f32 v69, v70, v71
	v_cvt_pk_bf16_f32 v70, v64, v65
	v_lshl_add_u64 v[64:65], v[174:175], 0, s[34:35]
	v_addc_co_u32_e32 v57, vcc, 0, v175, vcc
	v_cvt_pk_bf16_f32 v44, v44, v45
	v_cvt_pk_bf16_f32 v45, v46, v47
	v_cvt_pk_bf16_f32 v46, v40, v41
	v_cvt_pk_bf16_f32 v47, v42, v43
	v_cvt_pk_bf16_f32 v108, v108, v109
	v_cvt_pk_bf16_f32 v109, v110, v111
	v_cvt_pk_bf16_f32 v110, v104, v105
	v_or_b32_e32 v104, 16, v170
	global_store_dwordx4 v[64:65], v[44:47], off offset:256
	v_ashrrev_i32_e32 v105, 31, v104
	v_cvt_pk_bf16_f32 v92, v92, v93
	v_add_co_u32_e32 v46, vcc, s91, v174
	v_cvt_pk_bf16_f32 v93, v94, v95
	v_cvt_pk_bf16_f32 v94, v88, v89
	v_or_b32_e32 v88, 32, v170
	v_lshl_add_u64 v[44:45], v[174:175], 0, s[36:37]
	v_addc_co_u32_e32 v47, vcc, 0, v175, vcc
	v_cvt_pk_bf16_f32 v28, v28, v29
	v_cvt_pk_bf16_f32 v29, v30, v31
	v_cvt_pk_bf16_f32 v30, v24, v25
	v_cvt_pk_bf16_f32 v31, v26, v27
	v_lshlrev_b64 v[104:105], 11, v[104:105]
	v_ashrrev_i32_e32 v89, 31, v88
	v_cvt_pk_bf16_f32 v76, v76, v77
	v_cvt_pk_bf16_f32 v77, v78, v79
	v_cvt_pk_bf16_f32 v78, v72, v73
	v_or_b32_e32 v72, 48, v170
	global_store_dwordx4 v[44:45], v[28:31], off offset:256
	v_cvt_pk_bf16_f32 v111, v106, v107
	v_lshl_add_u64 v[104:105], s[14:15], 0, v[104:105]
	v_add_co_u32_e32 v30, vcc, s92, v174
	v_lshlrev_b64 v[88:89], 11, v[88:89]
	v_ashrrev_i32_e32 v73, 31, v72
	v_lshl_add_u64 v[28:29], v[174:175], 0, s[52:53]
	v_addc_co_u32_e32 v31, vcc, 0, v175, vcc
	v_cvt_pk_bf16_f32 v12, v12, v13
	v_cvt_pk_bf16_f32 v13, v14, v15
	v_cvt_pk_bf16_f32 v14, v8, v9
	v_cvt_pk_bf16_f32 v15, v10, v11
	global_store_dwordx4 v[174:175], v[108:111], off offset:256
	v_cvt_pk_bf16_f32 v95, v90, v91
	v_lshl_add_u64 v[88:89], s[14:15], 0, v[88:89]
	v_lshl_add_u64 v[108:109], v[104:105], 0, v[172:173]
	v_lshlrev_b64 v[72:73], 11, v[72:73]
	global_store_dwordx4 v[28:29], v[12:15], off offset:256
	global_store_dwordx4 v[108:109], v[92:95], off offset:256
	v_cvt_pk_bf16_f32 v79, v74, v75
	v_add_co_u32_e32 v14, vcc, s93, v174
	v_lshl_add_u64 v[92:93], v[88:89], 0, v[172:173]
	v_lshl_add_u64 v[72:73], s[14:15], 0, v[72:73]
	v_addc_co_u32_e32 v15, vcc, 0, v175, vcc
	v_cvt_pk_bf16_f32 v124, v124, v125
	v_cvt_pk_bf16_f32 v125, v126, v127
	v_cvt_pk_bf16_f32 v126, v120, v121
	v_cvt_pk_bf16_f32 v127, v122, v123
	v_cvt_pk_bf16_f32 v104, v116, v117
	v_cvt_pk_bf16_f32 v105, v118, v119
	v_cvt_pk_bf16_f32 v106, v112, v113
	v_cvt_pk_bf16_f32 v107, v114, v115
	v_cvt_pk_bf16_f32 v88, v100, v101
	v_cvt_pk_bf16_f32 v89, v102, v103
	v_cvt_pk_bf16_f32 v90, v96, v97
	v_cvt_pk_bf16_f32 v91, v98, v99
	global_store_dwordx4 v[92:93], v[76:79], off offset:256
	v_cvt_pk_bf16_f32 v74, v80, v81
	v_cvt_pk_bf16_f32 v75, v82, v83
	v_lshl_add_u64 v[76:77], v[72:73], 0, v[172:173]
	v_cvt_pk_bf16_f32 v72, v84, v85
	v_cvt_pk_bf16_f32 v73, v86, v87
	v_cvt_pk_bf16_f32 v71, v66, v67
	v_cvt_pk_bf16_f32 v63, v58, v59
	v_cvt_pk_bf16_f32 v40, v52, v53
	v_cvt_pk_bf16_f32 v41, v54, v55
	v_cvt_pk_bf16_f32 v42, v48, v49
	v_cvt_pk_bf16_f32 v43, v50, v51
	v_cvt_pk_bf16_f32 v24, v36, v37
	v_cvt_pk_bf16_f32 v25, v38, v39
	v_cvt_pk_bf16_f32 v26, v32, v33
	v_cvt_pk_bf16_f32 v27, v34, v35
	v_lshl_add_u64 v[12:13], v[174:175], 0, s[54:55]
	v_cvt_pk_bf16_f32 v8, v20, v21
	v_cvt_pk_bf16_f32 v9, v22, v23
	v_cvt_pk_bf16_f32 v10, v16, v17
	v_cvt_pk_bf16_f32 v11, v18, v19
	v_cvt_pk_bf16_f32 v4, v4, v5
	v_cvt_pk_bf16_f32 v5, v6, v7
	v_cvt_pk_bf16_f32 v6, v0, v1
	v_cvt_pk_bf16_f32 v7, v2, v3
	s_and_b64 vcc, exec, s[2:3]
	s_mov_b32 s97, s95
	s_mov_b32 s94, s96
	s_mov_b64 s[58:59], s[0:1]
	s_mov_b64 s[56:57], s[4:5]
	global_store_dwordx4 v[174:175], v[124:127], off
	global_store_dwordx4 v[108:109], v[104:107], off
	global_store_dwordx4 v[92:93], v[88:91], off
	global_store_dwordx4 v[76:77], v[72:75], off
	global_store_dwordx4 v[76:77], v[68:71], off offset:256
	global_store_dwordx4 v[56:57], v[60:63], off
	global_store_dwordx4 v[46:47], v[40:43], off
	global_store_dwordx4 v[30:31], v[24:27], off
	global_store_dwordx4 v[14:15], v[8:11], off
	global_store_dwordx4 v[12:13], v[4:7], off offset:256
	s_cbranch_vccz .LBB0_374
	s_waitcnt vmcnt(0)
	s_cmpk_gt_u32 s65, 0xff
	s_cbranch_scc1 .LBB0_389
	s_barrier

; #define PG8_STAGE(bufoff, gbase, voff) do { _Pragma("unroll") for (int _i = 0; _i < 2; ++_i) \
;         __builtin_amdgcn_global_load_lds((const unsigned*)((const char*)(gbase) + (voff)[_i]), (PG8_LAS unsigned*)(lds + (bufoff) + ldsw + _i * 8192), 16, 0, 0); } while (0)
; #define PG8_LDA(dst, b, h) do { _Pragma("unroll") for (int m = 0; m < 4; ++m) _Pragma("unroll") for (int k = 0; k < 2; ++k) dst[m][k] = *(const PG8_LAS bf16x8*)(lds + PG8_SA(b, h) + aoff + m * 2048 + k * 1024); } while (0)
; #define PG8_LDB(dst, b, h) do { _Pragma("unroll") for (int n = 0; n < 2; ++n) _Pragma("unroll") for (int k = 0; k < 2; ++k) dst[n][k] = *(const PG8_LAS bf16x8*)(lds + PG8_SB(b, h) + boff + n * 2048 + k * 1024); } while (0)
; #define PG8_MMA(ai, bj, At, Bt) do { __builtin_amdgcn_s_setprio(1); _Pragma("unroll") for (int m = 0; m < 4; ++m) _Pragma("unroll") for (int n = 0; n < 2; ++n) _Pragma("unroll") for (int k = 0; k < 2; ++k) \
;         acc[ai][bj][m][n] = __builtin_amdgcn_mfma_f32_16x16x32_bf16(Bt[n][k], At[m][k], acc[ai][bj][m][n], 0, 0, 0); __builtin_amdgcn_s_setprio(0); } while (0)
; #define PG8_WAIT_V(n) asm volatile("s_waitcnt vmcnt(" #n ")" ::: "memory")
; #define PG8_WAIT_L(n) asm volatile("s_waitcnt lgkmcnt(" #n ")" ::: "memory")
; #define PG8_BAR __builtin_amdgcn_s_barrier()
; #define PG8_SCHED __builtin_amdgcn_sched_barrier(0)
; template <class Epi, class Sched, bool STAMP = false>
; __device__ __forceinline__ void gemm_phase(PG8_LAS unsigned char* lds, const Gemm g, const Sched& S, const Epi& E, unsigned long long* stamps) {
;     ...
;             PG8_LDB(B0, 1, 0); PG8_SCHED; PG8_LDA(At, 1, 0); PG8_STAGE(PG8_SA(0, 1), a2 + hstep, voffA);
;             PG8_WAIT_L(8); PG8_BAR; PG8_WAIT_L(0); PG8_MMA(0, 0, At, B0); PG8_BAR; PG8_SCHED;
;             PG8_LDB(B1, 1, 1); PG8_STAGE(PG8_SB(1, 0), b3, voffB);
;             PG8_BAR; PG8_WAIT_L(0); PG8_MMA(0, 1, At, B1); PG8_BAR;
;             PG8_LDA(At, 1, 1); PG8_STAGE(PG8_SA(1, 0), a3, voffA);
;             PG8_BAR; PG8_WAIT_L(0); PG8_MMA(1, 0, At, B0); PG8_BAR; PG8_SCHED;
;             PG8_STAGE(PG8_SB(1, 1), b3 + hstep, voffB);
;             PG8_WAIT_V(6); PG8_BAR; PG8_MMA(1, 1, At, B1); PG8_BAR;
.Lzp7_mid:
	ds_read_b128 v[140:143], v155
	ds_read_b128 v[170:173], v156
	ds_read_b128 v[174:177], v157
	ds_read_b128 v[178:181], v165
	s_add_u32 s34, s42, 0x44000
	s_addc_u32 s35, s43, 0
	s_mov_b32 m0, s56
	ds_read_b128 v[182:185], v145 offset:32768
	ds_read_b128 v[186:189], v145 offset:33792
	ds_read_b128 v[190:193], v145 offset:34816
	ds_read_b128 v[194:197], v145 offset:35840
	ds_read_b128 v[198:201], v145 offset:36864
	ds_read_b128 v[202:205], v145 offset:37888
	ds_read_b128 v[206:209], v145 offset:38912
	ds_read_b128 v[210:213], v145 offset:39936
	global_load_lds_dwordx4 v130, s[34:35]
	s_mov_b32 m0, s57
	s_nop 0
	global_load_lds_dwordx4 v128, s[34:35]
	s_waitcnt lgkmcnt(8)
	s_barrier
	s_waitcnt lgkmcnt(0)
	s_setprio 1
	s_waitcnt lgkmcnt(0)
	v_mfma_f32_16x16x32_bf16 v[124:127], v[140:143], v[182:185], v[124:127]
	v_mfma_f32_16x16x32_bf16 v[120:123], v[174:177], v[182:185], v[120:123]
	v_mfma_f32_16x16x32_bf16 v[108:111], v[140:143], v[190:193], v[108:111]
	v_mfma_f32_16x16x32_bf16 v[104:107], v[174:177], v[190:193], v[104:107]
	v_mfma_f32_16x16x32_bf16 v[92:95], v[140:143], v[198:201], v[92:95]
	v_mfma_f32_16x16x32_bf16 v[88:91], v[174:177], v[198:201], v[88:91]
	v_mfma_f32_16x16x32_bf16 v[76:79], v[140:143], v[206:209], v[76:79]
	v_mfma_f32_16x16x32_bf16 v[72:75], v[174:177], v[206:209], v[72:75]
	v_mfma_f32_16x16x32_bf16 v[124:127], v[170:173], v[186:189], v[124:127]
	v_mfma_f32_16x16x32_bf16 v[120:123], v[178:181], v[186:189], v[120:123]
	v_mfma_f32_16x16x32_bf16 v[108:111], v[170:173], v[194:197], v[108:111]
	v_mfma_f32_16x16x32_bf16 v[104:107], v[178:181], v[194:197], v[104:107]
	v_mfma_f32_16x16x32_bf16 v[92:95], v[170:173], v[202:205], v[92:95]
	v_mfma_f32_16x16x32_bf16 v[88:91], v[178:181], v[202:205], v[88:91]
	v_mfma_f32_16x16x32_bf16 v[76:79], v[170:173], v[210:213], v[76:79]
	v_mfma_f32_16x16x32_bf16 v[72:75], v[178:181], v[210:213], v[72:75]
	s_setprio 0
	s_barrier
	s_mov_b32 m0, s60
	ds_read_b128 v[214:217], v166
	ds_read_b128 v[218:221], v167
	ds_read_b128 v[222:225], v168
	ds_read_b128 v[226:229], v169
	s_add_u32 s100, s40, 0x80
	s_addc_u32 s101, s41, 0
	global_load_lds_dwordx4 v130, s[100:101]
	s_mov_b32 m0, s61
	s_nop 0
	global_load_lds_dwordx4 v128, s[100:101]
	s_barrier
	s_waitcnt lgkmcnt(0)
	s_setprio 1
	s_waitcnt lgkmcnt(0)
	v_mfma_f32_16x16x32_bf16 v[116:119], v[214:217], v[182:185], v[116:119]
	v_mfma_f32_16x16x32_bf16 v[112:115], v[222:225], v[182:185], v[112:115]
	v_mfma_f32_16x16x32_bf16 v[100:103], v[214:217], v[190:193], v[100:103]
	v_mfma_f32_16x16x32_bf16 v[96:99], v[222:225], v[190:193], v[96:99]
	v_mfma_f32_16x16x32_bf16 v[84:87], v[214:217], v[198:201], v[84:87]
	v_mfma_f32_16x16x32_bf16 v[80:83], v[222:225], v[198:201], v[80:83]
	v_mfma_f32_16x16x32_bf16 v[68:71], v[214:217], v[206:209], v[68:71]
	v_mfma_f32_16x16x32_bf16 v[64:67], v[222:225], v[206:209], v[64:67]
	v_mfma_f32_16x16x32_bf16 v[116:119], v[218:221], v[186:189], v[116:119]
	v_mfma_f32_16x16x32_bf16 v[112:115], v[226:229], v[186:189], v[112:115]
	v_mfma_f32_16x16x32_bf16 v[100:103], v[218:221], v[194:197], v[100:103]
	v_mfma_f32_16x16x32_bf16 v[96:99], v[226:229], v[194:197], v[96:99]
	v_mfma_f32_16x16x32_bf16 v[84:87], v[218:221], v[202:205], v[84:87]
	v_mfma_f32_16x16x32_bf16 v[80:83], v[226:229], v[202:205], v[80:83]
	v_mfma_f32_16x16x32_bf16 v[68:71], v[218:221], v[210:213], v[68:71]
	v_mfma_f32_16x16x32_bf16 v[64:67], v[226:229], v[210:213], v[64:67]
	s_setprio 0
	s_mov_b32 m0, s62
	s_barrier
	ds_read_b128 v[182:185], v145 offset:49152
	ds_read_b128 v[186:189], v145 offset:50176
	ds_read_b128 v[190:193], v145 offset:51200
	ds_read_b128 v[194:197], v145 offset:52224
	ds_read_b128 v[198:201], v145 offset:53248
	ds_read_b128 v[202:205], v145 offset:54272
	ds_read_b128 v[206:209], v145 offset:55296
	ds_read_b128 v[210:213], v145 offset:56320
	s_add_u32 s100, s42, 0x80
	s_addc_u32 s101, s43, 0
	global_load_lds_dwordx4 v130, s[100:101]
	s_mov_b32 m0, s63
	s_nop 0
	global_load_lds_dwordx4 v128, s[100:101]
	s_barrier
	s_waitcnt lgkmcnt(0)
	s_setprio 1
	s_waitcnt lgkmcnt(0)
	v_mfma_f32_16x16x32_bf16 v[60:63], v[140:143], v[182:185], v[60:63]
	v_mfma_f32_16x16x32_bf16 v[56:59], v[174:177], v[182:185], v[56:59]
	v_mfma_f32_16x16x32_bf16 v[44:47], v[140:143], v[190:193], v[44:47]
	v_mfma_f32_16x16x32_bf16 v[40:43], v[174:177], v[190:193], v[40:43]
	v_mfma_f32_16x16x32_bf16 v[28:31], v[140:143], v[198:201], v[28:31]
	v_mfma_f32_16x16x32_bf16 v[24:27], v[174:177], v[198:201], v[24:27]
	v_mfma_f32_16x16x32_bf16 v[12:15], v[140:143], v[206:209], v[12:15]
	v_mfma_f32_16x16x32_bf16 v[8:11], v[174:177], v[206:209], v[8:11]
	v_mfma_f32_16x16x32_bf16 v[60:63], v[170:173], v[186:189], v[60:63]
	v_mfma_f32_16x16x32_bf16 v[56:59], v[178:181], v[186:189], v[56:59]
	v_mfma_f32_16x16x32_bf16 v[44:47], v[170:173], v[194:197], v[44:47]
	v_mfma_f32_16x16x32_bf16 v[40:43], v[178:181], v[194:197], v[40:43]
	v_mfma_f32_16x16x32_bf16 v[28:31], v[170:173], v[202:205], v[28:31]
	v_mfma_f32_16x16x32_bf16 v[24:27], v[178:181], v[202:205], v[24:27]
	v_mfma_f32_16x16x32_bf16 v[12:15], v[170:173], v[210:213], v[12:15]
	v_mfma_f32_16x16x32_bf16 v[8:11], v[178:181], v[210:213], v[8:11]
	s_setprio 0
	s_barrier
	s_add_u32 s34, s40, 0x44080
	s_addc_u32 s35, s41, 0
	s_mov_b32 m0, s64
	s_nop 0
	global_load_lds_dwordx4 v130, s[34:35]
	s_mov_b32 m0, s65
	s_nop 0
	global_load_lds_dwordx4 v128, s[34:35]
	s_add_i32 s10, s10, 2
	s_add_u32 s77, s77, 0x100
	s_addc_u32 s78, s78, 0
	s_cmp_gt_u32 s10, 13
	s_mov_b64 s[34:35], s[36:37]
	s_waitcnt vmcnt(6)
	s_barrier
; DI float ex2(float x) { return __builtin_amdgcn_exp2f(x); }
; #define PG8_STAGE(bufoff, gbase, voff) do { _Pragma("unroll") for (int _i = 0; _i < 2; ++_i) \
;         __builtin_amdgcn_global_load_lds((const unsigned*)((const char*)(gbase) + (voff)[_i]), (PG8_LAS unsigned*)(lds + (bufoff) + ldsw + _i * 8192), 16, 0, 0); } while (0)
; #define PG8_LDA(dst, b, h) do { _Pragma("unroll") for (int m = 0; m < 4; ++m) _Pragma("unroll") for (int k = 0; k < 2; ++k) dst[m][k] = *(const PG8_LAS bf16x8*)(lds + PG8_SA(b, h) + aoff + m * 2048 + k * 1024); } while (0)
; #define PG8_WAIT_V(n) asm volatile("s_waitcnt vmcnt(" #n ")" ::: "memory")
; #define PG8_WAIT_L(n) asm volatile("s_waitcnt lgkmcnt(" #n ")" ::: "memory")
;     DI void operator()(const f32x4 (&acc)[2][2][4][2], const Unit& u, int wr, int wc, int fr, int fq) const {
;         const int row0 = u.pm * BM + wr * 64 + fr, hcol0 = ((u.pn * BM + wc * 32) >> 1) + 4 * fq;
; #pragma unroll
;         for (int ai = 0; ai < 2; ++ai)
; #pragma unroll
;             for (int m = 0; m < 4; ++m) { u16* rowp = O + (size_t)(row0 + ai * HALF + m * 16) * ldc + hcol0;
; #pragma unroll
;                 for (int bj = 0; bj < 2; ++bj) { const f32x4 g = acc[ai][bj][m][0], up = acc[ai][bj][m][1]; float r[4];
; #pragma unroll
;                     for (int j = 0; j < 4; ++j) r[j] = g[j] * up[j] * __builtin_amdgcn_rcpf(1.f + ex2(-LOG2E * g[j]));
;                     uint2 w = {pack2(r[0], r[1]), pack2(r[2], r[3])}; *(uint2*)(rowp + bj * (HALF / 2)) = w; } }
; template <class Epi, class Sched, bool STAMP = false>
; __device__ __forceinline__ void gemm_phase(PG8_LAS unsigned char* lds, const Gemm g, const Sched& S, const Epi& E, unsigned long long* stamps) {
;     ...
;             PG8_WAIT_V(6); PG8_BAR; PG8_MMA(1, 1, At, B1); PG8_BAR;
;             PG8_LDB(B0, 1, 0); PG8_SCHED; PG8_LDA(At, 1, 0); PG8_STAGE(PG8_SA(0, 1), a2 + hstep, voffA);
;             PG8_WAIT_L(8); PG8_BAR; PG8_WAIT_L(0); PG8_MMA(0, 0, At, B0); PG8_BAR; PG8_SCHED;
;             PG8_LDB(B1, 1, 1); PG8_STAGE(PG8_SB(1, 0), b3, voffB);
;             PG8_BAR; PG8_WAIT_L(0); PG8_MMA(0, 1, At, B1); PG8_BAR;
;             PG8_LDA(At, 1, 1); PG8_STAGE(PG8_SA(1, 0), a3, voffA);
;             PG8_BAR; PG8_WAIT_L(0); PG8_MMA(1, 0, At, B0); PG8_BAR; PG8_SCHED;
;             PG8_STAGE(PG8_SB(1, 1), b3 + hstep, voffB);
;             PG8_WAIT_V(6); PG8_BAR; PG8_MMA(1, 1, At, B1); PG8_BAR;
	s_setprio 1
	v_mfma_f32_16x16x32_bf16 v[52:55], v[214:217], v[182:185], v[52:55]
	v_mfma_f32_16x16x32_bf16 v[48:51], v[222:225], v[182:185], v[48:51]
	v_mfma_f32_16x16x32_bf16 v[36:39], v[214:217], v[190:193], v[36:39]
	v_mfma_f32_16x16x32_bf16 v[32:35], v[222:225], v[190:193], v[32:35]
	v_mfma_f32_16x16x32_bf16 v[20:23], v[214:217], v[198:201], v[20:23]
	v_mfma_f32_16x16x32_bf16 v[16:19], v[222:225], v[198:201], v[16:19]
	v_mfma_f32_16x16x32_bf16 v[4:7], v[214:217], v[206:209], v[4:7]
	v_mfma_f32_16x16x32_bf16 v[0:3], v[222:225], v[206:209], v[0:3]
	v_mfma_f32_16x16x32_bf16 v[52:55], v[218:221], v[186:189], v[52:55]
	v_mfma_f32_16x16x32_bf16 v[48:51], v[226:229], v[186:189], v[48:51]
	v_mfma_f32_16x16x32_bf16 v[36:39], v[218:221], v[194:197], v[36:39]
	v_mfma_f32_16x16x32_bf16 v[32:35], v[226:229], v[194:197], v[32:35]
	v_mfma_f32_16x16x32_bf16 v[20:23], v[218:221], v[202:205], v[20:23]
	v_mfma_f32_16x16x32_bf16 v[16:19], v[226:229], v[202:205], v[16:19]
	v_mfma_f32_16x16x32_bf16 v[4:7], v[218:221], v[210:213], v[4:7]
	v_mfma_f32_16x16x32_bf16 v[0:3], v[226:229], v[210:213], v[0:3]
	s_setprio 0
	s_barrier
	s_cbranch_scc0 .LBB0_439
	v_exp_f32_e64 v171, -v124
	v_exp_f32_e64 v175, -v125
	s_lshl_b32 s10, s76, 8
	v_add_f32_e32 v171, 1.0, v171
	v_rcp_f32_e32 v174, v171
	v_add_f32_e32 v171, 1.0, v175
	v_exp_f32_e64 v176, -v126
	v_exp_f32_e64 v177, -v127
	v_rcp_f32_e32 v175, v171
	v_add_f32_e32 v171, 1.0, v176
	v_rcp_f32_e32 v176, v171
	v_add_f32_e32 v171, 1.0, v177
	v_rcp_f32_e32 v177, v171
	v_pk_mul_f32 v[122:123], v[126:127], v[122:123]
	v_pk_mul_f32 v[120:121], v[124:125], v[120:121]
	s_or_b32 s10, s10, s59
	v_pk_mul_f32 v[120:121], v[120:121], v[174:175]
	v_pk_mul_f32 v[122:123], v[122:123], v[176:177]
	s_ashr_i32 s10, s10, 1
	v_cvt_pk_bf16_f32 v120, v120, v121
	v_cvt_pk_bf16_f32 v121, v122, v123
	v_or_b32_e32 v140, s10, v146
	v_exp_f32_e64 v122, -v116
	v_exp_f32_e64 v123, -v117
	v_lshl_add_u32 v170, s75, 8, v144
	v_ashrrev_i32_e32 v141, 31, v140
	v_mov_b64_e32 v[142:143], s[12:13]
	v_mad_i64_i32 v[172:173], s[34:35], v170, s69, v[142:143]
	v_lshlrev_b64 v[140:141], 1, v[140:141]
	v_lshl_add_u64 v[172:173], v[172:173], 0, v[140:141]
	global_store_dwordx2 v[172:173], v[120:121], off
	v_add_f32_e32 v120, 1.0, v122
	v_add_f32_e32 v121, 1.0, v123
	v_exp_f32_e64 v122, -v118
	v_exp_f32_e64 v123, -v119
	v_rcp_f32_e32 v120, v120
	v_rcp_f32_e32 v121, v121
	v_add_f32_e32 v122, 1.0, v122
	v_add_f32_e32 v123, 1.0, v123
	v_rcp_f32_e32 v122, v122
	v_rcp_f32_e32 v123, v123
	v_pk_mul_f32 v[114:115], v[118:119], v[114:115]
	v_pk_mul_f32 v[112:113], v[116:117], v[112:113]
	v_pk_mul_f32 v[112:113], v[112:113], v[120:121]
	v_pk_mul_f32 v[114:115], v[114:115], v[122:123]
	v_cvt_pk_bf16_f32 v112, v112, v113
	v_cvt_pk_bf16_f32 v113, v114, v115
	v_exp_f32_e64 v114, -v108
	v_exp_f32_e64 v115, -v109
	v_exp_f32_e64 v116, -v110
	v_exp_f32_e64 v117, -v111
	v_add_f32_e32 v114, 1.0, v114
	v_add_f32_e32 v115, 1.0, v115
	v_add_f32_e32 v116, 1.0, v116
	v_add_f32_e32 v117, 1.0, v117
	v_rcp_f32_e32 v114, v114
	v_rcp_f32_e32 v115, v115
	v_rcp_f32_e32 v116, v116
	v_rcp_f32_e32 v117, v117
	v_pk_mul_f32 v[106:107], v[110:111], v[106:107]
	v_pk_mul_f32 v[104:105], v[108:109], v[104:105]
	global_store_dwordx2 v[172:173], v[112:113], off offset:128
	v_pk_mul_f32 v[104:105], v[104:105], v[114:115]
	v_pk_mul_f32 v[106:107], v[106:107], v[116:117]
	v_cvt_pk_bf16_f32 v104, v104, v105
	v_cvt_pk_bf16_f32 v105, v106, v107
	v_exp_f32_e64 v106, -v100
	v_exp_f32_e64 v107, -v101
	v_or_b32_e32 v112, 16, v170
	v_mad_i64_i32 v[112:113], s[34:35], v112, s69, v[142:143]
	v_lshl_add_u64 v[112:113], v[112:113], 0, v[140:141]
	global_store_dwordx2 v[112:113], v[104:105], off
	v_add_f32_e32 v104, 1.0, v106
	v_add_f32_e32 v105, 1.0, v107
	v_exp_f32_e64 v106, -v102
	v_exp_f32_e64 v107, -v103
	v_rcp_f32_e32 v104, v104
	v_rcp_f32_e32 v105, v105
	v_add_f32_e32 v106, 1.0, v106
	v_add_f32_e32 v107, 1.0, v107
	v_rcp_f32_e32 v106, v106
	v_rcp_f32_e32 v107, v107
	v_pk_mul_f32 v[98:99], v[102:103], v[98:99]
	v_pk_mul_f32 v[96:97], v[100:101], v[96:97]
	v_pk_mul_f32 v[96:97], v[96:97], v[104:105]
	v_pk_mul_f32 v[98:99], v[98:99], v[106:107]
	v_cvt_pk_bf16_f32 v96, v96, v97
	v_cvt_pk_bf16_f32 v97, v98, v99
	v_exp_f32_e64 v98, -v92
	v_exp_f32_e64 v99, -v93
	v_exp_f32_e64 v100, -v94
	v_exp_f32_e64 v101, -v95
	v_add_f32_e32 v98, 1.0, v98
	v_add_f32_e32 v99, 1.0, v99
	v_add_f32_e32 v100, 1.0, v100
	v_add_f32_e32 v101, 1.0, v101
	v_rcp_f32_e32 v98, v98
	v_rcp_f32_e32 v99, v99
	v_rcp_f32_e32 v100, v100
	v_rcp_f32_e32 v101, v101
	v_pk_mul_f32 v[90:91], v[94:95], v[90:91]
	v_pk_mul_f32 v[88:89], v[92:93], v[88:89]
	global_store_dwordx2 v[112:113], v[96:97], off offset:128
	v_pk_mul_f32 v[88:89], v[88:89], v[98:99]
	v_pk_mul_f32 v[90:91], v[90:91], v[100:101]
	v_cvt_pk_bf16_f32 v88, v88, v89
	v_cvt_pk_bf16_f32 v89, v90, v91
	v_exp_f32_e64 v90, -v84
	v_exp_f32_e64 v91, -v85
	v_or_b32_e32 v96, 32, v170
	v_mad_i64_i32 v[96:97], s[34:35], v96, s69, v[142:143]
	v_lshl_add_u64 v[96:97], v[96:97], 0, v[140:141]
	global_store_dwordx2 v[96:97], v[88:89], off
	v_add_f32_e32 v88, 1.0, v90
	v_add_f32_e32 v89, 1.0, v91
	v_exp_f32_e64 v90, -v86
	v_exp_f32_e64 v91, -v87
	v_rcp_f32_e32 v88, v88
	v_rcp_f32_e32 v89, v89
	v_add_f32_e32 v90, 1.0, v90
	v_add_f32_e32 v91, 1.0, v91
	v_rcp_f32_e32 v90, v90
	v_rcp_f32_e32 v91, v91
	v_pk_mul_f32 v[82:83], v[86:87], v[82:83]
	v_pk_mul_f32 v[80:81], v[84:85], v[80:81]
	v_pk_mul_f32 v[80:81], v[80:81], v[88:89]
	v_pk_mul_f32 v[82:83], v[82:83], v[90:91]
	v_cvt_pk_bf16_f32 v80, v80, v81
	v_cvt_pk_bf16_f32 v81, v82, v83
	v_exp_f32_e64 v82, -v76
	v_exp_f32_e64 v83, -v77
	v_exp_f32_e64 v84, -v78
; DI float ex2(float x) { return __builtin_amdgcn_exp2f(x); }
;     DI void operator()(const f32x4 (&acc)[2][2][4][2], const Unit& u, int wr, int wc, int fr, int fq) const {
;         const int row0 = u.pm * BM + wr * 64 + fr, hcol0 = ((u.pn * BM + wc * 32) >> 1) + 4 * fq;
; #pragma unroll
;         for (int ai = 0; ai < 2; ++ai)
; #pragma unroll
;             for (int m = 0; m < 4; ++m) { u16* rowp = O + (size_t)(row0 + ai * HALF + m * 16) * ldc + hcol0;
; #pragma unroll
;                 for (int bj = 0; bj < 2; ++bj) { const f32x4 g = acc[ai][bj][m][0], up = acc[ai][bj][m][1]; float r[4];
; #pragma unroll
;                     for (int j = 0; j < 4; ++j) r[j] = g[j] * up[j] * __builtin_amdgcn_rcpf(1.f + ex2(-LOG2E * g[j]));
;                     uint2 w = {pack2(r[0], r[1]), pack2(r[2], r[3])}; *(uint2*)(rowp + bj * (HALF / 2)) = w; } }
; template <class Epi, class Sched, bool STAMP = false>
; __device__ __forceinline__ void gemm_phase(PG8_LAS unsigned char* lds, const Gemm g, const Sched& S, const Epi& E, unsigned long long* stamps) {
;     ...
;         if (!has_next) break;
; #pragma unroll
;         for (int a = 0; a < 2; ++a)
; #pragma unroll
;             for (int b = 0; b < 2; ++b)
; #pragma unroll
;                 for (int m = 0; m < 4; ++m)
; #pragma unroll
;                     for (int n = 0; n < 2; ++n) acc[a][b][m][n] = (f32x4){0.f, 0.f, 0.f, 0.f};
;         cur = nxt; cA = nA; cB = nB; ++ui;
	v_exp_f32_e64 v85, -v79
	v_add_f32_e32 v82, 1.0, v82
	v_add_f32_e32 v83, 1.0, v83
	v_add_f32_e32 v84, 1.0, v84
	v_add_f32_e32 v85, 1.0, v85
	v_rcp_f32_e32 v82, v82
	v_rcp_f32_e32 v83, v83
	v_rcp_f32_e32 v84, v84
	v_rcp_f32_e32 v85, v85
	v_pk_mul_f32 v[74:75], v[78:79], v[74:75]
	v_pk_mul_f32 v[72:73], v[76:77], v[72:73]
	global_store_dwordx2 v[96:97], v[80:81], off offset:128
	v_pk_mul_f32 v[72:73], v[72:73], v[82:83]
	v_pk_mul_f32 v[74:75], v[74:75], v[84:85]
	v_cvt_pk_bf16_f32 v72, v72, v73
	v_cvt_pk_bf16_f32 v73, v74, v75
	v_exp_f32_e64 v74, -v68
	v_exp_f32_e64 v75, -v69
	v_or_b32_e32 v80, 48, v170
	v_mad_i64_i32 v[80:81], s[34:35], v80, s69, v[142:143]
	v_lshl_add_u64 v[80:81], v[80:81], 0, v[140:141]
	global_store_dwordx2 v[80:81], v[72:73], off
	v_add_f32_e32 v72, 1.0, v74
	v_add_f32_e32 v73, 1.0, v75
	v_exp_f32_e64 v74, -v70
	v_exp_f32_e64 v75, -v71
	v_rcp_f32_e32 v72, v72
	v_rcp_f32_e32 v73, v73
	v_add_f32_e32 v74, 1.0, v74
	v_add_f32_e32 v75, 1.0, v75
	v_rcp_f32_e32 v74, v74
	v_rcp_f32_e32 v75, v75
	v_pk_mul_f32 v[66:67], v[70:71], v[66:67]
	v_pk_mul_f32 v[64:65], v[68:69], v[64:65]
	v_pk_mul_f32 v[64:65], v[64:65], v[72:73]
	v_pk_mul_f32 v[66:67], v[66:67], v[74:75]
	v_cvt_pk_bf16_f32 v64, v64, v65
	v_cvt_pk_bf16_f32 v65, v66, v67
	v_exp_f32_e64 v66, -v60
	v_exp_f32_e64 v67, -v61
	v_exp_f32_e64 v68, -v62
	v_exp_f32_e64 v69, -v63
	v_add_f32_e32 v66, 1.0, v66
	v_add_f32_e32 v67, 1.0, v67
	v_add_f32_e32 v68, 1.0, v68
	v_add_f32_e32 v69, 1.0, v69
	v_rcp_f32_e32 v66, v66
	v_rcp_f32_e32 v67, v67
	v_rcp_f32_e32 v68, v68
	v_rcp_f32_e32 v69, v69
	v_pk_mul_f32 v[58:59], v[62:63], v[58:59]
	v_pk_mul_f32 v[56:57], v[60:61], v[56:57]
	global_store_dwordx2 v[80:81], v[64:65], off offset:128
	v_pk_mul_f32 v[56:57], v[56:57], v[66:67]
	v_pk_mul_f32 v[58:59], v[58:59], v[68:69]
	v_cvt_pk_bf16_f32 v56, v56, v57
	v_cvt_pk_bf16_f32 v57, v58, v59
	v_exp_f32_e64 v58, -v52
	v_exp_f32_e64 v59, -v53
	v_add_u32_e32 v64, 0x80, v170
	v_mad_i64_i32 v[64:65], s[34:35], v64, s69, v[142:143]
	v_lshl_add_u64 v[64:65], v[64:65], 0, v[140:141]
	global_store_dwordx2 v[64:65], v[56:57], off
	v_add_f32_e32 v56, 1.0, v58
	v_add_f32_e32 v57, 1.0, v59
	v_exp_f32_e64 v58, -v54
	v_exp_f32_e64 v59, -v55
	v_rcp_f32_e32 v56, v56
	v_rcp_f32_e32 v57, v57
	v_add_f32_e32 v58, 1.0, v58
	v_add_f32_e32 v59, 1.0, v59
	v_rcp_f32_e32 v58, v58
	v_rcp_f32_e32 v59, v59
	v_pk_mul_f32 v[50:51], v[54:55], v[50:51]
	v_pk_mul_f32 v[48:49], v[52:53], v[48:49]
	v_pk_mul_f32 v[48:49], v[48:49], v[56:57]
	v_pk_mul_f32 v[50:51], v[50:51], v[58:59]
	v_cvt_pk_bf16_f32 v48, v48, v49
	v_cvt_pk_bf16_f32 v49, v50, v51
	v_exp_f32_e64 v50, -v44
	v_exp_f32_e64 v51, -v45
	v_exp_f32_e64 v52, -v46
	v_exp_f32_e64 v53, -v47
	v_add_f32_e32 v50, 1.0, v50
	v_add_f32_e32 v51, 1.0, v51
	v_add_f32_e32 v52, 1.0, v52
	v_add_f32_e32 v53, 1.0, v53
	v_rcp_f32_e32 v50, v50
	v_rcp_f32_e32 v51, v51
	v_rcp_f32_e32 v52, v52
	v_rcp_f32_e32 v53, v53
	v_pk_mul_f32 v[42:43], v[46:47], v[42:43]
	v_pk_mul_f32 v[40:41], v[44:45], v[40:41]
	global_store_dwordx2 v[64:65], v[48:49], off offset:128
	v_pk_mul_f32 v[40:41], v[40:41], v[50:51]
	v_pk_mul_f32 v[42:43], v[42:43], v[52:53]
	v_cvt_pk_bf16_f32 v40, v40, v41
	v_cvt_pk_bf16_f32 v41, v42, v43
	v_exp_f32_e64 v42, -v36
	v_exp_f32_e64 v43, -v37
	v_add_u32_e32 v48, 0x90, v170
	v_mad_i64_i32 v[48:49], s[34:35], v48, s69, v[142:143]
	v_lshl_add_u64 v[48:49], v[48:49], 0, v[140:141]
	global_store_dwordx2 v[48:49], v[40:41], off
	v_add_f32_e32 v40, 1.0, v42
	v_add_f32_e32 v41, 1.0, v43
	v_exp_f32_e64 v42, -v38
	v_exp_f32_e64 v43, -v39
	v_rcp_f32_e32 v40, v40
	v_rcp_f32_e32 v41, v41
	v_add_f32_e32 v42, 1.0, v42
	v_add_f32_e32 v43, 1.0, v43
	v_rcp_f32_e32 v42, v42
	v_rcp_f32_e32 v43, v43
	v_pk_mul_f32 v[34:35], v[38:39], v[34:35]
	v_pk_mul_f32 v[32:33], v[36:37], v[32:33]
	v_pk_mul_f32 v[32:33], v[32:33], v[40:41]
	v_pk_mul_f32 v[34:35], v[34:35], v[42:43]
	v_cvt_pk_bf16_f32 v32, v32, v33
	v_cvt_pk_bf16_f32 v33, v34, v35
	v_exp_f32_e64 v34, -v28
	v_exp_f32_e64 v35, -v29
	v_exp_f32_e64 v36, -v30
	v_exp_f32_e64 v37, -v31
	v_add_f32_e32 v34, 1.0, v34
	v_add_f32_e32 v35, 1.0, v35
	v_add_f32_e32 v36, 1.0, v36
	v_add_f32_e32 v37, 1.0, v37
	v_rcp_f32_e32 v34, v34
	v_rcp_f32_e32 v35, v35
	v_rcp_f32_e32 v36, v36
	v_rcp_f32_e32 v37, v37
	v_pk_mul_f32 v[26:27], v[30:31], v[26:27]
	v_pk_mul_f32 v[24:25], v[28:29], v[24:25]
	global_store_dwordx2 v[48:49], v[32:33], off offset:128
	v_pk_mul_f32 v[24:25], v[24:25], v[34:35]
	v_pk_mul_f32 v[26:27], v[26:27], v[36:37]
	v_cvt_pk_bf16_f32 v24, v24, v25
	v_cvt_pk_bf16_f32 v25, v26, v27
	v_exp_f32_e64 v26, -v20
	v_exp_f32_e64 v27, -v21
	v_add_u32_e32 v32, 0xa0, v170
	v_mad_i64_i32 v[32:33], s[34:35], v32, s69, v[142:143]
	v_lshl_add_u64 v[32:33], v[32:33], 0, v[140:141]
	global_store_dwordx2 v[32:33], v[24:25], off
	v_add_f32_e32 v24, 1.0, v26
	v_add_f32_e32 v25, 1.0, v27
	v_exp_f32_e64 v26, -v22
	v_exp_f32_e64 v27, -v23
	v_rcp_f32_e32 v24, v24
	v_rcp_f32_e32 v25, v25
	v_add_f32_e32 v26, 1.0, v26
	v_add_f32_e32 v27, 1.0, v27
	v_rcp_f32_e32 v26, v26
	v_rcp_f32_e32 v27, v27
	v_pk_mul_f32 v[18:19], v[22:23], v[18:19]
	v_pk_mul_f32 v[16:17], v[20:21], v[16:17]
	v_pk_mul_f32 v[16:17], v[16:17], v[24:25]
	v_pk_mul_f32 v[18:19], v[18:19], v[26:27]
	v_cvt_pk_bf16_f32 v16, v16, v17
	v_cvt_pk_bf16_f32 v17, v18, v19
	v_exp_f32_e64 v18, -v12
	v_exp_f32_e64 v19, -v13
	v_exp_f32_e64 v20, -v14
	v_exp_f32_e64 v21, -v15
	v_add_f32_e32 v18, 1.0, v18
	v_add_f32_e32 v19, 1.0, v19
	v_add_f32_e32 v20, 1.0, v20
	v_add_f32_e32 v21, 1.0, v21
	v_rcp_f32_e32 v18, v18
	v_rcp_f32_e32 v19, v19
	v_rcp_f32_e32 v20, v20
	v_rcp_f32_e32 v21, v21
	v_pk_mul_f32 v[10:11], v[14:15], v[10:11]
	v_pk_mul_f32 v[8:9], v[12:13], v[8:9]
	global_store_dwordx2 v[32:33], v[16:17], off offset:128
	v_pk_mul_f32 v[8:9], v[8:9], v[18:19]
	v_pk_mul_f32 v[10:11], v[10:11], v[20:21]
	v_cvt_pk_bf16_f32 v8, v8, v9
	v_cvt_pk_bf16_f32 v9, v10, v11
	v_exp_f32_e64 v10, -v4
	v_exp_f32_e64 v11, -v5
	v_add_u32_e32 v16, 0xb0, v170
	v_mad_i64_i32 v[16:17], s[34:35], v16, s69, v[142:143]
	v_lshl_add_u64 v[16:17], v[16:17], 0, v[140:141]
	global_store_dwordx2 v[16:17], v[8:9], off
	v_add_f32_e32 v8, 1.0, v10
	v_add_f32_e32 v9, 1.0, v11
	v_exp_f32_e64 v10, -v6
	v_exp_f32_e64 v11, -v7
	v_rcp_f32_e32 v8, v8
	v_rcp_f32_e32 v9, v9
	v_add_f32_e32 v10, 1.0, v10
	v_add_f32_e32 v11, 1.0, v11
	v_rcp_f32_e32 v10, v10
	v_rcp_f32_e32 v11, v11
	v_pk_mul_f32 v[2:3], v[6:7], v[2:3]
	v_pk_mul_f32 v[0:1], v[4:5], v[0:1]
	s_and_b64 vcc, exec, s[2:3]
	v_pk_mul_f32 v[0:1], v[0:1], v[8:9]
	v_pk_mul_f32 v[2:3], v[2:3], v[10:11]
	v_cvt_pk_bf16_f32 v0, v0, v1
	v_cvt_pk_bf16_f32 v1, v2, v3
	s_mov_b32 s76, s70
	s_mov_b32 s75, s71
	s_mov_b64 s[36:37], s[0:1]
	s_mov_b64 s[34:35], s[4:5]
	global_store_dwordx2 v[16:17], v[0:1], off offset:128
	s_cbranch_vccz .LBB0_432
	s_branch .Lgu3_done

; #define PG8_STAGE(bufoff, gbase, voff) do { _Pragma("unroll") for (int _i = 0; _i < 2; ++_i) \
;         __builtin_amdgcn_global_load_lds((const unsigned*)((const char*)(gbase) + (voff)[_i]), (PG8_LAS unsigned*)(lds + (bufoff) + ldsw + _i * 8192), 16, 0, 0); } while (0)
; #define PG8_LDA(dst, b, h) do { _Pragma("unroll") for (int m = 0; m < 4; ++m) _Pragma("unroll") for (int k = 0; k < 2; ++k) dst[m][k] = *(const PG8_LAS bf16x8*)(lds + PG8_SA(b, h) + aoff + m * 2048 + k * 1024); } while (0)
; #define PG8_BAR __builtin_amdgcn_s_barrier()
; template <class Epi, class Sched, bool STAMP = false>
; __device__ __forceinline__ void gemm_phase(PG8_LAS unsigned char* lds, const Gemm g, const Sched& S, const Epi& E, unsigned long long* stamps) {
;     ...
;         for (int t = 0; t < nt; t += 2) {
;             const bool last = (t == nt - 2);
;             const char* a1 = cA + (size_t)(t + 1) * kstep;
;             const char* a2 = last ? nA : cA + (size_t)(t + 2) * kstep; const char* b2 = last ? nB : cB + (size_t)(t + 2) * kstep;
;             const char* a3 = a2 + kstep; const char* b3 = b2 + kstep;
;             if (last && has_next) S.a_ready(nxt);
;             PG8_LDB(B0, 0, 0); PG8_SCHED; PG8_LDA(At, 0, 0); PG8_STAGE(PG8_SA(1, 1), a1 + hstep, voffA);
;             PG8_WAIT_L(8); PG8_BAR; PG8_WAIT_L(0); PG8_MMA(0, 0, At, B0); PG8_BAR; PG8_SCHED;
;             PG8_LDB(B1, 0, 1); PG8_STAGE(PG8_SB(0, 0), b2, voffB);
;             PG8_BAR; PG8_WAIT_L(0); PG8_MMA(0, 1, At, B1); PG8_BAR;
;             PG8_LDA(At, 0, 1); PG8_STAGE(PG8_SA(0, 0), a2, voffA);
;             PG8_BAR; PG8_WAIT_L(0); PG8_MMA(1, 0, At, B0); PG8_BAR; PG8_SCHED;
;             PG8_STAGE(PG8_SB(0, 1), b2 + hstep, voffB);
;             PG8_WAIT_V(6); PG8_BAR; PG8_MMA(1, 1, At, B1); PG8_BAR;
;             PG8_LDB(B0, 1, 0); PG8_SCHED; PG8_LDA(At, 1, 0); PG8_STAGE(PG8_SA(0, 1), a2 + hstep, voffA);
;             PG8_WAIT_L(8); PG8_BAR; PG8_WAIT_L(0); PG8_MMA(0, 0, At, B0); PG8_BAR; PG8_SCHED;
;             PG8_LDB(B1, 1, 1); PG8_STAGE(PG8_SB(1, 0), b3, voffB);
;             PG8_BAR; PG8_WAIT_L(0); PG8_MMA(0, 1, At, B1); PG8_BAR;
;             PG8_LDA(At, 1, 1); PG8_STAGE(PG8_SA(1, 0), a3, voffA);
;             PG8_BAR; PG8_WAIT_L(0); PG8_MMA(1, 0, At, B0); PG8_BAR; PG8_SCHED;
;             PG8_STAGE(PG8_SB(1, 1), b3 + hstep, voffB);
;             PG8_WAIT_V(6); PG8_BAR; PG8_MMA(1, 1, At, B1); PG8_BAR;
.Lgu3_half_loop:
	ds_read_b128 v[140:143], v147
	ds_read_b128 v[170:173], v148
	ds_read_b128 v[174:177], v149
	ds_read_b128 v[178:181], v150
	s_add_u32 s36, s34, 0x100
	s_addc_u32 s37, s35, 0
	s_cmp_eq_u32 s10, 12
	s_cselect_b32 s43, s5, s37
	s_cselect_b32 s42, s4, s36
	s_cselect_b32 s41, s1, s78
	s_cselect_b32 s40, s0, s77
	s_mov_b32 m0, s67
	ds_read_b128 v[182:185], v145
	ds_read_b128 v[186:189], v145 offset:1024
	ds_read_b128 v[190:193], v145 offset:2048
	ds_read_b128 v[194:197], v145 offset:3072
	ds_read_b128 v[198:201], v145 offset:4096
	ds_read_b128 v[202:205], v145 offset:5120
	ds_read_b128 v[206:209], v145 offset:6144
	ds_read_b128 v[210:213], v145 offset:7168
	global_load_lds_dwordx4 v132, s[34:35]
	s_mov_b32 m0, s68
	s_nop 0
	global_load_lds_dwordx4 v134, s[34:35]
	s_waitcnt lgkmcnt(8)
	s_barrier
	s_waitcnt lgkmcnt(0)
	s_setprio 1
	s_waitcnt lgkmcnt(0)
	v_mfma_f32_16x16x32_bf16 v[124:127], v[140:143], v[182:185], v[124:127]
	v_mfma_f32_16x16x32_bf16 v[120:123], v[174:177], v[182:185], v[120:123]
	v_mfma_f32_16x16x32_bf16 v[108:111], v[140:143], v[190:193], v[108:111]
	v_mfma_f32_16x16x32_bf16 v[104:107], v[174:177], v[190:193], v[104:107]
	v_mfma_f32_16x16x32_bf16 v[92:95], v[140:143], v[198:201], v[92:95]
	v_mfma_f32_16x16x32_bf16 v[88:91], v[174:177], v[198:201], v[88:91]
	v_mfma_f32_16x16x32_bf16 v[76:79], v[140:143], v[206:209], v[76:79]
	v_mfma_f32_16x16x32_bf16 v[72:75], v[174:177], v[206:209], v[72:75]
	v_mfma_f32_16x16x32_bf16 v[124:127], v[170:173], v[186:189], v[124:127]
	v_mfma_f32_16x16x32_bf16 v[120:123], v[178:181], v[186:189], v[120:123]
	v_mfma_f32_16x16x32_bf16 v[108:111], v[170:173], v[194:197], v[108:111]
	v_mfma_f32_16x16x32_bf16 v[104:107], v[178:181], v[194:197], v[104:107]
	v_mfma_f32_16x16x32_bf16 v[92:95], v[170:173], v[202:205], v[92:95]
	v_mfma_f32_16x16x32_bf16 v[88:91], v[178:181], v[202:205], v[88:91]
	v_mfma_f32_16x16x32_bf16 v[76:79], v[170:173], v[210:213], v[76:79]
	v_mfma_f32_16x16x32_bf16 v[72:75], v[178:181], v[210:213], v[72:75]
	s_setprio 0
	s_barrier
	s_mov_b32 m0, s49
	s_nop 0
	global_load_lds_dwordx4 v130, s[40:41]
	s_mov_b32 m0, s52
	s_nop 0
	global_load_lds_dwordx4 v128, s[40:41]
	s_barrier
	s_waitcnt lgkmcnt(0)
	s_setprio 1
	s_waitcnt lgkmcnt(0)
	s_setprio 0
	s_mov_b32 m0, s46
	s_barrier
	ds_read_b128 v[182:185], v145 offset:16384
	ds_read_b128 v[186:189], v145 offset:17408
	ds_read_b128 v[190:193], v145 offset:18432
	ds_read_b128 v[194:197], v145 offset:19456
	ds_read_b128 v[198:201], v145 offset:20480
	ds_read_b128 v[202:205], v145 offset:21504
	ds_read_b128 v[206:209], v145 offset:22528
	ds_read_b128 v[210:213], v145 offset:23552
	global_load_lds_dwordx4 v130, s[42:43]
	s_mov_b32 m0, s53
	s_nop 0
	global_load_lds_dwordx4 v128, s[42:43]
	s_barrier
	s_waitcnt lgkmcnt(0)
	s_setprio 1
	s_waitcnt lgkmcnt(0)
	v_mfma_f32_16x16x32_bf16 v[60:63], v[140:143], v[182:185], v[60:63]
	v_mfma_f32_16x16x32_bf16 v[56:59], v[174:177], v[182:185], v[56:59]
	v_mfma_f32_16x16x32_bf16 v[44:47], v[140:143], v[190:193], v[44:47]
	v_mfma_f32_16x16x32_bf16 v[40:43], v[174:177], v[190:193], v[40:43]
	v_mfma_f32_16x16x32_bf16 v[28:31], v[140:143], v[198:201], v[28:31]
	v_mfma_f32_16x16x32_bf16 v[24:27], v[174:177], v[198:201], v[24:27]
	v_mfma_f32_16x16x32_bf16 v[12:15], v[140:143], v[206:209], v[12:15]
	v_mfma_f32_16x16x32_bf16 v[8:11], v[174:177], v[206:209], v[8:11]
	v_mfma_f32_16x16x32_bf16 v[60:63], v[170:173], v[186:189], v[60:63]
	v_mfma_f32_16x16x32_bf16 v[56:59], v[178:181], v[186:189], v[56:59]
	v_mfma_f32_16x16x32_bf16 v[44:47], v[170:173], v[194:197], v[44:47]
	v_mfma_f32_16x16x32_bf16 v[40:43], v[178:181], v[194:197], v[40:43]
	v_mfma_f32_16x16x32_bf16 v[28:31], v[170:173], v[202:205], v[28:31]
	v_mfma_f32_16x16x32_bf16 v[24:27], v[178:181], v[202:205], v[24:27]
	v_mfma_f32_16x16x32_bf16 v[12:15], v[170:173], v[210:213], v[12:15]
	v_mfma_f32_16x16x32_bf16 v[8:11], v[178:181], v[210:213], v[8:11]
	s_setprio 0
	s_barrier
	s_add_u32 s34, s40, 0x44000
	s_addc_u32 s35, s41, 0
	s_mov_b32 m0, s54
	s_nop 0
	s_mov_b32 m0, s55
	s_nop 0
	s_waitcnt vmcnt(4)
	s_barrier
	s_setprio 1
	s_setprio 0
	s_barrier
	ds_read_b128 v[140:143], v155
	ds_read_b128 v[170:173], v156
	ds_read_b128 v[174:177], v157
	ds_read_b128 v[178:181], v165
	s_add_u32 s34, s42, 0x44000
	s_addc_u32 s35, s43, 0
	s_mov_b32 m0, s56
	ds_read_b128 v[182:185], v145 offset:32768
	ds_read_b128 v[186:189], v145 offset:33792
	ds_read_b128 v[190:193], v145 offset:34816
	ds_read_b128 v[194:197], v145 offset:35840
	ds_read_b128 v[198:201], v145 offset:36864
	ds_read_b128 v[202:205], v145 offset:37888
	ds_read_b128 v[206:209], v145 offset:38912
	ds_read_b128 v[210:213], v145 offset:39936
	global_load_lds_dwordx4 v130, s[34:35]
	s_mov_b32 m0, s57
	s_nop 0
	global_load_lds_dwordx4 v128, s[34:35]
	s_waitcnt lgkmcnt(8)
	s_barrier
	s_waitcnt lgkmcnt(0)
	s_setprio 1
	s_waitcnt lgkmcnt(0)
	v_mfma_f32_16x16x32_bf16 v[124:127], v[140:143], v[182:185], v[124:127]
	v_mfma_f32_16x16x32_bf16 v[120:123], v[174:177], v[182:185], v[120:123]
	v_mfma_f32_16x16x32_bf16 v[108:111], v[140:143], v[190:193], v[108:111]
	v_mfma_f32_16x16x32_bf16 v[104:107], v[174:177], v[190:193], v[104:107]
	v_mfma_f32_16x16x32_bf16 v[92:95], v[140:143], v[198:201], v[92:95]
	v_mfma_f32_16x16x32_bf16 v[88:91], v[174:177], v[198:201], v[88:91]
	v_mfma_f32_16x16x32_bf16 v[76:79], v[140:143], v[206:209], v[76:79]
	v_mfma_f32_16x16x32_bf16 v[72:75], v[174:177], v[206:209], v[72:75]
	v_mfma_f32_16x16x32_bf16 v[124:127], v[170:173], v[186:189], v[124:127]
	v_mfma_f32_16x16x32_bf16 v[120:123], v[178:181], v[186:189], v[120:123]
	v_mfma_f32_16x16x32_bf16 v[108:111], v[170:173], v[194:197], v[108:111]
	v_mfma_f32_16x16x32_bf16 v[104:107], v[178:181], v[194:197], v[104:107]
	v_mfma_f32_16x16x32_bf16 v[92:95], v[170:173], v[202:205], v[92:95]
	v_mfma_f32_16x16x32_bf16 v[88:91], v[178:181], v[202:205], v[88:91]
	v_mfma_f32_16x16x32_bf16 v[76:79], v[170:173], v[210:213], v[76:79]
	v_mfma_f32_16x16x32_bf16 v[72:75], v[178:181], v[210:213], v[72:75]
	s_setprio 0
	s_barrier
; #define PG8_STAGE(bufoff, gbase, voff) do { _Pragma("unroll") for (int _i = 0; _i < 2; ++_i) \
;         __builtin_amdgcn_global_load_lds((const unsigned*)((const char*)(gbase) + (voff)[_i]), (PG8_LAS unsigned*)(lds + (bufoff) + ldsw + _i * 8192), 16, 0, 0); } while (0)
; #define PG8_LDA(dst, b, h) do { _Pragma("unroll") for (int m = 0; m < 4; ++m) _Pragma("unroll") for (int k = 0; k < 2; ++k) dst[m][k] = *(const PG8_LAS bf16x8*)(lds + PG8_SA(b, h) + aoff + m * 2048 + k * 1024); } while (0)
; #define PG8_LDB(dst, b, h) do { _Pragma("unroll") for (int n = 0; n < 2; ++n) _Pragma("unroll") for (int k = 0; k < 2; ++k) dst[n][k] = *(const PG8_LAS bf16x8*)(lds + PG8_SB(b, h) + boff + n * 2048 + k * 1024); } while (0)
; #define PG8_MMA(ai, bj, At, Bt) do { __builtin_amdgcn_s_setprio(1); _Pragma("unroll") for (int m = 0; m < 4; ++m) _Pragma("unroll") for (int n = 0; n < 2; ++n) _Pragma("unroll") for (int k = 0; k < 2; ++k) \
;         acc[ai][bj][m][n] = __builtin_amdgcn_mfma_f32_16x16x32_bf16(Bt[n][k], At[m][k], acc[ai][bj][m][n], 0, 0, 0); __builtin_amdgcn_s_setprio(0); } while (0)
; #define PG8_WAIT_V(n) asm volatile("s_waitcnt vmcnt(" #n ")" ::: "memory")
; #define PG8_WAIT_L(n) asm volatile("s_waitcnt lgkmcnt(" #n ")" ::: "memory")
; #define PG8_BAR __builtin_amdgcn_s_barrier()
; #define PG8_SCHED __builtin_amdgcn_sched_barrier(0)
; template <class Epi, class Sched, bool STAMP = false>
; __device__ __forceinline__ void gemm_phase(PG8_LAS unsigned char* lds, const Gemm g, const Sched& S, const Epi& E, unsigned long long* stamps) {
;     ...
;             PG8_LDB(B0, 1, 0); PG8_SCHED; PG8_LDA(At, 1, 0); PG8_STAGE(PG8_SA(0, 1), a2 + hstep, voffA);
;             PG8_WAIT_L(8); PG8_BAR; PG8_WAIT_L(0); PG8_MMA(0, 0, At, B0); PG8_BAR; PG8_SCHED;
;             PG8_LDB(B1, 1, 1); PG8_STAGE(PG8_SB(1, 0), b3, voffB);
;             PG8_BAR; PG8_WAIT_L(0); PG8_MMA(0, 1, At, B1); PG8_BAR;
;             PG8_LDA(At, 1, 1); PG8_STAGE(PG8_SA(1, 0), a3, voffA);
;             PG8_BAR; PG8_WAIT_L(0); PG8_MMA(1, 0, At, B0); PG8_BAR; PG8_SCHED;
;             PG8_STAGE(PG8_SB(1, 1), b3 + hstep, voffB);
;             PG8_WAIT_V(6); PG8_BAR; PG8_MMA(1, 1, At, B1); PG8_BAR;
;         }
	s_mov_b32 m0, s60
	s_add_u32 s100, s40, 0x80
	s_addc_u32 s101, s41, 0
	global_load_lds_dwordx4 v130, s[100:101]
	s_mov_b32 m0, s61
	s_nop 0
	global_load_lds_dwordx4 v128, s[100:101]
	s_barrier
	s_waitcnt lgkmcnt(0)
	s_setprio 1
	s_waitcnt lgkmcnt(0)
	s_setprio 0
	s_mov_b32 m0, s62
	s_barrier
	ds_read_b128 v[182:185], v145 offset:49152
	ds_read_b128 v[186:189], v145 offset:50176
	ds_read_b128 v[190:193], v145 offset:51200
	ds_read_b128 v[194:197], v145 offset:52224
	ds_read_b128 v[198:201], v145 offset:53248
	ds_read_b128 v[202:205], v145 offset:54272
	ds_read_b128 v[206:209], v145 offset:55296
	ds_read_b128 v[210:213], v145 offset:56320
	s_add_u32 s100, s42, 0x80
	s_addc_u32 s101, s43, 0
	global_load_lds_dwordx4 v130, s[100:101]
	s_mov_b32 m0, s63
	s_nop 0
	global_load_lds_dwordx4 v128, s[100:101]
	s_barrier
	s_waitcnt lgkmcnt(0)
	s_setprio 1
	s_waitcnt lgkmcnt(0)
	v_mfma_f32_16x16x32_bf16 v[60:63], v[140:143], v[182:185], v[60:63]
	v_mfma_f32_16x16x32_bf16 v[56:59], v[174:177], v[182:185], v[56:59]
	v_mfma_f32_16x16x32_bf16 v[44:47], v[140:143], v[190:193], v[44:47]
	v_mfma_f32_16x16x32_bf16 v[40:43], v[174:177], v[190:193], v[40:43]
	v_mfma_f32_16x16x32_bf16 v[28:31], v[140:143], v[198:201], v[28:31]
	v_mfma_f32_16x16x32_bf16 v[24:27], v[174:177], v[198:201], v[24:27]
	v_mfma_f32_16x16x32_bf16 v[12:15], v[140:143], v[206:209], v[12:15]
	v_mfma_f32_16x16x32_bf16 v[8:11], v[174:177], v[206:209], v[8:11]
	v_mfma_f32_16x16x32_bf16 v[60:63], v[170:173], v[186:189], v[60:63]
	v_mfma_f32_16x16x32_bf16 v[56:59], v[178:181], v[186:189], v[56:59]
	v_mfma_f32_16x16x32_bf16 v[44:47], v[170:173], v[194:197], v[44:47]
	v_mfma_f32_16x16x32_bf16 v[40:43], v[178:181], v[194:197], v[40:43]
	v_mfma_f32_16x16x32_bf16 v[28:31], v[170:173], v[202:205], v[28:31]
	v_mfma_f32_16x16x32_bf16 v[24:27], v[178:181], v[202:205], v[24:27]
	v_mfma_f32_16x16x32_bf16 v[12:15], v[170:173], v[210:213], v[12:15]
	v_mfma_f32_16x16x32_bf16 v[8:11], v[178:181], v[210:213], v[8:11]
	s_setprio 0
	s_barrier
	s_add_u32 s34, s40, 0x44080
	s_addc_u32 s35, s41, 0
	s_mov_b32 m0, s64
	s_nop 0
	s_mov_b32 m0, s65
	s_nop 0
	s_add_i32 s10, s10, 2
	s_add_u32 s77, s77, 0x100
	s_addc_u32 s78, s78, 0
	s_cmp_gt_u32 s10, 13
	s_mov_b64 s[34:35], s[36:37]
	s_waitcnt vmcnt(4)
	s_barrier
	s_setprio 1
	s_setprio 0
	s_barrier
	s_cbranch_scc0 .Lgu3_half_loop
; DI float ex2(float x) { return __builtin_amdgcn_exp2f(x); }
;     DI void operator()(const f32x4 (&acc)[2][2][4][2], const Unit& u, int wr, int wc, int fr, int fq) const {
;         const int row0 = u.pm * BM + wr * 64 + fr, hcol0 = ((u.pn * BM + wc * 32) >> 1) + 4 * fq;
; #pragma unroll
;         for (int ai = 0; ai < 2; ++ai)
; #pragma unroll
;             for (int m = 0; m < 4; ++m) { u16* rowp = O + (size_t)(row0 + ai * HALF + m * 16) * ldc + hcol0;
; #pragma unroll
;                 for (int bj = 0; bj < 2; ++bj) { const f32x4 g = acc[ai][bj][m][0], up = acc[ai][bj][m][1]; float r[4];
; #pragma unroll
;                     for (int j = 0; j < 4; ++j) r[j] = g[j] * up[j] * __builtin_amdgcn_rcpf(1.f + ex2(-LOG2E * g[j]));
;                     uint2 w = {pack2(r[0], r[1]), pack2(r[2], r[3])}; *(uint2*)(rowp + bj * (HALF / 2)) = w; } }
	v_exp_f32_e64 v171, -v124
	v_exp_f32_e64 v175, -v125
	s_lshl_b32 s10, s76, 8
	v_add_f32_e32 v171, 1.0, v171
	v_rcp_f32_e32 v174, v171
	v_add_f32_e32 v171, 1.0, v175
	v_exp_f32_e64 v176, -v126
	v_exp_f32_e64 v177, -v127
	v_rcp_f32_e32 v175, v171
	v_add_f32_e32 v171, 1.0, v176
	v_rcp_f32_e32 v176, v171
	v_add_f32_e32 v171, 1.0, v177
	v_rcp_f32_e32 v177, v171
	v_pk_mul_f32 v[122:123], v[126:127], v[122:123]
	v_pk_mul_f32 v[120:121], v[124:125], v[120:121]
	s_or_b32 s10, s10, s59
	s_or_b32 s10, s10, s98
	v_pk_mul_f32 v[120:121], v[120:121], v[174:175]
	v_pk_mul_f32 v[122:123], v[122:123], v[176:177]
	s_ashr_i32 s10, s10, 1
	v_cvt_pk_bf16_f32 v120, v120, v121
	v_cvt_pk_bf16_f32 v121, v122, v123
	v_or_b32_e32 v140, s10, v146
	v_lshl_add_u32 v170, s75, 8, v144
	v_ashrrev_i32_e32 v141, 31, v140
	v_mov_b64_e32 v[142:143], s[12:13]
	v_mad_i64_i32 v[172:173], s[34:35], v170, s69, v[142:143]
	v_lshlrev_b64 v[140:141], 1, v[140:141]
	v_lshl_add_u64 v[172:173], v[172:173], 0, v[140:141]
	global_store_dwordx2 v[172:173], v[120:121], off
	v_exp_f32_e64 v114, -v108
	v_exp_f32_e64 v115, -v109
	v_exp_f32_e64 v116, -v110
	v_exp_f32_e64 v117, -v111
	v_add_f32_e32 v114, 1.0, v114
	v_add_f32_e32 v115, 1.0, v115
	v_add_f32_e32 v116, 1.0, v116
	v_add_f32_e32 v117, 1.0, v117
	v_rcp_f32_e32 v114, v114
	v_rcp_f32_e32 v115, v115
	v_rcp_f32_e32 v116, v116
	v_rcp_f32_e32 v117, v117
	v_pk_mul_f32 v[106:107], v[110:111], v[106:107]
	v_pk_mul_f32 v[104:105], v[108:109], v[104:105]
	v_pk_mul_f32 v[104:105], v[104:105], v[114:115]
	v_pk_mul_f32 v[106:107], v[106:107], v[116:117]
	v_cvt_pk_bf16_f32 v104, v104, v105
	v_cvt_pk_bf16_f32 v105, v106, v107
	v_or_b32_e32 v112, 16, v170
	v_mad_i64_i32 v[112:113], s[34:35], v112, s69, v[142:143]
	v_lshl_add_u64 v[112:113], v[112:113], 0, v[140:141]
	global_store_dwordx2 v[112:113], v[104:105], off
	v_exp_f32_e64 v98, -v92
	v_exp_f32_e64 v99, -v93
	v_exp_f32_e64 v100, -v94
	v_exp_f32_e64 v101, -v95
	v_add_f32_e32 v98, 1.0, v98
	v_add_f32_e32 v99, 1.0, v99
	v_add_f32_e32 v100, 1.0, v100
	v_add_f32_e32 v101, 1.0, v101
	v_rcp_f32_e32 v98, v98
	v_rcp_f32_e32 v99, v99
	v_rcp_f32_e32 v100, v100
	v_rcp_f32_e32 v101, v101
	v_pk_mul_f32 v[90:91], v[94:95], v[90:91]
	v_pk_mul_f32 v[88:89], v[92:93], v[88:89]
	v_pk_mul_f32 v[88:89], v[88:89], v[98:99]
	v_pk_mul_f32 v[90:91], v[90:91], v[100:101]
	v_cvt_pk_bf16_f32 v88, v88, v89
	v_cvt_pk_bf16_f32 v89, v90, v91
	v_or_b32_e32 v96, 32, v170
	v_mad_i64_i32 v[96:97], s[34:35], v96, s69, v[142:143]
	v_lshl_add_u64 v[96:97], v[96:97], 0, v[140:141]
	global_store_dwordx2 v[96:97], v[88:89], off
	v_exp_f32_e64 v82, -v76
	v_exp_f32_e64 v83, -v77
	v_exp_f32_e64 v84, -v78
	v_exp_f32_e64 v85, -v79
	v_add_f32_e32 v82, 1.0, v82
	v_add_f32_e32 v83, 1.0, v83
	v_add_f32_e32 v84, 1.0, v84
	v_add_f32_e32 v85, 1.0, v85
	v_rcp_f32_e32 v82, v82
	v_rcp_f32_e32 v83, v83
	v_rcp_f32_e32 v84, v84
	v_rcp_f32_e32 v85, v85
	v_pk_mul_f32 v[74:75], v[78:79], v[74:75]
	v_pk_mul_f32 v[72:73], v[76:77], v[72:73]
	v_pk_mul_f32 v[72:73], v[72:73], v[82:83]
	v_pk_mul_f32 v[74:75], v[74:75], v[84:85]
	v_cvt_pk_bf16_f32 v72, v72, v73
	v_cvt_pk_bf16_f32 v73, v74, v75
	v_or_b32_e32 v80, 48, v170
	v_mad_i64_i32 v[80:81], s[34:35], v80, s69, v[142:143]
	v_lshl_add_u64 v[80:81], v[80:81], 0, v[140:141]
	global_store_dwordx2 v[80:81], v[72:73], off
	v_exp_f32_e64 v66, -v60
	v_exp_f32_e64 v67, -v61
	v_exp_f32_e64 v68, -v62
	v_exp_f32_e64 v69, -v63
	v_add_f32_e32 v66, 1.0, v66
	v_add_f32_e32 v67, 1.0, v67
	v_add_f32_e32 v68, 1.0, v68
	v_add_f32_e32 v69, 1.0, v69
	v_rcp_f32_e32 v66, v66
	v_rcp_f32_e32 v67, v67
	v_rcp_f32_e32 v68, v68
	v_rcp_f32_e32 v69, v69
	v_pk_mul_f32 v[58:59], v[62:63], v[58:59]
	v_pk_mul_f32 v[56:57], v[60:61], v[56:57]
	v_pk_mul_f32 v[56:57], v[56:57], v[66:67]
	v_pk_mul_f32 v[58:59], v[58:59], v[68:69]
	v_cvt_pk_bf16_f32 v56, v56, v57
	v_cvt_pk_bf16_f32 v57, v58, v59
	v_add_u32_e32 v64, 0x80, v170
	v_mad_i64_i32 v[64:65], s[34:35], v64, s69, v[142:143]
	v_lshl_add_u64 v[64:65], v[64:65], 0, v[140:141]
	global_store_dwordx2 v[64:65], v[56:57], off
	v_exp_f32_e64 v50, -v44
	v_exp_f32_e64 v51, -v45
	v_exp_f32_e64 v52, -v46
	v_exp_f32_e64 v53, -v47
	v_add_f32_e32 v50, 1.0, v50
	v_add_f32_e32 v51, 1.0, v51
	v_add_f32_e32 v52, 1.0, v52
	v_add_f32_e32 v53, 1.0, v53
	v_rcp_f32_e32 v50, v50
	v_rcp_f32_e32 v51, v51
	v_rcp_f32_e32 v52, v52
	v_rcp_f32_e32 v53, v53
	v_pk_mul_f32 v[42:43], v[46:47], v[42:43]
	v_pk_mul_f32 v[40:41], v[44:45], v[40:41]
	v_pk_mul_f32 v[40:41], v[40:41], v[50:51]
	v_pk_mul_f32 v[42:43], v[42:43], v[52:53]
	v_cvt_pk_bf16_f32 v40, v40, v41
	v_cvt_pk_bf16_f32 v41, v42, v43
	v_add_u32_e32 v48, 0x90, v170
	v_mad_i64_i32 v[48:49], s[34:35], v48, s69, v[142:143]
	v_lshl_add_u64 v[48:49], v[48:49], 0, v[140:141]
	global_store_dwordx2 v[48:49], v[40:41], off
	v_exp_f32_e64 v34, -v28
	v_exp_f32_e64 v35, -v29
	v_exp_f32_e64 v36, -v30
	v_exp_f32_e64 v37, -v31
	v_add_f32_e32 v34, 1.0, v34
	v_add_f32_e32 v35, 1.0, v35
	v_add_f32_e32 v36, 1.0, v36
	v_add_f32_e32 v37, 1.0, v37
	v_rcp_f32_e32 v34, v34
	v_rcp_f32_e32 v35, v35
	v_rcp_f32_e32 v36, v36
	v_rcp_f32_e32 v37, v37
	v_pk_mul_f32 v[26:27], v[30:31], v[26:27]
	v_pk_mul_f32 v[24:25], v[28:29], v[24:25]
	v_pk_mul_f32 v[24:25], v[24:25], v[34:35]
	v_pk_mul_f32 v[26:27], v[26:27], v[36:37]
	v_cvt_pk_bf16_f32 v24, v24, v25
	v_cvt_pk_bf16_f32 v25, v26, v27
	v_add_u32_e32 v32, 0xa0, v170
	v_mad_i64_i32 v[32:33], s[34:35], v32, s69, v[142:143]
	v_lshl_add_u64 v[32:33], v[32:33], 0, v[140:141]
	global_store_dwordx2 v[32:33], v[24:25], off
	v_exp_f32_e64 v18, -v12
	v_exp_f32_e64 v19, -v13
	v_exp_f32_e64 v20, -v14
	v_exp_f32_e64 v21, -v15
	v_add_f32_e32 v18, 1.0, v18
	v_add_f32_e32 v19, 1.0, v19
	v_add_f32_e32 v20, 1.0, v20
	v_add_f32_e32 v21, 1.0, v21
	v_rcp_f32_e32 v18, v18
	v_rcp_f32_e32 v19, v19
	v_rcp_f32_e32 v20, v20
	v_rcp_f32_e32 v21, v21
	v_pk_mul_f32 v[10:11], v[14:15], v[10:11]
	v_pk_mul_f32 v[8:9], v[12:13], v[8:9]
	v_pk_mul_f32 v[8:9], v[8:9], v[18:19]
	v_pk_mul_f32 v[10:11], v[10:11], v[20:21]
	v_cvt_pk_bf16_f32 v8, v8, v9
	v_cvt_pk_bf16_f32 v9, v10, v11
	v_add_u32_e32 v16, 0xb0, v170
	v_mad_i64_i32 v[16:17], s[34:35], v16, s69, v[142:143]
	v_lshl_add_u64 v[16:17], v[16:17], 0, v[140:141]
	global_store_dwordx2 v[16:17], v[8:9], off
	s_and_b64 vcc, exec, s[2:3]
	s_mov_b32 s76, s70
	s_mov_b32 s75, s71
	s_mov_b64 s[36:37], s[0:1]
	s_mov_b64 s[34:35], s[4:5]

; #define PG8_STAGE(bufoff, gbase, voff) do { _Pragma("unroll") for (int _i = 0; _i < 2; ++_i) \
;         __builtin_amdgcn_global_load_lds((const unsigned*)((const char*)(gbase) + (voff)[_i]), (PG8_LAS unsigned*)(lds + (bufoff) + ldsw + _i * 8192), 16, 0, 0); } while (0)
; #define PG8_LDA(dst, b, h) do { _Pragma("unroll") for (int m = 0; m < 4; ++m) _Pragma("unroll") for (int k = 0; k < 2; ++k) dst[m][k] = *(const PG8_LAS bf16x8*)(lds + PG8_SA(b, h) + aoff + m * 2048 + k * 1024); } while (0)
; #define PG8_LDB(dst, b, h) do { _Pragma("unroll") for (int n = 0; n < 2; ++n) _Pragma("unroll") for (int k = 0; k < 2; ++k) dst[n][k] = *(const PG8_LAS bf16x8*)(lds + PG8_SB(b, h) + boff + n * 2048 + k * 1024); } while (0)
; #define PG8_MMA(ai, bj, At, Bt) do { __builtin_amdgcn_s_setprio(1); _Pragma("unroll") for (int m = 0; m < 4; ++m) _Pragma("unroll") for (int n = 0; n < 2; ++n) _Pragma("unroll") for (int k = 0; k < 2; ++k) \
;         acc[ai][bj][m][n] = __builtin_amdgcn_mfma_f32_16x16x32_bf16(Bt[n][k], At[m][k], acc[ai][bj][m][n], 0, 0, 0); __builtin_amdgcn_s_setprio(0); } while (0)
; #define PG8_WAIT_V(n) asm volatile("s_waitcnt vmcnt(" #n ")" ::: "memory")
; #define PG8_WAIT_L(n) asm volatile("s_waitcnt lgkmcnt(" #n ")" ::: "memory")
; #define PG8_BAR __builtin_amdgcn_s_barrier()
; #define PG8_SCHED __builtin_amdgcn_sched_barrier(0)
; template <class Epi, class Sched, bool STAMP = false>
; __device__ __forceinline__ void gemm_phase(PG8_LAS unsigned char* lds, const Gemm g, const Sched& S, const Epi& E, unsigned long long* stamps) {
;     ...
;             PG8_LDB(B0, 1, 0); PG8_SCHED; PG8_LDA(At, 1, 0); PG8_STAGE(PG8_SA(0, 1), a2 + hstep, voffA);
;             PG8_WAIT_L(8); PG8_BAR; PG8_WAIT_L(0); PG8_MMA(0, 0, At, B0); PG8_BAR; PG8_SCHED;
;             PG8_LDB(B1, 1, 1); PG8_STAGE(PG8_SB(1, 0), b3, voffB);
;             PG8_BAR; PG8_WAIT_L(0); PG8_MMA(0, 1, At, B1); PG8_BAR;
;             PG8_LDA(At, 1, 1); PG8_STAGE(PG8_SA(1, 0), a3, voffA);
;             PG8_BAR; PG8_WAIT_L(0); PG8_MMA(1, 0, At, B0); PG8_BAR; PG8_SCHED;
;             PG8_STAGE(PG8_SB(1, 1), b3 + hstep, voffB);
;             PG8_WAIT_V(6); PG8_BAR; PG8_MMA(1, 1, At, B1); PG8_BAR;
.Lzp8_mid:
	ds_read_b128 v[170:173], v155
	ds_read_b128 v[174:177], v156
	ds_read_b128 v[178:181], v157
	ds_read_b128 v[182:185], v165
	s_add_u32 s44, s52, 0xb4000
	s_addc_u32 s45, s53, 0
	s_mov_b32 m0, s63
	ds_read_b128 v[186:189], v145 offset:32768
	ds_read_b128 v[190:193], v145 offset:33792
	ds_read_b128 v[194:197], v145 offset:34816
	ds_read_b128 v[198:201], v145 offset:35840
	ds_read_b128 v[202:205], v145 offset:36864
	ds_read_b128 v[206:209], v145 offset:37888
	ds_read_b128 v[210:213], v145 offset:38912
	ds_read_b128 v[214:217], v145 offset:39936
	global_load_lds_dwordx4 v128, s[44:45]
	s_mov_b32 m0, s64
	s_nop 0
	global_load_lds_dwordx4 v132, s[44:45]
	s_waitcnt lgkmcnt(8)
	s_barrier
	s_waitcnt lgkmcnt(0)
	s_setprio 1
	s_waitcnt lgkmcnt(0)
	v_mfma_f32_16x16x32_bf16 v[124:127], v[170:173], v[186:189], v[124:127]
	v_mfma_f32_16x16x32_bf16 v[120:123], v[178:181], v[186:189], v[120:123]
	v_mfma_f32_16x16x32_bf16 v[116:119], v[170:173], v[194:197], v[116:119]
	v_mfma_f32_16x16x32_bf16 v[112:115], v[178:181], v[194:197], v[112:115]
	v_mfma_f32_16x16x32_bf16 v[100:103], v[170:173], v[202:205], v[100:103]
	v_mfma_f32_16x16x32_bf16 v[96:99], v[178:181], v[202:205], v[96:99]
	v_mfma_f32_16x16x32_bf16 v[84:87], v[170:173], v[210:213], v[84:87]
	v_mfma_f32_16x16x32_bf16 v[80:83], v[178:181], v[210:213], v[80:83]
	v_mfma_f32_16x16x32_bf16 v[124:127], v[174:177], v[190:193], v[124:127]
	v_mfma_f32_16x16x32_bf16 v[120:123], v[182:185], v[190:193], v[120:123]
	v_mfma_f32_16x16x32_bf16 v[116:119], v[174:177], v[198:201], v[116:119]
	v_mfma_f32_16x16x32_bf16 v[112:115], v[182:185], v[198:201], v[112:115]
	v_mfma_f32_16x16x32_bf16 v[100:103], v[174:177], v[206:209], v[100:103]
	v_mfma_f32_16x16x32_bf16 v[96:99], v[182:185], v[206:209], v[96:99]
	v_mfma_f32_16x16x32_bf16 v[84:87], v[174:177], v[214:217], v[84:87]
	v_mfma_f32_16x16x32_bf16 v[80:83], v[182:185], v[214:217], v[80:83]
	s_setprio 0
	s_barrier
	s_mov_b32 m0, s65
	ds_read_b128 v[218:221], v166
	ds_read_b128 v[222:225], v167
	ds_read_b128 v[226:229], v168
	ds_read_b128 v[230:233], v169
	s_add_u32 s100, s48, 0x80
	s_addc_u32 s101, s49, 0
	global_load_lds_dwordx4 v130, s[100:101]
	s_mov_b32 m0, s66
	s_nop 0
	global_load_lds_dwordx4 v134, s[100:101]
	s_barrier
	s_waitcnt lgkmcnt(0)
	s_setprio 1
	s_waitcnt lgkmcnt(0)
	v_mfma_f32_16x16x32_bf16 v[108:111], v[218:221], v[186:189], v[108:111]
	v_mfma_f32_16x16x32_bf16 v[104:107], v[226:229], v[186:189], v[104:107]
	v_mfma_f32_16x16x32_bf16 v[92:95], v[218:221], v[194:197], v[92:95]
	v_mfma_f32_16x16x32_bf16 v[88:91], v[226:229], v[194:197], v[88:91]
	v_mfma_f32_16x16x32_bf16 v[76:79], v[218:221], v[202:205], v[76:79]
	v_mfma_f32_16x16x32_bf16 v[72:75], v[226:229], v[202:205], v[72:75]
	v_mfma_f32_16x16x32_bf16 v[68:71], v[218:221], v[210:213], v[68:71]
	v_mfma_f32_16x16x32_bf16 v[64:67], v[226:229], v[210:213], v[64:67]
	v_mfma_f32_16x16x32_bf16 v[108:111], v[222:225], v[190:193], v[108:111]
	v_mfma_f32_16x16x32_bf16 v[104:107], v[230:233], v[190:193], v[104:107]
	v_mfma_f32_16x16x32_bf16 v[92:95], v[222:225], v[198:201], v[92:95]
	v_mfma_f32_16x16x32_bf16 v[88:91], v[230:233], v[198:201], v[88:91]
	v_mfma_f32_16x16x32_bf16 v[76:79], v[222:225], v[206:209], v[76:79]
	v_mfma_f32_16x16x32_bf16 v[72:75], v[230:233], v[206:209], v[72:75]
	v_mfma_f32_16x16x32_bf16 v[68:71], v[222:225], v[214:217], v[68:71]
	v_mfma_f32_16x16x32_bf16 v[64:67], v[230:233], v[214:217], v[64:67]
	s_setprio 0
	s_mov_b32 m0, s67
	s_barrier
	ds_read_b128 v[186:189], v145 offset:49152
	ds_read_b128 v[190:193], v145 offset:50176
	ds_read_b128 v[194:197], v145 offset:51200
	ds_read_b128 v[198:201], v145 offset:52224
	ds_read_b128 v[202:205], v145 offset:53248
	ds_read_b128 v[206:209], v145 offset:54272
	ds_read_b128 v[210:213], v145 offset:55296
	ds_read_b128 v[214:217], v145 offset:56320
	s_add_u32 s100, s52, 0x80
	s_addc_u32 s101, s53, 0
	global_load_lds_dwordx4 v128, s[100:101]
	s_mov_b32 m0, s68
	s_nop 0
	global_load_lds_dwordx4 v132, s[100:101]
	s_barrier
	s_waitcnt lgkmcnt(0)
	s_setprio 1
	s_waitcnt lgkmcnt(0)
	v_mfma_f32_16x16x32_bf16 v[60:63], v[170:173], v[186:189], v[60:63]
	v_mfma_f32_16x16x32_bf16 v[56:59], v[178:181], v[186:189], v[56:59]
	v_mfma_f32_16x16x32_bf16 v[52:55], v[170:173], v[194:197], v[52:55]
	v_mfma_f32_16x16x32_bf16 v[48:51], v[178:181], v[194:197], v[48:51]
	v_mfma_f32_16x16x32_bf16 v[36:39], v[170:173], v[202:205], v[36:39]
	v_mfma_f32_16x16x32_bf16 v[32:35], v[178:181], v[202:205], v[32:35]
	v_mfma_f32_16x16x32_bf16 v[20:23], v[170:173], v[210:213], v[20:23]
	v_mfma_f32_16x16x32_bf16 v[16:19], v[178:181], v[210:213], v[16:19]
	v_mfma_f32_16x16x32_bf16 v[60:63], v[174:177], v[190:193], v[60:63]
	v_mfma_f32_16x16x32_bf16 v[56:59], v[182:185], v[190:193], v[56:59]
	v_mfma_f32_16x16x32_bf16 v[52:55], v[174:177], v[198:201], v[52:55]
	v_mfma_f32_16x16x32_bf16 v[48:51], v[182:185], v[198:201], v[48:51]
	v_mfma_f32_16x16x32_bf16 v[36:39], v[174:177], v[206:209], v[36:39]
	v_mfma_f32_16x16x32_bf16 v[32:35], v[182:185], v[206:209], v[32:35]
	v_mfma_f32_16x16x32_bf16 v[20:23], v[174:177], v[214:217], v[20:23]
	v_mfma_f32_16x16x32_bf16 v[16:19], v[182:185], v[214:217], v[16:19]
	s_setprio 0
	s_barrier
	s_add_u32 s44, s48, 0xb4080
	s_addc_u32 s45, s49, 0
	s_mov_b32 m0, s69
	s_nop 0
	global_load_lds_dwordx4 v130, s[44:45]
	s_mov_b32 m0, s70
	s_nop 0
	global_load_lds_dwordx4 v134, s[44:45]
	s_add_i32 s10, s10, 2
	s_add_u32 s88, s88, 0x100
	s_addc_u32 s89, s89, 0
	s_cmp_gt_u32 s10, 41
	s_mov_b64 s[44:45], s[46:47]
	s_waitcnt vmcnt(6)
	s_barrier
; #define PG8_STAMP() do { if (STAMP && wid == 0 && nts < 64) { const unsigned long long _c = 0ull; \
;         ts_lo = (lane == nts) ? (int)(unsigned)_c : ts_lo; ts_hi = (lane == nts) ? (int)(unsigned)(_c >> 32) : ts_hi; ++nts; } } while (0)
;     DI void operator()(const f32x4 (&acc)[2][2][4][2], const Unit& u, int wr, int wc, int fr, int fq) const {
;         const int row0 = u.pm * BM + wr * 64 + fr, col0 = u.pn * BM + wc * 32 + 8 * fq;
; #pragma unroll
;         for (int ai = 0; ai < 2; ++ai)
; #pragma unroll
;             for (int m = 0; m < 4; ++m) { u16* rowp = O + (size_t)(row0 + ai * HALF + m * 16) * ldc + col0;
; #pragma unroll
;                 for (int bj = 0; bj < 2; ++bj) { const f32x4 v0 = acc[ai][bj][m][0], v1 = acc[ai][bj][m][1];
;                     uint4 w = {pack2(v0[0], v0[1]), pack2(v0[2], v0[3]), pack2(v1[0], v1[1]), pack2(v1[2], v1[3])}; *(uint4*)(rowp + bj * HALF) = w; } }
; template <class Epi, class Sched, bool STAMP = false>
; __device__ __forceinline__ void gemm_phase(PG8_LAS unsigned char* lds, const Gemm g, const Sched& S, const Epi& E, unsigned long long* stamps) {
;     ...
;             PG8_WAIT_V(6); PG8_BAR; PG8_MMA(1, 1, At, B1); PG8_BAR;
;             PG8_LDB(B0, 1, 0); PG8_SCHED; PG8_LDA(At, 1, 0); PG8_STAGE(PG8_SA(0, 1), a2 + hstep, voffA);
;             PG8_WAIT_L(8); PG8_BAR; PG8_WAIT_L(0); PG8_MMA(0, 0, At, B0); PG8_BAR; PG8_SCHED;
;             PG8_LDB(B1, 1, 1); PG8_STAGE(PG8_SB(1, 0), b3, voffB);
;             PG8_BAR; PG8_WAIT_L(0); PG8_MMA(0, 1, At, B1); PG8_BAR;
;             PG8_LDA(At, 1, 1); PG8_STAGE(PG8_SA(1, 0), a3, voffA);
;             PG8_BAR; PG8_WAIT_L(0); PG8_MMA(1, 0, At, B0); PG8_BAR; PG8_SCHED;
;             PG8_STAGE(PG8_SB(1, 1), b3 + hstep, voffB);
;             PG8_WAIT_V(6); PG8_BAR; PG8_MMA(1, 1, At, B1); PG8_BAR;
;         }
;         PG8_STAMP();
;         if constexpr (!Epi::AFTER_DRAIN) { E(acc, cur, wr, wc, fr, fq); S.done(cur); }
;         PG8_STAMP();
;         if (!has_next) break;
; #pragma unroll
;         for (int a = 0; a < 2; ++a)
; #pragma unroll
;             for (int b = 0; b < 2; ++b)
; #pragma unroll
;                 for (int m = 0; m < 4; ++m)
; #pragma unroll
;                     for (int n = 0; n < 2; ++n) acc[a][b][m][n] = (f32x4){0.f, 0.f, 0.f, 0.f};
;         cur = nxt; cA = nA; cB = nB; ++ui;
;     }
;     PG8_WAIT_V(0);
;     if (wr == 0) PG8_BAR;
;     PG8_BAR;
	s_setprio 1
	v_mfma_f32_16x16x32_bf16 v[44:47], v[218:221], v[186:189], v[44:47]
	v_mfma_f32_16x16x32_bf16 v[40:43], v[226:229], v[186:189], v[40:43]
	v_mfma_f32_16x16x32_bf16 v[28:31], v[218:221], v[194:197], v[28:31]
	v_mfma_f32_16x16x32_bf16 v[24:27], v[226:229], v[194:197], v[24:27]
	v_mfma_f32_16x16x32_bf16 v[12:15], v[218:221], v[202:205], v[12:15]
	v_mfma_f32_16x16x32_bf16 v[8:11], v[226:229], v[202:205], v[8:11]
	v_mfma_f32_16x16x32_bf16 v[4:7], v[218:221], v[210:213], v[4:7]
	v_mfma_f32_16x16x32_bf16 v[0:3], v[226:229], v[210:213], v[0:3]
	v_mfma_f32_16x16x32_bf16 v[44:47], v[222:225], v[190:193], v[44:47]
	v_mfma_f32_16x16x32_bf16 v[40:43], v[230:233], v[190:193], v[40:43]
	v_mfma_f32_16x16x32_bf16 v[28:31], v[222:225], v[198:201], v[28:31]
	v_mfma_f32_16x16x32_bf16 v[24:27], v[230:233], v[198:201], v[24:27]
	v_mfma_f32_16x16x32_bf16 v[12:15], v[222:225], v[206:209], v[12:15]
	v_mfma_f32_16x16x32_bf16 v[8:11], v[230:233], v[206:209], v[8:11]
	v_mfma_f32_16x16x32_bf16 v[4:7], v[222:225], v[214:217], v[4:7]
	v_mfma_f32_16x16x32_bf16 v[0:3], v[230:233], v[214:217], v[0:3]
	s_setprio 0
	s_barrier
	s_cbranch_scc0 .LBB0_473
	v_lshl_add_u32 v170, s84, 8, v144
	v_lshl_or_b32 v172, s87, 8, v146
	v_ashrrev_i32_e32 v171, 31, v170
	v_ashrrev_i32_e32 v173, 31, v172
	v_lshlrev_b64 v[174:175], 11, v[170:171]
	v_lshl_add_u64 v[174:175], s[14:15], 0, v[174:175]
	v_lshlrev_b64 v[172:173], 1, v[172:173]
	v_lshl_add_u64 v[174:175], v[174:175], 0, v[172:173]
	v_cvt_pk_bf16_f32 v60, v60, v61
	v_cvt_pk_bf16_f32 v61, v62, v63
	v_cvt_pk_bf16_f32 v62, v56, v57
	v_add_co_u32_e32 v56, vcc, s78, v174
	v_cvt_pk_bf16_f32 v68, v68, v69
	v_cvt_pk_bf16_f32 v69, v70, v71
	v_cvt_pk_bf16_f32 v70, v64, v65
	v_lshl_add_u64 v[64:65], v[174:175], 0, s[34:35]
	v_addc_co_u32_e32 v57, vcc, 0, v175, vcc
	v_cvt_pk_bf16_f32 v44, v44, v45
	v_cvt_pk_bf16_f32 v45, v46, v47
	v_cvt_pk_bf16_f32 v46, v40, v41
	v_cvt_pk_bf16_f32 v47, v42, v43
	v_cvt_pk_bf16_f32 v108, v108, v109
	v_cvt_pk_bf16_f32 v109, v110, v111
	v_cvt_pk_bf16_f32 v110, v104, v105
	v_or_b32_e32 v104, 16, v170
	global_store_dwordx4 v[64:65], v[44:47], off offset:256
	v_ashrrev_i32_e32 v105, 31, v104
	v_cvt_pk_bf16_f32 v92, v92, v93
	v_add_co_u32_e32 v46, vcc, s79, v174
	v_cvt_pk_bf16_f32 v93, v94, v95
	v_cvt_pk_bf16_f32 v94, v88, v89
	v_or_b32_e32 v88, 32, v170
	v_lshl_add_u64 v[44:45], v[174:175], 0, s[36:37]
	v_addc_co_u32_e32 v47, vcc, 0, v175, vcc
	v_cvt_pk_bf16_f32 v28, v28, v29
	v_cvt_pk_bf16_f32 v29, v30, v31
	v_cvt_pk_bf16_f32 v30, v24, v25
	v_cvt_pk_bf16_f32 v31, v26, v27
	v_lshlrev_b64 v[104:105], 11, v[104:105]
	v_ashrrev_i32_e32 v89, 31, v88
	v_cvt_pk_bf16_f32 v76, v76, v77
	v_cvt_pk_bf16_f32 v77, v78, v79
	v_cvt_pk_bf16_f32 v78, v72, v73
	v_or_b32_e32 v72, 48, v170
	global_store_dwordx4 v[44:45], v[28:31], off offset:256
	v_cvt_pk_bf16_f32 v111, v106, v107
	v_lshl_add_u64 v[104:105], s[14:15], 0, v[104:105]
	v_add_co_u32_e32 v30, vcc, s82, v174
	v_lshlrev_b64 v[88:89], 11, v[88:89]
	v_ashrrev_i32_e32 v73, 31, v72
	v_lshl_add_u64 v[28:29], v[174:175], 0, s[40:41]
	v_addc_co_u32_e32 v31, vcc, 0, v175, vcc
	v_cvt_pk_bf16_f32 v12, v12, v13
	v_cvt_pk_bf16_f32 v13, v14, v15
	v_cvt_pk_bf16_f32 v14, v8, v9
	v_cvt_pk_bf16_f32 v15, v10, v11
	global_store_dwordx4 v[174:175], v[108:111], off offset:256
	v_cvt_pk_bf16_f32 v95, v90, v91
	v_lshl_add_u64 v[88:89], s[14:15], 0, v[88:89]
	v_lshl_add_u64 v[108:109], v[104:105], 0, v[172:173]
	v_lshlrev_b64 v[72:73], 11, v[72:73]
	global_store_dwordx4 v[28:29], v[12:15], off offset:256
	global_store_dwordx4 v[108:109], v[92:95], off offset:256
	v_cvt_pk_bf16_f32 v79, v74, v75
	v_add_co_u32_e32 v14, vcc, s83, v174
	v_lshl_add_u64 v[92:93], v[88:89], 0, v[172:173]
	v_lshl_add_u64 v[72:73], s[14:15], 0, v[72:73]
	v_addc_co_u32_e32 v15, vcc, 0, v175, vcc
	v_cvt_pk_bf16_f32 v124, v124, v125
	v_cvt_pk_bf16_f32 v125, v126, v127
	v_cvt_pk_bf16_f32 v126, v120, v121
	v_cvt_pk_bf16_f32 v127, v122, v123
	v_cvt_pk_bf16_f32 v104, v116, v117
	v_cvt_pk_bf16_f32 v105, v118, v119
	v_cvt_pk_bf16_f32 v106, v112, v113
	v_cvt_pk_bf16_f32 v107, v114, v115
	v_cvt_pk_bf16_f32 v88, v100, v101
	v_cvt_pk_bf16_f32 v89, v102, v103
	v_cvt_pk_bf16_f32 v90, v96, v97
	v_cvt_pk_bf16_f32 v91, v98, v99
	global_store_dwordx4 v[92:93], v[76:79], off offset:256
	v_cvt_pk_bf16_f32 v74, v80, v81
	v_cvt_pk_bf16_f32 v75, v82, v83
	v_lshl_add_u64 v[76:77], v[72:73], 0, v[172:173]
	v_cvt_pk_bf16_f32 v72, v84, v85
	v_cvt_pk_bf16_f32 v73, v86, v87
	v_cvt_pk_bf16_f32 v71, v66, v67
	v_cvt_pk_bf16_f32 v63, v58, v59
	v_cvt_pk_bf16_f32 v40, v52, v53
	v_cvt_pk_bf16_f32 v41, v54, v55
	v_cvt_pk_bf16_f32 v42, v48, v49
	v_cvt_pk_bf16_f32 v43, v50, v51
	v_cvt_pk_bf16_f32 v24, v36, v37
	v_cvt_pk_bf16_f32 v25, v38, v39
	v_cvt_pk_bf16_f32 v26, v32, v33
	v_cvt_pk_bf16_f32 v27, v34, v35
	v_lshl_add_u64 v[12:13], v[174:175], 0, s[42:43]
	v_cvt_pk_bf16_f32 v8, v20, v21
	v_cvt_pk_bf16_f32 v9, v22, v23
	v_cvt_pk_bf16_f32 v10, v16, v17
	v_cvt_pk_bf16_f32 v11, v18, v19
	v_cvt_pk_bf16_f32 v4, v4, v5
	v_cvt_pk_bf16_f32 v5, v6, v7
	v_cvt_pk_bf16_f32 v6, v0, v1
	v_cvt_pk_bf16_f32 v7, v2, v3
	s_and_b64 vcc, exec, s[2:3]
	s_mov_b32 s87, s85
	s_mov_b32 s84, s86
	s_mov_b64 s[46:47], s[0:1]
	s_mov_b64 s[44:45], s[4:5]
	global_store_dwordx4 v[174:175], v[124:127], off
	global_store_dwordx4 v[108:109], v[104:107], off
	global_store_dwordx4 v[92:93], v[88:91], off
	global_store_dwordx4 v[76:77], v[72:75], off
	global_store_dwordx4 v[76:77], v[68:71], off offset:256
	global_store_dwordx4 v[56:57], v[60:63], off
	global_store_dwordx4 v[46:47], v[40:43], off
	global_store_dwordx4 v[30:31], v[24:27], off
	global_store_dwordx4 v[14:15], v[8:11], off
	global_store_dwordx4 v[12:13], v[4:7], off offset:256
	s_cbranch_vccz .LBB0_462
	s_waitcnt vmcnt(0)
	s_cmpk_gt_u32 s55, 0xff
	s_cbranch_scc1 .LBB0_477
	s_barrier

; #define PG8_STAGE(bufoff, gbase, voff) do { _Pragma("unroll") for (int _i = 0; _i < 2; ++_i) \
;         __builtin_amdgcn_global_load_lds((const unsigned*)((const char*)(gbase) + (voff)[_i]), (PG8_LAS unsigned*)(lds + (bufoff) + ldsw + _i * 8192), 16, 0, 0); } while (0)
; #define PG8_LDA(dst, b, h) do { _Pragma("unroll") for (int m = 0; m < 4; ++m) _Pragma("unroll") for (int k = 0; k < 2; ++k) dst[m][k] = *(const PG8_LAS bf16x8*)(lds + PG8_SA(b, h) + aoff + m * 2048 + k * 1024); } while (0)
; #define PG8_LDB(dst, b, h) do { _Pragma("unroll") for (int n = 0; n < 2; ++n) _Pragma("unroll") for (int k = 0; k < 2; ++k) dst[n][k] = *(const PG8_LAS bf16x8*)(lds + PG8_SB(b, h) + boff + n * 2048 + k * 1024); } while (0)
; #define PG8_MMA(ai, bj, At, Bt) do { __builtin_amdgcn_s_setprio(1); _Pragma("unroll") for (int m = 0; m < 4; ++m) _Pragma("unroll") for (int n = 0; n < 2; ++n) _Pragma("unroll") for (int k = 0; k < 2; ++k) \
;         acc[ai][bj][m][n] = __builtin_amdgcn_mfma_f32_16x16x32_bf16(Bt[n][k], At[m][k], acc[ai][bj][m][n], 0, 0, 0); __builtin_amdgcn_s_setprio(0); } while (0)
; #define PG8_WAIT_V(n) asm volatile("s_waitcnt vmcnt(" #n ")" ::: "memory")
; #define PG8_WAIT_L(n) asm volatile("s_waitcnt lgkmcnt(" #n ")" ::: "memory")
; #define PG8_BAR __builtin_amdgcn_s_barrier()
; #define PG8_SCHED __builtin_amdgcn_sched_barrier(0)
; template <class Epi, class Sched, bool STAMP = false>
; __device__ __forceinline__ void gemm_phase(PG8_LAS unsigned char* lds, const Gemm g, const Sched& S, const Epi& E, unsigned long long* stamps) {
;     ...
;             PG8_LDB(B0, 1, 0); PG8_SCHED; PG8_LDA(At, 1, 0); PG8_STAGE(PG8_SA(0, 1), a2 + hstep, voffA);
;             PG8_WAIT_L(8); PG8_BAR; PG8_WAIT_L(0); PG8_MMA(0, 0, At, B0); PG8_BAR; PG8_SCHED;
;             PG8_LDB(B1, 1, 1); PG8_STAGE(PG8_SB(1, 0), b3, voffB);
;             PG8_BAR; PG8_WAIT_L(0); PG8_MMA(0, 1, At, B1); PG8_BAR;
;             PG8_LDA(At, 1, 1); PG8_STAGE(PG8_SA(1, 0), a3, voffA);
;             PG8_BAR; PG8_WAIT_L(0); PG8_MMA(1, 0, At, B0); PG8_BAR; PG8_SCHED;
;             PG8_STAGE(PG8_SB(1, 1), b3 + hstep, voffB);
;             PG8_WAIT_V(6); PG8_BAR; PG8_MMA(1, 1, At, B1); PG8_BAR;
.Lzp9_mid:
	ds_read_b128 v[170:173], v155
	ds_read_b128 v[174:177], v156
	ds_read_b128 v[178:181], v157
	ds_read_b128 v[182:185], v165
	s_add_u32 s40, s46, 0x44000
	s_addc_u32 s41, s47, 0
	s_mov_b32 m0, s60
	ds_read_b128 v[186:189], v145 offset:32768
	ds_read_b128 v[190:193], v145 offset:33792
	ds_read_b128 v[194:197], v145 offset:34816
	ds_read_b128 v[198:201], v145 offset:35840
	ds_read_b128 v[202:205], v145 offset:36864
	ds_read_b128 v[206:209], v145 offset:37888
	ds_read_b128 v[210:213], v145 offset:38912
	ds_read_b128 v[214:217], v145 offset:39936
	global_load_lds_dwordx4 v134, s[40:41]
	s_mov_b32 m0, s61
	s_nop 0
	global_load_lds_dwordx4 v130, s[40:41]
	s_waitcnt lgkmcnt(8)
	s_barrier
	s_waitcnt lgkmcnt(0)
	s_setprio 1
	s_waitcnt lgkmcnt(0)
	v_mfma_f32_16x16x32_bf16 v[124:127], v[170:173], v[186:189], v[124:127]
	v_mfma_f32_16x16x32_bf16 v[120:123], v[178:181], v[186:189], v[120:123]
	v_mfma_f32_16x16x32_bf16 v[116:119], v[170:173], v[194:197], v[116:119]
	v_mfma_f32_16x16x32_bf16 v[112:115], v[178:181], v[194:197], v[112:115]
	v_mfma_f32_16x16x32_bf16 v[108:111], v[170:173], v[202:205], v[108:111]
	v_mfma_f32_16x16x32_bf16 v[104:107], v[178:181], v[202:205], v[104:107]
	v_mfma_f32_16x16x32_bf16 v[100:103], v[170:173], v[210:213], v[100:103]
	v_mfma_f32_16x16x32_bf16 v[96:99], v[178:181], v[210:213], v[96:99]
	v_mfma_f32_16x16x32_bf16 v[124:127], v[174:177], v[190:193], v[124:127]
	v_mfma_f32_16x16x32_bf16 v[120:123], v[182:185], v[190:193], v[120:123]
	v_mfma_f32_16x16x32_bf16 v[116:119], v[174:177], v[198:201], v[116:119]
	v_mfma_f32_16x16x32_bf16 v[112:115], v[182:185], v[198:201], v[112:115]
	v_mfma_f32_16x16x32_bf16 v[108:111], v[174:177], v[206:209], v[108:111]
	v_mfma_f32_16x16x32_bf16 v[104:107], v[182:185], v[206:209], v[104:107]
	v_mfma_f32_16x16x32_bf16 v[100:103], v[174:177], v[214:217], v[100:103]
	v_mfma_f32_16x16x32_bf16 v[96:99], v[182:185], v[214:217], v[96:99]
	s_setprio 0
	s_barrier
	s_mov_b32 m0, s64
	ds_read_b128 v[218:221], v166
	ds_read_b128 v[222:225], v167
	ds_read_b128 v[226:229], v168
	ds_read_b128 v[230:233], v169
	s_add_u32 s100, s44, 0x80
	s_addc_u32 s101, s45, 0
	global_load_lds_dwordx4 v132, s[100:101]
	s_mov_b32 m0, s65
	s_nop 0
	global_load_lds_dwordx4 v128, s[100:101]
	s_barrier
	s_waitcnt lgkmcnt(0)
	s_setprio 1
	s_waitcnt lgkmcnt(0)
	v_mfma_f32_16x16x32_bf16 v[60:63], v[218:221], v[186:189], v[60:63]
	v_mfma_f32_16x16x32_bf16 v[56:59], v[226:229], v[186:189], v[56:59]
	v_mfma_f32_16x16x32_bf16 v[52:55], v[218:221], v[194:197], v[52:55]
	v_mfma_f32_16x16x32_bf16 v[48:51], v[226:229], v[194:197], v[48:51]
	v_mfma_f32_16x16x32_bf16 v[44:47], v[218:221], v[202:205], v[44:47]
	v_mfma_f32_16x16x32_bf16 v[40:43], v[226:229], v[202:205], v[40:43]
	v_mfma_f32_16x16x32_bf16 v[36:39], v[218:221], v[210:213], v[36:39]
	v_mfma_f32_16x16x32_bf16 v[32:35], v[226:229], v[210:213], v[32:35]
	v_mfma_f32_16x16x32_bf16 v[60:63], v[222:225], v[190:193], v[60:63]
	v_mfma_f32_16x16x32_bf16 v[56:59], v[230:233], v[190:193], v[56:59]
	v_mfma_f32_16x16x32_bf16 v[52:55], v[222:225], v[198:201], v[52:55]
	v_mfma_f32_16x16x32_bf16 v[48:51], v[230:233], v[198:201], v[48:51]
	v_mfma_f32_16x16x32_bf16 v[44:47], v[222:225], v[206:209], v[44:47]
	v_mfma_f32_16x16x32_bf16 v[40:43], v[230:233], v[206:209], v[40:43]
	v_mfma_f32_16x16x32_bf16 v[36:39], v[222:225], v[214:217], v[36:39]
	v_mfma_f32_16x16x32_bf16 v[32:35], v[230:233], v[214:217], v[32:35]
	s_setprio 0
	s_mov_b32 m0, s66
	s_barrier
	ds_read_b128 v[186:189], v145 offset:49152
	ds_read_b128 v[190:193], v145 offset:50176
	ds_read_b128 v[194:197], v145 offset:51200
	ds_read_b128 v[198:201], v145 offset:52224
	ds_read_b128 v[202:205], v145 offset:53248
	ds_read_b128 v[206:209], v145 offset:54272
	ds_read_b128 v[210:213], v145 offset:55296
	ds_read_b128 v[214:217], v145 offset:56320
	s_add_u32 s100, s46, 0x80
	s_addc_u32 s101, s47, 0
	global_load_lds_dwordx4 v134, s[100:101]
	s_mov_b32 m0, s67
	s_nop 0
	global_load_lds_dwordx4 v130, s[100:101]
	s_barrier
	s_waitcnt lgkmcnt(0)
	s_setprio 1
	s_waitcnt lgkmcnt(0)
	v_mfma_f32_16x16x32_bf16 v[92:95], v[170:173], v[186:189], v[92:95]
	v_mfma_f32_16x16x32_bf16 v[88:91], v[178:181], v[186:189], v[88:91]
	v_mfma_f32_16x16x32_bf16 v[84:87], v[170:173], v[194:197], v[84:87]
	v_mfma_f32_16x16x32_bf16 v[80:83], v[178:181], v[194:197], v[80:83]
	v_mfma_f32_16x16x32_bf16 v[76:79], v[170:173], v[202:205], v[76:79]
	v_mfma_f32_16x16x32_bf16 v[72:75], v[178:181], v[202:205], v[72:75]
	v_mfma_f32_16x16x32_bf16 v[68:71], v[170:173], v[210:213], v[68:71]
	v_mfma_f32_16x16x32_bf16 v[64:67], v[178:181], v[210:213], v[64:67]
	v_mfma_f32_16x16x32_bf16 v[92:95], v[174:177], v[190:193], v[92:95]
	v_mfma_f32_16x16x32_bf16 v[88:91], v[182:185], v[190:193], v[88:91]
	v_mfma_f32_16x16x32_bf16 v[84:87], v[174:177], v[198:201], v[84:87]
	v_mfma_f32_16x16x32_bf16 v[80:83], v[182:185], v[198:201], v[80:83]
	v_mfma_f32_16x16x32_bf16 v[76:79], v[174:177], v[206:209], v[76:79]
	v_mfma_f32_16x16x32_bf16 v[72:75], v[182:185], v[206:209], v[72:75]
	v_mfma_f32_16x16x32_bf16 v[68:71], v[174:177], v[214:217], v[68:71]
	v_mfma_f32_16x16x32_bf16 v[64:67], v[182:185], v[214:217], v[64:67]
	s_setprio 0
	s_barrier
	s_add_u32 s40, s44, 0x44080
	s_addc_u32 s41, s45, 0
	s_mov_b32 m0, s68
	s_nop 0
	global_load_lds_dwordx4 v132, s[40:41]
	s_mov_b32 m0, s69
	s_nop 0
	global_load_lds_dwordx4 v128, s[40:41]
	s_add_i32 s10, s10, 2
	s_add_u32 s81, s81, 0x100
	s_addc_u32 s82, s82, 0
	s_cmp_gt_u32 s10, 13
	s_mov_b64 s[40:41], s[42:43]
	s_waitcnt vmcnt(6)
	s_barrier
; #define PG8_STAGE(bufoff, gbase, voff) do { _Pragma("unroll") for (int _i = 0; _i < 2; ++_i) \
;         __builtin_amdgcn_global_load_lds((const unsigned*)((const char*)(gbase) + (voff)[_i]), (PG8_LAS unsigned*)(lds + (bufoff) + ldsw + _i * 8192), 16, 0, 0); } while (0)
; #define PG8_LDA(dst, b, h) do { _Pragma("unroll") for (int m = 0; m < 4; ++m) _Pragma("unroll") for (int k = 0; k < 2; ++k) dst[m][k] = *(const PG8_LAS bf16x8*)(lds + PG8_SA(b, h) + aoff + m * 2048 + k * 1024); } while (0)
; #define PG8_BAR __builtin_amdgcn_s_barrier()
;     DI void operator()(const f32x4 (&acc)[2][2][4][2], const Unit& u, int wr, int wc, int fr, int fq) const {
;         const int row0 = u.pm * BM + wr * 64 + fr, col0 = u.pn * BM + wc * 32 + 8 * fq;
; #pragma unroll
;         for (int ai = 0; ai < 2; ++ai)
; #pragma unroll
;             for (int m = 0; m < 4; ++m) { u16* rowp = O + (size_t)(row0 + ai * HALF + m * 16) * ldc + col0;
; #pragma unroll
;                 for (int bj = 0; bj < 2; ++bj) { const f32x4 v0 = acc[ai][bj][m][0], v1 = acc[ai][bj][m][1];
;                     uint4 w = {pack2(v0[0], v0[1]), pack2(v0[2], v0[3]), pack2(v1[0], v1[1]), pack2(v1[2], v1[3])}; *(uint4*)(rowp + bj * HALF) = w; } }
;         if (kmaxp) {
; #pragma unroll
;             for (int bj = 0; bj < 2; ++bj) {
;                 const int cb = u.pn * BM + bj * HALF + wc * 32;
;                 const bool isA = (cb >= 384 && cb < 768), isB = (cb >= 1408 && cb < 1664);
;                 if (isA || isB) {
; template <class Epi, class Sched, bool STAMP = false>
; __device__ __forceinline__ void gemm_phase(PG8_LAS unsigned char* lds, const Gemm g, const Sched& S, const Epi& E, unsigned long long* stamps) {
;     ...
;             PG8_WAIT_V(6); PG8_BAR; PG8_MMA(1, 1, At, B1); PG8_BAR;
;             PG8_LDB(B0, 1, 0); PG8_SCHED; PG8_LDA(At, 1, 0); PG8_STAGE(PG8_SA(0, 1), a2 + hstep, voffA);
;             PG8_WAIT_L(8); PG8_BAR; PG8_WAIT_L(0); PG8_MMA(0, 0, At, B0); PG8_BAR; PG8_SCHED;
;             PG8_LDB(B1, 1, 1); PG8_STAGE(PG8_SB(1, 0), b3, voffB);
;             PG8_BAR; PG8_WAIT_L(0); PG8_MMA(0, 1, At, B1); PG8_BAR;
;             PG8_LDA(At, 1, 1); PG8_STAGE(PG8_SA(1, 0), a3, voffA);
;             PG8_BAR; PG8_WAIT_L(0); PG8_MMA(1, 0, At, B0); PG8_BAR; PG8_SCHED;
;             PG8_STAGE(PG8_SB(1, 1), b3 + hstep, voffB);
;             PG8_WAIT_V(6); PG8_BAR; PG8_MMA(1, 1, At, B1); PG8_BAR;
	s_setprio 1
	v_mfma_f32_16x16x32_bf16 v[28:31], v[218:221], v[186:189], v[28:31]
	v_mfma_f32_16x16x32_bf16 v[24:27], v[226:229], v[186:189], v[24:27]
	v_mfma_f32_16x16x32_bf16 v[20:23], v[218:221], v[194:197], v[20:23]
	v_mfma_f32_16x16x32_bf16 v[16:19], v[226:229], v[194:197], v[16:19]
	v_mfma_f32_16x16x32_bf16 v[12:15], v[218:221], v[202:205], v[12:15]
	v_mfma_f32_16x16x32_bf16 v[8:11], v[226:229], v[202:205], v[8:11]
	v_mfma_f32_16x16x32_bf16 v[4:7], v[218:221], v[210:213], v[4:7]
	v_mfma_f32_16x16x32_bf16 v[0:3], v[226:229], v[210:213], v[0:3]
	v_mfma_f32_16x16x32_bf16 v[28:31], v[222:225], v[190:193], v[28:31]
	v_mfma_f32_16x16x32_bf16 v[24:27], v[230:233], v[190:193], v[24:27]
	v_mfma_f32_16x16x32_bf16 v[20:23], v[222:225], v[198:201], v[20:23]
	v_mfma_f32_16x16x32_bf16 v[16:19], v[230:233], v[198:201], v[16:19]
	v_mfma_f32_16x16x32_bf16 v[12:15], v[222:225], v[206:209], v[12:15]
	v_mfma_f32_16x16x32_bf16 v[8:11], v[230:233], v[206:209], v[8:11]
	v_mfma_f32_16x16x32_bf16 v[4:7], v[222:225], v[214:217], v[4:7]
	v_mfma_f32_16x16x32_bf16 v[0:3], v[230:233], v[214:217], v[0:3]
	s_setprio 0
	s_barrier
	s_cbranch_scc0 .LBB0_514
	s_lshl_b32 s46, s79, 8
	v_or_b32_e32 v170, s46, v146
	v_lshl_add_u32 v180, s80, 8, v144
	v_ashrrev_i32_e32 v171, 31, v170
	v_mov_b64_e32 v[174:175], s[12:13]
	v_mad_i64_i32 v[172:173], s[40:41], v180, s76, v[174:175]
	v_lshlrev_b64 v[176:177], 1, v[170:171]
	v_lshl_add_u64 v[178:179], v[172:173], 0, v[176:177]
	v_cvt_pk_bf16_f32 v170, v124, v125
	v_cvt_pk_bf16_f32 v171, v126, v127
	v_cvt_pk_bf16_f32 v172, v120, v121
	v_cvt_pk_bf16_f32 v173, v122, v123
	global_store_dwordx4 v[178:179], v[170:173], off
	s_or_b32 s10, s46, s63
	s_nop 0
	v_cvt_pk_bf16_f32 v170, v60, v61
	v_cvt_pk_bf16_f32 v171, v62, v63
	v_cvt_pk_bf16_f32 v172, v56, v57
	v_cvt_pk_bf16_f32 v173, v58, v59
	global_store_dwordx4 v[178:179], v[170:173], off offset:256
	s_nop 1
	v_or_b32_e32 v170, 16, v180
	v_mad_i64_i32 v[170:171], s[40:41], v170, s76, v[174:175]
	v_lshl_add_u64 v[178:179], v[170:171], 0, v[176:177]
	v_cvt_pk_bf16_f32 v170, v116, v117
	v_cvt_pk_bf16_f32 v171, v118, v119
	v_cvt_pk_bf16_f32 v172, v112, v113
	v_cvt_pk_bf16_f32 v173, v114, v115
	global_store_dwordx4 v[178:179], v[170:173], off
	s_nop 1
	v_cvt_pk_bf16_f32 v170, v52, v53
	v_cvt_pk_bf16_f32 v171, v54, v55
	v_cvt_pk_bf16_f32 v172, v48, v49
	v_cvt_pk_bf16_f32 v173, v50, v51
	global_store_dwordx4 v[178:179], v[170:173], off offset:256
	s_nop 1
	v_or_b32_e32 v170, 32, v180
	v_mad_i64_i32 v[170:171], s[40:41], v170, s76, v[174:175]
	v_lshl_add_u64 v[178:179], v[170:171], 0, v[176:177]
	v_cvt_pk_bf16_f32 v170, v108, v109
	v_cvt_pk_bf16_f32 v171, v110, v111
	v_cvt_pk_bf16_f32 v172, v104, v105
	v_cvt_pk_bf16_f32 v173, v106, v107
	global_store_dwordx4 v[178:179], v[170:173], off
	s_nop 1
	v_cvt_pk_bf16_f32 v170, v44, v45
	v_cvt_pk_bf16_f32 v171, v46, v47
	v_cvt_pk_bf16_f32 v172, v40, v41
	v_cvt_pk_bf16_f32 v173, v42, v43
	global_store_dwordx4 v[178:179], v[170:173], off offset:256
	s_nop 1
	v_or_b32_e32 v170, 48, v180
	v_mad_i64_i32 v[170:171], s[40:41], v170, s76, v[174:175]
	v_lshl_add_u64 v[178:179], v[170:171], 0, v[176:177]
	v_cvt_pk_bf16_f32 v170, v100, v101
	v_cvt_pk_bf16_f32 v171, v102, v103
	v_cvt_pk_bf16_f32 v172, v96, v97
	v_cvt_pk_bf16_f32 v173, v98, v99
	global_store_dwordx4 v[178:179], v[170:173], off
	s_nop 1
	v_cvt_pk_bf16_f32 v170, v36, v37
	v_cvt_pk_bf16_f32 v171, v38, v39
	v_cvt_pk_bf16_f32 v172, v32, v33
	v_cvt_pk_bf16_f32 v173, v34, v35
	global_store_dwordx4 v[178:179], v[170:173], off offset:256
	s_nop 1
	v_add_u32_e32 v170, 0x80, v180
	v_mad_i64_i32 v[170:171], s[40:41], v170, s76, v[174:175]
	v_lshl_add_u64 v[178:179], v[170:171], 0, v[176:177]
	v_cvt_pk_bf16_f32 v170, v92, v93
	v_cvt_pk_bf16_f32 v171, v94, v95
	v_cvt_pk_bf16_f32 v172, v88, v89
	v_cvt_pk_bf16_f32 v173, v90, v91
	global_store_dwordx4 v[178:179], v[170:173], off
	s_nop 1
	v_cvt_pk_bf16_f32 v170, v28, v29
	v_cvt_pk_bf16_f32 v171, v30, v31
	v_cvt_pk_bf16_f32 v172, v24, v25
	v_cvt_pk_bf16_f32 v173, v26, v27
	global_store_dwordx4 v[178:179], v[170:173], off offset:256
	s_nop 1
	v_add_u32_e32 v170, 0x90, v180
	v_mad_i64_i32 v[170:171], s[40:41], v170, s76, v[174:175]
	v_lshl_add_u64 v[178:179], v[170:171], 0, v[176:177]
	v_cvt_pk_bf16_f32 v170, v84, v85
	v_cvt_pk_bf16_f32 v171, v86, v87
	v_cvt_pk_bf16_f32 v172, v80, v81
	v_cvt_pk_bf16_f32 v173, v82, v83
	global_store_dwordx4 v[178:179], v[170:173], off
	s_nop 1
	v_cvt_pk_bf16_f32 v170, v20, v21
	v_cvt_pk_bf16_f32 v171, v22, v23
	v_cvt_pk_bf16_f32 v172, v16, v17
	v_cvt_pk_bf16_f32 v173, v18, v19
	global_store_dwordx4 v[178:179], v[170:173], off offset:256
	s_nop 1
	v_add_u32_e32 v170, 0xa0, v180
	v_mad_i64_i32 v[170:171], s[40:41], v170, s76, v[174:175]
	v_lshl_add_u64 v[178:179], v[170:171], 0, v[176:177]
	v_cvt_pk_bf16_f32 v170, v76, v77
	v_cvt_pk_bf16_f32 v171, v78, v79
	v_cvt_pk_bf16_f32 v172, v72, v73
	v_cvt_pk_bf16_f32 v173, v74, v75
	global_store_dwordx4 v[178:179], v[170:173], off
	s_nop 1
	v_cvt_pk_bf16_f32 v170, v12, v13
	v_cvt_pk_bf16_f32 v171, v14, v15
	v_cvt_pk_bf16_f32 v172, v8, v9
	v_cvt_pk_bf16_f32 v173, v10, v11
	global_store_dwordx4 v[178:179], v[170:173], off offset:256
	s_nop 1
	v_add_u32_e32 v170, 0xb0, v180
	v_mad_i64_i32 v[170:171], s[40:41], v170, s76, v[174:175]
	s_add_i32 s40, s46, 0xfffffe80
	s_cmpk_gt_u32 s40, 0x17f
	s_cselect_b64 s[40:41], -1, 0
	s_add_i32 s42, s46, 0xfffffa80
	s_cmpk_gt_u32 s42, 0xff
	s_cselect_b64 s[42:43], -1, 0
	v_lshl_add_u64 v[174:175], v[170:171], 0, v[176:177]
	v_cvt_pk_bf16_f32 v170, v68, v69
	v_cvt_pk_bf16_f32 v171, v70, v71
	v_cvt_pk_bf16_f32 v172, v64, v65
	v_cvt_pk_bf16_f32 v173, v66, v67
	s_and_b64 s[42:43], s[40:41], s[42:43]
	global_store_dwordx4 v[174:175], v[170:173], off
	s_and_b64 vcc, exec, s[42:43]
	s_nop 0
	v_cvt_pk_bf16_f32 v170, v4, v5
	v_cvt_pk_bf16_f32 v171, v6, v7
	v_cvt_pk_bf16_f32 v172, v0, v1
	v_cvt_pk_bf16_f32 v173, v2, v3
	global_store_dwordx4 v[174:175], v[170:173], off offset:256
	s_cbranch_vccnz .LBB0_526
;     DI void operator()(const f32x4 (&acc)[2][2][4][2], const Unit& u, int wr, int wc, int fr, int fq) const {
;     ...
;                     float mx = 0.f;
; #pragma unroll
;                     for (int ai = 0; ai < 2; ++ai)
; #pragma unroll
;                         for (int m = 0; m < 4; ++m) {
;                             const f32x4 a = acc[ai][bj][m][0], b = acc[ai][bj][m][1];
;                             float s0 = a[0] * a[0] + a[1] * a[1] + a[2] * a[2] + a[3] * a[3] + b[0] * b[0] + b[1] * b[1] + b[2] * b[2] + b[3] * b[3];
;                             s0 += __shfl_xor(s0, 16);
;                             s0 += __shfl_xor(s0, 32);
;                             mx = fmaxf(mx, s0);
;                         }
; #pragma unroll
;                     for (int o = 1; o <= 8; o <<= 1) mx = fmaxf(mx, __shfl_xor(mx, o));
;                     if ((threadIdx.x & 63) == 0) atomicMax((unsigned*)kmaxp + (isA ? ((cb - 384) >> 5) : (12 + ((cb - 1408) >> 5))), __float_as_uint(mx));
	v_mul_f32_e32 v125, v125, v125
	v_mul_f32_e32 v117, v117, v117
	v_fmac_f32_e32 v125, v124, v124
	v_fmac_f32_e32 v117, v116, v116
	v_mul_f32_e32 v109, v109, v109
	v_mul_f32_e32 v101, v101, v101
	v_fmac_f32_e32 v125, v126, v126
	v_fmac_f32_e32 v117, v118, v118
	v_fmac_f32_e32 v109, v108, v108
	v_fmac_f32_e32 v101, v100, v100
	v_fmac_f32_e32 v125, v127, v127
	v_fmac_f32_e32 v117, v119, v119
	v_fmac_f32_e32 v109, v110, v110
	v_fmac_f32_e32 v101, v102, v102
	v_fmac_f32_e32 v125, v120, v120
	v_fmac_f32_e32 v117, v112, v112
	v_fmac_f32_e32 v109, v111, v111
	v_fmac_f32_e32 v101, v103, v103
	v_fmac_f32_e32 v125, v121, v121
	v_fmac_f32_e32 v117, v113, v113
	v_fmac_f32_e32 v109, v104, v104
	v_fmac_f32_e32 v101, v96, v96
	v_fmac_f32_e32 v125, v122, v122
	v_fmac_f32_e32 v117, v114, v114
	v_fmac_f32_e32 v109, v105, v105
	v_fmac_f32_e32 v101, v97, v97
	v_fmac_f32_e32 v125, v123, v123
	v_fmac_f32_e32 v117, v115, v115
	v_fmac_f32_e32 v109, v106, v106
	v_fmac_f32_e32 v101, v98, v98
	v_mul_f32_e32 v93, v93, v93
	v_mul_f32_e32 v85, v85, v85
	ds_bpermute_b32 v120, v160, v125
	ds_bpermute_b32 v112, v160, v117
	v_fmac_f32_e32 v109, v107, v107
	v_fmac_f32_e32 v101, v99, v99
	v_fmac_f32_e32 v93, v92, v92
	v_fmac_f32_e32 v85, v84, v84
	v_mul_f32_e32 v77, v77, v77
	v_mul_f32_e32 v69, v69, v69
	ds_bpermute_b32 v104, v160, v109
	ds_bpermute_b32 v96, v160, v101
	v_fmac_f32_e32 v93, v94, v94
	v_fmac_f32_e32 v85, v86, v86
	v_fmac_f32_e32 v77, v76, v76
	v_fmac_f32_e32 v69, v68, v68
	v_fmac_f32_e32 v93, v95, v95
	v_fmac_f32_e32 v85, v87, v87
	v_fmac_f32_e32 v77, v78, v78
	v_fmac_f32_e32 v69, v70, v70
	v_fmac_f32_e32 v93, v88, v88
	v_fmac_f32_e32 v85, v80, v80
	v_fmac_f32_e32 v77, v79, v79
	v_fmac_f32_e32 v69, v71, v71
	v_fmac_f32_e32 v93, v89, v89
	v_fmac_f32_e32 v85, v81, v81
	v_fmac_f32_e32 v77, v72, v72
	v_fmac_f32_e32 v69, v64, v64
	s_waitcnt lgkmcnt(0)
	v_add_f32_e32 v113, v125, v120
	v_add_f32_e32 v112, v117, v112
	v_fmac_f32_e32 v93, v90, v90
	v_fmac_f32_e32 v85, v82, v82
	v_fmac_f32_e32 v77, v73, v73
	v_fmac_f32_e32 v69, v65, v65
	ds_bpermute_b32 v114, v159, v113
	ds_bpermute_b32 v115, v159, v112
	v_add_f32_e32 v99, v109, v104
	v_add_f32_e32 v96, v101, v96
	v_fmac_f32_e32 v93, v91, v91
	v_fmac_f32_e32 v85, v83, v83
	v_fmac_f32_e32 v77, v74, v74
	v_fmac_f32_e32 v69, v66, v66
	ds_bpermute_b32 v100, v159, v99
	ds_bpermute_b32 v101, v159, v96
	ds_bpermute_b32 v88, v160, v93
	ds_bpermute_b32 v80, v160, v85
	v_fmac_f32_e32 v77, v75, v75
	v_fmac_f32_e32 v69, v67, v67
	ds_bpermute_b32 v72, v160, v77
	ds_bpermute_b32 v64, v160, v69
	s_waitcnt lgkmcnt(0)
	v_add_f32_e32 v97, v113, v114
	v_add_f32_e32 v98, v112, v115
	v_max3_f32 v89, v97, 0, v98
	v_add_f32_e32 v90, v99, v100
	v_add_f32_e32 v91, v96, v101
	v_add_f32_e32 v88, v93, v88
	v_add_f32_e32 v65, v85, v80
	v_max3_f32 v89, v89, v90, v91
	ds_bpermute_b32 v90, v159, v88
	ds_bpermute_b32 v66, v159, v65
	v_add_f32_e32 v67, v77, v72
	v_add_f32_e32 v64, v69, v64
	ds_bpermute_b32 v68, v159, v67
	ds_bpermute_b32 v69, v159, v64
	s_waitcnt lgkmcnt(0)
	v_add_f32_e32 v70, v88, v90
	v_add_f32_e32 v65, v65, v66
	v_max3_f32 v65, v89, v70, v65
	v_add_f32_e32 v66, v67, v68
	v_add_f32_e32 v64, v64, v69
	v_max3_f32 v64, v65, v66, v64
	ds_bpermute_b32 v65, v164, v64
	s_waitcnt lgkmcnt(0)
	v_max_f32_e32 v65, v65, v65
	v_max_f32_e32 v64, v64, v65
	ds_bpermute_b32 v65, v163, v64
	s_waitcnt lgkmcnt(0)
	v_max_f32_e32 v65, v65, v65
	v_max_f32_e32 v64, v64, v65
	ds_bpermute_b32 v65, v162, v64
	s_waitcnt lgkmcnt(0)
	v_max_f32_e32 v65, v65, v65
	v_max_f32_e32 v64, v64, v65
	ds_bpermute_b32 v65, v161, v64
	s_and_saveexec_b64 s[42:43], s[2:3]
	s_cbranch_execz .LBB0_525
	s_mov_b64 s[44:45], -1
	s_and_b64 vcc, exec, s[40:41]
	s_cbranch_vccz .LBB0_519
	s_add_i32 s40, s10, 0xfffffa80
	s_ashr_i32 s40, s40, 5
	s_add_i32 s40, s40, 12
	s_mov_b64 s[44:45], 0

; #define PG8_STAGE(bufoff, gbase, voff) do { _Pragma("unroll") for (int _i = 0; _i < 2; ++_i) \
;         __builtin_amdgcn_global_load_lds((const unsigned*)((const char*)(gbase) + (voff)[_i]), (PG8_LAS unsigned*)(lds + (bufoff) + ldsw + _i * 8192), 16, 0, 0); } while (0)
; #define PG8_LDA(dst, b, h) do { _Pragma("unroll") for (int m = 0; m < 4; ++m) _Pragma("unroll") for (int k = 0; k < 2; ++k) dst[m][k] = *(const PG8_LAS bf16x8*)(lds + PG8_SA(b, h) + aoff + m * 2048 + k * 1024); } while (0)
; #define PG8_LDB(dst, b, h) do { _Pragma("unroll") for (int n = 0; n < 2; ++n) _Pragma("unroll") for (int k = 0; k < 2; ++k) dst[n][k] = *(const PG8_LAS bf16x8*)(lds + PG8_SB(b, h) + boff + n * 2048 + k * 1024); } while (0)
; #define PG8_MMA(ai, bj, At, Bt) do { __builtin_amdgcn_s_setprio(1); _Pragma("unroll") for (int m = 0; m < 4; ++m) _Pragma("unroll") for (int n = 0; n < 2; ++n) _Pragma("unroll") for (int k = 0; k < 2; ++k) \
;         acc[ai][bj][m][n] = __builtin_amdgcn_mfma_f32_16x16x32_bf16(Bt[n][k], At[m][k], acc[ai][bj][m][n], 0, 0, 0); __builtin_amdgcn_s_setprio(0); } while (0)
; #define PG8_WAIT_V(n) asm volatile("s_waitcnt vmcnt(" #n ")" ::: "memory")
; #define PG8_WAIT_L(n) asm volatile("s_waitcnt lgkmcnt(" #n ")" ::: "memory")
; #define PG8_BAR __builtin_amdgcn_s_barrier()
; #define PG8_SCHED __builtin_amdgcn_sched_barrier(0)
; template <class Epi, class Sched, bool STAMP = false>
; __device__ __forceinline__ void gemm_phase(PG8_LAS unsigned char* lds, const Gemm g, const Sched& S, const Epi& E, unsigned long long* stamps) {
;     ...
;             PG8_LDB(B0, 1, 0); PG8_SCHED; PG8_LDA(At, 1, 0); PG8_STAGE(PG8_SA(0, 1), a2 + hstep, voffA);
;             PG8_WAIT_L(8); PG8_BAR; PG8_WAIT_L(0); PG8_MMA(0, 0, At, B0); PG8_BAR; PG8_SCHED;
;             PG8_LDB(B1, 1, 1); PG8_STAGE(PG8_SB(1, 0), b3, voffB);
;             PG8_BAR; PG8_WAIT_L(0); PG8_MMA(0, 1, At, B1); PG8_BAR;
;             PG8_LDA(At, 1, 1); PG8_STAGE(PG8_SA(1, 0), a3, voffA);
;             PG8_BAR; PG8_WAIT_L(0); PG8_MMA(1, 0, At, B0); PG8_BAR; PG8_SCHED;
;             PG8_STAGE(PG8_SB(1, 1), b3 + hstep, voffB);
;             PG8_WAIT_V(6); PG8_BAR; PG8_MMA(1, 1, At, B1); PG8_BAR;
.Lzp10_mid:
	ds_read_b128 v[170:173], v155
	ds_read_b128 v[174:177], v156
	ds_read_b128 v[178:181], v157
	ds_read_b128 v[182:185], v165
	s_add_u32 s34, s42, 0x44000
	s_addc_u32 s35, s43, 0
	s_mov_b32 m0, s53
	ds_read_b128 v[186:189], v145 offset:32768
	ds_read_b128 v[190:193], v145 offset:33792
	ds_read_b128 v[194:197], v145 offset:34816
	ds_read_b128 v[198:201], v145 offset:35840
	ds_read_b128 v[202:205], v145 offset:36864
	ds_read_b128 v[206:209], v145 offset:37888
	ds_read_b128 v[210:213], v145 offset:38912
	ds_read_b128 v[214:217], v145 offset:39936
	global_load_lds_dwordx4 v128, s[34:35]
	s_mov_b32 m0, s54
	s_nop 0
	global_load_lds_dwordx4 v132, s[34:35]
	s_waitcnt lgkmcnt(8)
	s_barrier
	s_waitcnt lgkmcnt(0)
	s_setprio 1
	s_waitcnt lgkmcnt(0)
	v_mfma_f32_16x16x32_bf16 v[124:127], v[170:173], v[186:189], v[124:127]
	v_mfma_f32_16x16x32_bf16 v[120:123], v[178:181], v[186:189], v[120:123]
	v_mfma_f32_16x16x32_bf16 v[116:119], v[170:173], v[194:197], v[116:119]
	v_mfma_f32_16x16x32_bf16 v[112:115], v[178:181], v[194:197], v[112:115]
	v_mfma_f32_16x16x32_bf16 v[100:103], v[170:173], v[202:205], v[100:103]
	v_mfma_f32_16x16x32_bf16 v[96:99], v[178:181], v[202:205], v[96:99]
	v_mfma_f32_16x16x32_bf16 v[84:87], v[170:173], v[210:213], v[84:87]
	v_mfma_f32_16x16x32_bf16 v[80:83], v[178:181], v[210:213], v[80:83]
	v_mfma_f32_16x16x32_bf16 v[124:127], v[174:177], v[190:193], v[124:127]
	v_mfma_f32_16x16x32_bf16 v[120:123], v[182:185], v[190:193], v[120:123]
	v_mfma_f32_16x16x32_bf16 v[116:119], v[174:177], v[198:201], v[116:119]
	v_mfma_f32_16x16x32_bf16 v[112:115], v[182:185], v[198:201], v[112:115]
	v_mfma_f32_16x16x32_bf16 v[100:103], v[174:177], v[206:209], v[100:103]
	v_mfma_f32_16x16x32_bf16 v[96:99], v[182:185], v[206:209], v[96:99]
	v_mfma_f32_16x16x32_bf16 v[84:87], v[174:177], v[214:217], v[84:87]
	v_mfma_f32_16x16x32_bf16 v[80:83], v[182:185], v[214:217], v[80:83]
	s_setprio 0
	s_barrier
	s_mov_b32 m0, s55
	ds_read_b128 v[218:221], v166
	ds_read_b128 v[222:225], v167
	ds_read_b128 v[226:229], v168
	ds_read_b128 v[230:233], v169
	s_add_u32 s100, s40, 0x80
	s_addc_u32 s101, s41, 0
	global_load_lds_dwordx4 v130, s[100:101]
	s_mov_b32 m0, s56
	s_nop 0
	global_load_lds_dwordx4 v134, s[100:101]
	s_barrier
	s_waitcnt lgkmcnt(0)
	s_setprio 1
	s_waitcnt lgkmcnt(0)
	v_mfma_f32_16x16x32_bf16 v[108:111], v[218:221], v[186:189], v[108:111]
	v_mfma_f32_16x16x32_bf16 v[104:107], v[226:229], v[186:189], v[104:107]
	v_mfma_f32_16x16x32_bf16 v[92:95], v[218:221], v[194:197], v[92:95]
	v_mfma_f32_16x16x32_bf16 v[88:91], v[226:229], v[194:197], v[88:91]
	v_mfma_f32_16x16x32_bf16 v[76:79], v[218:221], v[202:205], v[76:79]
	v_mfma_f32_16x16x32_bf16 v[72:75], v[226:229], v[202:205], v[72:75]
	v_mfma_f32_16x16x32_bf16 v[68:71], v[218:221], v[210:213], v[68:71]
	v_mfma_f32_16x16x32_bf16 v[64:67], v[226:229], v[210:213], v[64:67]
	v_mfma_f32_16x16x32_bf16 v[108:111], v[222:225], v[190:193], v[108:111]
	v_mfma_f32_16x16x32_bf16 v[104:107], v[230:233], v[190:193], v[104:107]
	v_mfma_f32_16x16x32_bf16 v[92:95], v[222:225], v[198:201], v[92:95]
	v_mfma_f32_16x16x32_bf16 v[88:91], v[230:233], v[198:201], v[88:91]
	v_mfma_f32_16x16x32_bf16 v[76:79], v[222:225], v[206:209], v[76:79]
	v_mfma_f32_16x16x32_bf16 v[72:75], v[230:233], v[206:209], v[72:75]
	v_mfma_f32_16x16x32_bf16 v[68:71], v[222:225], v[214:217], v[68:71]
	v_mfma_f32_16x16x32_bf16 v[64:67], v[230:233], v[214:217], v[64:67]
	s_setprio 0
	s_mov_b32 m0, s57
	s_barrier
	ds_read_b128 v[186:189], v145 offset:49152
	ds_read_b128 v[190:193], v145 offset:50176
	ds_read_b128 v[194:197], v145 offset:51200
	ds_read_b128 v[198:201], v145 offset:52224
	ds_read_b128 v[202:205], v145 offset:53248
	ds_read_b128 v[206:209], v145 offset:54272
	ds_read_b128 v[210:213], v145 offset:55296
	ds_read_b128 v[214:217], v145 offset:56320
	s_add_u32 s100, s42, 0x80
	s_addc_u32 s101, s43, 0
	global_load_lds_dwordx4 v128, s[100:101]
	s_mov_b32 m0, s58
	s_nop 0
	global_load_lds_dwordx4 v132, s[100:101]
	s_barrier
	s_waitcnt lgkmcnt(0)
	s_setprio 1
	s_waitcnt lgkmcnt(0)
	v_mfma_f32_16x16x32_bf16 v[60:63], v[170:173], v[186:189], v[60:63]
	v_mfma_f32_16x16x32_bf16 v[56:59], v[178:181], v[186:189], v[56:59]
	v_mfma_f32_16x16x32_bf16 v[52:55], v[170:173], v[194:197], v[52:55]
	v_mfma_f32_16x16x32_bf16 v[48:51], v[178:181], v[194:197], v[48:51]
	v_mfma_f32_16x16x32_bf16 v[36:39], v[170:173], v[202:205], v[36:39]
	v_mfma_f32_16x16x32_bf16 v[32:35], v[178:181], v[202:205], v[32:35]
	v_mfma_f32_16x16x32_bf16 v[20:23], v[170:173], v[210:213], v[20:23]
	v_mfma_f32_16x16x32_bf16 v[16:19], v[178:181], v[210:213], v[16:19]
	v_mfma_f32_16x16x32_bf16 v[60:63], v[174:177], v[190:193], v[60:63]
	v_mfma_f32_16x16x32_bf16 v[56:59], v[182:185], v[190:193], v[56:59]
	v_mfma_f32_16x16x32_bf16 v[52:55], v[174:177], v[198:201], v[52:55]
	v_mfma_f32_16x16x32_bf16 v[48:51], v[182:185], v[198:201], v[48:51]
	v_mfma_f32_16x16x32_bf16 v[36:39], v[174:177], v[206:209], v[36:39]
	v_mfma_f32_16x16x32_bf16 v[32:35], v[182:185], v[206:209], v[32:35]
	v_mfma_f32_16x16x32_bf16 v[20:23], v[174:177], v[214:217], v[20:23]
	v_mfma_f32_16x16x32_bf16 v[16:19], v[182:185], v[214:217], v[16:19]
	s_setprio 0
	s_barrier
	s_add_u32 s34, s40, 0x44080
	s_addc_u32 s35, s41, 0
	s_mov_b32 m0, s59
	s_nop 0
	global_load_lds_dwordx4 v130, s[34:35]
	s_mov_b32 m0, s60
	s_nop 0
	global_load_lds_dwordx4 v134, s[34:35]
	s_add_i32 s10, s10, 2
	s_add_u32 s76, s76, 0x100
	s_addc_u32 s77, s77, 0
	s_cmp_gt_u32 s10, 13
	s_mov_b64 s[34:35], s[36:37]
	s_waitcnt vmcnt(6)
	s_barrier
; #define PG8_STAMP() do { if (STAMP && wid == 0 && nts < 64) { const unsigned long long _c = 0ull; \
;         ts_lo = (lane == nts) ? (int)(unsigned)_c : ts_lo; ts_hi = (lane == nts) ? (int)(unsigned)(_c >> 32) : ts_hi; ++nts; } } while (0)
;     DI void operator()(const f32x4 (&acc)[2][2][4][2], const Unit& u, int wr, int wc, int fr, int fq) const {
;         const int row0 = u.pm * BM + wr * 64 + fr, col0 = u.pn * BM + wc * 32 + 8 * fq;
; #pragma unroll
;         for (int ai = 0; ai < 2; ++ai)
; #pragma unroll
;             for (int m = 0; m < 4; ++m) { u16* rowp = O + (size_t)(row0 + ai * HALF + m * 16) * ldc + col0;
; #pragma unroll
;                 for (int bj = 0; bj < 2; ++bj) { const f32x4 v0 = acc[ai][bj][m][0], v1 = acc[ai][bj][m][1];
;                     uint4 w = {pack2(v0[0], v0[1]), pack2(v0[2], v0[3]), pack2(v1[0], v1[1]), pack2(v1[2], v1[3])}; *(uint4*)(rowp + bj * HALF) = w; } }
; template <class Epi, class Sched, bool STAMP = false>
; __device__ __forceinline__ void gemm_phase(PG8_LAS unsigned char* lds, const Gemm g, const Sched& S, const Epi& E, unsigned long long* stamps) {
;     ...
;             PG8_WAIT_V(6); PG8_BAR; PG8_MMA(1, 1, At, B1); PG8_BAR;
;             PG8_LDB(B0, 1, 0); PG8_SCHED; PG8_LDA(At, 1, 0); PG8_STAGE(PG8_SA(0, 1), a2 + hstep, voffA);
;             PG8_WAIT_L(8); PG8_BAR; PG8_WAIT_L(0); PG8_MMA(0, 0, At, B0); PG8_BAR; PG8_SCHED;
;             PG8_LDB(B1, 1, 1); PG8_STAGE(PG8_SB(1, 0), b3, voffB);
;             PG8_BAR; PG8_WAIT_L(0); PG8_MMA(0, 1, At, B1); PG8_BAR;
;             PG8_LDA(At, 1, 1); PG8_STAGE(PG8_SA(1, 0), a3, voffA);
;             PG8_BAR; PG8_WAIT_L(0); PG8_MMA(1, 0, At, B0); PG8_BAR; PG8_SCHED;
;             PG8_STAGE(PG8_SB(1, 1), b3 + hstep, voffB);
;             PG8_WAIT_V(6); PG8_BAR; PG8_MMA(1, 1, At, B1); PG8_BAR;
;         }
;         PG8_STAMP();
;         if constexpr (!Epi::AFTER_DRAIN) { E(acc, cur, wr, wc, fr, fq); S.done(cur); }
;         PG8_STAMP();
;         if (!has_next) break;
; #pragma unroll
;         for (int a = 0; a < 2; ++a)
; #pragma unroll
;             for (int b = 0; b < 2; ++b)
; #pragma unroll
;                 for (int m = 0; m < 4; ++m)
; #pragma unroll
;                     for (int n = 0; n < 2; ++n) acc[a][b][m][n] = (f32x4){0.f, 0.f, 0.f, 0.f};
;         cur = nxt; cA = nA; cB = nB; ++ui;
;     }
;     PG8_WAIT_V(0);
;     if (wr == 0) PG8_BAR;
;     PG8_BAR;
	s_setprio 1
	v_mfma_f32_16x16x32_bf16 v[44:47], v[218:221], v[186:189], v[44:47]
	v_mfma_f32_16x16x32_bf16 v[40:43], v[226:229], v[186:189], v[40:43]
	v_mfma_f32_16x16x32_bf16 v[28:31], v[218:221], v[194:197], v[28:31]
	v_mfma_f32_16x16x32_bf16 v[24:27], v[226:229], v[194:197], v[24:27]
	v_mfma_f32_16x16x32_bf16 v[12:15], v[218:221], v[202:205], v[12:15]
	v_mfma_f32_16x16x32_bf16 v[8:11], v[226:229], v[202:205], v[8:11]
	v_mfma_f32_16x16x32_bf16 v[4:7], v[218:221], v[210:213], v[4:7]
	v_mfma_f32_16x16x32_bf16 v[0:3], v[226:229], v[210:213], v[0:3]
	v_mfma_f32_16x16x32_bf16 v[44:47], v[222:225], v[190:193], v[44:47]
	v_mfma_f32_16x16x32_bf16 v[40:43], v[230:233], v[190:193], v[40:43]
	v_mfma_f32_16x16x32_bf16 v[28:31], v[222:225], v[198:201], v[28:31]
	v_mfma_f32_16x16x32_bf16 v[24:27], v[230:233], v[198:201], v[24:27]
	v_mfma_f32_16x16x32_bf16 v[12:15], v[222:225], v[206:209], v[12:15]
	v_mfma_f32_16x16x32_bf16 v[8:11], v[230:233], v[206:209], v[8:11]
	v_mfma_f32_16x16x32_bf16 v[4:7], v[222:225], v[214:217], v[4:7]
	v_mfma_f32_16x16x32_bf16 v[0:3], v[230:233], v[214:217], v[0:3]
	s_setprio 0
	s_barrier
	s_cbranch_scc0 .LBB0_688
	v_lshl_add_u32 v170, s69, 8, v144
	v_lshl_or_b32 v172, s75, 8, v146
	v_ashrrev_i32_e32 v171, 31, v170
	v_ashrrev_i32_e32 v173, 31, v172
	v_lshlrev_b64 v[174:175], 11, v[170:171]
	v_lshl_add_u64 v[174:175], s[14:15], 0, v[174:175]
	v_lshlrev_b64 v[172:173], 1, v[172:173]
	v_lshl_add_u64 v[174:175], v[174:175], 0, v[172:173]
	v_cvt_pk_bf16_f32 v60, v60, v61
	v_cvt_pk_bf16_f32 v61, v62, v63
	v_cvt_pk_bf16_f32 v62, v56, v57
	v_add_co_u32_e32 v56, vcc, s65, v174
	v_cvt_pk_bf16_f32 v68, v68, v69
	v_cvt_pk_bf16_f32 v69, v70, v71
	v_cvt_pk_bf16_f32 v70, v64, v65
	v_lshl_add_u64 v[64:65], v[174:175], 0, s[16:17]
	v_addc_co_u32_e32 v57, vcc, 0, v175, vcc
	v_cvt_pk_bf16_f32 v44, v44, v45
	v_cvt_pk_bf16_f32 v45, v46, v47
	v_cvt_pk_bf16_f32 v46, v40, v41
	v_cvt_pk_bf16_f32 v47, v42, v43
	v_cvt_pk_bf16_f32 v108, v108, v109
	v_cvt_pk_bf16_f32 v109, v110, v111
	v_cvt_pk_bf16_f32 v110, v104, v105
	v_or_b32_e32 v104, 16, v170
	global_store_dwordx4 v[64:65], v[44:47], off offset:256
	v_ashrrev_i32_e32 v105, 31, v104
	v_cvt_pk_bf16_f32 v92, v92, v93
	v_add_co_u32_e32 v46, vcc, s66, v174
	v_cvt_pk_bf16_f32 v93, v94, v95
	v_cvt_pk_bf16_f32 v94, v88, v89
	v_or_b32_e32 v88, 32, v170
	v_lshl_add_u64 v[44:45], v[174:175], 0, s[18:19]
	v_addc_co_u32_e32 v47, vcc, 0, v175, vcc
	v_cvt_pk_bf16_f32 v28, v28, v29
	v_cvt_pk_bf16_f32 v29, v30, v31
	v_cvt_pk_bf16_f32 v30, v24, v25
	v_cvt_pk_bf16_f32 v31, v26, v27
	v_lshlrev_b64 v[104:105], 11, v[104:105]
	v_ashrrev_i32_e32 v89, 31, v88
	v_cvt_pk_bf16_f32 v76, v76, v77
	v_cvt_pk_bf16_f32 v77, v78, v79
	v_cvt_pk_bf16_f32 v78, v72, v73
	v_or_b32_e32 v72, 48, v170
	global_store_dwordx4 v[44:45], v[28:31], off offset:256
	v_cvt_pk_bf16_f32 v111, v106, v107
	v_lshl_add_u64 v[104:105], s[14:15], 0, v[104:105]
	v_add_co_u32_e32 v30, vcc, s67, v174
	v_lshlrev_b64 v[88:89], 11, v[88:89]
	v_ashrrev_i32_e32 v73, 31, v72
	v_lshl_add_u64 v[28:29], v[174:175], 0, s[20:21]
	v_addc_co_u32_e32 v31, vcc, 0, v175, vcc
	v_cvt_pk_bf16_f32 v12, v12, v13
	v_cvt_pk_bf16_f32 v13, v14, v15
	v_cvt_pk_bf16_f32 v14, v8, v9
	v_cvt_pk_bf16_f32 v15, v10, v11
	global_store_dwordx4 v[174:175], v[108:111], off offset:256
	v_cvt_pk_bf16_f32 v95, v90, v91
	v_lshl_add_u64 v[88:89], s[14:15], 0, v[88:89]
	v_lshl_add_u64 v[108:109], v[104:105], 0, v[172:173]
	v_lshlrev_b64 v[72:73], 11, v[72:73]
	global_store_dwordx4 v[28:29], v[12:15], off offset:256
	global_store_dwordx4 v[108:109], v[92:95], off offset:256
	v_cvt_pk_bf16_f32 v79, v74, v75
	v_add_co_u32_e32 v14, vcc, s68, v174
	v_lshl_add_u64 v[92:93], v[88:89], 0, v[172:173]
	v_lshl_add_u64 v[72:73], s[14:15], 0, v[72:73]
	v_addc_co_u32_e32 v15, vcc, 0, v175, vcc
	v_cvt_pk_bf16_f32 v124, v124, v125
	v_cvt_pk_bf16_f32 v125, v126, v127
	v_cvt_pk_bf16_f32 v126, v120, v121
	v_cvt_pk_bf16_f32 v127, v122, v123
	v_cvt_pk_bf16_f32 v104, v116, v117
	v_cvt_pk_bf16_f32 v105, v118, v119
	v_cvt_pk_bf16_f32 v106, v112, v113
	v_cvt_pk_bf16_f32 v107, v114, v115
	v_cvt_pk_bf16_f32 v88, v100, v101
	v_cvt_pk_bf16_f32 v89, v102, v103
	v_cvt_pk_bf16_f32 v90, v96, v97
	v_cvt_pk_bf16_f32 v91, v98, v99
	global_store_dwordx4 v[92:93], v[76:79], off offset:256
	v_cvt_pk_bf16_f32 v74, v80, v81
	v_cvt_pk_bf16_f32 v75, v82, v83
	v_lshl_add_u64 v[76:77], v[72:73], 0, v[172:173]
	v_cvt_pk_bf16_f32 v72, v84, v85
	v_cvt_pk_bf16_f32 v73, v86, v87
	v_cvt_pk_bf16_f32 v71, v66, v67
	v_cvt_pk_bf16_f32 v63, v58, v59
	v_cvt_pk_bf16_f32 v40, v52, v53
	v_cvt_pk_bf16_f32 v41, v54, v55
	v_cvt_pk_bf16_f32 v42, v48, v49
	v_cvt_pk_bf16_f32 v43, v50, v51
	v_cvt_pk_bf16_f32 v24, v36, v37
	v_cvt_pk_bf16_f32 v25, v38, v39
	v_cvt_pk_bf16_f32 v26, v32, v33
	v_cvt_pk_bf16_f32 v27, v34, v35
	v_lshl_add_u64 v[12:13], v[174:175], 0, s[28:29]
	v_cvt_pk_bf16_f32 v8, v20, v21
	v_cvt_pk_bf16_f32 v9, v22, v23
	v_cvt_pk_bf16_f32 v10, v16, v17
	v_cvt_pk_bf16_f32 v11, v18, v19
	v_cvt_pk_bf16_f32 v4, v4, v5
	v_cvt_pk_bf16_f32 v5, v6, v7
	v_cvt_pk_bf16_f32 v6, v0, v1
	v_cvt_pk_bf16_f32 v7, v2, v3
	s_and_b64 vcc, exec, s[2:3]
	s_mov_b32 s75, s70
	s_mov_b32 s69, s71
	s_mov_b64 s[36:37], s[0:1]
	s_mov_b64 s[34:35], s[4:5]
	global_store_dwordx4 v[174:175], v[124:127], off
	global_store_dwordx4 v[108:109], v[104:107], off
	global_store_dwordx4 v[92:93], v[88:91], off
	global_store_dwordx4 v[76:77], v[72:75], off
	global_store_dwordx4 v[76:77], v[68:71], off offset:256
	global_store_dwordx4 v[56:57], v[60:63], off
	global_store_dwordx4 v[46:47], v[40:43], off
	global_store_dwordx4 v[30:31], v[24:27], off
	global_store_dwordx4 v[14:15], v[8:11], off
	global_store_dwordx4 v[12:13], v[4:7], off offset:256
	s_cbranch_vccz .LBB0_677
	s_waitcnt vmcnt(0)
	s_cmpk_gt_u32 s45, 0xff
	s_cbranch_scc1 .LBB0_692
	s_barrier

; #define PG8_STAGE(bufoff, gbase, voff) do { _Pragma("unroll") for (int _i = 0; _i < 2; ++_i) \
;         __builtin_amdgcn_global_load_lds((const unsigned*)((const char*)(gbase) + (voff)[_i]), (PG8_LAS unsigned*)(lds + (bufoff) + ldsw + _i * 8192), 16, 0, 0); } while (0)
; #define PG8_LDA(dst, b, h) do { _Pragma("unroll") for (int m = 0; m < 4; ++m) _Pragma("unroll") for (int k = 0; k < 2; ++k) dst[m][k] = *(const PG8_LAS bf16x8*)(lds + PG8_SA(b, h) + aoff + m * 2048 + k * 1024); } while (0)
; #define PG8_LDB(dst, b, h) do { _Pragma("unroll") for (int n = 0; n < 2; ++n) _Pragma("unroll") for (int k = 0; k < 2; ++k) dst[n][k] = *(const PG8_LAS bf16x8*)(lds + PG8_SB(b, h) + boff + n * 2048 + k * 1024); } while (0)
; #define PG8_MMA(ai, bj, At, Bt) do { __builtin_amdgcn_s_setprio(1); _Pragma("unroll") for (int m = 0; m < 4; ++m) _Pragma("unroll") for (int n = 0; n < 2; ++n) _Pragma("unroll") for (int k = 0; k < 2; ++k) \
;         acc[ai][bj][m][n] = __builtin_amdgcn_mfma_f32_16x16x32_bf16(Bt[n][k], At[m][k], acc[ai][bj][m][n], 0, 0, 0); __builtin_amdgcn_s_setprio(0); } while (0)
; #define PG8_WAIT_V(n) asm volatile("s_waitcnt vmcnt(" #n ")" ::: "memory")
; #define PG8_WAIT_L(n) asm volatile("s_waitcnt lgkmcnt(" #n ")" ::: "memory")
; #define PG8_BAR __builtin_amdgcn_s_barrier()
; #define PG8_SCHED __builtin_amdgcn_sched_barrier(0)
; template <class Epi, class Sched, bool STAMP = false>
; __device__ __forceinline__ void gemm_phase(PG8_LAS unsigned char* lds, const Gemm g, const Sched& S, const Epi& E, unsigned long long* stamps) {
;     ...
;             PG8_LDB(B0, 1, 0); PG8_SCHED; PG8_LDA(At, 1, 0); PG8_STAGE(PG8_SA(0, 1), a2 + hstep, voffA);
;             PG8_WAIT_L(8); PG8_BAR; PG8_WAIT_L(0); PG8_MMA(0, 0, At, B0); PG8_BAR; PG8_SCHED;
;             PG8_LDB(B1, 1, 1); PG8_STAGE(PG8_SB(1, 0), b3, voffB);
;             PG8_BAR; PG8_WAIT_L(0); PG8_MMA(0, 1, At, B1); PG8_BAR;
;             PG8_LDA(At, 1, 1); PG8_STAGE(PG8_SA(1, 0), a3, voffA);
;             PG8_BAR; PG8_WAIT_L(0); PG8_MMA(1, 0, At, B0); PG8_BAR; PG8_SCHED;
;             PG8_STAGE(PG8_SB(1, 1), b3 + hstep, voffB);
;             PG8_WAIT_V(6); PG8_BAR; PG8_MMA(1, 1, At, B1); PG8_BAR;
.Lzp11_mid:
	ds_read_b128 v[140:143], v155
	ds_read_b128 v[170:173], v156
	ds_read_b128 v[174:177], v157
	ds_read_b128 v[178:181], v165
	s_add_u32 s16, s28, 0x44000
	s_addc_u32 s17, s29, 0
	s_mov_b32 m0, s44
	ds_read_b128 v[182:185], v145 offset:32768
	ds_read_b128 v[186:189], v145 offset:33792
	ds_read_b128 v[190:193], v145 offset:34816
	ds_read_b128 v[194:197], v145 offset:35840
	ds_read_b128 v[198:201], v145 offset:36864
	ds_read_b128 v[202:205], v145 offset:37888
	ds_read_b128 v[206:209], v145 offset:38912
	ds_read_b128 v[210:213], v145 offset:39936
	global_load_lds_dwordx4 v130, s[16:17]
	s_mov_b32 m0, s45
	s_nop 0
	global_load_lds_dwordx4 v128, s[16:17]
	s_waitcnt lgkmcnt(8)
	s_barrier
	s_waitcnt lgkmcnt(0)
	s_setprio 1
	s_waitcnt lgkmcnt(0)
	v_mfma_f32_16x16x32_bf16 v[124:127], v[140:143], v[182:185], v[124:127]
	v_mfma_f32_16x16x32_bf16 v[120:123], v[174:177], v[182:185], v[120:123]
	v_mfma_f32_16x16x32_bf16 v[108:111], v[140:143], v[190:193], v[108:111]
	v_mfma_f32_16x16x32_bf16 v[104:107], v[174:177], v[190:193], v[104:107]
	v_mfma_f32_16x16x32_bf16 v[92:95], v[140:143], v[198:201], v[92:95]
	v_mfma_f32_16x16x32_bf16 v[88:91], v[174:177], v[198:201], v[88:91]
	v_mfma_f32_16x16x32_bf16 v[76:79], v[140:143], v[206:209], v[76:79]
	v_mfma_f32_16x16x32_bf16 v[72:75], v[174:177], v[206:209], v[72:75]
	v_mfma_f32_16x16x32_bf16 v[124:127], v[170:173], v[186:189], v[124:127]
	v_mfma_f32_16x16x32_bf16 v[120:123], v[178:181], v[186:189], v[120:123]
	v_mfma_f32_16x16x32_bf16 v[108:111], v[170:173], v[194:197], v[108:111]
	v_mfma_f32_16x16x32_bf16 v[104:107], v[178:181], v[194:197], v[104:107]
	v_mfma_f32_16x16x32_bf16 v[92:95], v[170:173], v[202:205], v[92:95]
	v_mfma_f32_16x16x32_bf16 v[88:91], v[178:181], v[202:205], v[88:91]
	v_mfma_f32_16x16x32_bf16 v[76:79], v[170:173], v[210:213], v[76:79]
	v_mfma_f32_16x16x32_bf16 v[72:75], v[178:181], v[210:213], v[72:75]
	s_setprio 0
	s_barrier
	s_mov_b32 m0, s48
	ds_read_b128 v[214:217], v166
	ds_read_b128 v[218:221], v167
	ds_read_b128 v[222:225], v168
	ds_read_b128 v[226:229], v169
	s_add_u32 s100, s20, 0x80
	s_addc_u32 s101, s21, 0
	global_load_lds_dwordx4 v130, s[100:101]
	s_mov_b32 m0, s49
	s_nop 0
	global_load_lds_dwordx4 v128, s[100:101]
	s_barrier
	s_waitcnt lgkmcnt(0)
	s_setprio 1
	s_waitcnt lgkmcnt(0)
	v_mfma_f32_16x16x32_bf16 v[116:119], v[214:217], v[182:185], v[116:119]
	v_mfma_f32_16x16x32_bf16 v[112:115], v[222:225], v[182:185], v[112:115]
	v_mfma_f32_16x16x32_bf16 v[100:103], v[214:217], v[190:193], v[100:103]
	v_mfma_f32_16x16x32_bf16 v[96:99], v[222:225], v[190:193], v[96:99]
	v_mfma_f32_16x16x32_bf16 v[84:87], v[214:217], v[198:201], v[84:87]
	v_mfma_f32_16x16x32_bf16 v[80:83], v[222:225], v[198:201], v[80:83]
	v_mfma_f32_16x16x32_bf16 v[68:71], v[214:217], v[206:209], v[68:71]
	v_mfma_f32_16x16x32_bf16 v[64:67], v[222:225], v[206:209], v[64:67]
	v_mfma_f32_16x16x32_bf16 v[116:119], v[218:221], v[186:189], v[116:119]
	v_mfma_f32_16x16x32_bf16 v[112:115], v[226:229], v[186:189], v[112:115]
	v_mfma_f32_16x16x32_bf16 v[100:103], v[218:221], v[194:197], v[100:103]
	v_mfma_f32_16x16x32_bf16 v[96:99], v[226:229], v[194:197], v[96:99]
	v_mfma_f32_16x16x32_bf16 v[84:87], v[218:221], v[202:205], v[84:87]
	v_mfma_f32_16x16x32_bf16 v[80:83], v[226:229], v[202:205], v[80:83]
	v_mfma_f32_16x16x32_bf16 v[68:71], v[218:221], v[210:213], v[68:71]
	v_mfma_f32_16x16x32_bf16 v[64:67], v[226:229], v[210:213], v[64:67]
	s_setprio 0
	s_mov_b32 m0, s50
	s_barrier
	ds_read_b128 v[182:185], v145 offset:49152
	ds_read_b128 v[186:189], v145 offset:50176
	ds_read_b128 v[190:193], v145 offset:51200
	ds_read_b128 v[194:197], v145 offset:52224
	ds_read_b128 v[198:201], v145 offset:53248
	ds_read_b128 v[202:205], v145 offset:54272
	ds_read_b128 v[206:209], v145 offset:55296
	ds_read_b128 v[210:213], v145 offset:56320
	s_add_u32 s100, s28, 0x80
	s_addc_u32 s101, s29, 0
	global_load_lds_dwordx4 v130, s[100:101]
	s_mov_b32 m0, s51
	s_nop 0
	global_load_lds_dwordx4 v128, s[100:101]
	s_barrier
	s_waitcnt lgkmcnt(0)
	s_setprio 1
	s_waitcnt lgkmcnt(0)
	v_mfma_f32_16x16x32_bf16 v[60:63], v[140:143], v[182:185], v[60:63]
	v_mfma_f32_16x16x32_bf16 v[56:59], v[174:177], v[182:185], v[56:59]
	v_mfma_f32_16x16x32_bf16 v[44:47], v[140:143], v[190:193], v[44:47]
	v_mfma_f32_16x16x32_bf16 v[40:43], v[174:177], v[190:193], v[40:43]
	v_mfma_f32_16x16x32_bf16 v[28:31], v[140:143], v[198:201], v[28:31]
	v_mfma_f32_16x16x32_bf16 v[24:27], v[174:177], v[198:201], v[24:27]
	v_mfma_f32_16x16x32_bf16 v[12:15], v[140:143], v[206:209], v[12:15]
	v_mfma_f32_16x16x32_bf16 v[8:11], v[174:177], v[206:209], v[8:11]
	v_mfma_f32_16x16x32_bf16 v[60:63], v[170:173], v[186:189], v[60:63]
	v_mfma_f32_16x16x32_bf16 v[56:59], v[178:181], v[186:189], v[56:59]
	v_mfma_f32_16x16x32_bf16 v[44:47], v[170:173], v[194:197], v[44:47]
	v_mfma_f32_16x16x32_bf16 v[40:43], v[178:181], v[194:197], v[40:43]
	v_mfma_f32_16x16x32_bf16 v[28:31], v[170:173], v[202:205], v[28:31]
	v_mfma_f32_16x16x32_bf16 v[24:27], v[178:181], v[202:205], v[24:27]
	v_mfma_f32_16x16x32_bf16 v[12:15], v[170:173], v[210:213], v[12:15]
	v_mfma_f32_16x16x32_bf16 v[8:11], v[178:181], v[210:213], v[8:11]
	s_setprio 0
	s_barrier
	s_add_u32 s16, s20, 0x44080
	s_addc_u32 s17, s21, 0
	s_mov_b32 m0, s52
	s_nop 0
	global_load_lds_dwordx4 v130, s[16:17]
	s_mov_b32 m0, s53
	s_nop 0
	global_load_lds_dwordx4 v128, s[16:17]
	s_add_i32 s10, s10, 2
	s_add_u32 s62, s62, 0x100
	s_addc_u32 s63, s63, 0
	s_cmp_gt_u32 s10, 13
	s_mov_b64 s[16:17], s[18:19]
	s_waitcnt vmcnt(6)
	s_barrier
; DI float ex2(float x) { return __builtin_amdgcn_exp2f(x); }
; #define PG8_STAGE(bufoff, gbase, voff) do { _Pragma("unroll") for (int _i = 0; _i < 2; ++_i) \
;         __builtin_amdgcn_global_load_lds((const unsigned*)((const char*)(gbase) + (voff)[_i]), (PG8_LAS unsigned*)(lds + (bufoff) + ldsw + _i * 8192), 16, 0, 0); } while (0)
; #define PG8_LDA(dst, b, h) do { _Pragma("unroll") for (int m = 0; m < 4; ++m) _Pragma("unroll") for (int k = 0; k < 2; ++k) dst[m][k] = *(const PG8_LAS bf16x8*)(lds + PG8_SA(b, h) + aoff + m * 2048 + k * 1024); } while (0)
; #define PG8_WAIT_V(n) asm volatile("s_waitcnt vmcnt(" #n ")" ::: "memory")
; #define PG8_WAIT_L(n) asm volatile("s_waitcnt lgkmcnt(" #n ")" ::: "memory")
;     DI void operator()(const f32x4 (&acc)[2][2][4][2], const Unit& u, int wr, int wc, int fr, int fq) const {
;         const int row0 = u.pm * BM + wr * 64 + fr, hcol0 = ((u.pn * BM + wc * 32) >> 1) + 4 * fq;
; #pragma unroll
;         for (int ai = 0; ai < 2; ++ai)
; #pragma unroll
;             for (int m = 0; m < 4; ++m) { u16* rowp = O + (size_t)(row0 + ai * HALF + m * 16) * ldc + hcol0;
; #pragma unroll
;                 for (int bj = 0; bj < 2; ++bj) { const f32x4 g = acc[ai][bj][m][0], up = acc[ai][bj][m][1]; float r[4];
; #pragma unroll
;                     for (int j = 0; j < 4; ++j) r[j] = g[j] * up[j] * __builtin_amdgcn_rcpf(1.f + ex2(-LOG2E * g[j]));
;                     uint2 w = {pack2(r[0], r[1]), pack2(r[2], r[3])}; *(uint2*)(rowp + bj * (HALF / 2)) = w; } }
; template <class Epi, class Sched, bool STAMP = false>
; __device__ __forceinline__ void gemm_phase(PG8_LAS unsigned char* lds, const Gemm g, const Sched& S, const Epi& E, unsigned long long* stamps) {
;     ...
;             PG8_WAIT_V(6); PG8_BAR; PG8_MMA(1, 1, At, B1); PG8_BAR;
;             PG8_LDB(B0, 1, 0); PG8_SCHED; PG8_LDA(At, 1, 0); PG8_STAGE(PG8_SA(0, 1), a2 + hstep, voffA);
;             PG8_WAIT_L(8); PG8_BAR; PG8_WAIT_L(0); PG8_MMA(0, 0, At, B0); PG8_BAR; PG8_SCHED;
;             PG8_LDB(B1, 1, 1); PG8_STAGE(PG8_SB(1, 0), b3, voffB);
;             PG8_BAR; PG8_WAIT_L(0); PG8_MMA(0, 1, At, B1); PG8_BAR;
;             PG8_LDA(At, 1, 1); PG8_STAGE(PG8_SA(1, 0), a3, voffA);
;             PG8_BAR; PG8_WAIT_L(0); PG8_MMA(1, 0, At, B0); PG8_BAR; PG8_SCHED;
;             PG8_STAGE(PG8_SB(1, 1), b3 + hstep, voffB);
;             PG8_WAIT_V(6); PG8_BAR; PG8_MMA(1, 1, At, B1); PG8_BAR;
	s_setprio 1
	v_mfma_f32_16x16x32_bf16 v[52:55], v[214:217], v[182:185], v[52:55]
	v_mfma_f32_16x16x32_bf16 v[48:51], v[222:225], v[182:185], v[48:51]
	v_mfma_f32_16x16x32_bf16 v[36:39], v[214:217], v[190:193], v[36:39]
	v_mfma_f32_16x16x32_bf16 v[32:35], v[222:225], v[190:193], v[32:35]
	v_mfma_f32_16x16x32_bf16 v[20:23], v[214:217], v[198:201], v[20:23]
	v_mfma_f32_16x16x32_bf16 v[16:19], v[222:225], v[198:201], v[16:19]
	v_mfma_f32_16x16x32_bf16 v[4:7], v[214:217], v[206:209], v[4:7]
	v_mfma_f32_16x16x32_bf16 v[0:3], v[222:225], v[206:209], v[0:3]
	v_mfma_f32_16x16x32_bf16 v[52:55], v[218:221], v[186:189], v[52:55]
	v_mfma_f32_16x16x32_bf16 v[48:51], v[226:229], v[186:189], v[48:51]
	v_mfma_f32_16x16x32_bf16 v[36:39], v[218:221], v[194:197], v[36:39]
	v_mfma_f32_16x16x32_bf16 v[32:35], v[226:229], v[194:197], v[32:35]
	v_mfma_f32_16x16x32_bf16 v[20:23], v[218:221], v[202:205], v[20:23]
	v_mfma_f32_16x16x32_bf16 v[16:19], v[226:229], v[202:205], v[16:19]
	v_mfma_f32_16x16x32_bf16 v[4:7], v[218:221], v[210:213], v[4:7]
	v_mfma_f32_16x16x32_bf16 v[0:3], v[226:229], v[210:213], v[0:3]
	s_setprio 0
	s_barrier
	s_cbranch_scc0 .LBB0_727
	v_exp_f32_e64 v171, -v124
	v_exp_f32_e64 v175, -v125
	s_lshl_b32 s10, s61, 8
	v_add_f32_e32 v171, 1.0, v171
	v_rcp_f32_e32 v174, v171
	v_add_f32_e32 v171, 1.0, v175
	v_exp_f32_e64 v176, -v126
	v_exp_f32_e64 v177, -v127
	v_rcp_f32_e32 v175, v171
	v_add_f32_e32 v171, 1.0, v176
	v_rcp_f32_e32 v176, v171
	v_add_f32_e32 v171, 1.0, v177
	v_rcp_f32_e32 v177, v171
	v_pk_mul_f32 v[122:123], v[126:127], v[122:123]
	v_pk_mul_f32 v[120:121], v[124:125], v[120:121]
	s_or_b32 s10, s10, s47
	v_pk_mul_f32 v[120:121], v[120:121], v[174:175]
	v_pk_mul_f32 v[122:123], v[122:123], v[176:177]
	s_ashr_i32 s10, s10, 1
	v_cvt_pk_bf16_f32 v120, v120, v121
	v_cvt_pk_bf16_f32 v121, v122, v123
	v_or_b32_e32 v140, s10, v146
	v_exp_f32_e64 v122, -v116
	v_exp_f32_e64 v123, -v117
	v_lshl_add_u32 v170, s60, 8, v144
	v_ashrrev_i32_e32 v141, 31, v140
	v_mov_b64_e32 v[142:143], s[12:13]
	v_mad_i64_i32 v[172:173], s[16:17], v170, s57, v[142:143]
	v_lshlrev_b64 v[140:141], 1, v[140:141]
	v_lshl_add_u64 v[172:173], v[172:173], 0, v[140:141]
	global_store_dwordx2 v[172:173], v[120:121], off
	v_add_f32_e32 v120, 1.0, v122
	v_add_f32_e32 v121, 1.0, v123
	v_exp_f32_e64 v122, -v118
	v_exp_f32_e64 v123, -v119
	v_rcp_f32_e32 v120, v120
	v_rcp_f32_e32 v121, v121
	v_add_f32_e32 v122, 1.0, v122
	v_add_f32_e32 v123, 1.0, v123
	v_rcp_f32_e32 v122, v122
	v_rcp_f32_e32 v123, v123
	v_pk_mul_f32 v[114:115], v[118:119], v[114:115]
	v_pk_mul_f32 v[112:113], v[116:117], v[112:113]
	v_pk_mul_f32 v[112:113], v[112:113], v[120:121]
	v_pk_mul_f32 v[114:115], v[114:115], v[122:123]
	v_cvt_pk_bf16_f32 v112, v112, v113
	v_cvt_pk_bf16_f32 v113, v114, v115
	v_exp_f32_e64 v114, -v108
	v_exp_f32_e64 v115, -v109
	v_exp_f32_e64 v116, -v110
	v_exp_f32_e64 v117, -v111
	v_add_f32_e32 v114, 1.0, v114
	v_add_f32_e32 v115, 1.0, v115
	v_add_f32_e32 v116, 1.0, v116
	v_add_f32_e32 v117, 1.0, v117
	v_rcp_f32_e32 v114, v114
	v_rcp_f32_e32 v115, v115
	v_rcp_f32_e32 v116, v116
	v_rcp_f32_e32 v117, v117
	v_pk_mul_f32 v[106:107], v[110:111], v[106:107]
	v_pk_mul_f32 v[104:105], v[108:109], v[104:105]
	global_store_dwordx2 v[172:173], v[112:113], off offset:128
	v_pk_mul_f32 v[104:105], v[104:105], v[114:115]
	v_pk_mul_f32 v[106:107], v[106:107], v[116:117]
	v_cvt_pk_bf16_f32 v104, v104, v105
	v_cvt_pk_bf16_f32 v105, v106, v107
	v_exp_f32_e64 v106, -v100
	v_exp_f32_e64 v107, -v101
	v_or_b32_e32 v112, 16, v170
	v_mad_i64_i32 v[112:113], s[16:17], v112, s57, v[142:143]
	v_lshl_add_u64 v[112:113], v[112:113], 0, v[140:141]
	global_store_dwordx2 v[112:113], v[104:105], off
	v_add_f32_e32 v104, 1.0, v106
	v_add_f32_e32 v105, 1.0, v107
	v_exp_f32_e64 v106, -v102
	v_exp_f32_e64 v107, -v103
	v_rcp_f32_e32 v104, v104
	v_rcp_f32_e32 v105, v105
	v_add_f32_e32 v106, 1.0, v106
	v_add_f32_e32 v107, 1.0, v107
	v_rcp_f32_e32 v106, v106
	v_rcp_f32_e32 v107, v107
	v_pk_mul_f32 v[98:99], v[102:103], v[98:99]
	v_pk_mul_f32 v[96:97], v[100:101], v[96:97]
	v_pk_mul_f32 v[96:97], v[96:97], v[104:105]
	v_pk_mul_f32 v[98:99], v[98:99], v[106:107]
	v_cvt_pk_bf16_f32 v96, v96, v97
	v_cvt_pk_bf16_f32 v97, v98, v99
	v_exp_f32_e64 v98, -v92
	v_exp_f32_e64 v99, -v93
	v_exp_f32_e64 v100, -v94
	v_exp_f32_e64 v101, -v95
	v_add_f32_e32 v98, 1.0, v98
	v_add_f32_e32 v99, 1.0, v99
	v_add_f32_e32 v100, 1.0, v100
	v_add_f32_e32 v101, 1.0, v101
	v_rcp_f32_e32 v98, v98
	v_rcp_f32_e32 v99, v99
	v_rcp_f32_e32 v100, v100
	v_rcp_f32_e32 v101, v101
	v_pk_mul_f32 v[90:91], v[94:95], v[90:91]
	v_pk_mul_f32 v[88:89], v[92:93], v[88:89]
	global_store_dwordx2 v[112:113], v[96:97], off offset:128
	v_pk_mul_f32 v[88:89], v[88:89], v[98:99]
	v_pk_mul_f32 v[90:91], v[90:91], v[100:101]
	v_cvt_pk_bf16_f32 v88, v88, v89
	v_cvt_pk_bf16_f32 v89, v90, v91
	v_exp_f32_e64 v90, -v84
	v_exp_f32_e64 v91, -v85
	v_or_b32_e32 v96, 32, v170
	v_mad_i64_i32 v[96:97], s[16:17], v96, s57, v[142:143]
	v_lshl_add_u64 v[96:97], v[96:97], 0, v[140:141]
	global_store_dwordx2 v[96:97], v[88:89], off
	v_add_f32_e32 v88, 1.0, v90
	v_add_f32_e32 v89, 1.0, v91
	v_exp_f32_e64 v90, -v86
	v_exp_f32_e64 v91, -v87
	v_rcp_f32_e32 v88, v88
	v_rcp_f32_e32 v89, v89
	v_add_f32_e32 v90, 1.0, v90
	v_add_f32_e32 v91, 1.0, v91
	v_rcp_f32_e32 v90, v90
	v_rcp_f32_e32 v91, v91
	v_pk_mul_f32 v[82:83], v[86:87], v[82:83]
	v_pk_mul_f32 v[80:81], v[84:85], v[80:81]
	v_pk_mul_f32 v[80:81], v[80:81], v[88:89]
	v_pk_mul_f32 v[82:83], v[82:83], v[90:91]
	v_cvt_pk_bf16_f32 v80, v80, v81
	v_cvt_pk_bf16_f32 v81, v82, v83
	v_exp_f32_e64 v82, -v76
	v_exp_f32_e64 v83, -v77
	v_exp_f32_e64 v84, -v78
; DI float ex2(float x) { return __builtin_amdgcn_exp2f(x); }
;     DI void operator()(const f32x4 (&acc)[2][2][4][2], const Unit& u, int wr, int wc, int fr, int fq) const {
;         const int row0 = u.pm * BM + wr * 64 + fr, hcol0 = ((u.pn * BM + wc * 32) >> 1) + 4 * fq;
; #pragma unroll
;         for (int ai = 0; ai < 2; ++ai)
; #pragma unroll
;             for (int m = 0; m < 4; ++m) { u16* rowp = O + (size_t)(row0 + ai * HALF + m * 16) * ldc + hcol0;
; #pragma unroll
;                 for (int bj = 0; bj < 2; ++bj) { const f32x4 g = acc[ai][bj][m][0], up = acc[ai][bj][m][1]; float r[4];
; #pragma unroll
;                     for (int j = 0; j < 4; ++j) r[j] = g[j] * up[j] * __builtin_amdgcn_rcpf(1.f + ex2(-LOG2E * g[j]));
;                     uint2 w = {pack2(r[0], r[1]), pack2(r[2], r[3])}; *(uint2*)(rowp + bj * (HALF / 2)) = w; } }
; template <class Epi, class Sched, bool STAMP = false>
; __device__ __forceinline__ void gemm_phase(PG8_LAS unsigned char* lds, const Gemm g, const Sched& S, const Epi& E, unsigned long long* stamps) {
;     ...
;         if (!has_next) break;
; #pragma unroll
;         for (int a = 0; a < 2; ++a)
; #pragma unroll
;             for (int b = 0; b < 2; ++b)
; #pragma unroll
;                 for (int m = 0; m < 4; ++m)
; #pragma unroll
;                     for (int n = 0; n < 2; ++n) acc[a][b][m][n] = (f32x4){0.f, 0.f, 0.f, 0.f};
;         cur = nxt; cA = nA; cB = nB; ++ui;
	v_exp_f32_e64 v85, -v79
	v_add_f32_e32 v82, 1.0, v82
	v_add_f32_e32 v83, 1.0, v83
	v_add_f32_e32 v84, 1.0, v84
	v_add_f32_e32 v85, 1.0, v85
	v_rcp_f32_e32 v82, v82
	v_rcp_f32_e32 v83, v83
	v_rcp_f32_e32 v84, v84
	v_rcp_f32_e32 v85, v85
	v_pk_mul_f32 v[74:75], v[78:79], v[74:75]
	v_pk_mul_f32 v[72:73], v[76:77], v[72:73]
	global_store_dwordx2 v[96:97], v[80:81], off offset:128
	v_pk_mul_f32 v[72:73], v[72:73], v[82:83]
	v_pk_mul_f32 v[74:75], v[74:75], v[84:85]
	v_cvt_pk_bf16_f32 v72, v72, v73
	v_cvt_pk_bf16_f32 v73, v74, v75
	v_exp_f32_e64 v74, -v68
	v_exp_f32_e64 v75, -v69
	v_or_b32_e32 v80, 48, v170
	v_mad_i64_i32 v[80:81], s[16:17], v80, s57, v[142:143]
	v_lshl_add_u64 v[80:81], v[80:81], 0, v[140:141]
	global_store_dwordx2 v[80:81], v[72:73], off
	v_add_f32_e32 v72, 1.0, v74
	v_add_f32_e32 v73, 1.0, v75
	v_exp_f32_e64 v74, -v70
	v_exp_f32_e64 v75, -v71
	v_rcp_f32_e32 v72, v72
	v_rcp_f32_e32 v73, v73
	v_add_f32_e32 v74, 1.0, v74
	v_add_f32_e32 v75, 1.0, v75
	v_rcp_f32_e32 v74, v74
	v_rcp_f32_e32 v75, v75
	v_pk_mul_f32 v[66:67], v[70:71], v[66:67]
	v_pk_mul_f32 v[64:65], v[68:69], v[64:65]
	v_pk_mul_f32 v[64:65], v[64:65], v[72:73]
	v_pk_mul_f32 v[66:67], v[66:67], v[74:75]
	v_cvt_pk_bf16_f32 v64, v64, v65
	v_cvt_pk_bf16_f32 v65, v66, v67
	v_exp_f32_e64 v66, -v60
	v_exp_f32_e64 v67, -v61
	v_exp_f32_e64 v68, -v62
	v_exp_f32_e64 v69, -v63
	v_add_f32_e32 v66, 1.0, v66
	v_add_f32_e32 v67, 1.0, v67
	v_add_f32_e32 v68, 1.0, v68
	v_add_f32_e32 v69, 1.0, v69
	v_rcp_f32_e32 v66, v66
	v_rcp_f32_e32 v67, v67
	v_rcp_f32_e32 v68, v68
	v_rcp_f32_e32 v69, v69
	v_pk_mul_f32 v[58:59], v[62:63], v[58:59]
	v_pk_mul_f32 v[56:57], v[60:61], v[56:57]
	global_store_dwordx2 v[80:81], v[64:65], off offset:128
	v_pk_mul_f32 v[56:57], v[56:57], v[66:67]
	v_pk_mul_f32 v[58:59], v[58:59], v[68:69]
	v_cvt_pk_bf16_f32 v56, v56, v57
	v_cvt_pk_bf16_f32 v57, v58, v59
	v_exp_f32_e64 v58, -v52
	v_exp_f32_e64 v59, -v53
	v_add_u32_e32 v64, 0x80, v170
	v_mad_i64_i32 v[64:65], s[16:17], v64, s57, v[142:143]
	v_lshl_add_u64 v[64:65], v[64:65], 0, v[140:141]
	global_store_dwordx2 v[64:65], v[56:57], off
	v_add_f32_e32 v56, 1.0, v58
	v_add_f32_e32 v57, 1.0, v59
	v_exp_f32_e64 v58, -v54
	v_exp_f32_e64 v59, -v55
	v_rcp_f32_e32 v56, v56
	v_rcp_f32_e32 v57, v57
	v_add_f32_e32 v58, 1.0, v58
	v_add_f32_e32 v59, 1.0, v59
	v_rcp_f32_e32 v58, v58
	v_rcp_f32_e32 v59, v59
	v_pk_mul_f32 v[50:51], v[54:55], v[50:51]
	v_pk_mul_f32 v[48:49], v[52:53], v[48:49]
	v_pk_mul_f32 v[48:49], v[48:49], v[56:57]
	v_pk_mul_f32 v[50:51], v[50:51], v[58:59]
	v_cvt_pk_bf16_f32 v48, v48, v49
	v_cvt_pk_bf16_f32 v49, v50, v51
	v_exp_f32_e64 v50, -v44
	v_exp_f32_e64 v51, -v45
	v_exp_f32_e64 v52, -v46
	v_exp_f32_e64 v53, -v47
	v_add_f32_e32 v50, 1.0, v50
	v_add_f32_e32 v51, 1.0, v51
	v_add_f32_e32 v52, 1.0, v52
	v_add_f32_e32 v53, 1.0, v53
	v_rcp_f32_e32 v50, v50
	v_rcp_f32_e32 v51, v51
	v_rcp_f32_e32 v52, v52
	v_rcp_f32_e32 v53, v53
	v_pk_mul_f32 v[42:43], v[46:47], v[42:43]
	v_pk_mul_f32 v[40:41], v[44:45], v[40:41]
	global_store_dwordx2 v[64:65], v[48:49], off offset:128
	v_pk_mul_f32 v[40:41], v[40:41], v[50:51]
	v_pk_mul_f32 v[42:43], v[42:43], v[52:53]
	v_cvt_pk_bf16_f32 v40, v40, v41
	v_cvt_pk_bf16_f32 v41, v42, v43
	v_exp_f32_e64 v42, -v36
	v_exp_f32_e64 v43, -v37
	v_add_u32_e32 v48, 0x90, v170
	v_mad_i64_i32 v[48:49], s[16:17], v48, s57, v[142:143]
	v_lshl_add_u64 v[48:49], v[48:49], 0, v[140:141]
	global_store_dwordx2 v[48:49], v[40:41], off
	v_add_f32_e32 v40, 1.0, v42
	v_add_f32_e32 v41, 1.0, v43
	v_exp_f32_e64 v42, -v38
	v_exp_f32_e64 v43, -v39
	v_rcp_f32_e32 v40, v40
	v_rcp_f32_e32 v41, v41
	v_add_f32_e32 v42, 1.0, v42
	v_add_f32_e32 v43, 1.0, v43
	v_rcp_f32_e32 v42, v42
	v_rcp_f32_e32 v43, v43
	v_pk_mul_f32 v[34:35], v[38:39], v[34:35]
	v_pk_mul_f32 v[32:33], v[36:37], v[32:33]
	v_pk_mul_f32 v[32:33], v[32:33], v[40:41]
	v_pk_mul_f32 v[34:35], v[34:35], v[42:43]
	v_cvt_pk_bf16_f32 v32, v32, v33
	v_cvt_pk_bf16_f32 v33, v34, v35
	v_exp_f32_e64 v34, -v28
	v_exp_f32_e64 v35, -v29
	v_exp_f32_e64 v36, -v30
	v_exp_f32_e64 v37, -v31
	v_add_f32_e32 v34, 1.0, v34
	v_add_f32_e32 v35, 1.0, v35
	v_add_f32_e32 v36, 1.0, v36
	v_add_f32_e32 v37, 1.0, v37
	v_rcp_f32_e32 v34, v34
	v_rcp_f32_e32 v35, v35
	v_rcp_f32_e32 v36, v36
	v_rcp_f32_e32 v37, v37
	v_pk_mul_f32 v[26:27], v[30:31], v[26:27]
	v_pk_mul_f32 v[24:25], v[28:29], v[24:25]
	global_store_dwordx2 v[48:49], v[32:33], off offset:128
	v_pk_mul_f32 v[24:25], v[24:25], v[34:35]
	v_pk_mul_f32 v[26:27], v[26:27], v[36:37]
	v_cvt_pk_bf16_f32 v24, v24, v25
	v_cvt_pk_bf16_f32 v25, v26, v27
	v_exp_f32_e64 v26, -v20
	v_exp_f32_e64 v27, -v21
	v_add_u32_e32 v32, 0xa0, v170
	v_mad_i64_i32 v[32:33], s[16:17], v32, s57, v[142:143]
	v_lshl_add_u64 v[32:33], v[32:33], 0, v[140:141]
	global_store_dwordx2 v[32:33], v[24:25], off
	v_add_f32_e32 v24, 1.0, v26
	v_add_f32_e32 v25, 1.0, v27
	v_exp_f32_e64 v26, -v22
	v_exp_f32_e64 v27, -v23
	v_rcp_f32_e32 v24, v24
	v_rcp_f32_e32 v25, v25
	v_add_f32_e32 v26, 1.0, v26
	v_add_f32_e32 v27, 1.0, v27
	v_rcp_f32_e32 v26, v26
	v_rcp_f32_e32 v27, v27
	v_pk_mul_f32 v[18:19], v[22:23], v[18:19]
	v_pk_mul_f32 v[16:17], v[20:21], v[16:17]
	v_pk_mul_f32 v[16:17], v[16:17], v[24:25]
	v_pk_mul_f32 v[18:19], v[18:19], v[26:27]
	v_cvt_pk_bf16_f32 v16, v16, v17
	v_cvt_pk_bf16_f32 v17, v18, v19
	v_exp_f32_e64 v18, -v12
	v_exp_f32_e64 v19, -v13
	v_exp_f32_e64 v20, -v14
	v_exp_f32_e64 v21, -v15
	v_add_f32_e32 v18, 1.0, v18
	v_add_f32_e32 v19, 1.0, v19
	v_add_f32_e32 v20, 1.0, v20
	v_add_f32_e32 v21, 1.0, v21
	v_rcp_f32_e32 v18, v18
	v_rcp_f32_e32 v19, v19
	v_rcp_f32_e32 v20, v20
	v_rcp_f32_e32 v21, v21
	v_pk_mul_f32 v[10:11], v[14:15], v[10:11]
	v_pk_mul_f32 v[8:9], v[12:13], v[8:9]
	global_store_dwordx2 v[32:33], v[16:17], off offset:128
	v_pk_mul_f32 v[8:9], v[8:9], v[18:19]
	v_pk_mul_f32 v[10:11], v[10:11], v[20:21]
	v_cvt_pk_bf16_f32 v8, v8, v9
	v_cvt_pk_bf16_f32 v9, v10, v11
	v_exp_f32_e64 v10, -v4
	v_exp_f32_e64 v11, -v5
	v_add_u32_e32 v16, 0xb0, v170
	v_mad_i64_i32 v[16:17], s[16:17], v16, s57, v[142:143]
	v_lshl_add_u64 v[16:17], v[16:17], 0, v[140:141]
	global_store_dwordx2 v[16:17], v[8:9], off
	v_add_f32_e32 v8, 1.0, v10
	v_add_f32_e32 v9, 1.0, v11
	v_exp_f32_e64 v10, -v6
	v_exp_f32_e64 v11, -v7
	v_rcp_f32_e32 v8, v8
	v_rcp_f32_e32 v9, v9
	v_add_f32_e32 v10, 1.0, v10
	v_add_f32_e32 v11, 1.0, v11
	v_rcp_f32_e32 v10, v10
	v_rcp_f32_e32 v11, v11
	v_pk_mul_f32 v[2:3], v[6:7], v[2:3]
	v_pk_mul_f32 v[0:1], v[4:5], v[0:1]
	s_and_b64 vcc, exec, s[2:3]
	v_pk_mul_f32 v[0:1], v[0:1], v[8:9]
	v_pk_mul_f32 v[2:3], v[2:3], v[10:11]
	v_cvt_pk_bf16_f32 v0, v0, v1
	v_cvt_pk_bf16_f32 v1, v2, v3
	s_mov_b32 s61, s58
	s_mov_b32 s60, s59
	s_mov_b64 s[18:19], s[0:1]
	s_mov_b64 s[16:17], s[4:5]
	global_store_dwordx2 v[16:17], v[0:1], off offset:128
	s_cbranch_vccz .LBB0_720
	s_branch .Lgu4_done

; #define PG8_STAGE(bufoff, gbase, voff) do { _Pragma("unroll") for (int _i = 0; _i < 2; ++_i) \
;         __builtin_amdgcn_global_load_lds((const unsigned*)((const char*)(gbase) + (voff)[_i]), (PG8_LAS unsigned*)(lds + (bufoff) + ldsw + _i * 8192), 16, 0, 0); } while (0)
; #define PG8_LDA(dst, b, h) do { _Pragma("unroll") for (int m = 0; m < 4; ++m) _Pragma("unroll") for (int k = 0; k < 2; ++k) dst[m][k] = *(const PG8_LAS bf16x8*)(lds + PG8_SA(b, h) + aoff + m * 2048 + k * 1024); } while (0)
; #define PG8_BAR __builtin_amdgcn_s_barrier()
; template <class Epi, class Sched, bool STAMP = false>
; __device__ __forceinline__ void gemm_phase(PG8_LAS unsigned char* lds, const Gemm g, const Sched& S, const Epi& E, unsigned long long* stamps) {
;     ...
;         for (int t = 0; t < nt; t += 2) {
;             const bool last = (t == nt - 2);
;             const char* a1 = cA + (size_t)(t + 1) * kstep;
;             const char* a2 = last ? nA : cA + (size_t)(t + 2) * kstep; const char* b2 = last ? nB : cB + (size_t)(t + 2) * kstep;
;             const char* a3 = a2 + kstep; const char* b3 = b2 + kstep;
;             if (last && has_next) S.a_ready(nxt);
;             PG8_LDB(B0, 0, 0); PG8_SCHED; PG8_LDA(At, 0, 0); PG8_STAGE(PG8_SA(1, 1), a1 + hstep, voffA);
;             PG8_WAIT_L(8); PG8_BAR; PG8_WAIT_L(0); PG8_MMA(0, 0, At, B0); PG8_BAR; PG8_SCHED;
;             PG8_LDB(B1, 0, 1); PG8_STAGE(PG8_SB(0, 0), b2, voffB);
;             PG8_BAR; PG8_WAIT_L(0); PG8_MMA(0, 1, At, B1); PG8_BAR;
;             PG8_LDA(At, 0, 1); PG8_STAGE(PG8_SA(0, 0), a2, voffA);
;             PG8_BAR; PG8_WAIT_L(0); PG8_MMA(1, 0, At, B0); PG8_BAR; PG8_SCHED;
;             PG8_STAGE(PG8_SB(0, 1), b2 + hstep, voffB);
;             PG8_WAIT_V(6); PG8_BAR; PG8_MMA(1, 1, At, B1); PG8_BAR;
;             PG8_LDB(B0, 1, 0); PG8_SCHED; PG8_LDA(At, 1, 0); PG8_STAGE(PG8_SA(0, 1), a2 + hstep, voffA);
;             PG8_WAIT_L(8); PG8_BAR; PG8_WAIT_L(0); PG8_MMA(0, 0, At, B0); PG8_BAR; PG8_SCHED;
;             PG8_LDB(B1, 1, 1); PG8_STAGE(PG8_SB(1, 0), b3, voffB);
;             PG8_BAR; PG8_WAIT_L(0); PG8_MMA(0, 1, At, B1); PG8_BAR;
;             PG8_LDA(At, 1, 1); PG8_STAGE(PG8_SA(1, 0), a3, voffA);
;             PG8_BAR; PG8_WAIT_L(0); PG8_MMA(1, 0, At, B0); PG8_BAR; PG8_SCHED;
;             PG8_STAGE(PG8_SB(1, 1), b3 + hstep, voffB);
;             PG8_WAIT_V(6); PG8_BAR; PG8_MMA(1, 1, At, B1); PG8_BAR;
.Lgu4_half_loop:
	ds_read_b128 v[140:143], v147
	ds_read_b128 v[170:173], v148
	ds_read_b128 v[174:177], v149
	ds_read_b128 v[178:181], v150
	s_add_u32 s18, s16, 0x100
	s_addc_u32 s19, s17, 0
	s_cmp_eq_u32 s10, 12
	s_cselect_b32 s29, s5, s19
	s_cselect_b32 s28, s4, s18
	s_cselect_b32 s21, s1, s63
	s_cselect_b32 s20, s0, s62
	s_mov_b32 m0, s55
	ds_read_b128 v[182:185], v145
	ds_read_b128 v[186:189], v145 offset:1024
	ds_read_b128 v[190:193], v145 offset:2048
	ds_read_b128 v[194:197], v145 offset:3072
	ds_read_b128 v[198:201], v145 offset:4096
	ds_read_b128 v[202:205], v145 offset:5120
	ds_read_b128 v[206:209], v145 offset:6144
	ds_read_b128 v[210:213], v145 offset:7168
	global_load_lds_dwordx4 v132, s[16:17]
	s_mov_b32 m0, s56
	s_nop 0
	global_load_lds_dwordx4 v134, s[16:17]
	s_waitcnt lgkmcnt(8)
	s_barrier
	s_waitcnt lgkmcnt(0)
	s_setprio 1
	s_waitcnt lgkmcnt(0)
	v_mfma_f32_16x16x32_bf16 v[124:127], v[140:143], v[182:185], v[124:127]
	v_mfma_f32_16x16x32_bf16 v[120:123], v[174:177], v[182:185], v[120:123]
	v_mfma_f32_16x16x32_bf16 v[108:111], v[140:143], v[190:193], v[108:111]
	v_mfma_f32_16x16x32_bf16 v[104:107], v[174:177], v[190:193], v[104:107]
	v_mfma_f32_16x16x32_bf16 v[92:95], v[140:143], v[198:201], v[92:95]
	v_mfma_f32_16x16x32_bf16 v[88:91], v[174:177], v[198:201], v[88:91]
	v_mfma_f32_16x16x32_bf16 v[76:79], v[140:143], v[206:209], v[76:79]
	v_mfma_f32_16x16x32_bf16 v[72:75], v[174:177], v[206:209], v[72:75]
	v_mfma_f32_16x16x32_bf16 v[124:127], v[170:173], v[186:189], v[124:127]
	v_mfma_f32_16x16x32_bf16 v[120:123], v[178:181], v[186:189], v[120:123]
	v_mfma_f32_16x16x32_bf16 v[108:111], v[170:173], v[194:197], v[108:111]
	v_mfma_f32_16x16x32_bf16 v[104:107], v[178:181], v[194:197], v[104:107]
	v_mfma_f32_16x16x32_bf16 v[92:95], v[170:173], v[202:205], v[92:95]
	v_mfma_f32_16x16x32_bf16 v[88:91], v[178:181], v[202:205], v[88:91]
	v_mfma_f32_16x16x32_bf16 v[76:79], v[170:173], v[210:213], v[76:79]
	v_mfma_f32_16x16x32_bf16 v[72:75], v[178:181], v[210:213], v[72:75]
	s_setprio 0
	s_barrier
	s_mov_b32 m0, s37
	s_nop 0
	global_load_lds_dwordx4 v130, s[20:21]
	s_mov_b32 m0, s40
	s_nop 0
	global_load_lds_dwordx4 v128, s[20:21]
	s_barrier
	s_waitcnt lgkmcnt(0)
	s_setprio 1
	s_waitcnt lgkmcnt(0)
	s_setprio 0
	s_mov_b32 m0, s34
	s_barrier
	ds_read_b128 v[182:185], v145 offset:16384
	ds_read_b128 v[186:189], v145 offset:17408
	ds_read_b128 v[190:193], v145 offset:18432
	ds_read_b128 v[194:197], v145 offset:19456
	ds_read_b128 v[198:201], v145 offset:20480
	ds_read_b128 v[202:205], v145 offset:21504
	ds_read_b128 v[206:209], v145 offset:22528
	ds_read_b128 v[210:213], v145 offset:23552
	global_load_lds_dwordx4 v130, s[28:29]
	s_mov_b32 m0, s41
	s_nop 0
	global_load_lds_dwordx4 v128, s[28:29]
	s_barrier
	s_waitcnt lgkmcnt(0)
	s_setprio 1
	s_waitcnt lgkmcnt(0)
	v_mfma_f32_16x16x32_bf16 v[60:63], v[140:143], v[182:185], v[60:63]
	v_mfma_f32_16x16x32_bf16 v[56:59], v[174:177], v[182:185], v[56:59]
	v_mfma_f32_16x16x32_bf16 v[44:47], v[140:143], v[190:193], v[44:47]
	v_mfma_f32_16x16x32_bf16 v[40:43], v[174:177], v[190:193], v[40:43]
	v_mfma_f32_16x16x32_bf16 v[28:31], v[140:143], v[198:201], v[28:31]
	v_mfma_f32_16x16x32_bf16 v[24:27], v[174:177], v[198:201], v[24:27]
	v_mfma_f32_16x16x32_bf16 v[12:15], v[140:143], v[206:209], v[12:15]
	v_mfma_f32_16x16x32_bf16 v[8:11], v[174:177], v[206:209], v[8:11]
	v_mfma_f32_16x16x32_bf16 v[60:63], v[170:173], v[186:189], v[60:63]
	v_mfma_f32_16x16x32_bf16 v[56:59], v[178:181], v[186:189], v[56:59]
	v_mfma_f32_16x16x32_bf16 v[44:47], v[170:173], v[194:197], v[44:47]
	v_mfma_f32_16x16x32_bf16 v[40:43], v[178:181], v[194:197], v[40:43]
	v_mfma_f32_16x16x32_bf16 v[28:31], v[170:173], v[202:205], v[28:31]
	v_mfma_f32_16x16x32_bf16 v[24:27], v[178:181], v[202:205], v[24:27]
	v_mfma_f32_16x16x32_bf16 v[12:15], v[170:173], v[210:213], v[12:15]
	v_mfma_f32_16x16x32_bf16 v[8:11], v[178:181], v[210:213], v[8:11]
	s_setprio 0
	s_barrier
	s_add_u32 s16, s20, 0x44000
	s_addc_u32 s17, s21, 0
	s_mov_b32 m0, s42
	s_nop 0
	s_mov_b32 m0, s43
	s_nop 0
	s_waitcnt vmcnt(4)
	s_barrier
	s_setprio 1
	s_setprio 0
	s_barrier
	ds_read_b128 v[140:143], v155
	ds_read_b128 v[170:173], v156
	ds_read_b128 v[174:177], v157
	ds_read_b128 v[178:181], v165
	s_add_u32 s16, s28, 0x44000
	s_addc_u32 s17, s29, 0
	s_mov_b32 m0, s44
	ds_read_b128 v[182:185], v145 offset:32768
	ds_read_b128 v[186:189], v145 offset:33792
	ds_read_b128 v[190:193], v145 offset:34816
	ds_read_b128 v[194:197], v145 offset:35840
	ds_read_b128 v[198:201], v145 offset:36864
	ds_read_b128 v[202:205], v145 offset:37888
	ds_read_b128 v[206:209], v145 offset:38912
	ds_read_b128 v[210:213], v145 offset:39936
	global_load_lds_dwordx4 v130, s[16:17]
	s_mov_b32 m0, s45
	s_nop 0
	global_load_lds_dwordx4 v128, s[16:17]
	s_waitcnt lgkmcnt(8)
	s_barrier
	s_waitcnt lgkmcnt(0)
	s_setprio 1
	s_waitcnt lgkmcnt(0)
	v_mfma_f32_16x16x32_bf16 v[124:127], v[140:143], v[182:185], v[124:127]
	v_mfma_f32_16x16x32_bf16 v[120:123], v[174:177], v[182:185], v[120:123]
	v_mfma_f32_16x16x32_bf16 v[108:111], v[140:143], v[190:193], v[108:111]
	v_mfma_f32_16x16x32_bf16 v[104:107], v[174:177], v[190:193], v[104:107]
	v_mfma_f32_16x16x32_bf16 v[92:95], v[140:143], v[198:201], v[92:95]
	v_mfma_f32_16x16x32_bf16 v[88:91], v[174:177], v[198:201], v[88:91]
	v_mfma_f32_16x16x32_bf16 v[76:79], v[140:143], v[206:209], v[76:79]
	v_mfma_f32_16x16x32_bf16 v[72:75], v[174:177], v[206:209], v[72:75]
	v_mfma_f32_16x16x32_bf16 v[124:127], v[170:173], v[186:189], v[124:127]
	v_mfma_f32_16x16x32_bf16 v[120:123], v[178:181], v[186:189], v[120:123]
	v_mfma_f32_16x16x32_bf16 v[108:111], v[170:173], v[194:197], v[108:111]
	v_mfma_f32_16x16x32_bf16 v[104:107], v[178:181], v[194:197], v[104:107]
	v_mfma_f32_16x16x32_bf16 v[92:95], v[170:173], v[202:205], v[92:95]
	v_mfma_f32_16x16x32_bf16 v[88:91], v[178:181], v[202:205], v[88:91]
	v_mfma_f32_16x16x32_bf16 v[76:79], v[170:173], v[210:213], v[76:79]
	v_mfma_f32_16x16x32_bf16 v[72:75], v[178:181], v[210:213], v[72:75]
	s_setprio 0
	s_barrier
; #define PG8_STAGE(bufoff, gbase, voff) do { _Pragma("unroll") for (int _i = 0; _i < 2; ++_i) \
;         __builtin_amdgcn_global_load_lds((const unsigned*)((const char*)(gbase) + (voff)[_i]), (PG8_LAS unsigned*)(lds + (bufoff) + ldsw + _i * 8192), 16, 0, 0); } while (0)
; #define PG8_LDA(dst, b, h) do { _Pragma("unroll") for (int m = 0; m < 4; ++m) _Pragma("unroll") for (int k = 0; k < 2; ++k) dst[m][k] = *(const PG8_LAS bf16x8*)(lds + PG8_SA(b, h) + aoff + m * 2048 + k * 1024); } while (0)
; #define PG8_LDB(dst, b, h) do { _Pragma("unroll") for (int n = 0; n < 2; ++n) _Pragma("unroll") for (int k = 0; k < 2; ++k) dst[n][k] = *(const PG8_LAS bf16x8*)(lds + PG8_SB(b, h) + boff + n * 2048 + k * 1024); } while (0)
; #define PG8_MMA(ai, bj, At, Bt) do { __builtin_amdgcn_s_setprio(1); _Pragma("unroll") for (int m = 0; m < 4; ++m) _Pragma("unroll") for (int n = 0; n < 2; ++n) _Pragma("unroll") for (int k = 0; k < 2; ++k) \
;         acc[ai][bj][m][n] = __builtin_amdgcn_mfma_f32_16x16x32_bf16(Bt[n][k], At[m][k], acc[ai][bj][m][n], 0, 0, 0); __builtin_amdgcn_s_setprio(0); } while (0)
; #define PG8_WAIT_V(n) asm volatile("s_waitcnt vmcnt(" #n ")" ::: "memory")
; #define PG8_WAIT_L(n) asm volatile("s_waitcnt lgkmcnt(" #n ")" ::: "memory")
; #define PG8_BAR __builtin_amdgcn_s_barrier()
; #define PG8_SCHED __builtin_amdgcn_sched_barrier(0)
; template <class Epi, class Sched, bool STAMP = false>
; __device__ __forceinline__ void gemm_phase(PG8_LAS unsigned char* lds, const Gemm g, const Sched& S, const Epi& E, unsigned long long* stamps) {
;     ...
;             PG8_LDB(B0, 1, 0); PG8_SCHED; PG8_LDA(At, 1, 0); PG8_STAGE(PG8_SA(0, 1), a2 + hstep, voffA);
;             PG8_WAIT_L(8); PG8_BAR; PG8_WAIT_L(0); PG8_MMA(0, 0, At, B0); PG8_BAR; PG8_SCHED;
;             PG8_LDB(B1, 1, 1); PG8_STAGE(PG8_SB(1, 0), b3, voffB);
;             PG8_BAR; PG8_WAIT_L(0); PG8_MMA(0, 1, At, B1); PG8_BAR;
;             PG8_LDA(At, 1, 1); PG8_STAGE(PG8_SA(1, 0), a3, voffA);
;             PG8_BAR; PG8_WAIT_L(0); PG8_MMA(1, 0, At, B0); PG8_BAR; PG8_SCHED;
;             PG8_STAGE(PG8_SB(1, 1), b3 + hstep, voffB);
;             PG8_WAIT_V(6); PG8_BAR; PG8_MMA(1, 1, At, B1); PG8_BAR;
;         }
	s_mov_b32 m0, s48
	s_add_u32 s100, s20, 0x80
	s_addc_u32 s101, s21, 0
	global_load_lds_dwordx4 v130, s[100:101]
	s_mov_b32 m0, s49
	s_nop 0
	global_load_lds_dwordx4 v128, s[100:101]
	s_barrier
	s_waitcnt lgkmcnt(0)
	s_setprio 1
	s_waitcnt lgkmcnt(0)
	s_setprio 0
	s_mov_b32 m0, s50
	s_barrier
	ds_read_b128 v[182:185], v145 offset:49152
	ds_read_b128 v[186:189], v145 offset:50176
	ds_read_b128 v[190:193], v145 offset:51200
	ds_read_b128 v[194:197], v145 offset:52224
	ds_read_b128 v[198:201], v145 offset:53248
	ds_read_b128 v[202:205], v145 offset:54272
	ds_read_b128 v[206:209], v145 offset:55296
	ds_read_b128 v[210:213], v145 offset:56320
	s_add_u32 s100, s28, 0x80
	s_addc_u32 s101, s29, 0
	global_load_lds_dwordx4 v130, s[100:101]
	s_mov_b32 m0, s51
	s_nop 0
	global_load_lds_dwordx4 v128, s[100:101]
	s_barrier
	s_waitcnt lgkmcnt(0)
	s_setprio 1
	s_waitcnt lgkmcnt(0)
	v_mfma_f32_16x16x32_bf16 v[60:63], v[140:143], v[182:185], v[60:63]
	v_mfma_f32_16x16x32_bf16 v[56:59], v[174:177], v[182:185], v[56:59]
	v_mfma_f32_16x16x32_bf16 v[44:47], v[140:143], v[190:193], v[44:47]
	v_mfma_f32_16x16x32_bf16 v[40:43], v[174:177], v[190:193], v[40:43]
	v_mfma_f32_16x16x32_bf16 v[28:31], v[140:143], v[198:201], v[28:31]
	v_mfma_f32_16x16x32_bf16 v[24:27], v[174:177], v[198:201], v[24:27]
	v_mfma_f32_16x16x32_bf16 v[12:15], v[140:143], v[206:209], v[12:15]
	v_mfma_f32_16x16x32_bf16 v[8:11], v[174:177], v[206:209], v[8:11]
	v_mfma_f32_16x16x32_bf16 v[60:63], v[170:173], v[186:189], v[60:63]
	v_mfma_f32_16x16x32_bf16 v[56:59], v[178:181], v[186:189], v[56:59]
	v_mfma_f32_16x16x32_bf16 v[44:47], v[170:173], v[194:197], v[44:47]
	v_mfma_f32_16x16x32_bf16 v[40:43], v[178:181], v[194:197], v[40:43]
	v_mfma_f32_16x16x32_bf16 v[28:31], v[170:173], v[202:205], v[28:31]
	v_mfma_f32_16x16x32_bf16 v[24:27], v[178:181], v[202:205], v[24:27]
	v_mfma_f32_16x16x32_bf16 v[12:15], v[170:173], v[210:213], v[12:15]
	v_mfma_f32_16x16x32_bf16 v[8:11], v[178:181], v[210:213], v[8:11]
	s_setprio 0
	s_barrier
	s_add_u32 s16, s20, 0x44080
	s_addc_u32 s17, s21, 0
	s_mov_b32 m0, s52
	s_nop 0
	s_mov_b32 m0, s53
	s_nop 0
	s_add_i32 s10, s10, 2
	s_add_u32 s62, s62, 0x100
	s_addc_u32 s63, s63, 0
	s_cmp_gt_u32 s10, 13
	s_mov_b64 s[16:17], s[18:19]
	s_waitcnt vmcnt(4)
	s_barrier
	s_setprio 1
	s_setprio 0
	s_barrier
	s_cbranch_scc0 .Lgu4_half_loop
; DI float ex2(float x) { return __builtin_amdgcn_exp2f(x); }
;     DI void operator()(const f32x4 (&acc)[2][2][4][2], const Unit& u, int wr, int wc, int fr, int fq) const {
;         const int row0 = u.pm * BM + wr * 64 + fr, hcol0 = ((u.pn * BM + wc * 32) >> 1) + 4 * fq;
; #pragma unroll
;         for (int ai = 0; ai < 2; ++ai)
; #pragma unroll
;             for (int m = 0; m < 4; ++m) { u16* rowp = O + (size_t)(row0 + ai * HALF + m * 16) * ldc + hcol0;
; #pragma unroll
;                 for (int bj = 0; bj < 2; ++bj) { const f32x4 g = acc[ai][bj][m][0], up = acc[ai][bj][m][1]; float r[4];
; #pragma unroll
;                     for (int j = 0; j < 4; ++j) r[j] = g[j] * up[j] * __builtin_amdgcn_rcpf(1.f + ex2(-LOG2E * g[j]));
;                     uint2 w = {pack2(r[0], r[1]), pack2(r[2], r[3])}; *(uint2*)(rowp + bj * (HALF / 2)) = w; } }
	v_exp_f32_e64 v171, -v124
	v_exp_f32_e64 v175, -v125
	s_lshl_b32 s10, s61, 8
	v_add_f32_e32 v171, 1.0, v171
	v_rcp_f32_e32 v174, v171
	v_add_f32_e32 v171, 1.0, v175
	v_exp_f32_e64 v176, -v126
	v_exp_f32_e64 v177, -v127
	v_rcp_f32_e32 v175, v171
	v_add_f32_e32 v171, 1.0, v176
	v_rcp_f32_e32 v176, v171
	v_add_f32_e32 v171, 1.0, v177
	v_rcp_f32_e32 v177, v171
	v_pk_mul_f32 v[122:123], v[126:127], v[122:123]
	v_pk_mul_f32 v[120:121], v[124:125], v[120:121]
	s_or_b32 s10, s10, s47
	s_or_b32 s10, s10, s98
	v_pk_mul_f32 v[120:121], v[120:121], v[174:175]
	v_pk_mul_f32 v[122:123], v[122:123], v[176:177]
	s_ashr_i32 s10, s10, 1
	v_cvt_pk_bf16_f32 v120, v120, v121
	v_cvt_pk_bf16_f32 v121, v122, v123
	v_or_b32_e32 v140, s10, v146
	v_lshl_add_u32 v170, s60, 8, v144
	v_ashrrev_i32_e32 v141, 31, v140
	v_mov_b64_e32 v[142:143], s[12:13]
	v_mad_i64_i32 v[172:173], s[16:17], v170, s57, v[142:143]
	v_lshlrev_b64 v[140:141], 1, v[140:141]
	v_lshl_add_u64 v[172:173], v[172:173], 0, v[140:141]
	global_store_dwordx2 v[172:173], v[120:121], off
	v_exp_f32_e64 v114, -v108
	v_exp_f32_e64 v115, -v109
	v_exp_f32_e64 v116, -v110
	v_exp_f32_e64 v117, -v111
	v_add_f32_e32 v114, 1.0, v114
	v_add_f32_e32 v115, 1.0, v115
	v_add_f32_e32 v116, 1.0, v116
	v_add_f32_e32 v117, 1.0, v117
	v_rcp_f32_e32 v114, v114
	v_rcp_f32_e32 v115, v115
	v_rcp_f32_e32 v116, v116
	v_rcp_f32_e32 v117, v117
	v_pk_mul_f32 v[106:107], v[110:111], v[106:107]
	v_pk_mul_f32 v[104:105], v[108:109], v[104:105]
	v_pk_mul_f32 v[104:105], v[104:105], v[114:115]
	v_pk_mul_f32 v[106:107], v[106:107], v[116:117]
	v_cvt_pk_bf16_f32 v104, v104, v105
	v_cvt_pk_bf16_f32 v105, v106, v107
	v_or_b32_e32 v112, 16, v170
	v_mad_i64_i32 v[112:113], s[16:17], v112, s57, v[142:143]
	v_lshl_add_u64 v[112:113], v[112:113], 0, v[140:141]
	global_store_dwordx2 v[112:113], v[104:105], off
	v_exp_f32_e64 v98, -v92
	v_exp_f32_e64 v99, -v93
	v_exp_f32_e64 v100, -v94
	v_exp_f32_e64 v101, -v95
	v_add_f32_e32 v98, 1.0, v98
	v_add_f32_e32 v99, 1.0, v99
	v_add_f32_e32 v100, 1.0, v100
	v_add_f32_e32 v101, 1.0, v101
	v_rcp_f32_e32 v98, v98
	v_rcp_f32_e32 v99, v99
	v_rcp_f32_e32 v100, v100
	v_rcp_f32_e32 v101, v101
	v_pk_mul_f32 v[90:91], v[94:95], v[90:91]
	v_pk_mul_f32 v[88:89], v[92:93], v[88:89]
	v_pk_mul_f32 v[88:89], v[88:89], v[98:99]
	v_pk_mul_f32 v[90:91], v[90:91], v[100:101]
	v_cvt_pk_bf16_f32 v88, v88, v89
	v_cvt_pk_bf16_f32 v89, v90, v91
	v_or_b32_e32 v96, 32, v170
	v_mad_i64_i32 v[96:97], s[16:17], v96, s57, v[142:143]
	v_lshl_add_u64 v[96:97], v[96:97], 0, v[140:141]
	global_store_dwordx2 v[96:97], v[88:89], off
	v_exp_f32_e64 v82, -v76
	v_exp_f32_e64 v83, -v77
	v_exp_f32_e64 v84, -v78
	v_exp_f32_e64 v85, -v79
	v_add_f32_e32 v82, 1.0, v82
	v_add_f32_e32 v83, 1.0, v83
	v_add_f32_e32 v84, 1.0, v84
	v_add_f32_e32 v85, 1.0, v85
	v_rcp_f32_e32 v82, v82
	v_rcp_f32_e32 v83, v83
	v_rcp_f32_e32 v84, v84
	v_rcp_f32_e32 v85, v85
	v_pk_mul_f32 v[74:75], v[78:79], v[74:75]
	v_pk_mul_f32 v[72:73], v[76:77], v[72:73]
	v_pk_mul_f32 v[72:73], v[72:73], v[82:83]
	v_pk_mul_f32 v[74:75], v[74:75], v[84:85]
	v_cvt_pk_bf16_f32 v72, v72, v73
	v_cvt_pk_bf16_f32 v73, v74, v75
	v_or_b32_e32 v80, 48, v170
	v_mad_i64_i32 v[80:81], s[16:17], v80, s57, v[142:143]
	v_lshl_add_u64 v[80:81], v[80:81], 0, v[140:141]
	global_store_dwordx2 v[80:81], v[72:73], off
	v_exp_f32_e64 v66, -v60
	v_exp_f32_e64 v67, -v61
	v_exp_f32_e64 v68, -v62
	v_exp_f32_e64 v69, -v63
	v_add_f32_e32 v66, 1.0, v66
	v_add_f32_e32 v67, 1.0, v67
	v_add_f32_e32 v68, 1.0, v68
	v_add_f32_e32 v69, 1.0, v69
	v_rcp_f32_e32 v66, v66
	v_rcp_f32_e32 v67, v67
	v_rcp_f32_e32 v68, v68
	v_rcp_f32_e32 v69, v69
	v_pk_mul_f32 v[58:59], v[62:63], v[58:59]
	v_pk_mul_f32 v[56:57], v[60:61], v[56:57]
	v_pk_mul_f32 v[56:57], v[56:57], v[66:67]
	v_pk_mul_f32 v[58:59], v[58:59], v[68:69]
	v_cvt_pk_bf16_f32 v56, v56, v57
	v_cvt_pk_bf16_f32 v57, v58, v59
	v_add_u32_e32 v64, 0x80, v170
	v_mad_i64_i32 v[64:65], s[16:17], v64, s57, v[142:143]
	v_lshl_add_u64 v[64:65], v[64:65], 0, v[140:141]
	global_store_dwordx2 v[64:65], v[56:57], off
	v_exp_f32_e64 v50, -v44
	v_exp_f32_e64 v51, -v45
	v_exp_f32_e64 v52, -v46
	v_exp_f32_e64 v53, -v47
	v_add_f32_e32 v50, 1.0, v50
	v_add_f32_e32 v51, 1.0, v51
	v_add_f32_e32 v52, 1.0, v52
	v_add_f32_e32 v53, 1.0, v53
	v_rcp_f32_e32 v50, v50
	v_rcp_f32_e32 v51, v51
	v_rcp_f32_e32 v52, v52
	v_rcp_f32_e32 v53, v53
	v_pk_mul_f32 v[42:43], v[46:47], v[42:43]
	v_pk_mul_f32 v[40:41], v[44:45], v[40:41]
	v_pk_mul_f32 v[40:41], v[40:41], v[50:51]
	v_pk_mul_f32 v[42:43], v[42:43], v[52:53]
	v_cvt_pk_bf16_f32 v40, v40, v41
	v_cvt_pk_bf16_f32 v41, v42, v43
	v_add_u32_e32 v48, 0x90, v170
	v_mad_i64_i32 v[48:49], s[16:17], v48, s57, v[142:143]
	v_lshl_add_u64 v[48:49], v[48:49], 0, v[140:141]
	global_store_dwordx2 v[48:49], v[40:41], off
	v_exp_f32_e64 v34, -v28
	v_exp_f32_e64 v35, -v29
	v_exp_f32_e64 v36, -v30
	v_exp_f32_e64 v37, -v31
	v_add_f32_e32 v34, 1.0, v34
	v_add_f32_e32 v35, 1.0, v35
	v_add_f32_e32 v36, 1.0, v36
	v_add_f32_e32 v37, 1.0, v37
	v_rcp_f32_e32 v34, v34
	v_rcp_f32_e32 v35, v35
	v_rcp_f32_e32 v36, v36
	v_rcp_f32_e32 v37, v37
	v_pk_mul_f32 v[26:27], v[30:31], v[26:27]
	v_pk_mul_f32 v[24:25], v[28:29], v[24:25]
	v_pk_mul_f32 v[24:25], v[24:25], v[34:35]
	v_pk_mul_f32 v[26:27], v[26:27], v[36:37]
	v_cvt_pk_bf16_f32 v24, v24, v25
	v_cvt_pk_bf16_f32 v25, v26, v27
	v_add_u32_e32 v32, 0xa0, v170
	v_mad_i64_i32 v[32:33], s[16:17], v32, s57, v[142:143]
	v_lshl_add_u64 v[32:33], v[32:33], 0, v[140:141]
	global_store_dwordx2 v[32:33], v[24:25], off
	v_exp_f32_e64 v18, -v12
	v_exp_f32_e64 v19, -v13
	v_exp_f32_e64 v20, -v14
	v_exp_f32_e64 v21, -v15
	v_add_f32_e32 v18, 1.0, v18
	v_add_f32_e32 v19, 1.0, v19
	v_add_f32_e32 v20, 1.0, v20
	v_add_f32_e32 v21, 1.0, v21
	v_rcp_f32_e32 v18, v18
	v_rcp_f32_e32 v19, v19
	v_rcp_f32_e32 v20, v20
	v_rcp_f32_e32 v21, v21
	v_pk_mul_f32 v[10:11], v[14:15], v[10:11]
	v_pk_mul_f32 v[8:9], v[12:13], v[8:9]
	v_pk_mul_f32 v[8:9], v[8:9], v[18:19]
	v_pk_mul_f32 v[10:11], v[10:11], v[20:21]
	v_cvt_pk_bf16_f32 v8, v8, v9
	v_cvt_pk_bf16_f32 v9, v10, v11
	v_add_u32_e32 v16, 0xb0, v170
	v_mad_i64_i32 v[16:17], s[16:17], v16, s57, v[142:143]
	v_lshl_add_u64 v[16:17], v[16:17], 0, v[140:141]
	global_store_dwordx2 v[16:17], v[8:9], off
	s_and_b64 vcc, exec, s[2:3]
	s_mov_b32 s61, s58
	s_mov_b32 s60, s59
	s_mov_b64 s[18:19], s[0:1]
	s_mov_b64 s[16:17], s[4:5]

; #define PG8_STAGE(bufoff, gbase, voff) do { _Pragma("unroll") for (int _i = 0; _i < 2; ++_i) \
;         __builtin_amdgcn_global_load_lds((const unsigned*)((const char*)(gbase) + (voff)[_i]), (PG8_LAS unsigned*)(lds + (bufoff) + ldsw + _i * 8192), 16, 0, 0); } while (0)
; #define PG8_LDA(dst, b, h) do { _Pragma("unroll") for (int m = 0; m < 4; ++m) _Pragma("unroll") for (int k = 0; k < 2; ++k) dst[m][k] = *(const PG8_LAS bf16x8*)(lds + PG8_SA(b, h) + aoff + m * 2048 + k * 1024); } while (0)
; #define PG8_LDB(dst, b, h) do { _Pragma("unroll") for (int n = 0; n < 2; ++n) _Pragma("unroll") for (int k = 0; k < 2; ++k) dst[n][k] = *(const PG8_LAS bf16x8*)(lds + PG8_SB(b, h) + boff + n * 2048 + k * 1024); } while (0)
; #define PG8_MMA(ai, bj, At, Bt) do { __builtin_amdgcn_s_setprio(1); _Pragma("unroll") for (int m = 0; m < 4; ++m) _Pragma("unroll") for (int n = 0; n < 2; ++n) _Pragma("unroll") for (int k = 0; k < 2; ++k) \
;         acc[ai][bj][m][n] = __builtin_amdgcn_mfma_f32_16x16x32_bf16(Bt[n][k], At[m][k], acc[ai][bj][m][n], 0, 0, 0); __builtin_amdgcn_s_setprio(0); } while (0)
; #define PG8_WAIT_V(n) asm volatile("s_waitcnt vmcnt(" #n ")" ::: "memory")
; #define PG8_WAIT_L(n) asm volatile("s_waitcnt lgkmcnt(" #n ")" ::: "memory")
; #define PG8_BAR __builtin_amdgcn_s_barrier()
; #define PG8_SCHED __builtin_amdgcn_sched_barrier(0)
; template <class Epi, class Sched, bool STAMP = false>
; __device__ __forceinline__ void gemm_phase(PG8_LAS unsigned char* lds, const Gemm g, const Sched& S, const Epi& E, unsigned long long* stamps) {
;     ...
;             PG8_LDB(B0, 1, 0); PG8_SCHED; PG8_LDA(At, 1, 0); PG8_STAGE(PG8_SA(0, 1), a2 + hstep, voffA);
;             PG8_WAIT_L(8); PG8_BAR; PG8_WAIT_L(0); PG8_MMA(0, 0, At, B0); PG8_BAR; PG8_SCHED;
;             PG8_LDB(B1, 1, 1); PG8_STAGE(PG8_SB(1, 0), b3, voffB);
;             PG8_BAR; PG8_WAIT_L(0); PG8_MMA(0, 1, At, B1); PG8_BAR;
;             PG8_LDA(At, 1, 1); PG8_STAGE(PG8_SA(1, 0), a3, voffA);
;             PG8_BAR; PG8_WAIT_L(0); PG8_MMA(1, 0, At, B0); PG8_BAR; PG8_SCHED;
;             PG8_STAGE(PG8_SB(1, 1), b3 + hstep, voffB);
;             PG8_WAIT_V(6); PG8_BAR; PG8_MMA(1, 1, At, B1); PG8_BAR;
.Lzp12_mid:
	ds_read_b128 v[170:173], v155
	ds_read_b128 v[174:177], v156
	ds_read_b128 v[178:181], v157
	ds_read_b128 v[182:185], v165
	s_add_u32 s28, s36, 0xb4000
	s_addc_u32 s29, s37, 0
	s_mov_b32 m0, s48
	ds_read_b128 v[186:189], v145 offset:32768
	ds_read_b128 v[190:193], v145 offset:33792
	ds_read_b128 v[194:197], v145 offset:34816
	ds_read_b128 v[198:201], v145 offset:35840
	ds_read_b128 v[202:205], v145 offset:36864
	ds_read_b128 v[206:209], v145 offset:37888
	ds_read_b128 v[210:213], v145 offset:38912
	ds_read_b128 v[214:217], v145 offset:39936
	global_load_lds_dwordx4 v128, s[28:29]
	s_mov_b32 m0, s49
	s_nop 0
	global_load_lds_dwordx4 v132, s[28:29]
	s_waitcnt lgkmcnt(8)
	s_barrier
	s_waitcnt lgkmcnt(0)
	s_setprio 1
	s_waitcnt lgkmcnt(0)
	v_mfma_f32_16x16x32_bf16 v[124:127], v[170:173], v[186:189], v[124:127]
	v_mfma_f32_16x16x32_bf16 v[120:123], v[178:181], v[186:189], v[120:123]
	v_mfma_f32_16x16x32_bf16 v[116:119], v[170:173], v[194:197], v[116:119]
	v_mfma_f32_16x16x32_bf16 v[112:115], v[178:181], v[194:197], v[112:115]
	v_mfma_f32_16x16x32_bf16 v[100:103], v[170:173], v[202:205], v[100:103]
	v_mfma_f32_16x16x32_bf16 v[96:99], v[178:181], v[202:205], v[96:99]
	v_mfma_f32_16x16x32_bf16 v[84:87], v[170:173], v[210:213], v[84:87]
	v_mfma_f32_16x16x32_bf16 v[80:83], v[178:181], v[210:213], v[80:83]
	v_mfma_f32_16x16x32_bf16 v[124:127], v[174:177], v[190:193], v[124:127]
	v_mfma_f32_16x16x32_bf16 v[120:123], v[182:185], v[190:193], v[120:123]
	v_mfma_f32_16x16x32_bf16 v[116:119], v[174:177], v[198:201], v[116:119]
	v_mfma_f32_16x16x32_bf16 v[112:115], v[182:185], v[198:201], v[112:115]
	v_mfma_f32_16x16x32_bf16 v[100:103], v[174:177], v[206:209], v[100:103]
	v_mfma_f32_16x16x32_bf16 v[96:99], v[182:185], v[206:209], v[96:99]
	v_mfma_f32_16x16x32_bf16 v[84:87], v[174:177], v[214:217], v[84:87]
	v_mfma_f32_16x16x32_bf16 v[80:83], v[182:185], v[214:217], v[80:83]
	s_setprio 0
	s_barrier
	s_mov_b32 m0, s50
	ds_read_b128 v[218:221], v166
	ds_read_b128 v[222:225], v167
	ds_read_b128 v[226:229], v168
	ds_read_b128 v[230:233], v169
	s_add_u32 s100, s34, 0x80
	s_addc_u32 s101, s35, 0
	global_load_lds_dwordx4 v130, s[100:101]
	s_mov_b32 m0, s51
	s_nop 0
	global_load_lds_dwordx4 v134, s[100:101]
	s_barrier
	s_waitcnt lgkmcnt(0)
	s_setprio 1
	s_waitcnt lgkmcnt(0)
	v_mfma_f32_16x16x32_bf16 v[108:111], v[218:221], v[186:189], v[108:111]
	v_mfma_f32_16x16x32_bf16 v[104:107], v[226:229], v[186:189], v[104:107]
	v_mfma_f32_16x16x32_bf16 v[92:95], v[218:221], v[194:197], v[92:95]
	v_mfma_f32_16x16x32_bf16 v[88:91], v[226:229], v[194:197], v[88:91]
	v_mfma_f32_16x16x32_bf16 v[76:79], v[218:221], v[202:205], v[76:79]
	v_mfma_f32_16x16x32_bf16 v[72:75], v[226:229], v[202:205], v[72:75]
	v_mfma_f32_16x16x32_bf16 v[68:71], v[218:221], v[210:213], v[68:71]
	v_mfma_f32_16x16x32_bf16 v[64:67], v[226:229], v[210:213], v[64:67]
	v_mfma_f32_16x16x32_bf16 v[108:111], v[222:225], v[190:193], v[108:111]
	v_mfma_f32_16x16x32_bf16 v[104:107], v[230:233], v[190:193], v[104:107]
	v_mfma_f32_16x16x32_bf16 v[92:95], v[222:225], v[198:201], v[92:95]
	v_mfma_f32_16x16x32_bf16 v[88:91], v[230:233], v[198:201], v[88:91]
	v_mfma_f32_16x16x32_bf16 v[76:79], v[222:225], v[206:209], v[76:79]
	v_mfma_f32_16x16x32_bf16 v[72:75], v[230:233], v[206:209], v[72:75]
	v_mfma_f32_16x16x32_bf16 v[68:71], v[222:225], v[214:217], v[68:71]
	v_mfma_f32_16x16x32_bf16 v[64:67], v[230:233], v[214:217], v[64:67]
	s_setprio 0
	s_mov_b32 m0, s52
	s_barrier
	ds_read_b128 v[186:189], v145 offset:49152
	ds_read_b128 v[190:193], v145 offset:50176
	ds_read_b128 v[194:197], v145 offset:51200
	ds_read_b128 v[198:201], v145 offset:52224
	ds_read_b128 v[202:205], v145 offset:53248
	ds_read_b128 v[206:209], v145 offset:54272
	ds_read_b128 v[210:213], v145 offset:55296
	ds_read_b128 v[214:217], v145 offset:56320
	s_add_u32 s100, s36, 0x80
	s_addc_u32 s101, s37, 0
	global_load_lds_dwordx4 v128, s[100:101]
	s_mov_b32 m0, s53
	s_nop 0
	global_load_lds_dwordx4 v132, s[100:101]
	s_barrier
	s_waitcnt lgkmcnt(0)
	s_setprio 1
	s_waitcnt lgkmcnt(0)
	v_mfma_f32_16x16x32_bf16 v[60:63], v[170:173], v[186:189], v[60:63]
	v_mfma_f32_16x16x32_bf16 v[56:59], v[178:181], v[186:189], v[56:59]
	v_mfma_f32_16x16x32_bf16 v[52:55], v[170:173], v[194:197], v[52:55]
	v_mfma_f32_16x16x32_bf16 v[48:51], v[178:181], v[194:197], v[48:51]
	v_mfma_f32_16x16x32_bf16 v[36:39], v[170:173], v[202:205], v[36:39]
	v_mfma_f32_16x16x32_bf16 v[32:35], v[178:181], v[202:205], v[32:35]
	v_mfma_f32_16x16x32_bf16 v[20:23], v[170:173], v[210:213], v[20:23]
	v_mfma_f32_16x16x32_bf16 v[16:19], v[178:181], v[210:213], v[16:19]
	v_mfma_f32_16x16x32_bf16 v[60:63], v[174:177], v[190:193], v[60:63]
	v_mfma_f32_16x16x32_bf16 v[56:59], v[182:185], v[190:193], v[56:59]
	v_mfma_f32_16x16x32_bf16 v[52:55], v[174:177], v[198:201], v[52:55]
	v_mfma_f32_16x16x32_bf16 v[48:51], v[182:185], v[198:201], v[48:51]
	v_mfma_f32_16x16x32_bf16 v[36:39], v[174:177], v[206:209], v[36:39]
	v_mfma_f32_16x16x32_bf16 v[32:35], v[182:185], v[206:209], v[32:35]
	v_mfma_f32_16x16x32_bf16 v[20:23], v[174:177], v[214:217], v[20:23]
	v_mfma_f32_16x16x32_bf16 v[16:19], v[182:185], v[214:217], v[16:19]
	s_setprio 0
	s_barrier
	s_add_u32 s28, s34, 0xb4080
	s_addc_u32 s29, s35, 0
	s_mov_b32 m0, s54
	s_nop 0
	global_load_lds_dwordx4 v130, s[28:29]
	s_mov_b32 m0, s55
	s_nop 0
	global_load_lds_dwordx4 v134, s[28:29]
	s_add_i32 s10, s10, 2
	s_add_u32 s68, s68, 0x100
	s_addc_u32 s69, s69, 0
	s_cmp_gt_u32 s10, 41
	s_mov_b64 s[28:29], s[30:31]
	s_waitcnt vmcnt(6)
	s_barrier
; #define PG8_STAMP() do { if (STAMP && wid == 0 && nts < 64) { const unsigned long long _c = 0ull; \
;         ts_lo = (lane == nts) ? (int)(unsigned)_c : ts_lo; ts_hi = (lane == nts) ? (int)(unsigned)(_c >> 32) : ts_hi; ++nts; } } while (0)
;     DI void operator()(const f32x4 (&acc)[2][2][4][2], const Unit& u, int wr, int wc, int fr, int fq) const {
;         const int row0 = u.pm * BM + wr * 64 + fr, col0 = u.pn * BM + wc * 32 + 8 * fq;
; #pragma unroll
;         for (int ai = 0; ai < 2; ++ai)
; #pragma unroll
;             for (int m = 0; m < 4; ++m) { u16* rowp = O + (size_t)(row0 + ai * HALF + m * 16) * ldc + col0;
; #pragma unroll
;                 for (int bj = 0; bj < 2; ++bj) { const f32x4 v0 = acc[ai][bj][m][0], v1 = acc[ai][bj][m][1];
;                     uint4 w = {pack2(v0[0], v0[1]), pack2(v0[2], v0[3]), pack2(v1[0], v1[1]), pack2(v1[2], v1[3])}; *(uint4*)(rowp + bj * HALF) = w; } }
; template <class Epi, class Sched, bool STAMP = false>
; __device__ __forceinline__ void gemm_phase(PG8_LAS unsigned char* lds, const Gemm g, const Sched& S, const Epi& E, unsigned long long* stamps) {
;     ...
;             PG8_WAIT_V(6); PG8_BAR; PG8_MMA(1, 1, At, B1); PG8_BAR;
;             PG8_LDB(B0, 1, 0); PG8_SCHED; PG8_LDA(At, 1, 0); PG8_STAGE(PG8_SA(0, 1), a2 + hstep, voffA);
;             PG8_WAIT_L(8); PG8_BAR; PG8_WAIT_L(0); PG8_MMA(0, 0, At, B0); PG8_BAR; PG8_SCHED;
;             PG8_LDB(B1, 1, 1); PG8_STAGE(PG8_SB(1, 0), b3, voffB);
;             PG8_BAR; PG8_WAIT_L(0); PG8_MMA(0, 1, At, B1); PG8_BAR;
;             PG8_LDA(At, 1, 1); PG8_STAGE(PG8_SA(1, 0), a3, voffA);
;             PG8_BAR; PG8_WAIT_L(0); PG8_MMA(1, 0, At, B0); PG8_BAR; PG8_SCHED;
;             PG8_STAGE(PG8_SB(1, 1), b3 + hstep, voffB);
;             PG8_WAIT_V(6); PG8_BAR; PG8_MMA(1, 1, At, B1); PG8_BAR;
;         }
;         PG8_STAMP();
;         if constexpr (!Epi::AFTER_DRAIN) { E(acc, cur, wr, wc, fr, fq); S.done(cur); }
;         PG8_STAMP();
;         if (!has_next) break;
; #pragma unroll
;         for (int a = 0; a < 2; ++a)
; #pragma unroll
;             for (int b = 0; b < 2; ++b)
; #pragma unroll
;                 for (int m = 0; m < 4; ++m)
; #pragma unroll
;                     for (int n = 0; n < 2; ++n) acc[a][b][m][n] = (f32x4){0.f, 0.f, 0.f, 0.f};
;         cur = nxt; cA = nA; cB = nB; ++ui;
;     }
;     PG8_WAIT_V(0);
;     if (wr == 0) PG8_BAR;
;     PG8_BAR;
	s_setprio 1
	v_mfma_f32_16x16x32_bf16 v[44:47], v[218:221], v[186:189], v[44:47]
	v_mfma_f32_16x16x32_bf16 v[40:43], v[226:229], v[186:189], v[40:43]
	v_mfma_f32_16x16x32_bf16 v[28:31], v[218:221], v[194:197], v[28:31]
	v_mfma_f32_16x16x32_bf16 v[24:27], v[226:229], v[194:197], v[24:27]
	v_mfma_f32_16x16x32_bf16 v[12:15], v[218:221], v[202:205], v[12:15]
	v_mfma_f32_16x16x32_bf16 v[8:11], v[226:229], v[202:205], v[8:11]
	v_mfma_f32_16x16x32_bf16 v[4:7], v[218:221], v[210:213], v[4:7]
	v_mfma_f32_16x16x32_bf16 v[0:3], v[226:229], v[210:213], v[0:3]
	v_mfma_f32_16x16x32_bf16 v[44:47], v[222:225], v[190:193], v[44:47]
	v_mfma_f32_16x16x32_bf16 v[40:43], v[230:233], v[190:193], v[40:43]
	v_mfma_f32_16x16x32_bf16 v[28:31], v[222:225], v[198:201], v[28:31]
	v_mfma_f32_16x16x32_bf16 v[24:27], v[230:233], v[198:201], v[24:27]
	v_mfma_f32_16x16x32_bf16 v[12:15], v[222:225], v[206:209], v[12:15]
	v_mfma_f32_16x16x32_bf16 v[8:11], v[230:233], v[206:209], v[8:11]
	v_mfma_f32_16x16x32_bf16 v[4:7], v[222:225], v[214:217], v[4:7]
	v_mfma_f32_16x16x32_bf16 v[0:3], v[230:233], v[214:217], v[0:3]
	s_setprio 0
	s_barrier
	s_cbranch_scc0 .LBB0_761
	v_lshl_add_u32 v170, s64, 8, v144
	v_lshl_or_b32 v172, s67, 8, v146
	v_ashrrev_i32_e32 v171, 31, v170
	v_ashrrev_i32_e32 v173, 31, v172
	v_lshlrev_b64 v[174:175], 11, v[170:171]
	v_lshl_add_u64 v[174:175], s[14:15], 0, v[174:175]
	v_lshlrev_b64 v[172:173], 1, v[172:173]
	v_lshl_add_u64 v[174:175], v[174:175], 0, v[172:173]
	v_cvt_pk_bf16_f32 v60, v60, v61
	v_cvt_pk_bf16_f32 v61, v62, v63
	v_cvt_pk_bf16_f32 v62, v56, v57
	v_add_co_u32_e32 v56, vcc, s60, v174
	v_cvt_pk_bf16_f32 v68, v68, v69
	v_cvt_pk_bf16_f32 v69, v70, v71
	v_cvt_pk_bf16_f32 v70, v64, v65
	v_lshl_add_u64 v[64:65], v[174:175], 0, s[16:17]
	v_addc_co_u32_e32 v57, vcc, 0, v175, vcc
	v_cvt_pk_bf16_f32 v44, v44, v45
	v_cvt_pk_bf16_f32 v45, v46, v47
	v_cvt_pk_bf16_f32 v46, v40, v41
	v_cvt_pk_bf16_f32 v47, v42, v43
	v_cvt_pk_bf16_f32 v108, v108, v109
	v_cvt_pk_bf16_f32 v109, v110, v111
	v_cvt_pk_bf16_f32 v110, v104, v105
	v_or_b32_e32 v104, 16, v170
	global_store_dwordx4 v[64:65], v[44:47], off offset:256
	v_ashrrev_i32_e32 v105, 31, v104
	v_cvt_pk_bf16_f32 v92, v92, v93
	v_add_co_u32_e32 v46, vcc, s61, v174
	v_cvt_pk_bf16_f32 v93, v94, v95
	v_cvt_pk_bf16_f32 v94, v88, v89
	v_or_b32_e32 v88, 32, v170
	v_lshl_add_u64 v[44:45], v[174:175], 0, s[18:19]
	v_addc_co_u32_e32 v47, vcc, 0, v175, vcc
	v_cvt_pk_bf16_f32 v28, v28, v29
	v_cvt_pk_bf16_f32 v29, v30, v31
	v_cvt_pk_bf16_f32 v30, v24, v25
	v_cvt_pk_bf16_f32 v31, v26, v27
	v_lshlrev_b64 v[104:105], 11, v[104:105]
	v_ashrrev_i32_e32 v89, 31, v88
	v_cvt_pk_bf16_f32 v76, v76, v77
	v_cvt_pk_bf16_f32 v77, v78, v79
	v_cvt_pk_bf16_f32 v78, v72, v73
	v_or_b32_e32 v72, 48, v170
	global_store_dwordx4 v[44:45], v[28:31], off offset:256
	v_cvt_pk_bf16_f32 v111, v106, v107
	v_lshl_add_u64 v[104:105], s[14:15], 0, v[104:105]
	v_add_co_u32_e32 v30, vcc, s62, v174
	v_lshlrev_b64 v[88:89], 11, v[88:89]
	v_ashrrev_i32_e32 v73, 31, v72
	v_lshl_add_u64 v[28:29], v[174:175], 0, s[20:21]
	v_addc_co_u32_e32 v31, vcc, 0, v175, vcc
	v_cvt_pk_bf16_f32 v12, v12, v13
	v_cvt_pk_bf16_f32 v13, v14, v15
	v_cvt_pk_bf16_f32 v14, v8, v9
	v_cvt_pk_bf16_f32 v15, v10, v11
	global_store_dwordx4 v[174:175], v[108:111], off offset:256
	v_cvt_pk_bf16_f32 v95, v90, v91
	v_lshl_add_u64 v[88:89], s[14:15], 0, v[88:89]
	v_lshl_add_u64 v[108:109], v[104:105], 0, v[172:173]
	v_lshlrev_b64 v[72:73], 11, v[72:73]
	global_store_dwordx4 v[28:29], v[12:15], off offset:256
	global_store_dwordx4 v[108:109], v[92:95], off offset:256
	v_cvt_pk_bf16_f32 v79, v74, v75
	v_add_co_u32_e32 v14, vcc, s63, v174
	v_lshl_add_u64 v[92:93], v[88:89], 0, v[172:173]
	v_lshl_add_u64 v[72:73], s[14:15], 0, v[72:73]
	v_addc_co_u32_e32 v15, vcc, 0, v175, vcc
	v_cvt_pk_bf16_f32 v124, v124, v125
	v_cvt_pk_bf16_f32 v125, v126, v127
	v_cvt_pk_bf16_f32 v126, v120, v121
	v_cvt_pk_bf16_f32 v127, v122, v123
	v_cvt_pk_bf16_f32 v104, v116, v117
	v_cvt_pk_bf16_f32 v105, v118, v119
	v_cvt_pk_bf16_f32 v106, v112, v113
	v_cvt_pk_bf16_f32 v107, v114, v115
	v_cvt_pk_bf16_f32 v88, v100, v101
	v_cvt_pk_bf16_f32 v89, v102, v103
	v_cvt_pk_bf16_f32 v90, v96, v97
	v_cvt_pk_bf16_f32 v91, v98, v99
	global_store_dwordx4 v[92:93], v[76:79], off offset:256
	v_cvt_pk_bf16_f32 v74, v80, v81
	v_cvt_pk_bf16_f32 v75, v82, v83
	v_lshl_add_u64 v[76:77], v[72:73], 0, v[172:173]
	v_cvt_pk_bf16_f32 v72, v84, v85
	v_cvt_pk_bf16_f32 v73, v86, v87
	v_cvt_pk_bf16_f32 v71, v66, v67
	v_cvt_pk_bf16_f32 v63, v58, v59
	v_cvt_pk_bf16_f32 v40, v52, v53
	v_cvt_pk_bf16_f32 v41, v54, v55
	v_cvt_pk_bf16_f32 v42, v48, v49
	v_cvt_pk_bf16_f32 v43, v50, v51
	v_cvt_pk_bf16_f32 v24, v36, v37
	v_cvt_pk_bf16_f32 v25, v38, v39
	v_cvt_pk_bf16_f32 v26, v32, v33
	v_cvt_pk_bf16_f32 v27, v34, v35
	v_lshl_add_u64 v[12:13], v[174:175], 0, s[26:27]
	v_cvt_pk_bf16_f32 v8, v20, v21
	v_cvt_pk_bf16_f32 v9, v22, v23
	v_cvt_pk_bf16_f32 v10, v16, v17
	v_cvt_pk_bf16_f32 v11, v18, v19
	v_cvt_pk_bf16_f32 v4, v4, v5
	v_cvt_pk_bf16_f32 v5, v6, v7
	v_cvt_pk_bf16_f32 v6, v0, v1
	v_cvt_pk_bf16_f32 v7, v2, v3
	s_and_b64 vcc, exec, s[2:3]
	s_mov_b32 s67, s65
	s_mov_b32 s64, s66
	s_mov_b64 s[30:31], s[0:1]
	s_mov_b64 s[28:29], s[4:5]
	global_store_dwordx4 v[174:175], v[124:127], off
	global_store_dwordx4 v[108:109], v[104:107], off
	global_store_dwordx4 v[92:93], v[88:91], off
	global_store_dwordx4 v[76:77], v[72:75], off
	global_store_dwordx4 v[76:77], v[68:71], off offset:256
	global_store_dwordx4 v[56:57], v[60:63], off
	global_store_dwordx4 v[46:47], v[40:43], off
	global_store_dwordx4 v[30:31], v[24:27], off
	global_store_dwordx4 v[14:15], v[8:11], off
	global_store_dwordx4 v[12:13], v[4:7], off offset:256
	s_cbranch_vccz .LBB0_750
	s_waitcnt vmcnt(0)
	s_cmpk_gt_u32 s40, 0xff
	s_cbranch_scc1 .LBB0_765
	s_barrier
